# stagemove
# speedup vs baseline: 1.0062x; 1.0062x over previous
; #define STAGE(P, BASE, LD, br, kt) do { const char* _g = (const char*)((BASE) + (size_t)(br) * (LD) + (size_t)(kt) * 64); \
;     for (int _i = 0; _i < 2; ++_i) { int _b = tidx * 16 + _i * 8192; int _r, _c; stage_rc(_b, _r, _c); \
;       __builtin_amdgcn_global_load_lds((const unsigned*)(_g + (unsigned)((_r * (LD) + _c) * 2)), (unsigned*)((char*)(P) + _b), 16, 0, 0); } } while (0)
; #define LDA(dst, b, h) for (int m = 0; m < 4; ++m) for (int k = 0; k < 2; ++k) \
;     dst[m][k] = *reinterpret_cast<const bf16x8*>((char*)SA(b, h) + lds_byte(wr * 64 + m * 16 + fr, k * 32 + fq * 8))
; #define LDB(dst, b, h) for (int n = 0; n < 2; ++n) for (int k = 0; k < 2; ++k) \
;     dst[n][k] = *reinterpret_cast<const bf16x8*>((char*)SB(b, h) + lds_byte(wc * 32 + n * 16 + fr, k * 32 + fq * 8))
; #define MMA(ai, bj, At_, Bt_) do { __builtin_amdgcn_s_setprio(1); \
;     for (int k = 0; k < 2; ++k) for (int m = 0; m < 4; ++m) for (int n = 0; n < 2; ++n) \
;       acc[ai][bj][m][n] = __builtin_amdgcn_mfma_f32_16x16x32_bf16(At_[m][k], Bt_[n][k], acc[ai][bj][m][n], 0, 0, 0); \
;     __builtin_amdgcn_s_setprio(0); } while (0)
; #define WAIT_L(n) asm volatile("s_waitcnt lgkmcnt(" #n ")" ::: "memory")
; #define BAR __builtin_amdgcn_s_barrier()
; #define SCHED __builtin_amdgcn_sched_barrier(0)
; template <int EPI, int lda, int ldb, int N, int K>
; __device__ __forceinline__ void gemm_phase(const u16* __restrict__ A, const u16* __restrict__ Bt, const GemmEpi ep, int wv) {
;     ...
;       LDB(B0, 0, 0); SCHED; LDA(At, 0, 0); STAGE(SA(1, 1), Ab, lda, brow + HALF, t + 1);
;       WAIT_L(8); BAR; WAIT_L(0); MMA(0, 0, At, B0); BAR; SCHED;
;       LDB(B1, 0, 1); STAGE(SB(0, 0), Bt, ldb, bcol, t + 2);
;       BAR; WAIT_L(0); MMA(0, 1, At, B1); BAR;
;       LDA(At, 0, 1); STAGE(SA(0, 0), Ab, lda, brow, t + 2);
;       BAR; WAIT_L(0); MMA(1, 0, At, B0); BAR; SCHED;
.LBB0_53:
	ds_read_b128 v[172:175], v161
	ds_read_b128 v[176:179], v161 offset:1024
	ds_read_b128 v[180:183], v161 offset:2048
	ds_read_b128 v[184:187], v161 offset:3072
	v_add_u32_e32 v169, 0xc000, v148
	v_lshl_add_u64 v[236:237], v[136:137], 0, s[42:43]
	v_readfirstlane_b32 s45, v169
	v_add_u32_e32 v170, 0xe000, v148
	v_lshl_add_u64 v[162:163], v[236:237], 0, s[14:15]
	s_mov_b32 m0, s45
	v_lshl_add_u64 v[238:239], v[134:135], 0, s[42:43]
	v_readfirstlane_b32 s45, v170
	ds_read_b128 v[164:167], v152
	ds_read_b128 v[188:191], v152 offset:1024
	ds_read_b128 v[192:195], v151
	ds_read_b128 v[196:199], v151 offset:1024
	ds_read_b128 v[200:203], v150
	ds_read_b128 v[204:207], v150 offset:1024
	ds_read_b128 v[208:211], v149
	ds_read_b128 v[212:215], v149 offset:1024
	global_load_lds_dwordx4 v[162:163], off
	s_waitcnt lgkmcnt(8)
	s_barrier
	s_waitcnt lgkmcnt(0)
	s_waitcnt lgkmcnt(0)
	v_mfma_f32_16x16x32_bf16 v[124:127], v[172:175], v[164:167], v[124:127]
	v_mfma_f32_16x16x32_bf16 v[120:123], v[180:183], v[164:167], v[120:123]
	v_mfma_f32_16x16x32_bf16 v[116:119], v[172:175], v[192:195], v[116:119]
	v_mfma_f32_16x16x32_bf16 v[112:115], v[180:183], v[192:195], v[112:115]
	v_mfma_f32_16x16x32_bf16 v[108:111], v[172:175], v[200:203], v[108:111]
	v_mfma_f32_16x16x32_bf16 v[104:107], v[180:183], v[200:203], v[104:107]
	v_mfma_f32_16x16x32_bf16 v[100:103], v[172:175], v[208:211], v[100:103]
	v_mfma_f32_16x16x32_bf16 v[96:99], v[180:183], v[208:211], v[96:99]
	v_lshl_add_u64 v[162:163], v[238:239], 0, s[14:15]
	s_mov_b32 m0, s45
	s_nop 0
	global_load_lds_dwordx4 v[162:163], off
	v_mfma_f32_16x16x32_bf16 v[124:127], v[176:179], v[188:191], v[124:127]
	v_mfma_f32_16x16x32_bf16 v[120:123], v[184:187], v[188:191], v[120:123]
	v_mfma_f32_16x16x32_bf16 v[116:119], v[176:179], v[196:199], v[116:119]
	v_mfma_f32_16x16x32_bf16 v[112:115], v[184:187], v[196:199], v[112:115]
	v_mfma_f32_16x16x32_bf16 v[108:111], v[176:179], v[204:207], v[108:111]
	v_mfma_f32_16x16x32_bf16 v[104:107], v[184:187], v[204:207], v[104:107]
	v_mfma_f32_16x16x32_bf16 v[100:103], v[176:179], v[212:215], v[100:103]
	v_mfma_f32_16x16x32_bf16 v[96:99], v[184:187], v[212:215], v[96:99]
	s_barrier
	v_add_u32_e32 v162, s54, v153
	v_lshl_add_u64 v[240:241], v[140:141], 0, s[42:43]
	v_readfirstlane_b32 s45, v162
	v_add_u32_e32 v163, 0x2000, v162
	v_lshl_add_u64 v[232:233], v[240:241], 0, s[16:17]
	s_mov_b32 m0, s45
	v_lshl_add_u64 v[242:243], v[138:139], 0, s[42:43]
	v_readfirstlane_b32 s45, v163
	ds_read_b128 v[216:219], v160
	ds_read_b128 v[220:223], v160 offset:1024
	ds_read_b128 v[224:227], v160 offset:2048
	ds_read_b128 v[228:231], v160 offset:3072
	global_load_lds_dwordx4 v[232:233], off
	v_lshl_add_u64 v[232:233], v[242:243], 0, s[16:17]
	s_mov_b32 m0, s45
	s_nop 0
	global_load_lds_dwordx4 v[232:233], off
	s_barrier
	s_waitcnt lgkmcnt(0)
	s_waitcnt lgkmcnt(0)
	v_mfma_f32_16x16x32_bf16 v[92:95], v[216:219], v[164:167], v[92:95]
	v_mfma_f32_16x16x32_bf16 v[88:91], v[224:227], v[164:167], v[88:91]
	v_mfma_f32_16x16x32_bf16 v[84:87], v[216:219], v[192:195], v[84:87]
	v_mfma_f32_16x16x32_bf16 v[80:83], v[224:227], v[192:195], v[80:83]
	v_mfma_f32_16x16x32_bf16 v[76:79], v[216:219], v[200:203], v[76:79]
	v_mfma_f32_16x16x32_bf16 v[72:75], v[224:227], v[200:203], v[72:75]
	v_mfma_f32_16x16x32_bf16 v[68:71], v[216:219], v[208:211], v[68:71]
	v_mfma_f32_16x16x32_bf16 v[64:67], v[224:227], v[208:211], v[64:67]
	v_mfma_f32_16x16x32_bf16 v[92:95], v[220:223], v[188:191], v[92:95]
	v_mfma_f32_16x16x32_bf16 v[88:91], v[228:231], v[188:191], v[88:91]
	v_mfma_f32_16x16x32_bf16 v[84:87], v[220:223], v[196:199], v[84:87]
	v_mfma_f32_16x16x32_bf16 v[80:83], v[228:231], v[196:199], v[80:83]
	v_mfma_f32_16x16x32_bf16 v[76:79], v[220:223], v[204:207], v[76:79]
	v_mfma_f32_16x16x32_bf16 v[72:75], v[228:231], v[204:207], v[72:75]
	v_mfma_f32_16x16x32_bf16 v[68:71], v[220:223], v[212:215], v[68:71]
	v_mfma_f32_16x16x32_bf16 v[64:67], v[228:231], v[212:215], v[64:67]
	s_barrier
	v_readfirstlane_b32 s45, v148
	v_lshl_add_u64 v[164:165], v[236:237], 0, s[18:19]
	s_mov_b32 m0, s45
	ds_read_b128 v[188:191], v152 offset:16384
	ds_read_b128 v[192:195], v152 offset:17408
	ds_read_b128 v[196:199], v151 offset:16384
	ds_read_b128 v[200:203], v151 offset:17408
	ds_read_b128 v[204:207], v150 offset:16384
	ds_read_b128 v[208:211], v150 offset:17408
	ds_read_b128 v[212:215], v149 offset:16384
	ds_read_b128 v[232:235], v149 offset:17408
	global_load_lds_dwordx4 v[164:165], off
	v_add_u32_e32 v164, 0x2000, v148
	v_lshl_add_u64 v[166:167], v[238:239], 0, s[18:19]
	v_readfirstlane_b32 s45, v164
	s_mov_b32 m0, s45
	s_nop 0
	global_load_lds_dwordx4 v[166:167], off
	s_barrier
	s_waitcnt lgkmcnt(0)
	s_waitcnt lgkmcnt(0)
	v_mfma_f32_16x16x32_bf16 v[60:63], v[172:175], v[188:191], v[60:63]
	v_mfma_f32_16x16x32_bf16 v[56:59], v[180:183], v[188:191], v[56:59]
	v_mfma_f32_16x16x32_bf16 v[52:55], v[172:175], v[196:199], v[52:55]
	v_mfma_f32_16x16x32_bf16 v[48:51], v[180:183], v[196:199], v[48:51]
	v_mfma_f32_16x16x32_bf16 v[44:47], v[172:175], v[204:207], v[44:47]
	v_mfma_f32_16x16x32_bf16 v[40:43], v[180:183], v[204:207], v[40:43]
	v_mfma_f32_16x16x32_bf16 v[36:39], v[172:175], v[212:215], v[36:39]
	v_mfma_f32_16x16x32_bf16 v[32:35], v[180:183], v[212:215], v[32:35]
	v_mfma_f32_16x16x32_bf16 v[60:63], v[176:179], v[192:195], v[60:63]
	v_mfma_f32_16x16x32_bf16 v[56:59], v[184:187], v[192:195], v[56:59]
	v_mfma_f32_16x16x32_bf16 v[52:55], v[176:179], v[200:203], v[52:55]
	v_mfma_f32_16x16x32_bf16 v[48:51], v[184:187], v[200:203], v[48:51]
	v_mfma_f32_16x16x32_bf16 v[44:47], v[176:179], v[208:211], v[44:47]
	v_mfma_f32_16x16x32_bf16 v[40:43], v[184:187], v[208:211], v[40:43]
	v_mfma_f32_16x16x32_bf16 v[36:39], v[176:179], v[232:235], v[36:39]
	v_mfma_f32_16x16x32_bf16 v[32:35], v[184:187], v[232:235], v[32:35]
	s_barrier
; #define STAGE(P, BASE, LD, br, kt) do { const char* _g = (const char*)((BASE) + (size_t)(br) * (LD) + (size_t)(kt) * 64); \
;     for (int _i = 0; _i < 2; ++_i) { int _b = tidx * 16 + _i * 8192; int _r, _c; stage_rc(_b, _r, _c); \
;       __builtin_amdgcn_global_load_lds((const unsigned*)(_g + (unsigned)((_r * (LD) + _c) * 2)), (unsigned*)((char*)(P) + _b), 16, 0, 0); } } while (0)
; #define LDA(dst, b, h) for (int m = 0; m < 4; ++m) for (int k = 0; k < 2; ++k) \
;     dst[m][k] = *reinterpret_cast<const bf16x8*>((char*)SA(b, h) + lds_byte(wr * 64 + m * 16 + fr, k * 32 + fq * 8))
; #define LDB(dst, b, h) for (int n = 0; n < 2; ++n) for (int k = 0; k < 2; ++k) \
;     dst[n][k] = *reinterpret_cast<const bf16x8*>((char*)SB(b, h) + lds_byte(wc * 32 + n * 16 + fr, k * 32 + fq * 8))
; #define MMA(ai, bj, At_, Bt_) do { __builtin_amdgcn_s_setprio(1); \
;     for (int k = 0; k < 2; ++k) for (int m = 0; m < 4; ++m) for (int n = 0; n < 2; ++n) \
;       acc[ai][bj][m][n] = __builtin_amdgcn_mfma_f32_16x16x32_bf16(At_[m][k], Bt_[n][k], acc[ai][bj][m][n], 0, 0, 0); \
;     __builtin_amdgcn_s_setprio(0); } while (0)
; #define WAIT_V(n) asm volatile("s_waitcnt vmcnt(" #n ")" ::: "memory")
; #define WAIT_L(n) asm volatile("s_waitcnt lgkmcnt(" #n ")" ::: "memory")
; #define BAR __builtin_amdgcn_s_barrier()
; #define SCHED __builtin_amdgcn_sched_barrier(0)
; template <int EPI, int lda, int ldb, int N, int K>
; __device__ __forceinline__ void gemm_phase(const u16* __restrict__ A, const u16* __restrict__ Bt, const GemmEpi ep, int wv) {
;     ...
;       STAGE(SB(0, 1), Bt, ldb, bcol + HALF, t + 2);
;       WAIT_V(6); BAR; MMA(1, 1, At, B1); BAR;
;       LDB(B0, 1, 0); SCHED; LDA(At, 1, 0); STAGE(SA(0, 1), Ab, lda, brow + HALF, t + 2);
;       WAIT_L(8); BAR; WAIT_L(0); MMA(0, 0, At, B0); BAR; SCHED;
;       LDB(B1, 1, 1); STAGE(SB(1, 0), Bt, ldb, bcol, t + 3);
;       BAR; WAIT_L(0); MMA(0, 1, At, B1); BAR;
;       LDA(At, 1, 1); STAGE(SA(1, 0), Ab, lda, brow, t + 3);
;       BAR; WAIT_L(0); MMA(1, 0, At, B0); BAR; SCHED;
	v_add_u32_e32 v165, s55, v153
	v_lshl_add_u64 v[166:167], v[240:241], 0, s[20:21]
	v_readfirstlane_b32 s45, v165
	s_mov_b32 m0, s45
	v_lshl_add_u64 v[172:173], v[242:243], 0, s[20:21]
	global_load_lds_dwordx4 v[166:167], off
	v_add_u32_e32 v166, 0x2000, v165
	s_nop 0
	v_readfirstlane_b32 s45, v166
	s_mov_b32 m0, s45
	s_nop 0
	global_load_lds_dwordx4 v[172:173], off
	s_waitcnt vmcnt(6)
	s_barrier
	v_mfma_f32_16x16x32_bf16 v[28:31], v[216:219], v[188:191], v[28:31]
	v_mfma_f32_16x16x32_bf16 v[24:27], v[224:227], v[188:191], v[24:27]
	v_mfma_f32_16x16x32_bf16 v[20:23], v[216:219], v[196:199], v[20:23]
	v_mfma_f32_16x16x32_bf16 v[16:19], v[224:227], v[196:199], v[16:19]
	v_mfma_f32_16x16x32_bf16 v[12:15], v[216:219], v[204:207], v[12:15]
	v_mfma_f32_16x16x32_bf16 v[8:11], v[224:227], v[204:207], v[8:11]
	v_mfma_f32_16x16x32_bf16 v[4:7], v[216:219], v[212:215], v[4:7]
	v_mfma_f32_16x16x32_bf16 v[0:3], v[224:227], v[212:215], v[0:3]
	v_mfma_f32_16x16x32_bf16 v[28:31], v[220:223], v[192:195], v[28:31]
	v_mfma_f32_16x16x32_bf16 v[24:27], v[228:231], v[192:195], v[24:27]
	v_mfma_f32_16x16x32_bf16 v[20:23], v[220:223], v[200:203], v[20:23]
	v_mfma_f32_16x16x32_bf16 v[16:19], v[228:231], v[200:203], v[16:19]
	v_mfma_f32_16x16x32_bf16 v[12:15], v[220:223], v[208:211], v[12:15]
	v_mfma_f32_16x16x32_bf16 v[8:11], v[228:231], v[208:211], v[8:11]
	v_mfma_f32_16x16x32_bf16 v[4:7], v[220:223], v[232:235], v[4:7]
	v_mfma_f32_16x16x32_bf16 v[0:3], v[228:231], v[232:235], v[0:3]
	s_barrier
	ds_read_b128 v[172:175], v156
	ds_read_b128 v[176:179], v156 offset:1024
	ds_read_b128 v[180:183], v156 offset:2048
	ds_read_b128 v[184:187], v156 offset:3072
	v_add_u32_e32 v167, 0x4000, v148
	v_add_u32_e32 v168, 0x6000, v148
	v_readfirstlane_b32 s45, v167
	v_lshl_add_u64 v[220:221], v[236:237], 0, s[22:23]
	s_mov_b32 m0, s45
	v_readfirstlane_b32 s45, v168
	ds_read_b128 v[188:191], v152 offset:32768
	ds_read_b128 v[192:195], v152 offset:33792
	ds_read_b128 v[196:199], v151 offset:32768
	ds_read_b128 v[200:203], v151 offset:33792
	ds_read_b128 v[204:207], v150 offset:32768
	ds_read_b128 v[208:211], v150 offset:33792
	ds_read_b128 v[212:215], v149 offset:32768
	ds_read_b128 v[216:219], v149 offset:33792
	global_load_lds_dwordx4 v[220:221], off
	s_waitcnt lgkmcnt(8)
	s_barrier
	s_waitcnt lgkmcnt(0)
	s_waitcnt lgkmcnt(0)
	v_mfma_f32_16x16x32_bf16 v[124:127], v[172:175], v[188:191], v[124:127]
	v_mfma_f32_16x16x32_bf16 v[120:123], v[180:183], v[188:191], v[120:123]
	v_mfma_f32_16x16x32_bf16 v[116:119], v[172:175], v[196:199], v[116:119]
	v_mfma_f32_16x16x32_bf16 v[112:115], v[180:183], v[196:199], v[112:115]
	v_mfma_f32_16x16x32_bf16 v[108:111], v[172:175], v[204:207], v[108:111]
	v_mfma_f32_16x16x32_bf16 v[104:107], v[180:183], v[204:207], v[104:107]
	v_mfma_f32_16x16x32_bf16 v[100:103], v[172:175], v[212:215], v[100:103]
	v_mfma_f32_16x16x32_bf16 v[96:99], v[180:183], v[212:215], v[96:99]
	v_lshl_add_u64 v[220:221], v[238:239], 0, s[22:23]
	s_mov_b32 m0, s45
	s_nop 0
	global_load_lds_dwordx4 v[220:221], off
	v_mfma_f32_16x16x32_bf16 v[124:127], v[176:179], v[192:195], v[124:127]
	v_mfma_f32_16x16x32_bf16 v[120:123], v[184:187], v[192:195], v[120:123]
	v_mfma_f32_16x16x32_bf16 v[116:119], v[176:179], v[200:203], v[116:119]
	v_mfma_f32_16x16x32_bf16 v[112:115], v[184:187], v[200:203], v[112:115]
	v_mfma_f32_16x16x32_bf16 v[108:111], v[176:179], v[208:211], v[108:111]
	v_mfma_f32_16x16x32_bf16 v[104:107], v[184:187], v[208:211], v[104:107]
	v_mfma_f32_16x16x32_bf16 v[100:103], v[176:179], v[216:219], v[100:103]
	v_mfma_f32_16x16x32_bf16 v[96:99], v[184:187], v[216:219], v[96:99]
	s_barrier
	v_readfirstlane_b32 s45, v155
	v_add_u32_e32 v171, 0x2000, v155
	v_lshl_add_u64 v[244:245], v[240:241], 0, s[24:25]
	s_mov_b32 m0, s45
	v_readfirstlane_b32 s45, v171
	ds_read_b128 v[220:223], v154
	ds_read_b128 v[224:227], v154 offset:1024
	ds_read_b128 v[228:231], v154 offset:2048
	ds_read_b128 v[232:235], v154 offset:3072
	global_load_lds_dwordx4 v[244:245], off
	v_lshl_add_u64 v[244:245], v[242:243], 0, s[24:25]
	s_mov_b32 m0, s45
	s_nop 0
	global_load_lds_dwordx4 v[244:245], off
	s_barrier
	s_waitcnt lgkmcnt(0)
	s_waitcnt lgkmcnt(0)
	v_mfma_f32_16x16x32_bf16 v[92:95], v[220:223], v[188:191], v[92:95]
	v_mfma_f32_16x16x32_bf16 v[88:91], v[228:231], v[188:191], v[88:91]
	v_mfma_f32_16x16x32_bf16 v[84:87], v[220:223], v[196:199], v[84:87]
	v_mfma_f32_16x16x32_bf16 v[80:83], v[228:231], v[196:199], v[80:83]
	v_mfma_f32_16x16x32_bf16 v[76:79], v[220:223], v[204:207], v[76:79]
	v_mfma_f32_16x16x32_bf16 v[72:75], v[228:231], v[204:207], v[72:75]
	v_mfma_f32_16x16x32_bf16 v[68:71], v[220:223], v[212:215], v[68:71]
	v_mfma_f32_16x16x32_bf16 v[64:67], v[228:231], v[212:215], v[64:67]
	v_mfma_f32_16x16x32_bf16 v[92:95], v[224:227], v[192:195], v[92:95]
	v_mfma_f32_16x16x32_bf16 v[88:91], v[232:235], v[192:195], v[88:91]
	v_mfma_f32_16x16x32_bf16 v[84:87], v[224:227], v[200:203], v[84:87]
	v_mfma_f32_16x16x32_bf16 v[80:83], v[232:235], v[200:203], v[80:83]
	v_mfma_f32_16x16x32_bf16 v[76:79], v[224:227], v[208:211], v[76:79]
	v_mfma_f32_16x16x32_bf16 v[72:75], v[232:235], v[208:211], v[72:75]
	v_mfma_f32_16x16x32_bf16 v[68:71], v[224:227], v[216:219], v[68:71]
	v_mfma_f32_16x16x32_bf16 v[64:67], v[232:235], v[216:219], v[64:67]
	s_barrier
	v_readfirstlane_b32 s45, v157
	v_lshl_add_u64 v[236:237], v[236:237], 0, s[26:27]
	s_mov_b32 m0, s45
	v_readfirstlane_b32 s45, v158
	ds_read_b128 v[188:191], v152 offset:49152
	ds_read_b128 v[192:195], v152 offset:50176
	ds_read_b128 v[196:199], v151 offset:49152
	ds_read_b128 v[200:203], v151 offset:50176
	ds_read_b128 v[204:207], v150 offset:49152
	ds_read_b128 v[208:211], v150 offset:50176
	ds_read_b128 v[212:215], v149 offset:49152
	ds_read_b128 v[216:219], v149 offset:50176
	global_load_lds_dwordx4 v[236:237], off
	v_lshl_add_u64 v[236:237], v[238:239], 0, s[26:27]
	s_mov_b32 m0, s45
	s_nop 0
	global_load_lds_dwordx4 v[236:237], off
	s_barrier
; #define STAGE(P, BASE, LD, br, kt) do { const char* _g = (const char*)((BASE) + (size_t)(br) * (LD) + (size_t)(kt) * 64); \
;     for (int _i = 0; _i < 2; ++_i) { int _b = tidx * 16 + _i * 8192; int _r, _c; stage_rc(_b, _r, _c); \
;       __builtin_amdgcn_global_load_lds((const unsigned*)(_g + (unsigned)((_r * (LD) + _c) * 2)), (unsigned*)((char*)(P) + _b), 16, 0, 0); } } while (0)
; #define LDA(dst, b, h) for (int m = 0; m < 4; ++m) for (int k = 0; k < 2; ++k) \
;     dst[m][k] = *reinterpret_cast<const bf16x8*>((char*)SA(b, h) + lds_byte(wr * 64 + m * 16 + fr, k * 32 + fq * 8))
; #define LDB(dst, b, h) for (int n = 0; n < 2; ++n) for (int k = 0; k < 2; ++k) \
;     dst[n][k] = *reinterpret_cast<const bf16x8*>((char*)SB(b, h) + lds_byte(wc * 32 + n * 16 + fr, k * 32 + fq * 8))
; #define MMA(ai, bj, At_, Bt_) do { __builtin_amdgcn_s_setprio(1); \
;     for (int k = 0; k < 2; ++k) for (int m = 0; m < 4; ++m) for (int n = 0; n < 2; ++n) \
;       acc[ai][bj][m][n] = __builtin_amdgcn_mfma_f32_16x16x32_bf16(At_[m][k], Bt_[n][k], acc[ai][bj][m][n], 0, 0, 0); \
;     __builtin_amdgcn_s_setprio(0); } while (0)
; #define WAIT_V(n) asm volatile("s_waitcnt vmcnt(" #n ")" ::: "memory")
; #define WAIT_L(n) asm volatile("s_waitcnt lgkmcnt(" #n ")" ::: "memory")
; #define BAR __builtin_amdgcn_s_barrier()
; #define SCHED __builtin_amdgcn_sched_barrier(0)
; template <int EPI, int lda, int ldb, int N, int K>
; __device__ __forceinline__ void gemm_phase(const u16* __restrict__ A, const u16* __restrict__ Bt, const GemmEpi ep, int wv) {
;     ...
;       BAR; WAIT_L(0); MMA(1, 0, At, B0); BAR; SCHED;
;       STAGE(SB(1, 1), Bt, ldb, bcol + HALF, t + 3);
;       WAIT_V(6); BAR; MMA(1, 1, At, B1); BAR;
;     }
;     { LDB(B0, 0, 0); LDA(At, 0, 0); STAGE(SA(1, 1), Ab, lda, brow + HALF, nt - 1);
;       BAR; WAIT_L(0); MMA(0, 0, At, B0); BAR;
;       LDB(B1, 0, 1); BAR; WAIT_L(0); MMA(0, 1, At, B1); BAR;
	s_waitcnt lgkmcnt(0)
	s_waitcnt lgkmcnt(0)
	v_mfma_f32_16x16x32_bf16 v[60:63], v[172:175], v[188:191], v[60:63]
	v_mfma_f32_16x16x32_bf16 v[56:59], v[180:183], v[188:191], v[56:59]
	v_mfma_f32_16x16x32_bf16 v[52:55], v[172:175], v[196:199], v[52:55]
	v_mfma_f32_16x16x32_bf16 v[48:51], v[180:183], v[196:199], v[48:51]
	v_mfma_f32_16x16x32_bf16 v[44:47], v[172:175], v[204:207], v[44:47]
	v_mfma_f32_16x16x32_bf16 v[40:43], v[180:183], v[204:207], v[40:43]
	v_mfma_f32_16x16x32_bf16 v[36:39], v[172:175], v[212:215], v[36:39]
	v_mfma_f32_16x16x32_bf16 v[32:35], v[180:183], v[212:215], v[32:35]
	v_mfma_f32_16x16x32_bf16 v[60:63], v[176:179], v[192:195], v[60:63]
	v_mfma_f32_16x16x32_bf16 v[56:59], v[184:187], v[192:195], v[56:59]
	v_mfma_f32_16x16x32_bf16 v[52:55], v[176:179], v[200:203], v[52:55]
	v_mfma_f32_16x16x32_bf16 v[48:51], v[184:187], v[200:203], v[48:51]
	v_mfma_f32_16x16x32_bf16 v[44:47], v[176:179], v[208:211], v[44:47]
	v_mfma_f32_16x16x32_bf16 v[40:43], v[184:187], v[208:211], v[40:43]
	v_mfma_f32_16x16x32_bf16 v[36:39], v[176:179], v[216:219], v[36:39]
	v_mfma_f32_16x16x32_bf16 v[32:35], v[184:187], v[216:219], v[32:35]
	s_barrier
	v_readfirstlane_b32 s45, v159
	v_add_u32_e32 v171, 0x2000, v159
	v_lshl_add_u64 v[172:173], v[240:241], 0, s[34:35]
	s_mov_b32 m0, s45
	v_readfirstlane_b32 s45, v171
	global_load_lds_dwordx4 v[172:173], off
	v_lshl_add_u64 v[172:173], v[242:243], 0, s[34:35]
	s_mov_b32 m0, s45
	s_nop 0
	global_load_lds_dwordx4 v[172:173], off
	s_waitcnt vmcnt(6)
	s_barrier
	v_mfma_f32_16x16x32_bf16 v[28:31], v[220:223], v[188:191], v[28:31]
	v_mfma_f32_16x16x32_bf16 v[24:27], v[228:231], v[188:191], v[24:27]
	v_mfma_f32_16x16x32_bf16 v[20:23], v[220:223], v[196:199], v[20:23]
	v_mfma_f32_16x16x32_bf16 v[16:19], v[228:231], v[196:199], v[16:19]
	v_mfma_f32_16x16x32_bf16 v[12:15], v[220:223], v[204:207], v[12:15]
	v_mfma_f32_16x16x32_bf16 v[8:11], v[228:231], v[204:207], v[8:11]
	v_mfma_f32_16x16x32_bf16 v[4:7], v[220:223], v[212:215], v[4:7]
	v_mfma_f32_16x16x32_bf16 v[0:3], v[228:231], v[212:215], v[0:3]
	v_mfma_f32_16x16x32_bf16 v[28:31], v[224:227], v[192:195], v[28:31]
	v_mfma_f32_16x16x32_bf16 v[24:27], v[232:235], v[192:195], v[24:27]
	v_mfma_f32_16x16x32_bf16 v[20:23], v[224:227], v[200:203], v[20:23]
	v_mfma_f32_16x16x32_bf16 v[16:19], v[232:235], v[200:203], v[16:19]
	v_mfma_f32_16x16x32_bf16 v[12:15], v[224:227], v[208:211], v[12:15]
	v_mfma_f32_16x16x32_bf16 v[8:11], v[232:235], v[208:211], v[8:11]
	v_mfma_f32_16x16x32_bf16 v[4:7], v[224:227], v[216:219], v[4:7]
	v_mfma_f32_16x16x32_bf16 v[0:3], v[232:235], v[216:219], v[0:3]
	s_add_i32 s44, s44, 2
	s_add_u32 s42, s42, 0x100
	s_addc_u32 s43, s43, 0
	s_cmp_gt_u32 s44, 27
	s_barrier
	s_cbranch_scc0 .LBB0_53
	s_add_i32 s42, s38, 0x80
	s_mul_hi_i32 s43, s42, 0x1080
	s_mulk_i32 s42, 0x1080
	s_add_u32 s42, s51, s42
	s_addc_u32 s43, s52, s43
	v_lshl_add_u64 v[158:159], s[42:43], 0, v[128:129]
	v_readfirstlane_b32 s44, v169
	v_lshl_add_u64 v[158:159], v[158:159], 0, s[36:37]
	s_mov_b32 m0, s44
	ds_read_b128 v[134:137], v161
	ds_read_b128 v[138:141], v161 offset:1024
	ds_read_b128 v[172:175], v161 offset:2048
	ds_read_b128 v[176:179], v161 offset:3072
	ds_read_b128 v[180:183], v152
	ds_read_b128 v[184:187], v152 offset:1024
	ds_read_b128 v[188:191], v151
	ds_read_b128 v[192:195], v151 offset:1024
	ds_read_b128 v[196:199], v150
	ds_read_b128 v[200:203], v150 offset:1024
	ds_read_b128 v[204:207], v149
	ds_read_b128 v[208:211], v149 offset:1024
	global_load_lds_dwordx4 v[158:159], off
	v_lshl_add_u64 v[158:159], s[42:43], 0, v[132:133]
	v_readfirstlane_b32 s42, v170
	v_lshl_add_u64 v[158:159], v[158:159], 0, s[36:37]
	s_mov_b32 m0, s42
	s_nop 0
	global_load_lds_dwordx4 v[158:159], off
	s_barrier
	s_waitcnt lgkmcnt(0)
	s_waitcnt lgkmcnt(0)
	v_mfma_f32_16x16x32_bf16 v[124:127], v[134:137], v[180:183], v[124:127]
	v_mfma_f32_16x16x32_bf16 v[120:123], v[172:175], v[180:183], v[120:123]
	v_mfma_f32_16x16x32_bf16 v[116:119], v[134:137], v[188:191], v[116:119]
	v_mfma_f32_16x16x32_bf16 v[112:115], v[172:175], v[188:191], v[112:115]
	v_mfma_f32_16x16x32_bf16 v[108:111], v[134:137], v[196:199], v[108:111]
	v_mfma_f32_16x16x32_bf16 v[104:107], v[172:175], v[196:199], v[104:107]
	v_mfma_f32_16x16x32_bf16 v[100:103], v[134:137], v[204:207], v[100:103]
	v_mfma_f32_16x16x32_bf16 v[96:99], v[172:175], v[204:207], v[96:99]
	v_mfma_f32_16x16x32_bf16 v[124:127], v[138:141], v[184:187], v[124:127]
	v_mfma_f32_16x16x32_bf16 v[120:123], v[176:179], v[184:187], v[120:123]
	v_mfma_f32_16x16x32_bf16 v[116:119], v[138:141], v[192:195], v[116:119]
	v_mfma_f32_16x16x32_bf16 v[112:115], v[176:179], v[192:195], v[112:115]
	v_mfma_f32_16x16x32_bf16 v[108:111], v[138:141], v[200:203], v[108:111]
	v_mfma_f32_16x16x32_bf16 v[104:107], v[176:179], v[200:203], v[104:107]
	v_mfma_f32_16x16x32_bf16 v[100:103], v[138:141], v[208:211], v[100:103]
	v_mfma_f32_16x16x32_bf16 v[96:99], v[176:179], v[208:211], v[96:99]
	s_barrier
	ds_read_b128 v[212:215], v160
	ds_read_b128 v[216:219], v160 offset:1024
	ds_read_b128 v[220:223], v160 offset:2048
	ds_read_b128 v[158:161], v160 offset:3072
	s_barrier
; #define LDA(dst, b, h) for (int m = 0; m < 4; ++m) for (int k = 0; k < 2; ++k) \
;     dst[m][k] = *reinterpret_cast<const bf16x8*>((char*)SA(b, h) + lds_byte(wr * 64 + m * 16 + fr, k * 32 + fq * 8))
; #define LDB(dst, b, h) for (int n = 0; n < 2; ++n) for (int k = 0; k < 2; ++k) \
;     dst[n][k] = *reinterpret_cast<const bf16x8*>((char*)SB(b, h) + lds_byte(wc * 32 + n * 16 + fr, k * 32 + fq * 8))
; #define MMA(ai, bj, At_, Bt_) do { __builtin_amdgcn_s_setprio(1); \
;     for (int k = 0; k < 2; ++k) for (int m = 0; m < 4; ++m) for (int n = 0; n < 2; ++n) \
;       acc[ai][bj][m][n] = __builtin_amdgcn_mfma_f32_16x16x32_bf16(At_[m][k], Bt_[n][k], acc[ai][bj][m][n], 0, 0, 0); \
;     __builtin_amdgcn_s_setprio(0); } while (0)
; #define WAIT_V(n) asm volatile("s_waitcnt vmcnt(" #n ")" ::: "memory")
; #define WAIT_L(n) asm volatile("s_waitcnt lgkmcnt(" #n ")" ::: "memory")
; #define BAR __builtin_amdgcn_s_barrier()
; template <int EPI, int lda, int ldb, int N, int K>
; __device__ __forceinline__ void gemm_phase(const u16* __restrict__ A, const u16* __restrict__ Bt, const GemmEpi ep, int wv) {
;     ...
;       LDB(B1, 0, 1); BAR; WAIT_L(0); MMA(0, 1, At, B1); BAR;
;       LDA(At, 0, 1); WAIT_V(4); BAR; WAIT_L(0); MMA(1, 0, At, B0); MMA(1, 1, At, B1); BAR; }
;     { LDB(B0, 1, 0); LDA(At, 1, 0); WAIT_V(2); BAR; WAIT_L(0); MMA(0, 0, At, B0); BAR;
	s_waitcnt lgkmcnt(0)
	s_waitcnt lgkmcnt(0)
	v_mfma_f32_16x16x32_bf16 v[92:95], v[212:215], v[180:183], v[92:95]
	v_mfma_f32_16x16x32_bf16 v[88:91], v[220:223], v[180:183], v[88:91]
	v_mfma_f32_16x16x32_bf16 v[76:79], v[212:215], v[196:199], v[76:79]
	v_mfma_f32_16x16x32_bf16 v[72:75], v[220:223], v[196:199], v[72:75]
	v_mfma_f32_16x16x32_bf16 v[84:87], v[212:215], v[188:191], v[84:87]
	v_mfma_f32_16x16x32_bf16 v[80:83], v[220:223], v[188:191], v[80:83]
	v_mfma_f32_16x16x32_bf16 v[68:71], v[212:215], v[204:207], v[68:71]
	v_mfma_f32_16x16x32_bf16 v[64:67], v[220:223], v[204:207], v[64:67]
	v_mfma_f32_16x16x32_bf16 v[92:95], v[216:219], v[184:187], v[92:95]
	v_mfma_f32_16x16x32_bf16 v[88:91], v[158:161], v[184:187], v[88:91]
	v_mfma_f32_16x16x32_bf16 v[76:79], v[216:219], v[200:203], v[76:79]
	v_mfma_f32_16x16x32_bf16 v[72:75], v[158:161], v[200:203], v[72:75]
	v_mfma_f32_16x16x32_bf16 v[180:183], v[216:219], v[192:195], v[84:87]
	v_mfma_f32_16x16x32_bf16 v[184:187], v[158:161], v[192:195], v[80:83]
	v_mfma_f32_16x16x32_bf16 v[188:191], v[216:219], v[208:211], v[68:71]
	v_mfma_f32_16x16x32_bf16 v[192:195], v[158:161], v[208:211], v[64:67]
	s_barrier
	s_nop 0
	ds_read_b128 v[64:67], v152 offset:16384
	ds_read_b128 v[68:71], v152 offset:17408
	ds_read_b128 v[80:83], v151 offset:16384
	ds_read_b128 v[84:87], v151 offset:17408
	ds_read_b128 v[196:199], v150 offset:16384
	ds_read_b128 v[200:203], v150 offset:17408
	ds_read_b128 v[204:207], v149 offset:16384
	ds_read_b128 v[208:211], v149 offset:17408
	s_waitcnt vmcnt(4)
	s_barrier
	s_waitcnt lgkmcnt(0)
	s_waitcnt lgkmcnt(0)
	v_mfma_f32_16x16x32_bf16 v[60:63], v[134:137], v[64:67], v[60:63]
	v_mfma_f32_16x16x32_bf16 v[56:59], v[172:175], v[64:67], v[56:59]
	v_mfma_f32_16x16x32_bf16 v[52:55], v[134:137], v[80:83], v[52:55]
	v_mfma_f32_16x16x32_bf16 v[48:51], v[172:175], v[80:83], v[48:51]
	v_mfma_f32_16x16x32_bf16 v[44:47], v[134:137], v[196:199], v[44:47]
	v_mfma_f32_16x16x32_bf16 v[40:43], v[172:175], v[196:199], v[40:43]
	v_mfma_f32_16x16x32_bf16 v[36:39], v[134:137], v[204:207], v[36:39]
	v_mfma_f32_16x16x32_bf16 v[32:35], v[172:175], v[204:207], v[32:35]
	v_mfma_f32_16x16x32_bf16 v[60:63], v[138:141], v[68:71], v[60:63]
	v_mfma_f32_16x16x32_bf16 v[56:59], v[176:179], v[68:71], v[56:59]
	v_mfma_f32_16x16x32_bf16 v[52:55], v[138:141], v[84:87], v[52:55]
	v_mfma_f32_16x16x32_bf16 v[48:51], v[176:179], v[84:87], v[48:51]
	v_mfma_f32_16x16x32_bf16 v[44:47], v[138:141], v[200:203], v[44:47]
	v_mfma_f32_16x16x32_bf16 v[40:43], v[176:179], v[200:203], v[40:43]
	v_mfma_f32_16x16x32_bf16 v[36:39], v[138:141], v[208:211], v[36:39]
	v_mfma_f32_16x16x32_bf16 v[32:35], v[176:179], v[208:211], v[32:35]
	v_mfma_f32_16x16x32_bf16 v[28:31], v[212:215], v[64:67], v[28:31]
	v_mfma_f32_16x16x32_bf16 v[24:27], v[220:223], v[64:67], v[24:27]
	v_mfma_f32_16x16x32_bf16 v[12:15], v[212:215], v[196:199], v[12:15]
	v_mfma_f32_16x16x32_bf16 v[8:11], v[220:223], v[196:199], v[8:11]
	v_mfma_f32_16x16x32_bf16 v[20:23], v[212:215], v[80:83], v[20:23]
	v_mfma_f32_16x16x32_bf16 v[16:19], v[220:223], v[80:83], v[16:19]
	v_mfma_f32_16x16x32_bf16 v[4:7], v[212:215], v[204:207], v[4:7]
	v_mfma_f32_16x16x32_bf16 v[0:3], v[220:223], v[204:207], v[0:3]
	v_mfma_f32_16x16x32_bf16 v[28:31], v[216:219], v[68:71], v[28:31]
	v_mfma_f32_16x16x32_bf16 v[24:27], v[158:161], v[68:71], v[24:27]
	v_mfma_f32_16x16x32_bf16 v[12:15], v[216:219], v[200:203], v[12:15]
	v_mfma_f32_16x16x32_bf16 v[8:11], v[158:161], v[200:203], v[8:11]
	v_mfma_f32_16x16x32_bf16 v[134:137], v[216:219], v[84:87], v[20:23]
	v_mfma_f32_16x16x32_bf16 v[138:141], v[158:161], v[84:87], v[16:19]
	v_mfma_f32_16x16x32_bf16 v[170:173], v[216:219], v[208:211], v[4:7]
	v_mfma_f32_16x16x32_bf16 v[158:161], v[158:161], v[208:211], v[0:3]
	s_barrier
	s_nop 0
	ds_read_b128 v[0:3], v156
	ds_read_b128 v[4:7], v156 offset:1024
	ds_read_b128 v[16:19], v156 offset:2048
	ds_read_b128 v[174:177], v156 offset:3072
	ds_read_b128 v[20:23], v152 offset:32768
	ds_read_b128 v[196:199], v152 offset:33792
	ds_read_b128 v[200:203], v151 offset:32768
	ds_read_b128 v[204:207], v151 offset:33792
	ds_read_b128 v[208:211], v150 offset:32768
	ds_read_b128 v[212:215], v150 offset:33792
	ds_read_b128 v[216:219], v149 offset:32768
	ds_read_b128 v[220:223], v149 offset:33792
	s_waitcnt vmcnt(2)
	s_barrier
; #define LDA(dst, b, h) for (int m = 0; m < 4; ++m) for (int k = 0; k < 2; ++k) \
;     dst[m][k] = *reinterpret_cast<const bf16x8*>((char*)SA(b, h) + lds_byte(wr * 64 + m * 16 + fr, k * 32 + fq * 8))
; #define LDB(dst, b, h) for (int n = 0; n < 2; ++n) for (int k = 0; k < 2; ++k) \
;     dst[n][k] = *reinterpret_cast<const bf16x8*>((char*)SB(b, h) + lds_byte(wc * 32 + n * 16 + fr, k * 32 + fq * 8))
; #define MMA(ai, bj, At_, Bt_) do { __builtin_amdgcn_s_setprio(1); \
;     for (int k = 0; k < 2; ++k) for (int m = 0; m < 4; ++m) for (int n = 0; n < 2; ++n) \
;       acc[ai][bj][m][n] = __builtin_amdgcn_mfma_f32_16x16x32_bf16(At_[m][k], Bt_[n][k], acc[ai][bj][m][n], 0, 0, 0); \
;     __builtin_amdgcn_s_setprio(0); } while (0)
; #define WAIT_V(n) asm volatile("s_waitcnt vmcnt(" #n ")" ::: "memory")
; #define WAIT_L(n) asm volatile("s_waitcnt lgkmcnt(" #n ")" ::: "memory")
; #define BAR __builtin_amdgcn_s_barrier()
; template <int EPI, int lda, int ldb, int N, int K>
; __device__ __forceinline__ void gemm_phase(const u16* __restrict__ A, const u16* __restrict__ Bt, const GemmEpi ep, int wv) {
;     ...
;     { LDB(B0, 1, 0); LDA(At, 1, 0); WAIT_V(2); BAR; WAIT_L(0); MMA(0, 0, At, B0); BAR;
;       LDB(B1, 1, 1); WAIT_V(0); BAR; WAIT_L(0); MMA(0, 1, At, B1); BAR;
;       LDA(At, 1, 1); BAR; WAIT_L(0); MMA(1, 0, At, B0); MMA(1, 1, At, B1); BAR; }
;     if (wr == 0) BAR;
	s_waitcnt lgkmcnt(0)
	s_waitcnt lgkmcnt(0)
	v_mfma_f32_16x16x32_bf16 v[64:67], v[0:3], v[20:23], v[124:127]
	v_mfma_f32_16x16x32_bf16 v[68:71], v[16:19], v[20:23], v[120:123]
	v_mfma_f32_16x16x32_bf16 v[80:83], v[0:3], v[200:203], v[116:119]
	v_mfma_f32_16x16x32_bf16 v[84:87], v[16:19], v[200:203], v[112:115]
	v_mfma_f32_16x16x32_bf16 v[108:111], v[0:3], v[208:211], v[108:111]
	v_mfma_f32_16x16x32_bf16 v[104:107], v[16:19], v[208:211], v[104:107]
	v_mfma_f32_16x16x32_bf16 v[120:123], v[0:3], v[216:219], v[100:103]
	v_mfma_f32_16x16x32_bf16 v[124:127], v[16:19], v[216:219], v[96:99]
	v_mfma_f32_16x16x32_bf16 v[116:119], v[4:7], v[196:199], v[64:67]
	v_mfma_f32_16x16x32_bf16 v[112:115], v[174:177], v[196:199], v[68:71]
	v_mfma_f32_16x16x32_bf16 v[100:103], v[4:7], v[204:207], v[80:83]
	v_mfma_f32_16x16x32_bf16 v[96:99], v[174:177], v[204:207], v[84:87]
	v_mfma_f32_16x16x32_bf16 v[84:87], v[4:7], v[212:215], v[108:111]
	v_mfma_f32_16x16x32_bf16 v[80:83], v[174:177], v[212:215], v[104:107]
	v_mfma_f32_16x16x32_bf16 v[68:71], v[4:7], v[220:223], v[120:123]
	v_mfma_f32_16x16x32_bf16 v[64:67], v[174:177], v[220:223], v[124:127]
	s_barrier
	ds_read_b128 v[224:227], v154
	ds_read_b128 v[228:231], v154 offset:1024
	ds_read_b128 v[232:235], v154 offset:2048
	ds_read_b128 v[154:157], v154 offset:3072
	s_waitcnt vmcnt(0)
	s_barrier
	s_waitcnt lgkmcnt(0)
	s_waitcnt lgkmcnt(0)
	v_mfma_f32_16x16x32_bf16 v[92:95], v[224:227], v[20:23], v[92:95]
	v_mfma_f32_16x16x32_bf16 v[20:23], v[232:235], v[20:23], v[88:91]
	v_mfma_f32_16x16x32_bf16 v[88:91], v[224:227], v[200:203], v[180:183]
	v_mfma_f32_16x16x32_bf16 v[104:107], v[232:235], v[200:203], v[184:187]
	v_mfma_f32_16x16x32_bf16 v[76:79], v[224:227], v[208:211], v[76:79]
	v_mfma_f32_16x16x32_bf16 v[72:75], v[232:235], v[208:211], v[72:75]
	v_mfma_f32_16x16x32_bf16 v[178:181], v[224:227], v[216:219], v[188:191]
	v_mfma_f32_16x16x32_bf16 v[182:185], v[232:235], v[216:219], v[192:195]
	v_mfma_f32_16x16x32_bf16 v[124:127], v[228:231], v[196:199], v[92:95]
	v_mfma_f32_16x16x32_bf16 v[120:123], v[154:157], v[196:199], v[20:23]
	v_mfma_f32_16x16x32_bf16 v[108:111], v[228:231], v[204:207], v[88:91]
	v_mfma_f32_16x16x32_bf16 v[104:107], v[154:157], v[204:207], v[104:107]
	v_mfma_f32_16x16x32_bf16 v[92:95], v[228:231], v[212:215], v[76:79]
	v_mfma_f32_16x16x32_bf16 v[88:91], v[154:157], v[212:215], v[72:75]
	v_mfma_f32_16x16x32_bf16 v[76:79], v[228:231], v[220:223], v[178:181]
	v_mfma_f32_16x16x32_bf16 v[72:75], v[154:157], v[220:223], v[182:185]
	s_barrier
	ds_read_b128 v[178:181], v152 offset:49152
	ds_read_b128 v[182:185], v152 offset:50176
	ds_read_b128 v[186:189], v151 offset:49152
	ds_read_b128 v[190:193], v151 offset:50176
	ds_read_b128 v[194:197], v150 offset:49152
	ds_read_b128 v[150:153], v150 offset:50176
	ds_read_b128 v[198:201], v149 offset:49152
	ds_read_b128 v[202:205], v149 offset:50176
	s_barrier
	s_waitcnt lgkmcnt(0)
	s_waitcnt lgkmcnt(0)
	v_mfma_f32_16x16x32_bf16 v[20:23], v[0:3], v[178:181], v[60:63]
	v_mfma_f32_16x16x32_bf16 v[56:59], v[16:19], v[178:181], v[56:59]
	v_mfma_f32_16x16x32_bf16 v[60:63], v[0:3], v[186:189], v[52:55]
	v_mfma_f32_16x16x32_bf16 v[206:209], v[16:19], v[186:189], v[48:51]
	v_mfma_f32_16x16x32_bf16 v[44:47], v[0:3], v[194:197], v[44:47]
	v_mfma_f32_16x16x32_bf16 v[40:43], v[16:19], v[194:197], v[40:43]
	v_mfma_f32_16x16x32_bf16 v[0:3], v[0:3], v[198:201], v[36:39]
	v_mfma_f32_16x16x32_bf16 v[210:213], v[16:19], v[198:201], v[32:35]
	v_mfma_f32_16x16x32_bf16 v[52:55], v[4:7], v[182:185], v[20:23]
	v_mfma_f32_16x16x32_bf16 v[48:51], v[174:177], v[182:185], v[56:59]
	v_mfma_f32_16x16x32_bf16 v[36:39], v[4:7], v[190:193], v[60:63]
	v_mfma_f32_16x16x32_bf16 v[32:35], v[174:177], v[190:193], v[206:209]
	v_mfma_f32_16x16x32_bf16 v[20:23], v[4:7], v[150:153], v[44:47]
	v_mfma_f32_16x16x32_bf16 v[16:19], v[174:177], v[150:153], v[40:43]
	v_mfma_f32_16x16x32_bf16 v[4:7], v[4:7], v[202:205], v[0:3]
	v_mfma_f32_16x16x32_bf16 v[0:3], v[174:177], v[202:205], v[210:213]
	v_mfma_f32_16x16x32_bf16 v[28:31], v[224:227], v[178:181], v[28:31]
	v_mfma_f32_16x16x32_bf16 v[24:27], v[232:235], v[178:181], v[24:27]
	v_mfma_f32_16x16x32_bf16 v[40:43], v[224:227], v[186:189], v[134:137]
	v_mfma_f32_16x16x32_bf16 v[134:137], v[232:235], v[186:189], v[138:141]
	v_mfma_f32_16x16x32_bf16 v[12:15], v[224:227], v[194:197], v[12:15]
	v_mfma_f32_16x16x32_bf16 v[8:11], v[232:235], v[194:197], v[8:11]
	v_mfma_f32_16x16x32_bf16 v[138:141], v[224:227], v[198:201], v[170:173]
	v_mfma_f32_16x16x32_bf16 v[158:161], v[232:235], v[198:201], v[158:161]
	v_mfma_f32_16x16x32_bf16 v[60:63], v[228:231], v[182:185], v[28:31]
	v_mfma_f32_16x16x32_bf16 v[56:59], v[154:157], v[182:185], v[24:27]
	v_mfma_f32_16x16x32_bf16 v[44:47], v[228:231], v[190:193], v[40:43]
	v_mfma_f32_16x16x32_bf16 v[40:43], v[154:157], v[190:193], v[134:137]
	v_mfma_f32_16x16x32_bf16 v[28:31], v[228:231], v[150:153], v[12:15]
	v_mfma_f32_16x16x32_bf16 v[24:27], v[154:157], v[150:153], v[8:11]
	v_mfma_f32_16x16x32_bf16 v[12:15], v[228:231], v[202:205], v[138:141]
	v_mfma_f32_16x16x32_bf16 v[8:11], v[154:157], v[202:205], v[158:161]
	v_cmp_gt_u32_e32 vcc, s56, v130
	s_barrier
	s_and_saveexec_b64 s[42:43], vcc
	s_cbranch_execz .LBB0_56
	s_barrier

; #define STAGE(P, BASE, LD, br, kt) do { const char* _g = (const char*)((BASE) + (size_t)(br) * (LD) + (size_t)(kt) * 64); \
;     for (int _i = 0; _i < 2; ++_i) { int _b = tidx * 16 + _i * 8192; int _r, _c; stage_rc(_b, _r, _c); \
;       __builtin_amdgcn_global_load_lds((const unsigned*)(_g + (unsigned)((_r * (LD) + _c) * 2)), (unsigned*)((char*)(P) + _b), 16, 0, 0); } } while (0)
; #define LDA(dst, b, h) for (int m = 0; m < 4; ++m) for (int k = 0; k < 2; ++k) \
;     dst[m][k] = *reinterpret_cast<const bf16x8*>((char*)SA(b, h) + lds_byte(wr * 64 + m * 16 + fr, k * 32 + fq * 8))
; #define LDB(dst, b, h) for (int n = 0; n < 2; ++n) for (int k = 0; k < 2; ++k) \
;     dst[n][k] = *reinterpret_cast<const bf16x8*>((char*)SB(b, h) + lds_byte(wc * 32 + n * 16 + fr, k * 32 + fq * 8))
; #define MMA(ai, bj, At_, Bt_) do { __builtin_amdgcn_s_setprio(1); \
;     for (int k = 0; k < 2; ++k) for (int m = 0; m < 4; ++m) for (int n = 0; n < 2; ++n) \
;       acc[ai][bj][m][n] = __builtin_amdgcn_mfma_f32_16x16x32_bf16(At_[m][k], Bt_[n][k], acc[ai][bj][m][n], 0, 0, 0); \
;     __builtin_amdgcn_s_setprio(0); } while (0)
; #define WAIT_L(n) asm volatile("s_waitcnt lgkmcnt(" #n ")" ::: "memory")
; #define BAR __builtin_amdgcn_s_barrier()
; #define SCHED __builtin_amdgcn_sched_barrier(0)
; template <int EPI, int lda, int ldb, int N, int K>
; __device__ __forceinline__ void gemm_phase(const u16* __restrict__ A, const u16* __restrict__ Bt, const GemmEpi ep, int wv) {
;     ...
;       LDB(B0, 0, 0); SCHED; LDA(At, 0, 0); STAGE(SA(1, 1), Ab, lda, brow + HALF, t + 1);
;       WAIT_L(8); BAR; WAIT_L(0); MMA(0, 0, At, B0); BAR; SCHED;
;       LDB(B1, 0, 1); STAGE(SB(0, 0), Bt, ldb, bcol, t + 2);
;       BAR; WAIT_L(0); MMA(0, 1, At, B1); BAR;
;       LDA(At, 0, 1); STAGE(SA(0, 0), Ab, lda, brow, t + 2);
;       BAR; WAIT_L(0); MMA(1, 0, At, B0); BAR; SCHED;
.LBB0_224:
	ds_read_b128 v[168:171], v164
	ds_read_b128 v[174:177], v164 offset:1024
	ds_read_b128 v[178:181], v164 offset:2048
	ds_read_b128 v[182:185], v164 offset:3072
	v_add_u32_e32 v172, 0xc000, v147
	v_lshl_add_u64 v[238:239], v[136:137], 0, s[44:45]
	v_readfirstlane_b32 s66, v172
	v_add_u32_e32 v173, 0xe000, v147
	v_lshl_add_u64 v[166:167], v[238:239], 0, s[18:19]
	s_mov_b32 m0, s66
	v_lshl_add_u64 v[240:241], v[134:135], 0, s[44:45]
	v_readfirstlane_b32 s66, v173
	ds_read_b128 v[186:189], v155
	ds_read_b128 v[190:193], v155 offset:1024
	ds_read_b128 v[194:197], v154
	ds_read_b128 v[198:201], v154 offset:1024
	ds_read_b128 v[202:205], v153
	ds_read_b128 v[206:209], v153 offset:1024
	ds_read_b128 v[210:213], v152
	ds_read_b128 v[214:217], v152 offset:1024
	global_load_lds_dwordx4 v[166:167], off
	s_waitcnt lgkmcnt(8)
	s_barrier
	s_waitcnt lgkmcnt(0)
	s_waitcnt lgkmcnt(0)
	v_mfma_f32_16x16x32_bf16 v[124:127], v[168:171], v[186:189], v[124:127]
	v_mfma_f32_16x16x32_bf16 v[120:123], v[178:181], v[186:189], v[120:123]
	v_mfma_f32_16x16x32_bf16 v[116:119], v[168:171], v[194:197], v[116:119]
	v_mfma_f32_16x16x32_bf16 v[112:115], v[178:181], v[194:197], v[112:115]
	v_mfma_f32_16x16x32_bf16 v[108:111], v[168:171], v[202:205], v[108:111]
	v_mfma_f32_16x16x32_bf16 v[104:107], v[178:181], v[202:205], v[104:107]
	v_mfma_f32_16x16x32_bf16 v[100:103], v[168:171], v[210:213], v[100:103]
	v_mfma_f32_16x16x32_bf16 v[96:99], v[178:181], v[210:213], v[96:99]
	v_lshl_add_u64 v[166:167], v[240:241], 0, s[18:19]
	s_mov_b32 m0, s66
	s_nop 0
	global_load_lds_dwordx4 v[166:167], off
	v_mfma_f32_16x16x32_bf16 v[124:127], v[174:177], v[190:193], v[124:127]
	v_mfma_f32_16x16x32_bf16 v[120:123], v[182:185], v[190:193], v[120:123]
	v_mfma_f32_16x16x32_bf16 v[116:119], v[174:177], v[198:201], v[116:119]
	v_mfma_f32_16x16x32_bf16 v[112:115], v[182:185], v[198:201], v[112:115]
	v_mfma_f32_16x16x32_bf16 v[108:111], v[174:177], v[206:209], v[108:111]
	v_mfma_f32_16x16x32_bf16 v[104:107], v[182:185], v[206:209], v[104:107]
	v_mfma_f32_16x16x32_bf16 v[100:103], v[174:177], v[214:217], v[100:103]
	v_mfma_f32_16x16x32_bf16 v[96:99], v[182:185], v[214:217], v[96:99]
	s_barrier
	v_add_u32_e32 v165, s55, v156
	v_lshl_add_u64 v[242:243], v[144:145], 0, s[44:45]
	v_readfirstlane_b32 s66, v165
	v_lshl_add_u64 v[166:167], v[242:243], 0, s[20:21]
	s_mov_b32 m0, s66
	ds_read_b128 v[218:221], v163
	ds_read_b128 v[222:225], v163 offset:1024
	ds_read_b128 v[226:229], v163 offset:2048
	ds_read_b128 v[230:233], v163 offset:3072
	global_load_lds_dwordx4 v[166:167], off
	v_add_u32_e32 v166, 0x2000, v165
	v_lshl_add_u64 v[244:245], v[142:143], 0, s[44:45]
	v_readfirstlane_b32 s66, v166
	v_lshl_add_u64 v[234:235], v[244:245], 0, s[20:21]
	s_mov_b32 m0, s66
	s_nop 0
	global_load_lds_dwordx4 v[234:235], off
	s_barrier
	s_waitcnt lgkmcnt(0)
	s_waitcnt lgkmcnt(0)
	v_mfma_f32_16x16x32_bf16 v[92:95], v[218:221], v[186:189], v[92:95]
	v_mfma_f32_16x16x32_bf16 v[88:91], v[226:229], v[186:189], v[88:91]
	v_mfma_f32_16x16x32_bf16 v[84:87], v[218:221], v[194:197], v[84:87]
	v_mfma_f32_16x16x32_bf16 v[80:83], v[226:229], v[194:197], v[80:83]
	v_mfma_f32_16x16x32_bf16 v[76:79], v[218:221], v[202:205], v[76:79]
	v_mfma_f32_16x16x32_bf16 v[72:75], v[226:229], v[202:205], v[72:75]
	v_mfma_f32_16x16x32_bf16 v[68:71], v[218:221], v[210:213], v[68:71]
	v_mfma_f32_16x16x32_bf16 v[64:67], v[226:229], v[210:213], v[64:67]
	v_mfma_f32_16x16x32_bf16 v[92:95], v[222:225], v[190:193], v[92:95]
	v_mfma_f32_16x16x32_bf16 v[88:91], v[230:233], v[190:193], v[88:91]
	v_mfma_f32_16x16x32_bf16 v[84:87], v[222:225], v[198:201], v[84:87]
	v_mfma_f32_16x16x32_bf16 v[80:83], v[230:233], v[198:201], v[80:83]
	v_mfma_f32_16x16x32_bf16 v[76:79], v[222:225], v[206:209], v[76:79]
	v_mfma_f32_16x16x32_bf16 v[72:75], v[230:233], v[206:209], v[72:75]
	v_mfma_f32_16x16x32_bf16 v[68:71], v[222:225], v[214:217], v[68:71]
	v_mfma_f32_16x16x32_bf16 v[64:67], v[230:233], v[214:217], v[64:67]
	s_barrier
	v_readfirstlane_b32 s66, v147
	v_add_u32_e32 v167, 0x2000, v147
	v_lshl_add_u64 v[234:235], v[238:239], 0, s[22:23]
	s_mov_b32 m0, s66
	v_readfirstlane_b32 s66, v167
	ds_read_b128 v[186:189], v155 offset:16384
	ds_read_b128 v[190:193], v155 offset:17408
	ds_read_b128 v[194:197], v154 offset:16384
	ds_read_b128 v[198:201], v154 offset:17408
	ds_read_b128 v[202:205], v153 offset:16384
	ds_read_b128 v[206:209], v153 offset:17408
	ds_read_b128 v[210:213], v152 offset:16384
	ds_read_b128 v[214:217], v152 offset:17408
	global_load_lds_dwordx4 v[234:235], off
	v_lshl_add_u64 v[234:235], v[240:241], 0, s[22:23]
	s_mov_b32 m0, s66
	s_nop 0
	global_load_lds_dwordx4 v[234:235], off
	s_barrier
	s_waitcnt lgkmcnt(0)
	s_waitcnt lgkmcnt(0)
	v_mfma_f32_16x16x32_bf16 v[60:63], v[168:171], v[186:189], v[60:63]
	v_mfma_f32_16x16x32_bf16 v[56:59], v[178:181], v[186:189], v[56:59]
	v_mfma_f32_16x16x32_bf16 v[52:55], v[168:171], v[194:197], v[52:55]
	v_mfma_f32_16x16x32_bf16 v[48:51], v[178:181], v[194:197], v[48:51]
	v_mfma_f32_16x16x32_bf16 v[44:47], v[168:171], v[202:205], v[44:47]
	v_mfma_f32_16x16x32_bf16 v[40:43], v[178:181], v[202:205], v[40:43]
	v_mfma_f32_16x16x32_bf16 v[36:39], v[168:171], v[210:213], v[36:39]
	v_mfma_f32_16x16x32_bf16 v[32:35], v[178:181], v[210:213], v[32:35]
	v_mfma_f32_16x16x32_bf16 v[60:63], v[174:177], v[190:193], v[60:63]
	v_mfma_f32_16x16x32_bf16 v[56:59], v[182:185], v[190:193], v[56:59]
	v_mfma_f32_16x16x32_bf16 v[52:55], v[174:177], v[198:201], v[52:55]
	v_mfma_f32_16x16x32_bf16 v[48:51], v[182:185], v[198:201], v[48:51]
	v_mfma_f32_16x16x32_bf16 v[44:47], v[174:177], v[206:209], v[44:47]
	v_mfma_f32_16x16x32_bf16 v[40:43], v[182:185], v[206:209], v[40:43]
	v_mfma_f32_16x16x32_bf16 v[36:39], v[174:177], v[214:217], v[36:39]
	v_mfma_f32_16x16x32_bf16 v[32:35], v[182:185], v[214:217], v[32:35]
	s_barrier
; #define STAGE(P, BASE, LD, br, kt) do { const char* _g = (const char*)((BASE) + (size_t)(br) * (LD) + (size_t)(kt) * 64); \
;     for (int _i = 0; _i < 2; ++_i) { int _b = tidx * 16 + _i * 8192; int _r, _c; stage_rc(_b, _r, _c); \
;       __builtin_amdgcn_global_load_lds((const unsigned*)(_g + (unsigned)((_r * (LD) + _c) * 2)), (unsigned*)((char*)(P) + _b), 16, 0, 0); } } while (0)
; #define LDA(dst, b, h) for (int m = 0; m < 4; ++m) for (int k = 0; k < 2; ++k) \
;     dst[m][k] = *reinterpret_cast<const bf16x8*>((char*)SA(b, h) + lds_byte(wr * 64 + m * 16 + fr, k * 32 + fq * 8))
; #define LDB(dst, b, h) for (int n = 0; n < 2; ++n) for (int k = 0; k < 2; ++k) \
;     dst[n][k] = *reinterpret_cast<const bf16x8*>((char*)SB(b, h) + lds_byte(wc * 32 + n * 16 + fr, k * 32 + fq * 8))
; #define MMA(ai, bj, At_, Bt_) do { __builtin_amdgcn_s_setprio(1); \
;     for (int k = 0; k < 2; ++k) for (int m = 0; m < 4; ++m) for (int n = 0; n < 2; ++n) \
;       acc[ai][bj][m][n] = __builtin_amdgcn_mfma_f32_16x16x32_bf16(At_[m][k], Bt_[n][k], acc[ai][bj][m][n], 0, 0, 0); \
;     __builtin_amdgcn_s_setprio(0); } while (0)
; #define WAIT_V(n) asm volatile("s_waitcnt vmcnt(" #n ")" ::: "memory")
; #define WAIT_L(n) asm volatile("s_waitcnt lgkmcnt(" #n ")" ::: "memory")
; #define BAR __builtin_amdgcn_s_barrier()
; #define SCHED __builtin_amdgcn_sched_barrier(0)
; template <int EPI, int lda, int ldb, int N, int K>
; __device__ __forceinline__ void gemm_phase(const u16* __restrict__ A, const u16* __restrict__ Bt, const GemmEpi ep, int wv) {
;     ...
;       STAGE(SB(0, 1), Bt, ldb, bcol + HALF, t + 2);
;       WAIT_V(6); BAR; MMA(1, 1, At, B1); BAR;
;       LDB(B0, 1, 0); SCHED; LDA(At, 1, 0); STAGE(SA(0, 1), Ab, lda, brow + HALF, t + 2);
;       WAIT_L(8); BAR; WAIT_L(0); MMA(0, 0, At, B0); BAR; SCHED;
;       LDB(B1, 1, 1); STAGE(SB(1, 0), Bt, ldb, bcol, t + 3);
;       BAR; WAIT_L(0); MMA(0, 1, At, B1); BAR;
	v_add_u32_e32 v168, s56, v156
	v_lshl_add_u64 v[246:247], v[140:141], 0, s[44:45]
	v_readfirstlane_b32 s66, v168
	v_add_u32_e32 v169, 0x2000, v168
	v_lshl_add_u64 v[170:171], v[246:247], 0, s[24:25]
	s_mov_b32 m0, s66
	v_lshl_add_u64 v[248:249], v[138:139], 0, s[44:45]
	v_readfirstlane_b32 s66, v169
	global_load_lds_dwordx4 v[170:171], off
	v_lshl_add_u64 v[170:171], v[248:249], 0, s[24:25]
	s_mov_b32 m0, s66
	s_nop 0
	global_load_lds_dwordx4 v[170:171], off
	s_waitcnt vmcnt(6)
	s_barrier
	v_mfma_f32_16x16x32_bf16 v[28:31], v[218:221], v[186:189], v[28:31]
	v_mfma_f32_16x16x32_bf16 v[24:27], v[226:229], v[186:189], v[24:27]
	v_mfma_f32_16x16x32_bf16 v[20:23], v[218:221], v[194:197], v[20:23]
	v_mfma_f32_16x16x32_bf16 v[16:19], v[226:229], v[194:197], v[16:19]
	v_mfma_f32_16x16x32_bf16 v[12:15], v[218:221], v[202:205], v[12:15]
	v_mfma_f32_16x16x32_bf16 v[8:11], v[226:229], v[202:205], v[8:11]
	v_mfma_f32_16x16x32_bf16 v[4:7], v[218:221], v[210:213], v[4:7]
	v_mfma_f32_16x16x32_bf16 v[0:3], v[226:229], v[210:213], v[0:3]
	v_mfma_f32_16x16x32_bf16 v[28:31], v[222:225], v[190:193], v[28:31]
	v_mfma_f32_16x16x32_bf16 v[24:27], v[230:233], v[190:193], v[24:27]
	v_mfma_f32_16x16x32_bf16 v[20:23], v[222:225], v[198:201], v[20:23]
	v_mfma_f32_16x16x32_bf16 v[16:19], v[230:233], v[198:201], v[16:19]
	v_mfma_f32_16x16x32_bf16 v[12:15], v[222:225], v[206:209], v[12:15]
	v_mfma_f32_16x16x32_bf16 v[8:11], v[230:233], v[206:209], v[8:11]
	v_mfma_f32_16x16x32_bf16 v[4:7], v[222:225], v[214:217], v[4:7]
	v_mfma_f32_16x16x32_bf16 v[0:3], v[230:233], v[214:217], v[0:3]
	s_barrier
	ds_read_b128 v[174:177], v159
	ds_read_b128 v[178:181], v159 offset:1024
	ds_read_b128 v[182:185], v159 offset:2048
	ds_read_b128 v[186:189], v159 offset:3072
	v_add_u32_e32 v170, 0x4000, v147
	v_add_u32_e32 v171, 0x6000, v147
	v_readfirstlane_b32 s66, v170
	v_lshl_add_u64 v[222:223], v[238:239], 0, s[26:27]
	s_mov_b32 m0, s66
	v_readfirstlane_b32 s66, v171
	ds_read_b128 v[190:193], v155 offset:32768
	ds_read_b128 v[194:197], v155 offset:33792
	ds_read_b128 v[198:201], v154 offset:32768
	ds_read_b128 v[202:205], v154 offset:33792
	ds_read_b128 v[206:209], v153 offset:32768
	ds_read_b128 v[210:213], v153 offset:33792
	ds_read_b128 v[214:217], v152 offset:32768
	ds_read_b128 v[218:221], v152 offset:33792
	global_load_lds_dwordx4 v[222:223], off
	s_waitcnt lgkmcnt(8)
	s_barrier
	s_waitcnt lgkmcnt(0)
	s_waitcnt lgkmcnt(0)
	v_mfma_f32_16x16x32_bf16 v[124:127], v[174:177], v[190:193], v[124:127]
	v_mfma_f32_16x16x32_bf16 v[120:123], v[182:185], v[190:193], v[120:123]
	v_mfma_f32_16x16x32_bf16 v[116:119], v[174:177], v[198:201], v[116:119]
	v_mfma_f32_16x16x32_bf16 v[112:115], v[182:185], v[198:201], v[112:115]
	v_mfma_f32_16x16x32_bf16 v[108:111], v[174:177], v[206:209], v[108:111]
	v_mfma_f32_16x16x32_bf16 v[104:107], v[182:185], v[206:209], v[104:107]
	v_mfma_f32_16x16x32_bf16 v[100:103], v[174:177], v[214:217], v[100:103]
	v_mfma_f32_16x16x32_bf16 v[96:99], v[182:185], v[214:217], v[96:99]
	v_lshl_add_u64 v[222:223], v[240:241], 0, s[26:27]
	s_mov_b32 m0, s66
	s_nop 0
	global_load_lds_dwordx4 v[222:223], off
	v_mfma_f32_16x16x32_bf16 v[124:127], v[178:181], v[194:197], v[124:127]
	v_mfma_f32_16x16x32_bf16 v[120:123], v[186:189], v[194:197], v[120:123]
	v_mfma_f32_16x16x32_bf16 v[116:119], v[178:181], v[202:205], v[116:119]
	v_mfma_f32_16x16x32_bf16 v[112:115], v[186:189], v[202:205], v[112:115]
	v_mfma_f32_16x16x32_bf16 v[108:111], v[178:181], v[210:213], v[108:111]
	v_mfma_f32_16x16x32_bf16 v[104:107], v[186:189], v[210:213], v[104:107]
	v_mfma_f32_16x16x32_bf16 v[100:103], v[178:181], v[218:221], v[100:103]
	v_mfma_f32_16x16x32_bf16 v[96:99], v[186:189], v[218:221], v[96:99]
	s_barrier
	v_readfirstlane_b32 s66, v158
	v_lshl_add_u64 v[242:243], v[242:243], 0, s[36:37]
	s_mov_b32 m0, s66
	ds_read_b128 v[222:225], v157
	ds_read_b128 v[226:229], v157 offset:1024
	ds_read_b128 v[230:233], v157 offset:2048
	ds_read_b128 v[234:237], v157 offset:3072
	global_load_lds_dwordx4 v[242:243], off
	v_lshl_add_u64 v[242:243], v[244:245], 0, s[36:37]
	v_add_u32_e32 v244, 0x2000, v158
	s_nop 0
	v_readfirstlane_b32 s66, v244
	s_mov_b32 m0, s66
	s_nop 0
	global_load_lds_dwordx4 v[242:243], off
	s_barrier
	s_waitcnt lgkmcnt(0)
	s_waitcnt lgkmcnt(0)
	v_mfma_f32_16x16x32_bf16 v[92:95], v[222:225], v[190:193], v[92:95]
	v_mfma_f32_16x16x32_bf16 v[88:91], v[230:233], v[190:193], v[88:91]
	v_mfma_f32_16x16x32_bf16 v[84:87], v[222:225], v[198:201], v[84:87]
	v_mfma_f32_16x16x32_bf16 v[80:83], v[230:233], v[198:201], v[80:83]
	v_mfma_f32_16x16x32_bf16 v[76:79], v[222:225], v[206:209], v[76:79]
	v_mfma_f32_16x16x32_bf16 v[72:75], v[230:233], v[206:209], v[72:75]
	v_mfma_f32_16x16x32_bf16 v[68:71], v[222:225], v[214:217], v[68:71]
	v_mfma_f32_16x16x32_bf16 v[64:67], v[230:233], v[214:217], v[64:67]
	v_mfma_f32_16x16x32_bf16 v[92:95], v[226:229], v[194:197], v[92:95]
	v_mfma_f32_16x16x32_bf16 v[88:91], v[234:237], v[194:197], v[88:91]
	v_mfma_f32_16x16x32_bf16 v[84:87], v[226:229], v[202:205], v[84:87]
	v_mfma_f32_16x16x32_bf16 v[80:83], v[234:237], v[202:205], v[80:83]
	v_mfma_f32_16x16x32_bf16 v[76:79], v[226:229], v[210:213], v[76:79]
	v_mfma_f32_16x16x32_bf16 v[72:75], v[234:237], v[210:213], v[72:75]
	v_mfma_f32_16x16x32_bf16 v[68:71], v[226:229], v[218:221], v[68:71]
	v_mfma_f32_16x16x32_bf16 v[64:67], v[234:237], v[218:221], v[64:67]
	s_barrier
; #define STAGE(P, BASE, LD, br, kt) do { const char* _g = (const char*)((BASE) + (size_t)(br) * (LD) + (size_t)(kt) * 64); \
;     for (int _i = 0; _i < 2; ++_i) { int _b = tidx * 16 + _i * 8192; int _r, _c; stage_rc(_b, _r, _c); \
;       __builtin_amdgcn_global_load_lds((const unsigned*)(_g + (unsigned)((_r * (LD) + _c) * 2)), (unsigned*)((char*)(P) + _b), 16, 0, 0); } } while (0)
; #define LDA(dst, b, h) for (int m = 0; m < 4; ++m) for (int k = 0; k < 2; ++k) \
;     dst[m][k] = *reinterpret_cast<const bf16x8*>((char*)SA(b, h) + lds_byte(wr * 64 + m * 16 + fr, k * 32 + fq * 8))
; #define LDB(dst, b, h) for (int n = 0; n < 2; ++n) for (int k = 0; k < 2; ++k) \
;     dst[n][k] = *reinterpret_cast<const bf16x8*>((char*)SB(b, h) + lds_byte(wc * 32 + n * 16 + fr, k * 32 + fq * 8))
; #define MMA(ai, bj, At_, Bt_) do { __builtin_amdgcn_s_setprio(1); \
;     for (int k = 0; k < 2; ++k) for (int m = 0; m < 4; ++m) for (int n = 0; n < 2; ++n) \
;       acc[ai][bj][m][n] = __builtin_amdgcn_mfma_f32_16x16x32_bf16(At_[m][k], Bt_[n][k], acc[ai][bj][m][n], 0, 0, 0); \
;     __builtin_amdgcn_s_setprio(0); } while (0)
; #define WAIT_V(n) asm volatile("s_waitcnt vmcnt(" #n ")" ::: "memory")
; #define WAIT_L(n) asm volatile("s_waitcnt lgkmcnt(" #n ")" ::: "memory")
; #define BAR __builtin_amdgcn_s_barrier()
; #define SCHED __builtin_amdgcn_sched_barrier(0)
; template <int EPI, int lda, int ldb, int N, int K>
; __device__ __forceinline__ void gemm_phase(const u16* __restrict__ A, const u16* __restrict__ Bt, const GemmEpi ep, int wv) {
;     ...
;       LDA(At, 1, 1); STAGE(SA(1, 0), Ab, lda, brow, t + 3);
;       BAR; WAIT_L(0); MMA(1, 0, At, B0); BAR; SCHED;
;       STAGE(SB(1, 1), Bt, ldb, bcol + HALF, t + 3);
;       WAIT_V(6); BAR; MMA(1, 1, At, B1); BAR;
;     }
;     { LDB(B0, 0, 0); LDA(At, 0, 0); STAGE(SA(1, 1), Ab, lda, brow + HALF, nt - 1);
;       BAR; WAIT_L(0); MMA(0, 0, At, B0); BAR;
	v_readfirstlane_b32 s66, v160
	v_lshl_add_u64 v[238:239], v[238:239], 0, s[38:39]
	s_mov_b32 m0, s66
	v_readfirstlane_b32 s66, v161
	ds_read_b128 v[190:193], v155 offset:49152
	ds_read_b128 v[194:197], v155 offset:50176
	ds_read_b128 v[198:201], v154 offset:49152
	ds_read_b128 v[202:205], v154 offset:50176
	ds_read_b128 v[206:209], v153 offset:49152
	ds_read_b128 v[210:213], v153 offset:50176
	ds_read_b128 v[214:217], v152 offset:49152
	ds_read_b128 v[218:221], v152 offset:50176
	global_load_lds_dwordx4 v[238:239], off
	v_lshl_add_u64 v[238:239], v[240:241], 0, s[38:39]
	s_mov_b32 m0, s66
	s_nop 0
	global_load_lds_dwordx4 v[238:239], off
	s_barrier
	s_waitcnt lgkmcnt(0)
	s_waitcnt lgkmcnt(0)
	v_mfma_f32_16x16x32_bf16 v[60:63], v[174:177], v[190:193], v[60:63]
	v_mfma_f32_16x16x32_bf16 v[56:59], v[182:185], v[190:193], v[56:59]
	v_mfma_f32_16x16x32_bf16 v[52:55], v[174:177], v[198:201], v[52:55]
	v_mfma_f32_16x16x32_bf16 v[48:51], v[182:185], v[198:201], v[48:51]
	v_mfma_f32_16x16x32_bf16 v[44:47], v[174:177], v[206:209], v[44:47]
	v_mfma_f32_16x16x32_bf16 v[40:43], v[182:185], v[206:209], v[40:43]
	v_mfma_f32_16x16x32_bf16 v[36:39], v[174:177], v[214:217], v[36:39]
	v_mfma_f32_16x16x32_bf16 v[32:35], v[182:185], v[214:217], v[32:35]
	v_mfma_f32_16x16x32_bf16 v[60:63], v[178:181], v[194:197], v[60:63]
	v_mfma_f32_16x16x32_bf16 v[56:59], v[186:189], v[194:197], v[56:59]
	v_mfma_f32_16x16x32_bf16 v[52:55], v[178:181], v[202:205], v[52:55]
	v_mfma_f32_16x16x32_bf16 v[48:51], v[186:189], v[202:205], v[48:51]
	v_mfma_f32_16x16x32_bf16 v[44:47], v[178:181], v[210:213], v[44:47]
	v_mfma_f32_16x16x32_bf16 v[40:43], v[186:189], v[210:213], v[40:43]
	v_mfma_f32_16x16x32_bf16 v[36:39], v[178:181], v[218:221], v[36:39]
	v_mfma_f32_16x16x32_bf16 v[32:35], v[186:189], v[218:221], v[32:35]
	s_barrier
	v_readfirstlane_b32 s66, v162
	v_add_u32_e32 v176, 0x2000, v162
	v_lshl_add_u64 v[174:175], v[246:247], 0, s[42:43]
	s_mov_b32 m0, s66
	v_readfirstlane_b32 s66, v176
	global_load_lds_dwordx4 v[174:175], off
	v_lshl_add_u64 v[174:175], v[248:249], 0, s[42:43]
	s_mov_b32 m0, s66
	s_nop 0
	global_load_lds_dwordx4 v[174:175], off
	s_waitcnt vmcnt(6)
	s_barrier
	v_mfma_f32_16x16x32_bf16 v[28:31], v[222:225], v[190:193], v[28:31]
	v_mfma_f32_16x16x32_bf16 v[24:27], v[230:233], v[190:193], v[24:27]
	v_mfma_f32_16x16x32_bf16 v[20:23], v[222:225], v[198:201], v[20:23]
	v_mfma_f32_16x16x32_bf16 v[16:19], v[230:233], v[198:201], v[16:19]
	v_mfma_f32_16x16x32_bf16 v[12:15], v[222:225], v[206:209], v[12:15]
	v_mfma_f32_16x16x32_bf16 v[8:11], v[230:233], v[206:209], v[8:11]
	v_mfma_f32_16x16x32_bf16 v[4:7], v[222:225], v[214:217], v[4:7]
	v_mfma_f32_16x16x32_bf16 v[0:3], v[230:233], v[214:217], v[0:3]
	v_mfma_f32_16x16x32_bf16 v[28:31], v[226:229], v[194:197], v[28:31]
	v_mfma_f32_16x16x32_bf16 v[24:27], v[234:237], v[194:197], v[24:27]
	v_mfma_f32_16x16x32_bf16 v[20:23], v[226:229], v[202:205], v[20:23]
	v_mfma_f32_16x16x32_bf16 v[16:19], v[234:237], v[202:205], v[16:19]
	v_mfma_f32_16x16x32_bf16 v[12:15], v[226:229], v[210:213], v[12:15]
	v_mfma_f32_16x16x32_bf16 v[8:11], v[234:237], v[210:213], v[8:11]
	v_mfma_f32_16x16x32_bf16 v[4:7], v[226:229], v[218:221], v[4:7]
	v_mfma_f32_16x16x32_bf16 v[0:3], v[234:237], v[218:221], v[0:3]
	s_add_i32 s65, s65, 2
	s_add_u32 s44, s44, 0x100
	s_addc_u32 s45, s45, 0
	s_cmpk_gt_u32 s65, 0x51
	s_barrier
	s_cbranch_scc0 .LBB0_224
	s_add_i32 s44, s14, 0x80
	s_mul_hi_i32 s45, s44, 0x2b00
	s_mulk_i32 s44, 0x2b00
	s_add_u32 s44, s48, s44
	s_addc_u32 s45, s49, s45
	s_add_u32 s44, s44, 0x2a80
	s_addc_u32 s45, s45, 0
	v_readfirstlane_b32 s65, v172
	v_lshl_add_u64 v[160:161], s[44:45], 0, v[128:129]
	s_mov_b32 m0, s65
	ds_read_b128 v[134:137], v164
	ds_read_b128 v[138:141], v164 offset:1024
	ds_read_b128 v[142:145], v164 offset:2048
	ds_read_b128 v[174:177], v164 offset:3072
	ds_read_b128 v[178:181], v155
	ds_read_b128 v[182:185], v155 offset:1024
	ds_read_b128 v[186:189], v154
	ds_read_b128 v[190:193], v154 offset:1024
	ds_read_b128 v[194:197], v153
	ds_read_b128 v[198:201], v153 offset:1024
	ds_read_b128 v[202:205], v152
	ds_read_b128 v[206:209], v152 offset:1024
	global_load_lds_dwordx4 v[160:161], off
	v_lshl_add_u64 v[160:161], s[44:45], 0, v[132:133]
	v_readfirstlane_b32 s44, v173
	s_mov_b32 m0, s44
	s_nop 0
	global_load_lds_dwordx4 v[160:161], off
	s_barrier
	s_waitcnt lgkmcnt(0)
	s_waitcnt lgkmcnt(0)
	v_mfma_f32_16x16x32_bf16 v[124:127], v[134:137], v[178:181], v[124:127]
	v_mfma_f32_16x16x32_bf16 v[120:123], v[142:145], v[178:181], v[120:123]
	v_mfma_f32_16x16x32_bf16 v[116:119], v[134:137], v[186:189], v[116:119]
	v_mfma_f32_16x16x32_bf16 v[112:115], v[142:145], v[186:189], v[112:115]
	v_mfma_f32_16x16x32_bf16 v[108:111], v[134:137], v[194:197], v[108:111]
	v_mfma_f32_16x16x32_bf16 v[104:107], v[142:145], v[194:197], v[104:107]
	v_mfma_f32_16x16x32_bf16 v[100:103], v[134:137], v[202:205], v[100:103]
	v_mfma_f32_16x16x32_bf16 v[96:99], v[142:145], v[202:205], v[96:99]
	v_mfma_f32_16x16x32_bf16 v[124:127], v[138:141], v[182:185], v[124:127]
	v_mfma_f32_16x16x32_bf16 v[120:123], v[174:177], v[182:185], v[120:123]
	v_mfma_f32_16x16x32_bf16 v[116:119], v[138:141], v[190:193], v[116:119]
	v_mfma_f32_16x16x32_bf16 v[112:115], v[174:177], v[190:193], v[112:115]
	v_mfma_f32_16x16x32_bf16 v[108:111], v[138:141], v[198:201], v[108:111]
	v_mfma_f32_16x16x32_bf16 v[104:107], v[174:177], v[198:201], v[104:107]
	v_mfma_f32_16x16x32_bf16 v[100:103], v[138:141], v[206:209], v[100:103]
	v_mfma_f32_16x16x32_bf16 v[96:99], v[174:177], v[206:209], v[96:99]
	s_barrier
; #define LDA(dst, b, h) for (int m = 0; m < 4; ++m) for (int k = 0; k < 2; ++k) \
;     dst[m][k] = *reinterpret_cast<const bf16x8*>((char*)SA(b, h) + lds_byte(wr * 64 + m * 16 + fr, k * 32 + fq * 8))
; #define LDB(dst, b, h) for (int n = 0; n < 2; ++n) for (int k = 0; k < 2; ++k) \
;     dst[n][k] = *reinterpret_cast<const bf16x8*>((char*)SB(b, h) + lds_byte(wc * 32 + n * 16 + fr, k * 32 + fq * 8))
; #define MMA(ai, bj, At_, Bt_) do { __builtin_amdgcn_s_setprio(1); \
;     for (int k = 0; k < 2; ++k) for (int m = 0; m < 4; ++m) for (int n = 0; n < 2; ++n) \
;       acc[ai][bj][m][n] = __builtin_amdgcn_mfma_f32_16x16x32_bf16(At_[m][k], Bt_[n][k], acc[ai][bj][m][n], 0, 0, 0); \
;     __builtin_amdgcn_s_setprio(0); } while (0)
; #define WAIT_V(n) asm volatile("s_waitcnt vmcnt(" #n ")" ::: "memory")
; #define WAIT_L(n) asm volatile("s_waitcnt lgkmcnt(" #n ")" ::: "memory")
; #define BAR __builtin_amdgcn_s_barrier()
; template <int EPI, int lda, int ldb, int N, int K>
; __device__ __forceinline__ void gemm_phase(const u16* __restrict__ A, const u16* __restrict__ Bt, const GemmEpi ep, int wv) {
;     ...
;       LDB(B1, 0, 1); BAR; WAIT_L(0); MMA(0, 1, At, B1); BAR;
;       LDA(At, 0, 1); WAIT_V(4); BAR; WAIT_L(0); MMA(1, 0, At, B0); MMA(1, 1, At, B1); BAR; }
;     { LDB(B0, 1, 0); LDA(At, 1, 0); WAIT_V(2); BAR; WAIT_L(0); MMA(0, 0, At, B0); BAR;
	ds_read_b128 v[210:213], v163
	ds_read_b128 v[214:217], v163 offset:1024
	ds_read_b128 v[218:221], v163 offset:2048
	ds_read_b128 v[160:163], v163 offset:3072
	s_barrier
	s_waitcnt lgkmcnt(0)
	s_waitcnt lgkmcnt(0)
	v_mfma_f32_16x16x32_bf16 v[92:95], v[210:213], v[178:181], v[92:95]
	v_mfma_f32_16x16x32_bf16 v[88:91], v[218:221], v[178:181], v[88:91]
	v_mfma_f32_16x16x32_bf16 v[76:79], v[210:213], v[194:197], v[76:79]
	v_mfma_f32_16x16x32_bf16 v[72:75], v[218:221], v[194:197], v[72:75]
	v_mfma_f32_16x16x32_bf16 v[84:87], v[210:213], v[186:189], v[84:87]
	v_mfma_f32_16x16x32_bf16 v[80:83], v[218:221], v[186:189], v[80:83]
	v_mfma_f32_16x16x32_bf16 v[68:71], v[210:213], v[202:205], v[68:71]
	v_mfma_f32_16x16x32_bf16 v[64:67], v[218:221], v[202:205], v[64:67]
	v_mfma_f32_16x16x32_bf16 v[92:95], v[214:217], v[182:185], v[92:95]
	v_mfma_f32_16x16x32_bf16 v[88:91], v[160:163], v[182:185], v[88:91]
	v_mfma_f32_16x16x32_bf16 v[76:79], v[214:217], v[198:201], v[76:79]
	v_mfma_f32_16x16x32_bf16 v[72:75], v[160:163], v[198:201], v[72:75]
	v_mfma_f32_16x16x32_bf16 v[178:181], v[214:217], v[190:193], v[84:87]
	v_mfma_f32_16x16x32_bf16 v[182:185], v[160:163], v[190:193], v[80:83]
	v_mfma_f32_16x16x32_bf16 v[186:189], v[214:217], v[206:209], v[68:71]
	v_mfma_f32_16x16x32_bf16 v[190:193], v[160:163], v[206:209], v[64:67]
	s_barrier
	s_nop 0
	ds_read_b128 v[64:67], v155 offset:16384
	ds_read_b128 v[68:71], v155 offset:17408
	ds_read_b128 v[80:83], v154 offset:16384
	ds_read_b128 v[84:87], v154 offset:17408
	ds_read_b128 v[194:197], v153 offset:16384
	ds_read_b128 v[198:201], v153 offset:17408
	ds_read_b128 v[202:205], v152 offset:16384
	ds_read_b128 v[206:209], v152 offset:17408
	s_waitcnt vmcnt(4)
	s_barrier
	s_waitcnt lgkmcnt(0)
	s_waitcnt lgkmcnt(0)
	v_mfma_f32_16x16x32_bf16 v[60:63], v[134:137], v[64:67], v[60:63]
	v_mfma_f32_16x16x32_bf16 v[56:59], v[142:145], v[64:67], v[56:59]
	v_mfma_f32_16x16x32_bf16 v[52:55], v[134:137], v[80:83], v[52:55]
	v_mfma_f32_16x16x32_bf16 v[48:51], v[142:145], v[80:83], v[48:51]
	v_mfma_f32_16x16x32_bf16 v[44:47], v[134:137], v[194:197], v[44:47]
	v_mfma_f32_16x16x32_bf16 v[40:43], v[142:145], v[194:197], v[40:43]
	v_mfma_f32_16x16x32_bf16 v[36:39], v[134:137], v[202:205], v[36:39]
	v_mfma_f32_16x16x32_bf16 v[32:35], v[142:145], v[202:205], v[32:35]
	v_mfma_f32_16x16x32_bf16 v[60:63], v[138:141], v[68:71], v[60:63]
	v_mfma_f32_16x16x32_bf16 v[56:59], v[174:177], v[68:71], v[56:59]
	v_mfma_f32_16x16x32_bf16 v[52:55], v[138:141], v[84:87], v[52:55]
	v_mfma_f32_16x16x32_bf16 v[48:51], v[174:177], v[84:87], v[48:51]
	v_mfma_f32_16x16x32_bf16 v[44:47], v[138:141], v[198:201], v[44:47]
	v_mfma_f32_16x16x32_bf16 v[40:43], v[174:177], v[198:201], v[40:43]
	v_mfma_f32_16x16x32_bf16 v[36:39], v[138:141], v[206:209], v[36:39]
	v_mfma_f32_16x16x32_bf16 v[32:35], v[174:177], v[206:209], v[32:35]
	v_mfma_f32_16x16x32_bf16 v[28:31], v[210:213], v[64:67], v[28:31]
	v_mfma_f32_16x16x32_bf16 v[16:19], v[218:221], v[80:83], v[16:19]
	v_mfma_f32_16x16x32_bf16 v[12:15], v[210:213], v[194:197], v[12:15]
	v_mfma_f32_16x16x32_bf16 v[0:3], v[218:221], v[202:205], v[0:3]
	v_mfma_f32_16x16x32_bf16 v[24:27], v[218:221], v[64:67], v[24:27]
	v_mfma_f32_16x16x32_bf16 v[20:23], v[210:213], v[80:83], v[20:23]
	v_mfma_f32_16x16x32_bf16 v[8:11], v[218:221], v[194:197], v[8:11]
	v_mfma_f32_16x16x32_bf16 v[4:7], v[210:213], v[202:205], v[4:7]
	v_mfma_f32_16x16x32_bf16 v[28:31], v[214:217], v[68:71], v[28:31]
	v_mfma_f32_16x16x32_bf16 v[16:19], v[160:163], v[84:87], v[16:19]
	v_mfma_f32_16x16x32_bf16 v[12:15], v[214:217], v[198:201], v[12:15]
	v_mfma_f32_16x16x32_bf16 v[0:3], v[160:163], v[206:209], v[0:3]
	v_mfma_f32_16x16x32_bf16 v[134:137], v[160:163], v[68:71], v[24:27]
	v_mfma_f32_16x16x32_bf16 v[138:141], v[214:217], v[84:87], v[20:23]
	v_mfma_f32_16x16x32_bf16 v[142:145], v[160:163], v[198:201], v[8:11]
	v_mfma_f32_16x16x32_bf16 v[172:175], v[214:217], v[206:209], v[4:7]
	s_barrier
	s_nop 0
	ds_read_b128 v[4:7], v159
	ds_read_b128 v[8:11], v159 offset:1024
	ds_read_b128 v[20:23], v159 offset:2048
	ds_read_b128 v[158:161], v159 offset:3072
	ds_read_b128 v[24:27], v155 offset:32768
	ds_read_b128 v[194:197], v155 offset:33792
	ds_read_b128 v[198:201], v154 offset:32768
	ds_read_b128 v[202:205], v154 offset:33792
	ds_read_b128 v[206:209], v153 offset:32768
	ds_read_b128 v[210:213], v153 offset:33792
	ds_read_b128 v[214:217], v152 offset:32768
	ds_read_b128 v[218:221], v152 offset:33792
	s_waitcnt vmcnt(2)
	s_barrier
; #define LDA(dst, b, h) for (int m = 0; m < 4; ++m) for (int k = 0; k < 2; ++k) \
;     dst[m][k] = *reinterpret_cast<const bf16x8*>((char*)SA(b, h) + lds_byte(wr * 64 + m * 16 + fr, k * 32 + fq * 8))
; #define LDB(dst, b, h) for (int n = 0; n < 2; ++n) for (int k = 0; k < 2; ++k) \
;     dst[n][k] = *reinterpret_cast<const bf16x8*>((char*)SB(b, h) + lds_byte(wc * 32 + n * 16 + fr, k * 32 + fq * 8))
; #define MMA(ai, bj, At_, Bt_) do { __builtin_amdgcn_s_setprio(1); \
;     for (int k = 0; k < 2; ++k) for (int m = 0; m < 4; ++m) for (int n = 0; n < 2; ++n) \
;       acc[ai][bj][m][n] = __builtin_amdgcn_mfma_f32_16x16x32_bf16(At_[m][k], Bt_[n][k], acc[ai][bj][m][n], 0, 0, 0); \
;     __builtin_amdgcn_s_setprio(0); } while (0)
; #define WAIT_V(n) asm volatile("s_waitcnt vmcnt(" #n ")" ::: "memory")
; #define WAIT_L(n) asm volatile("s_waitcnt lgkmcnt(" #n ")" ::: "memory")
; #define BAR __builtin_amdgcn_s_barrier()
; template <int EPI, int lda, int ldb, int N, int K>
; __device__ __forceinline__ void gemm_phase(const u16* __restrict__ A, const u16* __restrict__ Bt, const GemmEpi ep, int wv) {
;     ...
;     { LDB(B0, 1, 0); LDA(At, 1, 0); WAIT_V(2); BAR; WAIT_L(0); MMA(0, 0, At, B0); BAR;
;       LDB(B1, 1, 1); WAIT_V(0); BAR; WAIT_L(0); MMA(0, 1, At, B1); BAR;
;       LDA(At, 1, 1); BAR; WAIT_L(0); MMA(1, 0, At, B0); MMA(1, 1, At, B1); BAR; }
;     if (wr == 0) BAR;
	s_waitcnt lgkmcnt(0)
	s_waitcnt lgkmcnt(0)
	v_mfma_f32_16x16x32_bf16 v[64:67], v[4:7], v[24:27], v[124:127]
	v_mfma_f32_16x16x32_bf16 v[68:71], v[20:23], v[24:27], v[120:123]
	v_mfma_f32_16x16x32_bf16 v[80:83], v[4:7], v[198:201], v[116:119]
	v_mfma_f32_16x16x32_bf16 v[84:87], v[20:23], v[198:201], v[112:115]
	v_mfma_f32_16x16x32_bf16 v[108:111], v[4:7], v[206:209], v[108:111]
	v_mfma_f32_16x16x32_bf16 v[104:107], v[20:23], v[206:209], v[104:107]
	v_mfma_f32_16x16x32_bf16 v[120:123], v[4:7], v[214:217], v[100:103]
	v_mfma_f32_16x16x32_bf16 v[124:127], v[20:23], v[214:217], v[96:99]
	v_mfma_f32_16x16x32_bf16 v[116:119], v[8:11], v[194:197], v[64:67]
	v_mfma_f32_16x16x32_bf16 v[112:115], v[158:161], v[194:197], v[68:71]
	v_mfma_f32_16x16x32_bf16 v[100:103], v[8:11], v[202:205], v[80:83]
	v_mfma_f32_16x16x32_bf16 v[96:99], v[158:161], v[202:205], v[84:87]
	v_mfma_f32_16x16x32_bf16 v[84:87], v[8:11], v[210:213], v[108:111]
	v_mfma_f32_16x16x32_bf16 v[80:83], v[158:161], v[210:213], v[104:107]
	v_mfma_f32_16x16x32_bf16 v[68:71], v[8:11], v[218:221], v[120:123]
	v_mfma_f32_16x16x32_bf16 v[64:67], v[158:161], v[218:221], v[124:127]
	s_barrier
	ds_read_b128 v[222:225], v157
	ds_read_b128 v[226:229], v157 offset:1024
	ds_read_b128 v[230:233], v157 offset:2048
	ds_read_b128 v[234:237], v157 offset:3072
	s_waitcnt vmcnt(0)
	s_barrier
	s_waitcnt lgkmcnt(0)
	s_waitcnt lgkmcnt(0)
	v_mfma_f32_16x16x32_bf16 v[92:95], v[222:225], v[24:27], v[92:95]
	v_mfma_f32_16x16x32_bf16 v[24:27], v[230:233], v[24:27], v[88:91]
	v_mfma_f32_16x16x32_bf16 v[88:91], v[222:225], v[198:201], v[178:181]
	v_mfma_f32_16x16x32_bf16 v[104:107], v[230:233], v[198:201], v[182:185]
	v_mfma_f32_16x16x32_bf16 v[76:79], v[222:225], v[206:209], v[76:79]
	v_mfma_f32_16x16x32_bf16 v[72:75], v[230:233], v[206:209], v[72:75]
	v_mfma_f32_16x16x32_bf16 v[176:179], v[222:225], v[214:217], v[186:189]
	v_mfma_f32_16x16x32_bf16 v[180:183], v[230:233], v[214:217], v[190:193]
	v_mfma_f32_16x16x32_bf16 v[124:127], v[226:229], v[194:197], v[92:95]
	v_mfma_f32_16x16x32_bf16 v[120:123], v[234:237], v[194:197], v[24:27]
	v_mfma_f32_16x16x32_bf16 v[108:111], v[226:229], v[202:205], v[88:91]
	v_mfma_f32_16x16x32_bf16 v[104:107], v[234:237], v[202:205], v[104:107]
	v_mfma_f32_16x16x32_bf16 v[92:95], v[226:229], v[210:213], v[76:79]
	v_mfma_f32_16x16x32_bf16 v[88:91], v[234:237], v[210:213], v[72:75]
	v_mfma_f32_16x16x32_bf16 v[76:79], v[226:229], v[218:221], v[176:179]
	v_mfma_f32_16x16x32_bf16 v[72:75], v[234:237], v[218:221], v[180:183]
	s_barrier
	ds_read_b128 v[176:179], v155 offset:49152
	ds_read_b128 v[180:183], v155 offset:50176
	ds_read_b128 v[184:187], v154 offset:49152
	ds_read_b128 v[154:157], v154 offset:50176
	ds_read_b128 v[188:191], v153 offset:49152
	ds_read_b128 v[192:195], v153 offset:50176
	ds_read_b128 v[196:199], v152 offset:49152
	ds_read_b128 v[200:203], v152 offset:50176
	s_barrier
	s_waitcnt lgkmcnt(0)
	s_waitcnt lgkmcnt(0)
	v_mfma_f32_16x16x32_bf16 v[24:27], v[4:7], v[176:179], v[60:63]
	v_mfma_f32_16x16x32_bf16 v[60:63], v[20:23], v[176:179], v[56:59]
	v_mfma_f32_16x16x32_bf16 v[204:207], v[4:7], v[184:187], v[52:55]
	v_mfma_f32_16x16x32_bf16 v[48:51], v[20:23], v[184:187], v[48:51]
	v_mfma_f32_16x16x32_bf16 v[44:47], v[4:7], v[188:191], v[44:47]
	v_mfma_f32_16x16x32_bf16 v[208:211], v[20:23], v[188:191], v[40:43]
	v_mfma_f32_16x16x32_bf16 v[4:7], v[4:7], v[196:199], v[36:39]
	v_mfma_f32_16x16x32_bf16 v[32:35], v[20:23], v[196:199], v[32:35]
	v_mfma_f32_16x16x32_bf16 v[56:59], v[8:11], v[180:183], v[24:27]
	v_mfma_f32_16x16x32_bf16 v[52:55], v[158:161], v[180:183], v[60:63]
	v_mfma_f32_16x16x32_bf16 v[40:43], v[8:11], v[154:157], v[204:207]
	v_mfma_f32_16x16x32_bf16 v[36:39], v[158:161], v[154:157], v[48:51]
	v_mfma_f32_16x16x32_bf16 v[24:27], v[8:11], v[192:195], v[44:47]
	v_mfma_f32_16x16x32_bf16 v[20:23], v[158:161], v[192:195], v[208:211]
	v_mfma_f32_16x16x32_bf16 v[8:11], v[8:11], v[200:203], v[4:7]
	v_mfma_f32_16x16x32_bf16 v[4:7], v[158:161], v[200:203], v[32:35]
	v_mfma_f32_16x16x32_bf16 v[28:31], v[222:225], v[176:179], v[28:31]
	v_mfma_f32_16x16x32_bf16 v[32:35], v[230:233], v[176:179], v[134:137]
	v_mfma_f32_16x16x32_bf16 v[44:47], v[222:225], v[184:187], v[138:141]
	v_mfma_f32_16x16x32_bf16 v[16:19], v[230:233], v[184:187], v[16:19]
	v_mfma_f32_16x16x32_bf16 v[12:15], v[222:225], v[188:191], v[12:15]
	v_mfma_f32_16x16x32_bf16 v[134:137], v[230:233], v[188:191], v[142:145]
	v_mfma_f32_16x16x32_bf16 v[138:141], v[222:225], v[196:199], v[172:175]
	v_mfma_f32_16x16x32_bf16 v[0:3], v[230:233], v[196:199], v[0:3]
	v_mfma_f32_16x16x32_bf16 v[60:63], v[226:229], v[180:183], v[28:31]
	v_mfma_f32_16x16x32_bf16 v[48:51], v[234:237], v[180:183], v[32:35]
	v_mfma_f32_16x16x32_bf16 v[44:47], v[226:229], v[154:157], v[44:47]
	v_mfma_f32_16x16x32_bf16 v[32:35], v[234:237], v[154:157], v[16:19]
	v_mfma_f32_16x16x32_bf16 v[28:31], v[226:229], v[192:195], v[12:15]
	v_mfma_f32_16x16x32_bf16 v[16:19], v[234:237], v[192:195], v[134:137]
	v_mfma_f32_16x16x32_bf16 v[12:15], v[226:229], v[200:203], v[138:141]
	v_mfma_f32_16x16x32_bf16 v[0:3], v[234:237], v[200:203], v[0:3]
	v_cmp_gt_u32_e32 vcc, s62, v130
	s_barrier
	s_and_saveexec_b64 s[44:45], vcc
	s_cbranch_execz .LBB0_227
	s_barrier

; #define STAGE(P, BASE, LD, br, kt) do { const char* _g = (const char*)((BASE) + (size_t)(br) * (LD) + (size_t)(kt) * 64); \
;     for (int _i = 0; _i < 2; ++_i) { int _b = tidx * 16 + _i * 8192; int _r, _c; stage_rc(_b, _r, _c); \
;       __builtin_amdgcn_global_load_lds((const unsigned*)(_g + (unsigned)((_r * (LD) + _c) * 2)), (unsigned*)((char*)(P) + _b), 16, 0, 0); } } while (0)
; #define LDA(dst, b, h) for (int m = 0; m < 4; ++m) for (int k = 0; k < 2; ++k) \
;     dst[m][k] = *reinterpret_cast<const bf16x8*>((char*)SA(b, h) + lds_byte(wr * 64 + m * 16 + fr, k * 32 + fq * 8))
; #define LDB(dst, b, h) for (int n = 0; n < 2; ++n) for (int k = 0; k < 2; ++k) \
;     dst[n][k] = *reinterpret_cast<const bf16x8*>((char*)SB(b, h) + lds_byte(wc * 32 + n * 16 + fr, k * 32 + fq * 8))
; #define MMA(ai, bj, At_, Bt_) do { __builtin_amdgcn_s_setprio(1); \
;     for (int k = 0; k < 2; ++k) for (int m = 0; m < 4; ++m) for (int n = 0; n < 2; ++n) \
;       acc[ai][bj][m][n] = __builtin_amdgcn_mfma_f32_16x16x32_bf16(At_[m][k], Bt_[n][k], acc[ai][bj][m][n], 0, 0, 0); \
;     __builtin_amdgcn_s_setprio(0); } while (0)
; #define WAIT_L(n) asm volatile("s_waitcnt lgkmcnt(" #n ")" ::: "memory")
; #define BAR __builtin_amdgcn_s_barrier()
; #define SCHED __builtin_amdgcn_sched_barrier(0)
; template <int EPI, int lda, int ldb, int N, int K>
; __device__ __forceinline__ void gemm_phase(const u16* __restrict__ A, const u16* __restrict__ Bt, const GemmEpi ep, int wv) {
;     ...
;       LDB(B0, 0, 0); SCHED; LDA(At, 0, 0); STAGE(SA(1, 1), Ab, lda, brow + HALF, t + 1);
;       WAIT_L(8); BAR; WAIT_L(0); MMA(0, 0, At, B0); BAR; SCHED;
;       LDB(B1, 0, 1); STAGE(SB(0, 0), Bt, ldb, bcol, t + 2);
;       BAR; WAIT_L(0); MMA(0, 1, At, B1); BAR;
;       LDA(At, 0, 1); STAGE(SA(0, 0), Ab, lda, brow, t + 2);
;       BAR; WAIT_L(0); MMA(1, 0, At, B0); BAR; SCHED;
.LBB0_340:
	ds_read_b128 v[166:169], v162
	ds_read_b128 v[172:175], v162 offset:1024
	ds_read_b128 v[176:179], v162 offset:2048
	ds_read_b128 v[180:183], v162 offset:3072
	v_add_u32_e32 v170, 0xc000, v149
	v_lshl_add_u64 v[236:237], v[138:139], 0, s[48:49]
	v_readfirstlane_b32 s51, v170
	v_add_u32_e32 v171, 0xe000, v149
	v_lshl_add_u64 v[164:165], v[236:237], 0, s[18:19]
	s_mov_b32 m0, s51
	v_lshl_add_u64 v[238:239], v[140:141], 0, s[48:49]
	v_readfirstlane_b32 s51, v171
	ds_read_b128 v[184:187], v153
	ds_read_b128 v[188:191], v153 offset:1024
	ds_read_b128 v[192:195], v152
	ds_read_b128 v[196:199], v152 offset:1024
	ds_read_b128 v[200:203], v151
	ds_read_b128 v[204:207], v151 offset:1024
	ds_read_b128 v[208:211], v150
	ds_read_b128 v[212:215], v150 offset:1024
	global_load_lds_dwordx4 v[164:165], off
	s_waitcnt lgkmcnt(8)
	s_barrier
	s_waitcnt lgkmcnt(0)
	s_waitcnt lgkmcnt(0)
	v_mfma_f32_16x16x32_bf16 v[124:127], v[184:187], v[166:169], v[124:127]
	v_mfma_f32_16x16x32_bf16 v[120:123], v[184:187], v[176:179], v[120:123]
	v_mfma_f32_16x16x32_bf16 v[116:119], v[192:195], v[166:169], v[116:119]
	v_mfma_f32_16x16x32_bf16 v[112:115], v[192:195], v[176:179], v[112:115]
	v_mfma_f32_16x16x32_bf16 v[108:111], v[200:203], v[166:169], v[108:111]
	v_mfma_f32_16x16x32_bf16 v[104:107], v[200:203], v[176:179], v[104:107]
	v_mfma_f32_16x16x32_bf16 v[100:103], v[208:211], v[166:169], v[100:103]
	v_mfma_f32_16x16x32_bf16 v[96:99], v[208:211], v[176:179], v[96:99]
	v_lshl_add_u64 v[164:165], v[238:239], 0, s[18:19]
	s_mov_b32 m0, s51
	s_nop 0
	global_load_lds_dwordx4 v[164:165], off
	v_mfma_f32_16x16x32_bf16 v[124:127], v[188:191], v[172:175], v[124:127]
	v_mfma_f32_16x16x32_bf16 v[120:123], v[188:191], v[180:183], v[120:123]
	v_mfma_f32_16x16x32_bf16 v[116:119], v[196:199], v[172:175], v[116:119]
	v_mfma_f32_16x16x32_bf16 v[112:115], v[196:199], v[180:183], v[112:115]
	v_mfma_f32_16x16x32_bf16 v[108:111], v[204:207], v[172:175], v[108:111]
	v_mfma_f32_16x16x32_bf16 v[104:107], v[204:207], v[180:183], v[104:107]
	v_mfma_f32_16x16x32_bf16 v[100:103], v[212:215], v[172:175], v[100:103]
	v_mfma_f32_16x16x32_bf16 v[96:99], v[212:215], v[180:183], v[96:99]
	s_barrier
	v_add_u32_e32 v163, s62, v155
	v_lshl_add_u64 v[240:241], v[134:135], 0, s[48:49]
	v_readfirstlane_b32 s51, v163
	v_lshl_add_u64 v[164:165], v[240:241], 0, s[20:21]
	s_mov_b32 m0, s51
	ds_read_b128 v[216:219], v161
	ds_read_b128 v[220:223], v161 offset:1024
	ds_read_b128 v[224:227], v161 offset:2048
	ds_read_b128 v[228:231], v161 offset:3072
	global_load_lds_dwordx4 v[164:165], off
	v_add_u32_e32 v164, 0x2000, v163
	v_lshl_add_u64 v[242:243], v[136:137], 0, s[48:49]
	v_readfirstlane_b32 s51, v164
	v_lshl_add_u64 v[232:233], v[242:243], 0, s[20:21]
	s_mov_b32 m0, s51
	s_nop 0
	global_load_lds_dwordx4 v[232:233], off
	s_barrier
	s_waitcnt lgkmcnt(0)
	s_waitcnt lgkmcnt(0)
	v_mfma_f32_16x16x32_bf16 v[92:95], v[184:187], v[216:219], v[92:95]
	v_mfma_f32_16x16x32_bf16 v[88:91], v[184:187], v[224:227], v[88:91]
	v_mfma_f32_16x16x32_bf16 v[84:87], v[192:195], v[216:219], v[84:87]
	v_mfma_f32_16x16x32_bf16 v[80:83], v[192:195], v[224:227], v[80:83]
	v_mfma_f32_16x16x32_bf16 v[76:79], v[200:203], v[216:219], v[76:79]
	v_mfma_f32_16x16x32_bf16 v[72:75], v[200:203], v[224:227], v[72:75]
	v_mfma_f32_16x16x32_bf16 v[68:71], v[208:211], v[216:219], v[68:71]
	v_mfma_f32_16x16x32_bf16 v[64:67], v[208:211], v[224:227], v[64:67]
	v_mfma_f32_16x16x32_bf16 v[92:95], v[188:191], v[220:223], v[92:95]
	v_mfma_f32_16x16x32_bf16 v[88:91], v[188:191], v[228:231], v[88:91]
	v_mfma_f32_16x16x32_bf16 v[84:87], v[196:199], v[220:223], v[84:87]
	v_mfma_f32_16x16x32_bf16 v[80:83], v[196:199], v[228:231], v[80:83]
	v_mfma_f32_16x16x32_bf16 v[76:79], v[204:207], v[220:223], v[76:79]
	v_mfma_f32_16x16x32_bf16 v[72:75], v[204:207], v[228:231], v[72:75]
	v_mfma_f32_16x16x32_bf16 v[68:71], v[212:215], v[220:223], v[68:71]
	v_mfma_f32_16x16x32_bf16 v[64:67], v[212:215], v[228:231], v[64:67]
	s_barrier
	v_readfirstlane_b32 s51, v149
	v_add_u32_e32 v165, 0x2000, v149
	v_lshl_add_u64 v[232:233], v[236:237], 0, s[22:23]
	s_mov_b32 m0, s51
	v_readfirstlane_b32 s51, v165
	ds_read_b128 v[184:187], v153 offset:16384
	ds_read_b128 v[188:191], v153 offset:17408
	ds_read_b128 v[192:195], v152 offset:16384
	ds_read_b128 v[196:199], v152 offset:17408
	ds_read_b128 v[200:203], v151 offset:16384
	ds_read_b128 v[204:207], v151 offset:17408
	ds_read_b128 v[208:211], v150 offset:16384
	ds_read_b128 v[212:215], v150 offset:17408
	global_load_lds_dwordx4 v[232:233], off
	v_lshl_add_u64 v[232:233], v[238:239], 0, s[22:23]
	s_mov_b32 m0, s51
	s_nop 0
	global_load_lds_dwordx4 v[232:233], off
	s_barrier
	s_waitcnt lgkmcnt(0)
	s_waitcnt lgkmcnt(0)
	v_mfma_f32_16x16x32_bf16 v[60:63], v[184:187], v[166:169], v[60:63]
	v_mfma_f32_16x16x32_bf16 v[56:59], v[184:187], v[176:179], v[56:59]
	v_mfma_f32_16x16x32_bf16 v[52:55], v[192:195], v[166:169], v[52:55]
	v_mfma_f32_16x16x32_bf16 v[48:51], v[192:195], v[176:179], v[48:51]
	v_mfma_f32_16x16x32_bf16 v[44:47], v[200:203], v[166:169], v[44:47]
	v_mfma_f32_16x16x32_bf16 v[40:43], v[200:203], v[176:179], v[40:43]
	v_mfma_f32_16x16x32_bf16 v[36:39], v[208:211], v[166:169], v[36:39]
	v_mfma_f32_16x16x32_bf16 v[32:35], v[208:211], v[176:179], v[32:35]
	v_mfma_f32_16x16x32_bf16 v[60:63], v[188:191], v[172:175], v[60:63]
	v_mfma_f32_16x16x32_bf16 v[56:59], v[188:191], v[180:183], v[56:59]
	v_mfma_f32_16x16x32_bf16 v[52:55], v[196:199], v[172:175], v[52:55]
	v_mfma_f32_16x16x32_bf16 v[48:51], v[196:199], v[180:183], v[48:51]
	v_mfma_f32_16x16x32_bf16 v[44:47], v[204:207], v[172:175], v[44:47]
	v_mfma_f32_16x16x32_bf16 v[40:43], v[204:207], v[180:183], v[40:43]
	v_mfma_f32_16x16x32_bf16 v[36:39], v[212:215], v[172:175], v[36:39]
	v_mfma_f32_16x16x32_bf16 v[32:35], v[212:215], v[180:183], v[32:35]
	s_barrier
; #define STAGE(P, BASE, LD, br, kt) do { const char* _g = (const char*)((BASE) + (size_t)(br) * (LD) + (size_t)(kt) * 64); \
;     for (int _i = 0; _i < 2; ++_i) { int _b = tidx * 16 + _i * 8192; int _r, _c; stage_rc(_b, _r, _c); \
;       __builtin_amdgcn_global_load_lds((const unsigned*)(_g + (unsigned)((_r * (LD) + _c) * 2)), (unsigned*)((char*)(P) + _b), 16, 0, 0); } } while (0)
; #define LDA(dst, b, h) for (int m = 0; m < 4; ++m) for (int k = 0; k < 2; ++k) \
;     dst[m][k] = *reinterpret_cast<const bf16x8*>((char*)SA(b, h) + lds_byte(wr * 64 + m * 16 + fr, k * 32 + fq * 8))
; #define LDB(dst, b, h) for (int n = 0; n < 2; ++n) for (int k = 0; k < 2; ++k) \
;     dst[n][k] = *reinterpret_cast<const bf16x8*>((char*)SB(b, h) + lds_byte(wc * 32 + n * 16 + fr, k * 32 + fq * 8))
; #define MMA(ai, bj, At_, Bt_) do { __builtin_amdgcn_s_setprio(1); \
;     for (int k = 0; k < 2; ++k) for (int m = 0; m < 4; ++m) for (int n = 0; n < 2; ++n) \
;       acc[ai][bj][m][n] = __builtin_amdgcn_mfma_f32_16x16x32_bf16(At_[m][k], Bt_[n][k], acc[ai][bj][m][n], 0, 0, 0); \
;     __builtin_amdgcn_s_setprio(0); } while (0)
; #define WAIT_V(n) asm volatile("s_waitcnt vmcnt(" #n ")" ::: "memory")
; #define WAIT_L(n) asm volatile("s_waitcnt lgkmcnt(" #n ")" ::: "memory")
; #define BAR __builtin_amdgcn_s_barrier()
; #define SCHED __builtin_amdgcn_sched_barrier(0)
; template <int EPI, int lda, int ldb, int N, int K>
; __device__ __forceinline__ void gemm_phase(const u16* __restrict__ A, const u16* __restrict__ Bt, const GemmEpi ep, int wv) {
;     ...
;       STAGE(SB(0, 1), Bt, ldb, bcol + HALF, t + 2);
;       WAIT_V(6); BAR; MMA(1, 1, At, B1); BAR;
;       LDB(B0, 1, 0); SCHED; LDA(At, 1, 0); STAGE(SA(0, 1), Ab, lda, brow + HALF, t + 2);
;       WAIT_L(8); BAR; WAIT_L(0); MMA(0, 0, At, B0); BAR; SCHED;
;       LDB(B1, 1, 1); STAGE(SB(1, 0), Bt, ldb, bcol, t + 3);
;       BAR; WAIT_L(0); MMA(0, 1, At, B1); BAR;
;       LDA(At, 1, 1); STAGE(SA(1, 0), Ab, lda, brow, t + 3);
;       BAR; WAIT_L(0); MMA(1, 0, At, B0); BAR; SCHED;
	v_add_u32_e32 v166, s63, v155
	v_add_u32_e32 v167, 0x2000, v166
	v_readfirstlane_b32 s51, v166
	v_lshl_add_u64 v[168:169], v[240:241], 0, s[24:25]
	s_mov_b32 m0, s51
	v_readfirstlane_b32 s51, v167
	global_load_lds_dwordx4 v[168:169], off
	v_lshl_add_u64 v[168:169], v[242:243], 0, s[24:25]
	s_mov_b32 m0, s51
	s_nop 0
	global_load_lds_dwordx4 v[168:169], off
	s_waitcnt vmcnt(6)
	s_barrier
	v_mfma_f32_16x16x32_bf16 v[28:31], v[184:187], v[216:219], v[28:31]
	v_mfma_f32_16x16x32_bf16 v[24:27], v[184:187], v[224:227], v[24:27]
	v_mfma_f32_16x16x32_bf16 v[20:23], v[192:195], v[216:219], v[20:23]
	v_mfma_f32_16x16x32_bf16 v[16:19], v[192:195], v[224:227], v[16:19]
	v_mfma_f32_16x16x32_bf16 v[12:15], v[200:203], v[216:219], v[12:15]
	v_mfma_f32_16x16x32_bf16 v[8:11], v[200:203], v[224:227], v[8:11]
	v_mfma_f32_16x16x32_bf16 v[4:7], v[208:211], v[216:219], v[4:7]
	v_mfma_f32_16x16x32_bf16 v[0:3], v[208:211], v[224:227], v[0:3]
	v_mfma_f32_16x16x32_bf16 v[28:31], v[188:191], v[220:223], v[28:31]
	v_mfma_f32_16x16x32_bf16 v[24:27], v[188:191], v[228:231], v[24:27]
	v_mfma_f32_16x16x32_bf16 v[20:23], v[196:199], v[220:223], v[20:23]
	v_mfma_f32_16x16x32_bf16 v[16:19], v[196:199], v[228:231], v[16:19]
	v_mfma_f32_16x16x32_bf16 v[12:15], v[204:207], v[220:223], v[12:15]
	v_mfma_f32_16x16x32_bf16 v[8:11], v[204:207], v[228:231], v[8:11]
	v_mfma_f32_16x16x32_bf16 v[4:7], v[212:215], v[220:223], v[4:7]
	v_mfma_f32_16x16x32_bf16 v[0:3], v[212:215], v[228:231], v[0:3]
	s_barrier
	ds_read_b128 v[172:175], v156
	ds_read_b128 v[176:179], v156 offset:1024
	ds_read_b128 v[180:183], v156 offset:2048
	ds_read_b128 v[184:187], v156 offset:3072
	v_add_u32_e32 v168, 0x4000, v149
	v_add_u32_e32 v169, 0x6000, v149
	v_readfirstlane_b32 s51, v168
	v_lshl_add_u64 v[220:221], v[236:237], 0, s[26:27]
	s_mov_b32 m0, s51
	v_readfirstlane_b32 s51, v169
	ds_read_b128 v[188:191], v153 offset:32768
	ds_read_b128 v[192:195], v153 offset:33792
	ds_read_b128 v[196:199], v152 offset:32768
	ds_read_b128 v[200:203], v152 offset:33792
	ds_read_b128 v[204:207], v151 offset:32768
	ds_read_b128 v[208:211], v151 offset:33792
	ds_read_b128 v[212:215], v150 offset:32768
	ds_read_b128 v[216:219], v150 offset:33792
	global_load_lds_dwordx4 v[220:221], off
	s_waitcnt lgkmcnt(8)
	s_barrier
	s_waitcnt lgkmcnt(0)
	s_waitcnt lgkmcnt(0)
	v_mfma_f32_16x16x32_bf16 v[124:127], v[188:191], v[172:175], v[124:127]
	v_mfma_f32_16x16x32_bf16 v[120:123], v[188:191], v[180:183], v[120:123]
	v_mfma_f32_16x16x32_bf16 v[116:119], v[196:199], v[172:175], v[116:119]
	v_mfma_f32_16x16x32_bf16 v[112:115], v[196:199], v[180:183], v[112:115]
	v_mfma_f32_16x16x32_bf16 v[108:111], v[204:207], v[172:175], v[108:111]
	v_mfma_f32_16x16x32_bf16 v[104:107], v[204:207], v[180:183], v[104:107]
	v_mfma_f32_16x16x32_bf16 v[100:103], v[212:215], v[172:175], v[100:103]
	v_mfma_f32_16x16x32_bf16 v[96:99], v[212:215], v[180:183], v[96:99]
	v_lshl_add_u64 v[220:221], v[238:239], 0, s[26:27]
	s_mov_b32 m0, s51
	s_nop 0
	global_load_lds_dwordx4 v[220:221], off
	v_mfma_f32_16x16x32_bf16 v[124:127], v[192:195], v[176:179], v[124:127]
	v_mfma_f32_16x16x32_bf16 v[120:123], v[192:195], v[184:187], v[120:123]
	v_mfma_f32_16x16x32_bf16 v[116:119], v[200:203], v[176:179], v[116:119]
	v_mfma_f32_16x16x32_bf16 v[112:115], v[200:203], v[184:187], v[112:115]
	v_mfma_f32_16x16x32_bf16 v[108:111], v[208:211], v[176:179], v[108:111]
	v_mfma_f32_16x16x32_bf16 v[104:107], v[208:211], v[184:187], v[104:107]
	v_mfma_f32_16x16x32_bf16 v[100:103], v[216:219], v[176:179], v[100:103]
	v_mfma_f32_16x16x32_bf16 v[96:99], v[216:219], v[184:187], v[96:99]
	s_barrier
	v_readfirstlane_b32 s51, v157
	v_add_u32_e32 v246, 0x2000, v157
	v_lshl_add_u64 v[244:245], v[240:241], 0, s[36:37]
	s_mov_b32 m0, s51
	v_readfirstlane_b32 s51, v246
	ds_read_b128 v[220:223], v154
	ds_read_b128 v[224:227], v154 offset:1024
	ds_read_b128 v[228:231], v154 offset:2048
	ds_read_b128 v[232:235], v154 offset:3072
	global_load_lds_dwordx4 v[244:245], off
	v_lshl_add_u64 v[244:245], v[242:243], 0, s[36:37]
	s_mov_b32 m0, s51
	s_nop 0
	global_load_lds_dwordx4 v[244:245], off
	s_barrier
	s_waitcnt lgkmcnt(0)
	s_waitcnt lgkmcnt(0)
	v_mfma_f32_16x16x32_bf16 v[92:95], v[188:191], v[220:223], v[92:95]
	v_mfma_f32_16x16x32_bf16 v[88:91], v[188:191], v[228:231], v[88:91]
	v_mfma_f32_16x16x32_bf16 v[84:87], v[196:199], v[220:223], v[84:87]
	v_mfma_f32_16x16x32_bf16 v[80:83], v[196:199], v[228:231], v[80:83]
	v_mfma_f32_16x16x32_bf16 v[76:79], v[204:207], v[220:223], v[76:79]
	v_mfma_f32_16x16x32_bf16 v[72:75], v[204:207], v[228:231], v[72:75]
	v_mfma_f32_16x16x32_bf16 v[68:71], v[212:215], v[220:223], v[68:71]
	v_mfma_f32_16x16x32_bf16 v[64:67], v[212:215], v[228:231], v[64:67]
	v_mfma_f32_16x16x32_bf16 v[92:95], v[192:195], v[224:227], v[92:95]
	v_mfma_f32_16x16x32_bf16 v[88:91], v[192:195], v[232:235], v[88:91]
	v_mfma_f32_16x16x32_bf16 v[84:87], v[200:203], v[224:227], v[84:87]
	v_mfma_f32_16x16x32_bf16 v[80:83], v[200:203], v[232:235], v[80:83]
	v_mfma_f32_16x16x32_bf16 v[76:79], v[208:211], v[224:227], v[76:79]
	v_mfma_f32_16x16x32_bf16 v[72:75], v[208:211], v[232:235], v[72:75]
	v_mfma_f32_16x16x32_bf16 v[68:71], v[216:219], v[224:227], v[68:71]
	v_mfma_f32_16x16x32_bf16 v[64:67], v[216:219], v[232:235], v[64:67]
	s_barrier
	v_readfirstlane_b32 s51, v158
	v_lshl_add_u64 v[236:237], v[236:237], 0, s[38:39]
	s_mov_b32 m0, s51
	v_readfirstlane_b32 s51, v159
	ds_read_b128 v[188:191], v153 offset:49152
	ds_read_b128 v[192:195], v153 offset:50176
	ds_read_b128 v[196:199], v152 offset:49152
	ds_read_b128 v[200:203], v152 offset:50176
	ds_read_b128 v[204:207], v151 offset:49152
	ds_read_b128 v[208:211], v151 offset:50176
	ds_read_b128 v[212:215], v150 offset:49152
	ds_read_b128 v[216:219], v150 offset:50176
	global_load_lds_dwordx4 v[236:237], off
	v_lshl_add_u64 v[236:237], v[238:239], 0, s[38:39]
	s_mov_b32 m0, s51
	s_nop 0
	global_load_lds_dwordx4 v[236:237], off
	s_barrier
; #define STAGE(P, BASE, LD, br, kt) do { const char* _g = (const char*)((BASE) + (size_t)(br) * (LD) + (size_t)(kt) * 64); \
;     for (int _i = 0; _i < 2; ++_i) { int _b = tidx * 16 + _i * 8192; int _r, _c; stage_rc(_b, _r, _c); \
;       __builtin_amdgcn_global_load_lds((const unsigned*)(_g + (unsigned)((_r * (LD) + _c) * 2)), (unsigned*)((char*)(P) + _b), 16, 0, 0); } } while (0)
; #define LDA(dst, b, h) for (int m = 0; m < 4; ++m) for (int k = 0; k < 2; ++k) \
;     dst[m][k] = *reinterpret_cast<const bf16x8*>((char*)SA(b, h) + lds_byte(wr * 64 + m * 16 + fr, k * 32 + fq * 8))
; #define LDB(dst, b, h) for (int n = 0; n < 2; ++n) for (int k = 0; k < 2; ++k) \
;     dst[n][k] = *reinterpret_cast<const bf16x8*>((char*)SB(b, h) + lds_byte(wc * 32 + n * 16 + fr, k * 32 + fq * 8))
; #define MMA(ai, bj, At_, Bt_) do { __builtin_amdgcn_s_setprio(1); \
;     for (int k = 0; k < 2; ++k) for (int m = 0; m < 4; ++m) for (int n = 0; n < 2; ++n) \
;       acc[ai][bj][m][n] = __builtin_amdgcn_mfma_f32_16x16x32_bf16(At_[m][k], Bt_[n][k], acc[ai][bj][m][n], 0, 0, 0); \
;     __builtin_amdgcn_s_setprio(0); } while (0)
; #define WAIT_V(n) asm volatile("s_waitcnt vmcnt(" #n ")" ::: "memory")
; #define WAIT_L(n) asm volatile("s_waitcnt lgkmcnt(" #n ")" ::: "memory")
; #define BAR __builtin_amdgcn_s_barrier()
; #define SCHED __builtin_amdgcn_sched_barrier(0)
; template <int EPI, int lda, int ldb, int N, int K>
; __device__ __forceinline__ void gemm_phase(const u16* __restrict__ A, const u16* __restrict__ Bt, const GemmEpi ep, int wv) {
;     ...
;       BAR; WAIT_L(0); MMA(1, 0, At, B0); BAR; SCHED;
;       STAGE(SB(1, 1), Bt, ldb, bcol + HALF, t + 3);
;       WAIT_V(6); BAR; MMA(1, 1, At, B1); BAR;
;     }
;     { LDB(B0, 0, 0); LDA(At, 0, 0); STAGE(SA(1, 1), Ab, lda, brow + HALF, nt - 1);
;       BAR; WAIT_L(0); MMA(0, 0, At, B0); BAR;
;       LDB(B1, 0, 1); BAR; WAIT_L(0); MMA(0, 1, At, B1); BAR;
	s_waitcnt lgkmcnt(0)
	s_waitcnt lgkmcnt(0)
	v_mfma_f32_16x16x32_bf16 v[60:63], v[188:191], v[172:175], v[60:63]
	v_mfma_f32_16x16x32_bf16 v[56:59], v[188:191], v[180:183], v[56:59]
	v_mfma_f32_16x16x32_bf16 v[52:55], v[196:199], v[172:175], v[52:55]
	v_mfma_f32_16x16x32_bf16 v[48:51], v[196:199], v[180:183], v[48:51]
	v_mfma_f32_16x16x32_bf16 v[44:47], v[204:207], v[172:175], v[44:47]
	v_mfma_f32_16x16x32_bf16 v[40:43], v[204:207], v[180:183], v[40:43]
	v_mfma_f32_16x16x32_bf16 v[36:39], v[212:215], v[172:175], v[36:39]
	v_mfma_f32_16x16x32_bf16 v[32:35], v[212:215], v[180:183], v[32:35]
	v_mfma_f32_16x16x32_bf16 v[60:63], v[192:195], v[176:179], v[60:63]
	v_mfma_f32_16x16x32_bf16 v[56:59], v[192:195], v[184:187], v[56:59]
	v_mfma_f32_16x16x32_bf16 v[52:55], v[200:203], v[176:179], v[52:55]
	v_mfma_f32_16x16x32_bf16 v[48:51], v[200:203], v[184:187], v[48:51]
	v_mfma_f32_16x16x32_bf16 v[44:47], v[208:211], v[176:179], v[44:47]
	v_mfma_f32_16x16x32_bf16 v[40:43], v[208:211], v[184:187], v[40:43]
	v_mfma_f32_16x16x32_bf16 v[36:39], v[216:219], v[176:179], v[36:39]
	v_mfma_f32_16x16x32_bf16 v[32:35], v[216:219], v[184:187], v[32:35]
	s_barrier
	v_readfirstlane_b32 s51, v160
	v_add_u32_e32 v174, 0x2000, v160
	v_lshl_add_u64 v[172:173], v[240:241], 0, s[42:43]
	s_mov_b32 m0, s51
	v_readfirstlane_b32 s51, v174
	global_load_lds_dwordx4 v[172:173], off
	v_lshl_add_u64 v[172:173], v[242:243], 0, s[42:43]
	s_mov_b32 m0, s51
	s_nop 0
	global_load_lds_dwordx4 v[172:173], off
	s_waitcnt vmcnt(6)
	s_barrier
	v_mfma_f32_16x16x32_bf16 v[28:31], v[188:191], v[220:223], v[28:31]
	v_mfma_f32_16x16x32_bf16 v[24:27], v[188:191], v[228:231], v[24:27]
	v_mfma_f32_16x16x32_bf16 v[20:23], v[196:199], v[220:223], v[20:23]
	v_mfma_f32_16x16x32_bf16 v[16:19], v[196:199], v[228:231], v[16:19]
	v_mfma_f32_16x16x32_bf16 v[12:15], v[204:207], v[220:223], v[12:15]
	v_mfma_f32_16x16x32_bf16 v[8:11], v[204:207], v[228:231], v[8:11]
	v_mfma_f32_16x16x32_bf16 v[4:7], v[212:215], v[220:223], v[4:7]
	v_mfma_f32_16x16x32_bf16 v[0:3], v[212:215], v[228:231], v[0:3]
	v_mfma_f32_16x16x32_bf16 v[28:31], v[192:195], v[224:227], v[28:31]
	v_mfma_f32_16x16x32_bf16 v[24:27], v[192:195], v[232:235], v[24:27]
	v_mfma_f32_16x16x32_bf16 v[20:23], v[200:203], v[224:227], v[20:23]
	v_mfma_f32_16x16x32_bf16 v[16:19], v[200:203], v[232:235], v[16:19]
	v_mfma_f32_16x16x32_bf16 v[12:15], v[208:211], v[224:227], v[12:15]
	v_mfma_f32_16x16x32_bf16 v[8:11], v[208:211], v[232:235], v[8:11]
	v_mfma_f32_16x16x32_bf16 v[4:7], v[216:219], v[224:227], v[4:7]
	v_mfma_f32_16x16x32_bf16 v[0:3], v[216:219], v[232:235], v[0:3]
	s_add_i32 s50, s50, 2
	s_add_u32 s48, s48, 0x100
	s_addc_u32 s49, s49, 0
	s_cmp_gt_u32 s50, 27
	s_barrier
	s_cbranch_scc0 .LBB0_340
	s_add_i32 s48, s46, 0x80
	s_mul_hi_i32 s49, s48, 0x1080
	s_mulk_i32 s48, 0x1080
	s_add_u32 s48, s31, s48
	s_addc_u32 s49, s56, s49
	v_lshl_add_u64 v[158:159], s[48:49], 0, v[128:129]
	v_readfirstlane_b32 s50, v170
	v_lshl_add_u64 v[158:159], v[158:159], 0, s[44:45]
	s_mov_b32 m0, s50
	ds_read_b128 v[134:137], v162
	ds_read_b128 v[138:141], v162 offset:1024
	ds_read_b128 v[172:175], v162 offset:2048
	ds_read_b128 v[176:179], v162 offset:3072
	ds_read_b128 v[180:183], v153
	ds_read_b128 v[184:187], v153 offset:1024
	ds_read_b128 v[188:191], v152
	ds_read_b128 v[192:195], v152 offset:1024
	ds_read_b128 v[196:199], v151
	ds_read_b128 v[200:203], v151 offset:1024
	ds_read_b128 v[204:207], v150
	ds_read_b128 v[208:211], v150 offset:1024
	global_load_lds_dwordx4 v[158:159], off
	v_lshl_add_u64 v[158:159], s[48:49], 0, v[132:133]
	v_readfirstlane_b32 s48, v171
	v_lshl_add_u64 v[158:159], v[158:159], 0, s[44:45]
	s_mov_b32 m0, s48
	s_nop 0
	global_load_lds_dwordx4 v[158:159], off
	s_barrier
	s_waitcnt lgkmcnt(0)
	s_waitcnt lgkmcnt(0)
	v_mfma_f32_16x16x32_bf16 v[124:127], v[180:183], v[134:137], v[124:127]
	v_mfma_f32_16x16x32_bf16 v[120:123], v[180:183], v[172:175], v[120:123]
	v_mfma_f32_16x16x32_bf16 v[116:119], v[188:191], v[134:137], v[116:119]
	v_mfma_f32_16x16x32_bf16 v[112:115], v[188:191], v[172:175], v[112:115]
	v_mfma_f32_16x16x32_bf16 v[108:111], v[196:199], v[134:137], v[108:111]
	v_mfma_f32_16x16x32_bf16 v[104:107], v[196:199], v[172:175], v[104:107]
	v_mfma_f32_16x16x32_bf16 v[100:103], v[204:207], v[134:137], v[100:103]
	v_mfma_f32_16x16x32_bf16 v[96:99], v[204:207], v[172:175], v[96:99]
	v_mfma_f32_16x16x32_bf16 v[124:127], v[184:187], v[138:141], v[124:127]
	v_mfma_f32_16x16x32_bf16 v[120:123], v[184:187], v[176:179], v[120:123]
	v_mfma_f32_16x16x32_bf16 v[116:119], v[192:195], v[138:141], v[116:119]
	v_mfma_f32_16x16x32_bf16 v[112:115], v[192:195], v[176:179], v[112:115]
	v_mfma_f32_16x16x32_bf16 v[108:111], v[200:203], v[138:141], v[108:111]
	v_mfma_f32_16x16x32_bf16 v[104:107], v[200:203], v[176:179], v[104:107]
	v_mfma_f32_16x16x32_bf16 v[100:103], v[208:211], v[138:141], v[100:103]
	v_mfma_f32_16x16x32_bf16 v[96:99], v[208:211], v[176:179], v[96:99]
	s_barrier
	ds_read_b128 v[212:215], v161
	ds_read_b128 v[216:219], v161 offset:1024
	ds_read_b128 v[220:223], v161 offset:2048
	ds_read_b128 v[158:161], v161 offset:3072
	s_barrier
; #define LDA(dst, b, h) for (int m = 0; m < 4; ++m) for (int k = 0; k < 2; ++k) \
;     dst[m][k] = *reinterpret_cast<const bf16x8*>((char*)SA(b, h) + lds_byte(wr * 64 + m * 16 + fr, k * 32 + fq * 8))
; #define LDB(dst, b, h) for (int n = 0; n < 2; ++n) for (int k = 0; k < 2; ++k) \
;     dst[n][k] = *reinterpret_cast<const bf16x8*>((char*)SB(b, h) + lds_byte(wc * 32 + n * 16 + fr, k * 32 + fq * 8))
; #define MMA(ai, bj, At_, Bt_) do { __builtin_amdgcn_s_setprio(1); \
;     for (int k = 0; k < 2; ++k) for (int m = 0; m < 4; ++m) for (int n = 0; n < 2; ++n) \
;       acc[ai][bj][m][n] = __builtin_amdgcn_mfma_f32_16x16x32_bf16(At_[m][k], Bt_[n][k], acc[ai][bj][m][n], 0, 0, 0); \
;     __builtin_amdgcn_s_setprio(0); } while (0)
; #define WAIT_V(n) asm volatile("s_waitcnt vmcnt(" #n ")" ::: "memory")
; #define WAIT_L(n) asm volatile("s_waitcnt lgkmcnt(" #n ")" ::: "memory")
; #define BAR __builtin_amdgcn_s_barrier()
; template <int EPI, int lda, int ldb, int N, int K>
; __device__ __forceinline__ void gemm_phase(const u16* __restrict__ A, const u16* __restrict__ Bt, const GemmEpi ep, int wv) {
;     ...
;       LDB(B1, 0, 1); BAR; WAIT_L(0); MMA(0, 1, At, B1); BAR;
;       LDA(At, 0, 1); WAIT_V(4); BAR; WAIT_L(0); MMA(1, 0, At, B0); MMA(1, 1, At, B1); BAR; }
;     { LDB(B0, 1, 0); LDA(At, 1, 0); WAIT_V(2); BAR; WAIT_L(0); MMA(0, 0, At, B0); BAR;
	s_waitcnt lgkmcnt(0)
	s_waitcnt lgkmcnt(0)
	v_mfma_f32_16x16x32_bf16 v[92:95], v[180:183], v[212:215], v[92:95]
	v_mfma_f32_16x16x32_bf16 v[88:91], v[180:183], v[220:223], v[88:91]
	v_mfma_f32_16x16x32_bf16 v[76:79], v[196:199], v[212:215], v[76:79]
	v_mfma_f32_16x16x32_bf16 v[72:75], v[196:199], v[220:223], v[72:75]
	v_mfma_f32_16x16x32_bf16 v[68:71], v[204:207], v[212:215], v[68:71]
	v_mfma_f32_16x16x32_bf16 v[64:67], v[204:207], v[220:223], v[64:67]
	v_mfma_f32_16x16x32_bf16 v[84:87], v[188:191], v[212:215], v[84:87]
	v_mfma_f32_16x16x32_bf16 v[80:83], v[188:191], v[220:223], v[80:83]
	v_mfma_f32_16x16x32_bf16 v[92:95], v[184:187], v[216:219], v[92:95]
	v_mfma_f32_16x16x32_bf16 v[88:91], v[184:187], v[158:161], v[88:91]
	v_mfma_f32_16x16x32_bf16 v[76:79], v[200:203], v[216:219], v[76:79]
	v_mfma_f32_16x16x32_bf16 v[72:75], v[200:203], v[158:161], v[72:75]
	v_mfma_f32_16x16x32_bf16 v[68:71], v[208:211], v[216:219], v[68:71]
	v_mfma_f32_16x16x32_bf16 v[64:67], v[208:211], v[158:161], v[64:67]
	v_mfma_f32_16x16x32_bf16 v[180:183], v[192:195], v[216:219], v[84:87]
	v_mfma_f32_16x16x32_bf16 v[184:187], v[192:195], v[158:161], v[80:83]
	s_barrier
	s_nop 0
	ds_read_b128 v[80:83], v153 offset:16384
	ds_read_b128 v[84:87], v153 offset:17408
	ds_read_b128 v[188:191], v152 offset:16384
	ds_read_b128 v[192:195], v152 offset:17408
	ds_read_b128 v[196:199], v151 offset:16384
	ds_read_b128 v[200:203], v151 offset:17408
	ds_read_b128 v[204:207], v150 offset:16384
	ds_read_b128 v[208:211], v150 offset:17408
	s_waitcnt vmcnt(4)
	s_barrier
	s_waitcnt lgkmcnt(0)
	s_waitcnt lgkmcnt(0)
	v_mfma_f32_16x16x32_bf16 v[60:63], v[80:83], v[134:137], v[60:63]
	v_mfma_f32_16x16x32_bf16 v[44:47], v[196:199], v[134:137], v[44:47]
	v_mfma_f32_16x16x32_bf16 v[40:43], v[196:199], v[172:175], v[40:43]
	v_mfma_f32_16x16x32_bf16 v[36:39], v[204:207], v[134:137], v[36:39]
	v_mfma_f32_16x16x32_bf16 v[32:35], v[204:207], v[172:175], v[32:35]
	v_mfma_f32_16x16x32_bf16 v[56:59], v[80:83], v[172:175], v[56:59]
	v_mfma_f32_16x16x32_bf16 v[52:55], v[188:191], v[134:137], v[52:55]
	v_mfma_f32_16x16x32_bf16 v[48:51], v[188:191], v[172:175], v[48:51]
	v_mfma_f32_16x16x32_bf16 v[60:63], v[84:87], v[138:141], v[60:63]
	v_mfma_f32_16x16x32_bf16 v[44:47], v[200:203], v[138:141], v[44:47]
	v_mfma_f32_16x16x32_bf16 v[40:43], v[200:203], v[176:179], v[40:43]
	v_mfma_f32_16x16x32_bf16 v[36:39], v[208:211], v[138:141], v[36:39]
	v_mfma_f32_16x16x32_bf16 v[32:35], v[208:211], v[176:179], v[32:35]
	v_mfma_f32_16x16x32_bf16 v[134:137], v[84:87], v[176:179], v[56:59]
	v_mfma_f32_16x16x32_bf16 v[170:173], v[192:195], v[138:141], v[52:55]
	v_mfma_f32_16x16x32_bf16 v[224:227], v[192:195], v[176:179], v[48:51]
	v_mfma_f32_16x16x32_bf16 v[28:31], v[80:83], v[212:215], v[28:31]
	v_mfma_f32_16x16x32_bf16 v[20:23], v[188:191], v[212:215], v[20:23]
	v_mfma_f32_16x16x32_bf16 v[12:15], v[196:199], v[212:215], v[12:15]
	v_mfma_f32_16x16x32_bf16 v[4:7], v[204:207], v[212:215], v[4:7]
	v_mfma_f32_16x16x32_bf16 v[24:27], v[80:83], v[220:223], v[24:27]
	v_mfma_f32_16x16x32_bf16 v[16:19], v[188:191], v[220:223], v[16:19]
	v_mfma_f32_16x16x32_bf16 v[8:11], v[196:199], v[220:223], v[8:11]
	v_mfma_f32_16x16x32_bf16 v[0:3], v[204:207], v[220:223], v[0:3]
	v_mfma_f32_16x16x32_bf16 v[28:31], v[84:87], v[216:219], v[28:31]
	v_mfma_f32_16x16x32_bf16 v[20:23], v[192:195], v[216:219], v[20:23]
	v_mfma_f32_16x16x32_bf16 v[12:15], v[200:203], v[216:219], v[12:15]
	v_mfma_f32_16x16x32_bf16 v[4:7], v[208:211], v[216:219], v[4:7]
	v_mfma_f32_16x16x32_bf16 v[138:141], v[84:87], v[158:161], v[24:27]
	v_mfma_f32_16x16x32_bf16 v[174:177], v[192:195], v[158:161], v[16:19]
	v_mfma_f32_16x16x32_bf16 v[188:191], v[200:203], v[158:161], v[8:11]
	v_mfma_f32_16x16x32_bf16 v[158:161], v[208:211], v[158:161], v[0:3]
	s_barrier
	s_nop 0
	ds_read_b128 v[0:3], v156
	ds_read_b128 v[8:11], v156 offset:1024
	ds_read_b128 v[16:19], v156 offset:2048
	ds_read_b128 v[192:195], v156 offset:3072
	ds_read_b128 v[24:27], v153 offset:32768
	ds_read_b128 v[56:59], v153 offset:33792
	ds_read_b128 v[196:199], v152 offset:32768
	ds_read_b128 v[200:203], v152 offset:33792
	ds_read_b128 v[204:207], v151 offset:32768
	ds_read_b128 v[208:211], v151 offset:33792
	ds_read_b128 v[212:215], v150 offset:32768
	ds_read_b128 v[216:219], v150 offset:33792
	s_waitcnt vmcnt(2)
	s_barrier
; #define LDA(dst, b, h) for (int m = 0; m < 4; ++m) for (int k = 0; k < 2; ++k) \
;     dst[m][k] = *reinterpret_cast<const bf16x8*>((char*)SA(b, h) + lds_byte(wr * 64 + m * 16 + fr, k * 32 + fq * 8))
; #define LDB(dst, b, h) for (int n = 0; n < 2; ++n) for (int k = 0; k < 2; ++k) \
;     dst[n][k] = *reinterpret_cast<const bf16x8*>((char*)SB(b, h) + lds_byte(wc * 32 + n * 16 + fr, k * 32 + fq * 8))
; #define MMA(ai, bj, At_, Bt_) do { __builtin_amdgcn_s_setprio(1); \
;     for (int k = 0; k < 2; ++k) for (int m = 0; m < 4; ++m) for (int n = 0; n < 2; ++n) \
;       acc[ai][bj][m][n] = __builtin_amdgcn_mfma_f32_16x16x32_bf16(At_[m][k], Bt_[n][k], acc[ai][bj][m][n], 0, 0, 0); \
;     __builtin_amdgcn_s_setprio(0); } while (0)
; #define WAIT_V(n) asm volatile("s_waitcnt vmcnt(" #n ")" ::: "memory")
; #define WAIT_L(n) asm volatile("s_waitcnt lgkmcnt(" #n ")" ::: "memory")
; #define BAR __builtin_amdgcn_s_barrier()
; template <int EPI, int lda, int ldb, int N, int K>
; __device__ __forceinline__ void gemm_phase(const u16* __restrict__ A, const u16* __restrict__ Bt, const GemmEpi ep, int wv) {
;     ...
;     { LDB(B0, 1, 0); LDA(At, 1, 0); WAIT_V(2); BAR; WAIT_L(0); MMA(0, 0, At, B0); BAR;
;       LDB(B1, 1, 1); WAIT_V(0); BAR; WAIT_L(0); MMA(0, 1, At, B1); BAR;
;       LDA(At, 1, 1); BAR; WAIT_L(0); MMA(1, 0, At, B0); MMA(1, 1, At, B1); BAR; }
;     if (wr == 0) BAR;
	s_waitcnt lgkmcnt(0)
	s_waitcnt lgkmcnt(0)
	v_mfma_f32_16x16x32_bf16 v[48:51], v[24:27], v[0:3], v[124:127]
	v_mfma_f32_16x16x32_bf16 v[52:55], v[24:27], v[16:19], v[120:123]
	v_mfma_f32_16x16x32_bf16 v[80:83], v[196:199], v[0:3], v[116:119]
	v_mfma_f32_16x16x32_bf16 v[84:87], v[196:199], v[16:19], v[112:115]
	v_mfma_f32_16x16x32_bf16 v[108:111], v[204:207], v[0:3], v[108:111]
	v_mfma_f32_16x16x32_bf16 v[104:107], v[204:207], v[16:19], v[104:107]
	v_mfma_f32_16x16x32_bf16 v[112:115], v[212:215], v[0:3], v[100:103]
	v_mfma_f32_16x16x32_bf16 v[120:123], v[212:215], v[16:19], v[96:99]
	v_mfma_f32_16x16x32_bf16 v[124:127], v[56:59], v[8:11], v[48:51]
	v_mfma_f32_16x16x32_bf16 v[116:119], v[56:59], v[192:195], v[52:55]
	v_mfma_f32_16x16x32_bf16 v[100:103], v[200:203], v[8:11], v[80:83]
	v_mfma_f32_16x16x32_bf16 v[96:99], v[200:203], v[192:195], v[84:87]
	v_mfma_f32_16x16x32_bf16 v[84:87], v[208:211], v[8:11], v[108:111]
	v_mfma_f32_16x16x32_bf16 v[80:83], v[208:211], v[192:195], v[104:107]
	v_mfma_f32_16x16x32_bf16 v[52:55], v[216:219], v[8:11], v[112:115]
	v_mfma_f32_16x16x32_bf16 v[48:51], v[216:219], v[192:195], v[120:123]
	s_barrier
	ds_read_b128 v[220:223], v154
	ds_read_b128 v[228:231], v154 offset:1024
	ds_read_b128 v[232:235], v154 offset:2048
	ds_read_b128 v[154:157], v154 offset:3072
	s_waitcnt vmcnt(0)
	s_barrier
	s_waitcnt lgkmcnt(0)
	s_waitcnt lgkmcnt(0)
	v_mfma_f32_16x16x32_bf16 v[92:95], v[24:27], v[220:223], v[92:95]
	v_mfma_f32_16x16x32_bf16 v[24:27], v[24:27], v[232:235], v[88:91]
	v_mfma_f32_16x16x32_bf16 v[88:91], v[196:199], v[220:223], v[180:183]
	v_mfma_f32_16x16x32_bf16 v[104:107], v[196:199], v[232:235], v[184:187]
	v_mfma_f32_16x16x32_bf16 v[76:79], v[204:207], v[220:223], v[76:79]
	v_mfma_f32_16x16x32_bf16 v[72:75], v[204:207], v[232:235], v[72:75]
	v_mfma_f32_16x16x32_bf16 v[68:71], v[212:215], v[220:223], v[68:71]
	v_mfma_f32_16x16x32_bf16 v[64:67], v[212:215], v[232:235], v[64:67]
	v_mfma_f32_16x16x32_bf16 v[120:123], v[56:59], v[228:231], v[92:95]
	v_mfma_f32_16x16x32_bf16 v[112:115], v[56:59], v[154:157], v[24:27]
	v_mfma_f32_16x16x32_bf16 v[108:111], v[200:203], v[228:231], v[88:91]
	v_mfma_f32_16x16x32_bf16 v[104:107], v[200:203], v[154:157], v[104:107]
	v_mfma_f32_16x16x32_bf16 v[92:95], v[208:211], v[228:231], v[76:79]
	v_mfma_f32_16x16x32_bf16 v[88:91], v[208:211], v[154:157], v[72:75]
	v_mfma_f32_16x16x32_bf16 v[68:71], v[216:219], v[228:231], v[68:71]
	v_mfma_f32_16x16x32_bf16 v[56:59], v[216:219], v[154:157], v[64:67]
	s_barrier
	s_nop 0
	ds_read_b128 v[64:67], v153 offset:49152
	ds_read_b128 v[178:181], v153 offset:50176
	ds_read_b128 v[76:79], v152 offset:49152
	ds_read_b128 v[182:185], v152 offset:50176
	ds_read_b128 v[196:199], v151 offset:49152
	ds_read_b128 v[200:203], v151 offset:50176
	ds_read_b128 v[204:207], v150 offset:49152
	ds_read_b128 v[150:153], v150 offset:50176
	s_barrier
	s_waitcnt lgkmcnt(0)
	s_waitcnt lgkmcnt(0)
	v_mfma_f32_16x16x32_bf16 v[24:27], v[64:67], v[0:3], v[60:63]
	v_mfma_f32_16x16x32_bf16 v[60:63], v[64:67], v[16:19], v[134:137]
	v_mfma_f32_16x16x32_bf16 v[134:137], v[76:79], v[0:3], v[170:173]
	v_mfma_f32_16x16x32_bf16 v[170:173], v[76:79], v[16:19], v[224:227]
	v_mfma_f32_16x16x32_bf16 v[44:47], v[196:199], v[0:3], v[44:47]
	v_mfma_f32_16x16x32_bf16 v[208:211], v[196:199], v[16:19], v[40:43]
	v_mfma_f32_16x16x32_bf16 v[0:3], v[204:207], v[0:3], v[36:39]
	v_mfma_f32_16x16x32_bf16 v[36:39], v[204:207], v[16:19], v[32:35]
	v_mfma_f32_16x16x32_bf16 v[72:75], v[178:181], v[8:11], v[24:27]
	v_mfma_f32_16x16x32_bf16 v[60:63], v[178:181], v[192:195], v[60:63]
	v_mfma_f32_16x16x32_bf16 v[40:43], v[182:185], v[8:11], v[134:137]
	v_mfma_f32_16x16x32_bf16 v[32:35], v[182:185], v[192:195], v[170:173]
	v_mfma_f32_16x16x32_bf16 v[24:27], v[200:203], v[8:11], v[44:47]
	v_mfma_f32_16x16x32_bf16 v[16:19], v[200:203], v[192:195], v[208:211]
	v_mfma_f32_16x16x32_bf16 v[8:11], v[150:153], v[8:11], v[0:3]
	v_mfma_f32_16x16x32_bf16 v[0:3], v[150:153], v[192:195], v[36:39]
	v_mfma_f32_16x16x32_bf16 v[28:31], v[64:67], v[220:223], v[28:31]
	v_mfma_f32_16x16x32_bf16 v[36:39], v[64:67], v[232:235], v[138:141]
	v_mfma_f32_16x16x32_bf16 v[20:23], v[76:79], v[220:223], v[20:23]
	v_mfma_f32_16x16x32_bf16 v[134:137], v[76:79], v[232:235], v[174:177]
	v_mfma_f32_16x16x32_bf16 v[12:15], v[196:199], v[220:223], v[12:15]
	v_mfma_f32_16x16x32_bf16 v[138:141], v[196:199], v[232:235], v[188:191]
	v_mfma_f32_16x16x32_bf16 v[4:7], v[204:207], v[220:223], v[4:7]
	v_mfma_f32_16x16x32_bf16 v[158:161], v[204:207], v[232:235], v[158:161]
	v_mfma_f32_16x16x32_bf16 v[76:79], v[178:181], v[228:231], v[28:31]
	v_mfma_f32_16x16x32_bf16 v[64:67], v[178:181], v[154:157], v[36:39]
	v_mfma_f32_16x16x32_bf16 v[44:47], v[182:185], v[228:231], v[20:23]
	v_mfma_f32_16x16x32_bf16 v[36:39], v[182:185], v[154:157], v[134:137]
	v_mfma_f32_16x16x32_bf16 v[28:31], v[200:203], v[228:231], v[12:15]
	v_mfma_f32_16x16x32_bf16 v[20:23], v[200:203], v[154:157], v[138:141]
	v_mfma_f32_16x16x32_bf16 v[12:15], v[150:153], v[228:231], v[4:7]
	v_mfma_f32_16x16x32_bf16 v[4:7], v[150:153], v[154:157], v[158:161]
	v_cmp_gt_u32_e32 vcc, s64, v130
	s_barrier
	s_and_saveexec_b64 s[48:49], vcc
	s_cbranch_execz .LBB0_343
	s_barrier

; #define STAGE(P, BASE, LD, br, kt) do { const char* _g = (const char*)((BASE) + (size_t)(br) * (LD) + (size_t)(kt) * 64); \
;     for (int _i = 0; _i < 2; ++_i) { int _b = tidx * 16 + _i * 8192; int _r, _c; stage_rc(_b, _r, _c); \
;       __builtin_amdgcn_global_load_lds((const unsigned*)(_g + (unsigned)((_r * (LD) + _c) * 2)), (unsigned*)((char*)(P) + _b), 16, 0, 0); } } while (0)
; #define LDA(dst, b, h) for (int m = 0; m < 4; ++m) for (int k = 0; k < 2; ++k) \
;     dst[m][k] = *reinterpret_cast<const bf16x8*>((char*)SA(b, h) + lds_byte(wr * 64 + m * 16 + fr, k * 32 + fq * 8))
; #define LDB(dst, b, h) for (int n = 0; n < 2; ++n) for (int k = 0; k < 2; ++k) \
;     dst[n][k] = *reinterpret_cast<const bf16x8*>((char*)SB(b, h) + lds_byte(wc * 32 + n * 16 + fr, k * 32 + fq * 8))
; #define MMA(ai, bj, At_, Bt_) do { __builtin_amdgcn_s_setprio(1); \
;     for (int k = 0; k < 2; ++k) for (int m = 0; m < 4; ++m) for (int n = 0; n < 2; ++n) \
;       acc[ai][bj][m][n] = __builtin_amdgcn_mfma_f32_16x16x32_bf16(At_[m][k], Bt_[n][k], acc[ai][bj][m][n], 0, 0, 0); \
;     __builtin_amdgcn_s_setprio(0); } while (0)
; #define WAIT_L(n) asm volatile("s_waitcnt lgkmcnt(" #n ")" ::: "memory")
; #define BAR __builtin_amdgcn_s_barrier()
; #define SCHED __builtin_amdgcn_sched_barrier(0)
; template <int EPI, int lda, int ldb, int N, int K>
; __device__ __forceinline__ void gemm_phase(const u16* __restrict__ A, const u16* __restrict__ Bt, const GemmEpi ep, int wv) {
;     ...
;       LDB(B0, 0, 0); SCHED; LDA(At, 0, 0); STAGE(SA(1, 1), Ab, lda, brow + HALF, t + 1);
;       WAIT_L(8); BAR; WAIT_L(0); MMA(0, 0, At, B0); BAR; SCHED;
;       LDB(B1, 0, 1); STAGE(SB(0, 0), Bt, ldb, bcol, t + 2);
;       BAR; WAIT_L(0); MMA(0, 1, At, B1); BAR;
;       LDA(At, 0, 1); STAGE(SA(0, 0), Ab, lda, brow, t + 2);
;       BAR; WAIT_L(0); MMA(1, 0, At, B0); BAR; SCHED;
.LBB0_654:
	ds_read_b128 v[164:167], v160
	ds_read_b128 v[170:173], v160 offset:1024
	ds_read_b128 v[174:177], v160 offset:2048
	ds_read_b128 v[178:181], v160 offset:3072
	v_add_u32_e32 v168, 0xc000, v143
	v_lshl_add_u64 v[234:235], v[138:139], 0, s[52:53]
	v_readfirstlane_b32 s55, v168
	v_add_u32_e32 v169, 0xe000, v143
	v_lshl_add_u64 v[162:163], v[234:235], 0, s[20:21]
	s_mov_b32 m0, s55
	v_lshl_add_u64 v[236:237], v[140:141], 0, s[52:53]
	v_readfirstlane_b32 s55, v169
	ds_read_b128 v[182:185], v151
	ds_read_b128 v[186:189], v151 offset:1024
	ds_read_b128 v[190:193], v150
	ds_read_b128 v[194:197], v150 offset:1024
	ds_read_b128 v[198:201], v149
	ds_read_b128 v[202:205], v149 offset:1024
	ds_read_b128 v[206:209], v148
	ds_read_b128 v[210:213], v148 offset:1024
	global_load_lds_dwordx4 v[162:163], off
	s_waitcnt lgkmcnt(8)
	s_barrier
	s_waitcnt lgkmcnt(0)
	s_waitcnt lgkmcnt(0)
	v_mfma_f32_16x16x32_bf16 v[124:127], v[164:167], v[182:185], v[124:127]
	v_mfma_f32_16x16x32_bf16 v[120:123], v[174:177], v[182:185], v[120:123]
	v_mfma_f32_16x16x32_bf16 v[116:119], v[164:167], v[190:193], v[116:119]
	v_mfma_f32_16x16x32_bf16 v[112:115], v[174:177], v[190:193], v[112:115]
	v_mfma_f32_16x16x32_bf16 v[108:111], v[164:167], v[198:201], v[108:111]
	v_mfma_f32_16x16x32_bf16 v[104:107], v[174:177], v[198:201], v[104:107]
	v_mfma_f32_16x16x32_bf16 v[100:103], v[164:167], v[206:209], v[100:103]
	v_mfma_f32_16x16x32_bf16 v[96:99], v[174:177], v[206:209], v[96:99]
	v_lshl_add_u64 v[162:163], v[236:237], 0, s[20:21]
	s_mov_b32 m0, s55
	s_nop 0
	global_load_lds_dwordx4 v[162:163], off
	v_mfma_f32_16x16x32_bf16 v[124:127], v[170:173], v[186:189], v[124:127]
	v_mfma_f32_16x16x32_bf16 v[120:123], v[178:181], v[186:189], v[120:123]
	v_mfma_f32_16x16x32_bf16 v[116:119], v[170:173], v[194:197], v[116:119]
	v_mfma_f32_16x16x32_bf16 v[112:115], v[178:181], v[194:197], v[112:115]
	v_mfma_f32_16x16x32_bf16 v[108:111], v[170:173], v[202:205], v[108:111]
	v_mfma_f32_16x16x32_bf16 v[104:107], v[178:181], v[202:205], v[104:107]
	v_mfma_f32_16x16x32_bf16 v[100:103], v[170:173], v[210:213], v[100:103]
	v_mfma_f32_16x16x32_bf16 v[96:99], v[178:181], v[210:213], v[96:99]
	s_barrier
	v_add_u32_e32 v161, s65, v153
	v_lshl_add_u64 v[238:239], v[134:135], 0, s[52:53]
	v_readfirstlane_b32 s55, v161
	v_lshl_add_u64 v[162:163], v[238:239], 0, s[22:23]
	s_mov_b32 m0, s55
	ds_read_b128 v[214:217], v159
	ds_read_b128 v[218:221], v159 offset:1024
	ds_read_b128 v[222:225], v159 offset:2048
	ds_read_b128 v[226:229], v159 offset:3072
	global_load_lds_dwordx4 v[162:163], off
	v_add_u32_e32 v162, 0x2000, v161
	v_lshl_add_u64 v[240:241], v[136:137], 0, s[52:53]
	v_readfirstlane_b32 s55, v162
	v_lshl_add_u64 v[230:231], v[240:241], 0, s[22:23]
	s_mov_b32 m0, s55
	s_nop 0
	global_load_lds_dwordx4 v[230:231], off
	s_barrier
	s_waitcnt lgkmcnt(0)
	s_waitcnt lgkmcnt(0)
	v_mfma_f32_16x16x32_bf16 v[92:95], v[214:217], v[182:185], v[92:95]
	v_mfma_f32_16x16x32_bf16 v[88:91], v[222:225], v[182:185], v[88:91]
	v_mfma_f32_16x16x32_bf16 v[84:87], v[214:217], v[190:193], v[84:87]
	v_mfma_f32_16x16x32_bf16 v[80:83], v[222:225], v[190:193], v[80:83]
	v_mfma_f32_16x16x32_bf16 v[76:79], v[214:217], v[198:201], v[76:79]
	v_mfma_f32_16x16x32_bf16 v[72:75], v[222:225], v[198:201], v[72:75]
	v_mfma_f32_16x16x32_bf16 v[68:71], v[214:217], v[206:209], v[68:71]
	v_mfma_f32_16x16x32_bf16 v[64:67], v[222:225], v[206:209], v[64:67]
	v_mfma_f32_16x16x32_bf16 v[92:95], v[218:221], v[186:189], v[92:95]
	v_mfma_f32_16x16x32_bf16 v[88:91], v[226:229], v[186:189], v[88:91]
	v_mfma_f32_16x16x32_bf16 v[84:87], v[218:221], v[194:197], v[84:87]
	v_mfma_f32_16x16x32_bf16 v[80:83], v[226:229], v[194:197], v[80:83]
	v_mfma_f32_16x16x32_bf16 v[76:79], v[218:221], v[202:205], v[76:79]
	v_mfma_f32_16x16x32_bf16 v[72:75], v[226:229], v[202:205], v[72:75]
	v_mfma_f32_16x16x32_bf16 v[68:71], v[218:221], v[210:213], v[68:71]
	v_mfma_f32_16x16x32_bf16 v[64:67], v[226:229], v[210:213], v[64:67]
	s_barrier
	v_readfirstlane_b32 s55, v143
	v_add_u32_e32 v163, 0x2000, v143
	v_lshl_add_u64 v[230:231], v[234:235], 0, s[24:25]
	s_mov_b32 m0, s55
	v_readfirstlane_b32 s55, v163
	ds_read_b128 v[182:185], v151 offset:16384
	ds_read_b128 v[186:189], v151 offset:17408
	ds_read_b128 v[190:193], v150 offset:16384
	ds_read_b128 v[194:197], v150 offset:17408
	ds_read_b128 v[198:201], v149 offset:16384
	ds_read_b128 v[202:205], v149 offset:17408
	ds_read_b128 v[206:209], v148 offset:16384
	ds_read_b128 v[210:213], v148 offset:17408
	global_load_lds_dwordx4 v[230:231], off
	v_lshl_add_u64 v[230:231], v[236:237], 0, s[24:25]
	s_mov_b32 m0, s55
	s_nop 0
	global_load_lds_dwordx4 v[230:231], off
	s_barrier
	s_waitcnt lgkmcnt(0)
	s_waitcnt lgkmcnt(0)
	v_mfma_f32_16x16x32_bf16 v[60:63], v[164:167], v[182:185], v[60:63]
	v_mfma_f32_16x16x32_bf16 v[56:59], v[174:177], v[182:185], v[56:59]
	v_mfma_f32_16x16x32_bf16 v[52:55], v[164:167], v[190:193], v[52:55]
	v_mfma_f32_16x16x32_bf16 v[48:51], v[174:177], v[190:193], v[48:51]
	v_mfma_f32_16x16x32_bf16 v[44:47], v[164:167], v[198:201], v[44:47]
	v_mfma_f32_16x16x32_bf16 v[40:43], v[174:177], v[198:201], v[40:43]
	v_mfma_f32_16x16x32_bf16 v[36:39], v[164:167], v[206:209], v[36:39]
	v_mfma_f32_16x16x32_bf16 v[32:35], v[174:177], v[206:209], v[32:35]
	v_mfma_f32_16x16x32_bf16 v[60:63], v[170:173], v[186:189], v[60:63]
	v_mfma_f32_16x16x32_bf16 v[56:59], v[178:181], v[186:189], v[56:59]
	v_mfma_f32_16x16x32_bf16 v[52:55], v[170:173], v[194:197], v[52:55]
	v_mfma_f32_16x16x32_bf16 v[48:51], v[178:181], v[194:197], v[48:51]
	v_mfma_f32_16x16x32_bf16 v[44:47], v[170:173], v[202:205], v[44:47]
	v_mfma_f32_16x16x32_bf16 v[40:43], v[178:181], v[202:205], v[40:43]
	v_mfma_f32_16x16x32_bf16 v[36:39], v[170:173], v[210:213], v[36:39]
	v_mfma_f32_16x16x32_bf16 v[32:35], v[178:181], v[210:213], v[32:35]
	s_barrier
; #define STAGE(P, BASE, LD, br, kt) do { const char* _g = (const char*)((BASE) + (size_t)(br) * (LD) + (size_t)(kt) * 64); \
;     for (int _i = 0; _i < 2; ++_i) { int _b = tidx * 16 + _i * 8192; int _r, _c; stage_rc(_b, _r, _c); \
;       __builtin_amdgcn_global_load_lds((const unsigned*)(_g + (unsigned)((_r * (LD) + _c) * 2)), (unsigned*)((char*)(P) + _b), 16, 0, 0); } } while (0)
; #define LDA(dst, b, h) for (int m = 0; m < 4; ++m) for (int k = 0; k < 2; ++k) \
;     dst[m][k] = *reinterpret_cast<const bf16x8*>((char*)SA(b, h) + lds_byte(wr * 64 + m * 16 + fr, k * 32 + fq * 8))
; #define LDB(dst, b, h) for (int n = 0; n < 2; ++n) for (int k = 0; k < 2; ++k) \
;     dst[n][k] = *reinterpret_cast<const bf16x8*>((char*)SB(b, h) + lds_byte(wc * 32 + n * 16 + fr, k * 32 + fq * 8))
; #define MMA(ai, bj, At_, Bt_) do { __builtin_amdgcn_s_setprio(1); \
;     for (int k = 0; k < 2; ++k) for (int m = 0; m < 4; ++m) for (int n = 0; n < 2; ++n) \
;       acc[ai][bj][m][n] = __builtin_amdgcn_mfma_f32_16x16x32_bf16(At_[m][k], Bt_[n][k], acc[ai][bj][m][n], 0, 0, 0); \
;     __builtin_amdgcn_s_setprio(0); } while (0)
; #define WAIT_V(n) asm volatile("s_waitcnt vmcnt(" #n ")" ::: "memory")
; #define WAIT_L(n) asm volatile("s_waitcnt lgkmcnt(" #n ")" ::: "memory")
; #define BAR __builtin_amdgcn_s_barrier()
; #define SCHED __builtin_amdgcn_sched_barrier(0)
; template <int EPI, int lda, int ldb, int N, int K>
; __device__ __forceinline__ void gemm_phase(const u16* __restrict__ A, const u16* __restrict__ Bt, const GemmEpi ep, int wv) {
;     ...
;       STAGE(SB(0, 1), Bt, ldb, bcol + HALF, t + 2);
;       WAIT_V(6); BAR; MMA(1, 1, At, B1); BAR;
;       LDB(B0, 1, 0); SCHED; LDA(At, 1, 0); STAGE(SA(0, 1), Ab, lda, brow + HALF, t + 2);
;       WAIT_L(8); BAR; WAIT_L(0); MMA(0, 0, At, B0); BAR; SCHED;
;       LDB(B1, 1, 1); STAGE(SB(1, 0), Bt, ldb, bcol, t + 3);
;       BAR; WAIT_L(0); MMA(0, 1, At, B1); BAR;
;       LDA(At, 1, 1); STAGE(SA(1, 0), Ab, lda, brow, t + 3);
;       BAR; WAIT_L(0); MMA(1, 0, At, B0); BAR; SCHED;
	v_add_u32_e32 v164, s66, v153
	v_add_u32_e32 v165, 0x2000, v164
	v_readfirstlane_b32 s55, v164
	v_lshl_add_u64 v[166:167], v[238:239], 0, s[26:27]
	s_mov_b32 m0, s55
	v_readfirstlane_b32 s55, v165
	global_load_lds_dwordx4 v[166:167], off
	v_lshl_add_u64 v[166:167], v[240:241], 0, s[26:27]
	s_mov_b32 m0, s55
	s_nop 0
	global_load_lds_dwordx4 v[166:167], off
	s_waitcnt vmcnt(6)
	s_barrier
	v_mfma_f32_16x16x32_bf16 v[28:31], v[214:217], v[182:185], v[28:31]
	v_mfma_f32_16x16x32_bf16 v[24:27], v[222:225], v[182:185], v[24:27]
	v_mfma_f32_16x16x32_bf16 v[20:23], v[214:217], v[190:193], v[20:23]
	v_mfma_f32_16x16x32_bf16 v[16:19], v[222:225], v[190:193], v[16:19]
	v_mfma_f32_16x16x32_bf16 v[12:15], v[214:217], v[198:201], v[12:15]
	v_mfma_f32_16x16x32_bf16 v[8:11], v[222:225], v[198:201], v[8:11]
	v_mfma_f32_16x16x32_bf16 v[4:7], v[214:217], v[206:209], v[4:7]
	v_mfma_f32_16x16x32_bf16 v[0:3], v[222:225], v[206:209], v[0:3]
	v_mfma_f32_16x16x32_bf16 v[28:31], v[218:221], v[186:189], v[28:31]
	v_mfma_f32_16x16x32_bf16 v[24:27], v[226:229], v[186:189], v[24:27]
	v_mfma_f32_16x16x32_bf16 v[20:23], v[218:221], v[194:197], v[20:23]
	v_mfma_f32_16x16x32_bf16 v[16:19], v[226:229], v[194:197], v[16:19]
	v_mfma_f32_16x16x32_bf16 v[12:15], v[218:221], v[202:205], v[12:15]
	v_mfma_f32_16x16x32_bf16 v[8:11], v[226:229], v[202:205], v[8:11]
	v_mfma_f32_16x16x32_bf16 v[4:7], v[218:221], v[210:213], v[4:7]
	v_mfma_f32_16x16x32_bf16 v[0:3], v[226:229], v[210:213], v[0:3]
	s_barrier
	ds_read_b128 v[170:173], v154
	ds_read_b128 v[174:177], v154 offset:1024
	ds_read_b128 v[178:181], v154 offset:2048
	ds_read_b128 v[182:185], v154 offset:3072
	v_add_u32_e32 v166, 0x4000, v143
	v_add_u32_e32 v167, 0x6000, v143
	v_readfirstlane_b32 s55, v166
	v_lshl_add_u64 v[218:219], v[234:235], 0, s[42:43]
	s_mov_b32 m0, s55
	v_readfirstlane_b32 s55, v167
	ds_read_b128 v[186:189], v151 offset:32768
	ds_read_b128 v[190:193], v151 offset:33792
	ds_read_b128 v[194:197], v150 offset:32768
	ds_read_b128 v[198:201], v150 offset:33792
	ds_read_b128 v[202:205], v149 offset:32768
	ds_read_b128 v[206:209], v149 offset:33792
	ds_read_b128 v[210:213], v148 offset:32768
	ds_read_b128 v[214:217], v148 offset:33792
	global_load_lds_dwordx4 v[218:219], off
	s_waitcnt lgkmcnt(8)
	s_barrier
	s_waitcnt lgkmcnt(0)
	s_waitcnt lgkmcnt(0)
	v_mfma_f32_16x16x32_bf16 v[124:127], v[170:173], v[186:189], v[124:127]
	v_mfma_f32_16x16x32_bf16 v[120:123], v[178:181], v[186:189], v[120:123]
	v_mfma_f32_16x16x32_bf16 v[116:119], v[170:173], v[194:197], v[116:119]
	v_mfma_f32_16x16x32_bf16 v[112:115], v[178:181], v[194:197], v[112:115]
	v_mfma_f32_16x16x32_bf16 v[108:111], v[170:173], v[202:205], v[108:111]
	v_mfma_f32_16x16x32_bf16 v[104:107], v[178:181], v[202:205], v[104:107]
	v_mfma_f32_16x16x32_bf16 v[100:103], v[170:173], v[210:213], v[100:103]
	v_mfma_f32_16x16x32_bf16 v[96:99], v[178:181], v[210:213], v[96:99]
	v_lshl_add_u64 v[218:219], v[236:237], 0, s[42:43]
	s_mov_b32 m0, s55
	s_nop 0
	global_load_lds_dwordx4 v[218:219], off
	v_mfma_f32_16x16x32_bf16 v[124:127], v[174:177], v[190:193], v[124:127]
	v_mfma_f32_16x16x32_bf16 v[120:123], v[182:185], v[190:193], v[120:123]
	v_mfma_f32_16x16x32_bf16 v[116:119], v[174:177], v[198:201], v[116:119]
	v_mfma_f32_16x16x32_bf16 v[112:115], v[182:185], v[198:201], v[112:115]
	v_mfma_f32_16x16x32_bf16 v[108:111], v[174:177], v[206:209], v[108:111]
	v_mfma_f32_16x16x32_bf16 v[104:107], v[182:185], v[206:209], v[104:107]
	v_mfma_f32_16x16x32_bf16 v[100:103], v[174:177], v[214:217], v[100:103]
	v_mfma_f32_16x16x32_bf16 v[96:99], v[182:185], v[214:217], v[96:99]
	s_barrier
	v_readfirstlane_b32 s55, v155
	v_add_u32_e32 v244, 0x2000, v155
	v_lshl_add_u64 v[242:243], v[238:239], 0, s[44:45]
	s_mov_b32 m0, s55
	v_readfirstlane_b32 s55, v244
	ds_read_b128 v[218:221], v152
	ds_read_b128 v[222:225], v152 offset:1024
	ds_read_b128 v[226:229], v152 offset:2048
	ds_read_b128 v[230:233], v152 offset:3072
	global_load_lds_dwordx4 v[242:243], off
	v_lshl_add_u64 v[242:243], v[240:241], 0, s[44:45]
	s_mov_b32 m0, s55
	s_nop 0
	global_load_lds_dwordx4 v[242:243], off
	s_barrier
	s_waitcnt lgkmcnt(0)
	s_waitcnt lgkmcnt(0)
	v_mfma_f32_16x16x32_bf16 v[92:95], v[218:221], v[186:189], v[92:95]
	v_mfma_f32_16x16x32_bf16 v[88:91], v[226:229], v[186:189], v[88:91]
	v_mfma_f32_16x16x32_bf16 v[84:87], v[218:221], v[194:197], v[84:87]
	v_mfma_f32_16x16x32_bf16 v[80:83], v[226:229], v[194:197], v[80:83]
	v_mfma_f32_16x16x32_bf16 v[76:79], v[218:221], v[202:205], v[76:79]
	v_mfma_f32_16x16x32_bf16 v[72:75], v[226:229], v[202:205], v[72:75]
	v_mfma_f32_16x16x32_bf16 v[68:71], v[218:221], v[210:213], v[68:71]
	v_mfma_f32_16x16x32_bf16 v[64:67], v[226:229], v[210:213], v[64:67]
	v_mfma_f32_16x16x32_bf16 v[92:95], v[222:225], v[190:193], v[92:95]
	v_mfma_f32_16x16x32_bf16 v[88:91], v[230:233], v[190:193], v[88:91]
	v_mfma_f32_16x16x32_bf16 v[84:87], v[222:225], v[198:201], v[84:87]
	v_mfma_f32_16x16x32_bf16 v[80:83], v[230:233], v[198:201], v[80:83]
	v_mfma_f32_16x16x32_bf16 v[76:79], v[222:225], v[206:209], v[76:79]
	v_mfma_f32_16x16x32_bf16 v[72:75], v[230:233], v[206:209], v[72:75]
	v_mfma_f32_16x16x32_bf16 v[68:71], v[222:225], v[214:217], v[68:71]
	v_mfma_f32_16x16x32_bf16 v[64:67], v[230:233], v[214:217], v[64:67]
	s_barrier
	v_readfirstlane_b32 s55, v156
	v_lshl_add_u64 v[234:235], v[234:235], 0, s[46:47]
	s_mov_b32 m0, s55
	v_readfirstlane_b32 s55, v157
	ds_read_b128 v[186:189], v151 offset:49152
	ds_read_b128 v[190:193], v151 offset:50176
	ds_read_b128 v[194:197], v150 offset:49152
	ds_read_b128 v[198:201], v150 offset:50176
	ds_read_b128 v[202:205], v149 offset:49152
	ds_read_b128 v[206:209], v149 offset:50176
	ds_read_b128 v[210:213], v148 offset:49152
	ds_read_b128 v[214:217], v148 offset:50176
	global_load_lds_dwordx4 v[234:235], off
	v_lshl_add_u64 v[234:235], v[236:237], 0, s[46:47]
	s_mov_b32 m0, s55
	s_nop 0
	global_load_lds_dwordx4 v[234:235], off
	s_barrier
; #define STAGE(P, BASE, LD, br, kt) do { const char* _g = (const char*)((BASE) + (size_t)(br) * (LD) + (size_t)(kt) * 64); \
;     for (int _i = 0; _i < 2; ++_i) { int _b = tidx * 16 + _i * 8192; int _r, _c; stage_rc(_b, _r, _c); \
;       __builtin_amdgcn_global_load_lds((const unsigned*)(_g + (unsigned)((_r * (LD) + _c) * 2)), (unsigned*)((char*)(P) + _b), 16, 0, 0); } } while (0)
; #define LDA(dst, b, h) for (int m = 0; m < 4; ++m) for (int k = 0; k < 2; ++k) \
;     dst[m][k] = *reinterpret_cast<const bf16x8*>((char*)SA(b, h) + lds_byte(wr * 64 + m * 16 + fr, k * 32 + fq * 8))
; #define LDB(dst, b, h) for (int n = 0; n < 2; ++n) for (int k = 0; k < 2; ++k) \
;     dst[n][k] = *reinterpret_cast<const bf16x8*>((char*)SB(b, h) + lds_byte(wc * 32 + n * 16 + fr, k * 32 + fq * 8))
; #define MMA(ai, bj, At_, Bt_) do { __builtin_amdgcn_s_setprio(1); \
;     for (int k = 0; k < 2; ++k) for (int m = 0; m < 4; ++m) for (int n = 0; n < 2; ++n) \
;       acc[ai][bj][m][n] = __builtin_amdgcn_mfma_f32_16x16x32_bf16(At_[m][k], Bt_[n][k], acc[ai][bj][m][n], 0, 0, 0); \
;     __builtin_amdgcn_s_setprio(0); } while (0)
; #define WAIT_V(n) asm volatile("s_waitcnt vmcnt(" #n ")" ::: "memory")
; #define WAIT_L(n) asm volatile("s_waitcnt lgkmcnt(" #n ")" ::: "memory")
; #define BAR __builtin_amdgcn_s_barrier()
; #define SCHED __builtin_amdgcn_sched_barrier(0)
; template <int EPI, int lda, int ldb, int N, int K>
; __device__ __forceinline__ void gemm_phase(const u16* __restrict__ A, const u16* __restrict__ Bt, const GemmEpi ep, int wv) {
;     ...
;       BAR; WAIT_L(0); MMA(0, 1, At, B1); BAR;
;       LDA(At, 1, 1); STAGE(SA(1, 0), Ab, lda, brow, t + 3);
;       BAR; WAIT_L(0); MMA(1, 0, At, B0); BAR; SCHED;
;       STAGE(SB(1, 1), Bt, ldb, bcol + HALF, t + 3);
;       WAIT_V(6); BAR; MMA(1, 1, At, B1); BAR;
;     }
;     { LDB(B0, 0, 0); LDA(At, 0, 0); STAGE(SA(1, 1), Ab, lda, brow + HALF, nt - 1);
;       BAR; WAIT_L(0); MMA(0, 0, At, B0); BAR;
;       LDB(B1, 0, 1); BAR; WAIT_L(0); MMA(0, 1, At, B1); BAR;
	s_waitcnt lgkmcnt(0)
	s_waitcnt lgkmcnt(0)
	v_mfma_f32_16x16x32_bf16 v[60:63], v[170:173], v[186:189], v[60:63]
	v_mfma_f32_16x16x32_bf16 v[56:59], v[178:181], v[186:189], v[56:59]
	v_mfma_f32_16x16x32_bf16 v[52:55], v[170:173], v[194:197], v[52:55]
	v_mfma_f32_16x16x32_bf16 v[48:51], v[178:181], v[194:197], v[48:51]
	v_mfma_f32_16x16x32_bf16 v[44:47], v[170:173], v[202:205], v[44:47]
	v_mfma_f32_16x16x32_bf16 v[40:43], v[178:181], v[202:205], v[40:43]
	v_mfma_f32_16x16x32_bf16 v[36:39], v[170:173], v[210:213], v[36:39]
	v_mfma_f32_16x16x32_bf16 v[32:35], v[178:181], v[210:213], v[32:35]
	v_mfma_f32_16x16x32_bf16 v[60:63], v[174:177], v[190:193], v[60:63]
	v_mfma_f32_16x16x32_bf16 v[56:59], v[182:185], v[190:193], v[56:59]
	v_mfma_f32_16x16x32_bf16 v[52:55], v[174:177], v[198:201], v[52:55]
	v_mfma_f32_16x16x32_bf16 v[48:51], v[182:185], v[198:201], v[48:51]
	v_mfma_f32_16x16x32_bf16 v[44:47], v[174:177], v[206:209], v[44:47]
	v_mfma_f32_16x16x32_bf16 v[40:43], v[182:185], v[206:209], v[40:43]
	v_mfma_f32_16x16x32_bf16 v[36:39], v[174:177], v[214:217], v[36:39]
	v_mfma_f32_16x16x32_bf16 v[32:35], v[182:185], v[214:217], v[32:35]
	s_barrier
	v_readfirstlane_b32 s55, v158
	v_add_u32_e32 v172, 0x2000, v158
	v_lshl_add_u64 v[170:171], v[238:239], 0, s[48:49]
	s_mov_b32 m0, s55
	v_readfirstlane_b32 s55, v172
	global_load_lds_dwordx4 v[170:171], off
	v_lshl_add_u64 v[170:171], v[240:241], 0, s[48:49]
	s_mov_b32 m0, s55
	s_nop 0
	global_load_lds_dwordx4 v[170:171], off
	s_waitcnt vmcnt(6)
	s_barrier
	v_mfma_f32_16x16x32_bf16 v[28:31], v[218:221], v[186:189], v[28:31]
	v_mfma_f32_16x16x32_bf16 v[24:27], v[226:229], v[186:189], v[24:27]
	v_mfma_f32_16x16x32_bf16 v[20:23], v[218:221], v[194:197], v[20:23]
	v_mfma_f32_16x16x32_bf16 v[16:19], v[226:229], v[194:197], v[16:19]
	v_mfma_f32_16x16x32_bf16 v[12:15], v[218:221], v[202:205], v[12:15]
	v_mfma_f32_16x16x32_bf16 v[8:11], v[226:229], v[202:205], v[8:11]
	v_mfma_f32_16x16x32_bf16 v[4:7], v[218:221], v[210:213], v[4:7]
	v_mfma_f32_16x16x32_bf16 v[0:3], v[226:229], v[210:213], v[0:3]
	v_mfma_f32_16x16x32_bf16 v[28:31], v[222:225], v[190:193], v[28:31]
	v_mfma_f32_16x16x32_bf16 v[24:27], v[230:233], v[190:193], v[24:27]
	v_mfma_f32_16x16x32_bf16 v[20:23], v[222:225], v[198:201], v[20:23]
	v_mfma_f32_16x16x32_bf16 v[16:19], v[230:233], v[198:201], v[16:19]
	v_mfma_f32_16x16x32_bf16 v[12:15], v[222:225], v[206:209], v[12:15]
	v_mfma_f32_16x16x32_bf16 v[8:11], v[230:233], v[206:209], v[8:11]
	v_mfma_f32_16x16x32_bf16 v[4:7], v[222:225], v[214:217], v[4:7]
	v_mfma_f32_16x16x32_bf16 v[0:3], v[230:233], v[214:217], v[0:3]
	s_add_i32 s54, s54, 2
	s_add_u32 s52, s52, 0x100
	s_addc_u32 s53, s53, 0
	s_cmp_gt_u32 s54, 27
	s_barrier
	s_cbranch_scc0 .LBB0_654
	s_lshl_b64 s[52:53], s[16:17], 12
	s_add_u32 s52, s14, s52
	s_addc_u32 s53, s15, s53
	s_add_u32 s52, s52, 0x80000
	s_addc_u32 s53, s53, 0
	v_lshl_add_u64 v[156:157], s[52:53], 0, v[128:129]
	v_readfirstlane_b32 s54, v168
	v_lshl_add_u64 v[156:157], v[156:157], 0, s[50:51]
	s_mov_b32 m0, s54
	ds_read_b128 v[134:137], v160
	ds_read_b128 v[138:141], v160 offset:1024
	ds_read_b128 v[170:173], v160 offset:2048
	ds_read_b128 v[174:177], v160 offset:3072
	ds_read_b128 v[178:181], v151
	ds_read_b128 v[182:185], v151 offset:1024
	ds_read_b128 v[186:189], v150
	ds_read_b128 v[190:193], v150 offset:1024
	ds_read_b128 v[194:197], v149
	ds_read_b128 v[198:201], v149 offset:1024
	ds_read_b128 v[202:205], v148
	ds_read_b128 v[206:209], v148 offset:1024
	global_load_lds_dwordx4 v[156:157], off
	v_lshl_add_u64 v[156:157], s[52:53], 0, v[132:133]
	v_readfirstlane_b32 s52, v169
	v_lshl_add_u64 v[156:157], v[156:157], 0, s[50:51]
	s_mov_b32 m0, s52
	s_nop 0
	global_load_lds_dwordx4 v[156:157], off
	s_barrier
	s_waitcnt lgkmcnt(0)
	s_waitcnt lgkmcnt(0)
	v_mfma_f32_16x16x32_bf16 v[124:127], v[134:137], v[178:181], v[124:127]
	v_mfma_f32_16x16x32_bf16 v[120:123], v[170:173], v[178:181], v[120:123]
	v_mfma_f32_16x16x32_bf16 v[116:119], v[134:137], v[186:189], v[116:119]
	v_mfma_f32_16x16x32_bf16 v[112:115], v[170:173], v[186:189], v[112:115]
	v_mfma_f32_16x16x32_bf16 v[108:111], v[134:137], v[194:197], v[108:111]
	v_mfma_f32_16x16x32_bf16 v[104:107], v[170:173], v[194:197], v[104:107]
	v_mfma_f32_16x16x32_bf16 v[100:103], v[134:137], v[202:205], v[100:103]
	v_mfma_f32_16x16x32_bf16 v[96:99], v[170:173], v[202:205], v[96:99]
	v_mfma_f32_16x16x32_bf16 v[124:127], v[138:141], v[182:185], v[124:127]
	v_mfma_f32_16x16x32_bf16 v[120:123], v[174:177], v[182:185], v[120:123]
	v_mfma_f32_16x16x32_bf16 v[116:119], v[138:141], v[190:193], v[116:119]
	v_mfma_f32_16x16x32_bf16 v[112:115], v[174:177], v[190:193], v[112:115]
	v_mfma_f32_16x16x32_bf16 v[108:111], v[138:141], v[198:201], v[108:111]
	v_mfma_f32_16x16x32_bf16 v[104:107], v[174:177], v[198:201], v[104:107]
	v_mfma_f32_16x16x32_bf16 v[100:103], v[138:141], v[206:209], v[100:103]
	v_mfma_f32_16x16x32_bf16 v[96:99], v[174:177], v[206:209], v[96:99]
	s_barrier
	ds_read_b128 v[210:213], v159
	ds_read_b128 v[214:217], v159 offset:1024
	ds_read_b128 v[218:221], v159 offset:2048
	ds_read_b128 v[156:159], v159 offset:3072
	s_barrier
; #define LDA(dst, b, h) for (int m = 0; m < 4; ++m) for (int k = 0; k < 2; ++k) \
;     dst[m][k] = *reinterpret_cast<const bf16x8*>((char*)SA(b, h) + lds_byte(wr * 64 + m * 16 + fr, k * 32 + fq * 8))
; #define LDB(dst, b, h) for (int n = 0; n < 2; ++n) for (int k = 0; k < 2; ++k) \
;     dst[n][k] = *reinterpret_cast<const bf16x8*>((char*)SB(b, h) + lds_byte(wc * 32 + n * 16 + fr, k * 32 + fq * 8))
; #define MMA(ai, bj, At_, Bt_) do { __builtin_amdgcn_s_setprio(1); \
;     for (int k = 0; k < 2; ++k) for (int m = 0; m < 4; ++m) for (int n = 0; n < 2; ++n) \
;       acc[ai][bj][m][n] = __builtin_amdgcn_mfma_f32_16x16x32_bf16(At_[m][k], Bt_[n][k], acc[ai][bj][m][n], 0, 0, 0); \
;     __builtin_amdgcn_s_setprio(0); } while (0)
; #define WAIT_V(n) asm volatile("s_waitcnt vmcnt(" #n ")" ::: "memory")
; #define WAIT_L(n) asm volatile("s_waitcnt lgkmcnt(" #n ")" ::: "memory")
; #define BAR __builtin_amdgcn_s_barrier()
; template <int EPI, int lda, int ldb, int N, int K>
; __device__ __forceinline__ void gemm_phase(const u16* __restrict__ A, const u16* __restrict__ Bt, const GemmEpi ep, int wv) {
;     ...
;       LDB(B1, 0, 1); BAR; WAIT_L(0); MMA(0, 1, At, B1); BAR;
;       LDA(At, 0, 1); WAIT_V(4); BAR; WAIT_L(0); MMA(1, 0, At, B0); MMA(1, 1, At, B1); BAR; }
;     { LDB(B0, 1, 0); LDA(At, 1, 0); WAIT_V(2); BAR; WAIT_L(0); MMA(0, 0, At, B0); BAR;
	s_waitcnt lgkmcnt(0)
	s_waitcnt lgkmcnt(0)
	v_mfma_f32_16x16x32_bf16 v[92:95], v[210:213], v[178:181], v[92:95]
	v_mfma_f32_16x16x32_bf16 v[88:91], v[218:221], v[178:181], v[88:91]
	v_mfma_f32_16x16x32_bf16 v[76:79], v[210:213], v[194:197], v[76:79]
	v_mfma_f32_16x16x32_bf16 v[72:75], v[218:221], v[194:197], v[72:75]
	v_mfma_f32_16x16x32_bf16 v[84:87], v[210:213], v[186:189], v[84:87]
	v_mfma_f32_16x16x32_bf16 v[80:83], v[218:221], v[186:189], v[80:83]
	v_mfma_f32_16x16x32_bf16 v[68:71], v[210:213], v[202:205], v[68:71]
	v_mfma_f32_16x16x32_bf16 v[64:67], v[218:221], v[202:205], v[64:67]
	v_mfma_f32_16x16x32_bf16 v[92:95], v[214:217], v[182:185], v[92:95]
	v_mfma_f32_16x16x32_bf16 v[88:91], v[156:159], v[182:185], v[88:91]
	v_mfma_f32_16x16x32_bf16 v[76:79], v[214:217], v[198:201], v[76:79]
	v_mfma_f32_16x16x32_bf16 v[72:75], v[156:159], v[198:201], v[72:75]
	v_mfma_f32_16x16x32_bf16 v[178:181], v[214:217], v[190:193], v[84:87]
	v_mfma_f32_16x16x32_bf16 v[182:185], v[156:159], v[190:193], v[80:83]
	v_mfma_f32_16x16x32_bf16 v[186:189], v[214:217], v[206:209], v[68:71]
	v_mfma_f32_16x16x32_bf16 v[190:193], v[156:159], v[206:209], v[64:67]
	s_barrier
	s_nop 0
	ds_read_b128 v[64:67], v151 offset:16384
	ds_read_b128 v[68:71], v151 offset:17408
	ds_read_b128 v[80:83], v150 offset:16384
	ds_read_b128 v[84:87], v150 offset:17408
	ds_read_b128 v[194:197], v149 offset:16384
	ds_read_b128 v[198:201], v149 offset:17408
	ds_read_b128 v[202:205], v148 offset:16384
	ds_read_b128 v[206:209], v148 offset:17408
	s_waitcnt vmcnt(4)
	s_barrier
	s_waitcnt lgkmcnt(0)
	s_waitcnt lgkmcnt(0)
	v_mfma_f32_16x16x32_bf16 v[60:63], v[134:137], v[64:67], v[60:63]
	v_mfma_f32_16x16x32_bf16 v[56:59], v[170:173], v[64:67], v[56:59]
	v_mfma_f32_16x16x32_bf16 v[52:55], v[134:137], v[80:83], v[52:55]
	v_mfma_f32_16x16x32_bf16 v[48:51], v[170:173], v[80:83], v[48:51]
	v_mfma_f32_16x16x32_bf16 v[44:47], v[134:137], v[194:197], v[44:47]
	v_mfma_f32_16x16x32_bf16 v[40:43], v[170:173], v[194:197], v[40:43]
	v_mfma_f32_16x16x32_bf16 v[36:39], v[134:137], v[202:205], v[36:39]
	v_mfma_f32_16x16x32_bf16 v[32:35], v[170:173], v[202:205], v[32:35]
	v_mfma_f32_16x16x32_bf16 v[60:63], v[138:141], v[68:71], v[60:63]
	v_mfma_f32_16x16x32_bf16 v[56:59], v[174:177], v[68:71], v[56:59]
	v_mfma_f32_16x16x32_bf16 v[52:55], v[138:141], v[84:87], v[52:55]
	v_mfma_f32_16x16x32_bf16 v[48:51], v[174:177], v[84:87], v[48:51]
	v_mfma_f32_16x16x32_bf16 v[44:47], v[138:141], v[198:201], v[44:47]
	v_mfma_f32_16x16x32_bf16 v[40:43], v[174:177], v[198:201], v[40:43]
	v_mfma_f32_16x16x32_bf16 v[36:39], v[138:141], v[206:209], v[36:39]
	v_mfma_f32_16x16x32_bf16 v[32:35], v[174:177], v[206:209], v[32:35]
	v_mfma_f32_16x16x32_bf16 v[28:31], v[210:213], v[64:67], v[28:31]
	v_mfma_f32_16x16x32_bf16 v[20:23], v[210:213], v[80:83], v[20:23]
	v_mfma_f32_16x16x32_bf16 v[12:15], v[210:213], v[194:197], v[12:15]
	v_mfma_f32_16x16x32_bf16 v[4:7], v[210:213], v[202:205], v[4:7]
	v_mfma_f32_16x16x32_bf16 v[24:27], v[218:221], v[64:67], v[24:27]
	v_mfma_f32_16x16x32_bf16 v[16:19], v[218:221], v[80:83], v[16:19]
	v_mfma_f32_16x16x32_bf16 v[8:11], v[218:221], v[194:197], v[8:11]
	v_mfma_f32_16x16x32_bf16 v[0:3], v[218:221], v[202:205], v[0:3]
	v_mfma_f32_16x16x32_bf16 v[28:31], v[214:217], v[68:71], v[28:31]
	v_mfma_f32_16x16x32_bf16 v[20:23], v[214:217], v[84:87], v[20:23]
	v_mfma_f32_16x16x32_bf16 v[12:15], v[214:217], v[198:201], v[12:15]
	v_mfma_f32_16x16x32_bf16 v[4:7], v[214:217], v[206:209], v[4:7]
	v_mfma_f32_16x16x32_bf16 v[134:137], v[156:159], v[68:71], v[24:27]
	v_mfma_f32_16x16x32_bf16 v[138:141], v[156:159], v[84:87], v[16:19]
	v_mfma_f32_16x16x32_bf16 v[168:171], v[156:159], v[198:201], v[8:11]
	v_mfma_f32_16x16x32_bf16 v[156:159], v[156:159], v[206:209], v[0:3]
	s_barrier
	s_nop 0
	ds_read_b128 v[0:3], v154
	ds_read_b128 v[8:11], v154 offset:1024
	ds_read_b128 v[16:19], v154 offset:2048
	ds_read_b128 v[172:175], v154 offset:3072
	ds_read_b128 v[24:27], v151 offset:32768
	ds_read_b128 v[194:197], v151 offset:33792
	ds_read_b128 v[198:201], v150 offset:32768
	ds_read_b128 v[202:205], v150 offset:33792
	ds_read_b128 v[206:209], v149 offset:32768
	ds_read_b128 v[210:213], v149 offset:33792
	ds_read_b128 v[214:217], v148 offset:32768
	ds_read_b128 v[218:221], v148 offset:33792
	s_waitcnt vmcnt(2)
	s_barrier
; #define LDA(dst, b, h) for (int m = 0; m < 4; ++m) for (int k = 0; k < 2; ++k) \
;     dst[m][k] = *reinterpret_cast<const bf16x8*>((char*)SA(b, h) + lds_byte(wr * 64 + m * 16 + fr, k * 32 + fq * 8))
; #define LDB(dst, b, h) for (int n = 0; n < 2; ++n) for (int k = 0; k < 2; ++k) \
;     dst[n][k] = *reinterpret_cast<const bf16x8*>((char*)SB(b, h) + lds_byte(wc * 32 + n * 16 + fr, k * 32 + fq * 8))
; #define MMA(ai, bj, At_, Bt_) do { __builtin_amdgcn_s_setprio(1); \
;     for (int k = 0; k < 2; ++k) for (int m = 0; m < 4; ++m) for (int n = 0; n < 2; ++n) \
;       acc[ai][bj][m][n] = __builtin_amdgcn_mfma_f32_16x16x32_bf16(At_[m][k], Bt_[n][k], acc[ai][bj][m][n], 0, 0, 0); \
;     __builtin_amdgcn_s_setprio(0); } while (0)
; #define WAIT_V(n) asm volatile("s_waitcnt vmcnt(" #n ")" ::: "memory")
; #define WAIT_L(n) asm volatile("s_waitcnt lgkmcnt(" #n ")" ::: "memory")
; #define BAR __builtin_amdgcn_s_barrier()
; template <int EPI, int lda, int ldb, int N, int K>
; __device__ __forceinline__ void gemm_phase(const u16* __restrict__ A, const u16* __restrict__ Bt, const GemmEpi ep, int wv) {
;     ...
;     { LDB(B0, 1, 0); LDA(At, 1, 0); WAIT_V(2); BAR; WAIT_L(0); MMA(0, 0, At, B0); BAR;
;       LDB(B1, 1, 1); WAIT_V(0); BAR; WAIT_L(0); MMA(0, 1, At, B1); BAR;
;       LDA(At, 1, 1); BAR; WAIT_L(0); MMA(1, 0, At, B0); MMA(1, 1, At, B1); BAR; }
;     if (wr == 0) BAR;
	s_waitcnt lgkmcnt(0)
	s_waitcnt lgkmcnt(0)
	v_mfma_f32_16x16x32_bf16 v[64:67], v[0:3], v[24:27], v[124:127]
	v_mfma_f32_16x16x32_bf16 v[68:71], v[16:19], v[24:27], v[120:123]
	v_mfma_f32_16x16x32_bf16 v[80:83], v[0:3], v[198:201], v[116:119]
	v_mfma_f32_16x16x32_bf16 v[84:87], v[16:19], v[198:201], v[112:115]
	v_mfma_f32_16x16x32_bf16 v[108:111], v[0:3], v[206:209], v[108:111]
	v_mfma_f32_16x16x32_bf16 v[104:107], v[16:19], v[206:209], v[104:107]
	v_mfma_f32_16x16x32_bf16 v[120:123], v[0:3], v[214:217], v[100:103]
	v_mfma_f32_16x16x32_bf16 v[124:127], v[16:19], v[214:217], v[96:99]
	v_mfma_f32_16x16x32_bf16 v[116:119], v[8:11], v[194:197], v[64:67]
	v_mfma_f32_16x16x32_bf16 v[112:115], v[172:175], v[194:197], v[68:71]
	v_mfma_f32_16x16x32_bf16 v[100:103], v[8:11], v[202:205], v[80:83]
	v_mfma_f32_16x16x32_bf16 v[96:99], v[172:175], v[202:205], v[84:87]
	v_mfma_f32_16x16x32_bf16 v[84:87], v[8:11], v[210:213], v[108:111]
	v_mfma_f32_16x16x32_bf16 v[80:83], v[172:175], v[210:213], v[104:107]
	v_mfma_f32_16x16x32_bf16 v[68:71], v[8:11], v[218:221], v[120:123]
	v_mfma_f32_16x16x32_bf16 v[64:67], v[172:175], v[218:221], v[124:127]
	s_barrier
	ds_read_b128 v[222:225], v152
	ds_read_b128 v[226:229], v152 offset:1024
	ds_read_b128 v[230:233], v152 offset:2048
	ds_read_b128 v[152:155], v152 offset:3072
	s_waitcnt vmcnt(0)
	s_barrier
	s_waitcnt lgkmcnt(0)
	s_waitcnt lgkmcnt(0)
	v_mfma_f32_16x16x32_bf16 v[92:95], v[222:225], v[24:27], v[92:95]
	v_mfma_f32_16x16x32_bf16 v[24:27], v[230:233], v[24:27], v[88:91]
	v_mfma_f32_16x16x32_bf16 v[88:91], v[222:225], v[198:201], v[178:181]
	v_mfma_f32_16x16x32_bf16 v[104:107], v[230:233], v[198:201], v[182:185]
	v_mfma_f32_16x16x32_bf16 v[76:79], v[222:225], v[206:209], v[76:79]
	v_mfma_f32_16x16x32_bf16 v[72:75], v[230:233], v[206:209], v[72:75]
	v_mfma_f32_16x16x32_bf16 v[176:179], v[222:225], v[214:217], v[186:189]
	v_mfma_f32_16x16x32_bf16 v[180:183], v[230:233], v[214:217], v[190:193]
	v_mfma_f32_16x16x32_bf16 v[124:127], v[226:229], v[194:197], v[92:95]
	v_mfma_f32_16x16x32_bf16 v[120:123], v[152:155], v[194:197], v[24:27]
	v_mfma_f32_16x16x32_bf16 v[108:111], v[226:229], v[202:205], v[88:91]
	v_mfma_f32_16x16x32_bf16 v[104:107], v[152:155], v[202:205], v[104:107]
	v_mfma_f32_16x16x32_bf16 v[92:95], v[226:229], v[210:213], v[76:79]
	v_mfma_f32_16x16x32_bf16 v[88:91], v[152:155], v[210:213], v[72:75]
	v_mfma_f32_16x16x32_bf16 v[76:79], v[226:229], v[218:221], v[176:179]
	v_mfma_f32_16x16x32_bf16 v[72:75], v[152:155], v[218:221], v[180:183]
	s_barrier
	ds_read_b128 v[176:179], v151 offset:49152
	ds_read_b128 v[180:183], v151 offset:50176
	ds_read_b128 v[184:187], v150 offset:49152
	ds_read_b128 v[188:191], v150 offset:50176
	ds_read_b128 v[192:195], v149 offset:49152
	ds_read_b128 v[196:199], v149 offset:50176
	ds_read_b128 v[200:203], v148 offset:49152
	ds_read_b128 v[148:151], v148 offset:50176
	s_barrier
	s_waitcnt lgkmcnt(0)
	s_waitcnt lgkmcnt(0)
	v_mfma_f32_16x16x32_bf16 v[24:27], v[0:3], v[176:179], v[60:63]
	v_mfma_f32_16x16x32_bf16 v[60:63], v[16:19], v[176:179], v[56:59]
	v_mfma_f32_16x16x32_bf16 v[52:55], v[0:3], v[184:187], v[52:55]
	v_mfma_f32_16x16x32_bf16 v[204:207], v[16:19], v[184:187], v[48:51]
	v_mfma_f32_16x16x32_bf16 v[44:47], v[0:3], v[192:195], v[44:47]
	v_mfma_f32_16x16x32_bf16 v[208:211], v[16:19], v[192:195], v[40:43]
	v_mfma_f32_16x16x32_bf16 v[0:3], v[0:3], v[200:203], v[36:39]
	v_mfma_f32_16x16x32_bf16 v[36:39], v[16:19], v[200:203], v[32:35]
	v_mfma_f32_16x16x32_bf16 v[56:59], v[8:11], v[180:183], v[24:27]
	v_mfma_f32_16x16x32_bf16 v[48:51], v[172:175], v[180:183], v[60:63]
	v_mfma_f32_16x16x32_bf16 v[40:43], v[8:11], v[188:191], v[52:55]
	v_mfma_f32_16x16x32_bf16 v[32:35], v[172:175], v[188:191], v[204:207]
	v_mfma_f32_16x16x32_bf16 v[24:27], v[8:11], v[196:199], v[44:47]
	v_mfma_f32_16x16x32_bf16 v[16:19], v[172:175], v[196:199], v[208:211]
	v_mfma_f32_16x16x32_bf16 v[8:11], v[8:11], v[148:151], v[0:3]
	v_mfma_f32_16x16x32_bf16 v[0:3], v[172:175], v[148:151], v[36:39]
	v_mfma_f32_16x16x32_bf16 v[28:31], v[222:225], v[176:179], v[28:31]
	v_mfma_f32_16x16x32_bf16 v[36:39], v[230:233], v[176:179], v[134:137]
	v_mfma_f32_16x16x32_bf16 v[20:23], v[222:225], v[184:187], v[20:23]
	v_mfma_f32_16x16x32_bf16 v[134:137], v[230:233], v[184:187], v[138:141]
	v_mfma_f32_16x16x32_bf16 v[12:15], v[222:225], v[192:195], v[12:15]
	v_mfma_f32_16x16x32_bf16 v[138:141], v[230:233], v[192:195], v[168:171]
	v_mfma_f32_16x16x32_bf16 v[4:7], v[222:225], v[200:203], v[4:7]
	v_mfma_f32_16x16x32_bf16 v[156:159], v[230:233], v[200:203], v[156:159]
	v_mfma_f32_16x16x32_bf16 v[60:63], v[226:229], v[180:183], v[28:31]
	v_mfma_f32_16x16x32_bf16 v[52:55], v[152:155], v[180:183], v[36:39]
	v_mfma_f32_16x16x32_bf16 v[44:47], v[226:229], v[188:191], v[20:23]
	v_mfma_f32_16x16x32_bf16 v[36:39], v[152:155], v[188:191], v[134:137]
	v_mfma_f32_16x16x32_bf16 v[28:31], v[226:229], v[196:199], v[12:15]
	v_mfma_f32_16x16x32_bf16 v[20:23], v[152:155], v[196:199], v[138:141]
	v_mfma_f32_16x16x32_bf16 v[12:15], v[226:229], v[148:151], v[4:7]
	v_mfma_f32_16x16x32_bf16 v[4:7], v[152:155], v[148:151], v[156:159]
	v_cmp_gt_u32_e32 vcc, s70, v130
	s_barrier
	s_and_saveexec_b64 s[52:53], vcc
	s_cbranch_execz .LBB0_657
	s_barrier

; #define STAGE(P, BASE, LD, br, kt) do { const char* _g = (const char*)((BASE) + (size_t)(br) * (LD) + (size_t)(kt) * 64); \
;     for (int _i = 0; _i < 2; ++_i) { int _b = tidx * 16 + _i * 8192; int _r, _c; stage_rc(_b, _r, _c); \
;       __builtin_amdgcn_global_load_lds((const unsigned*)(_g + (unsigned)((_r * (LD) + _c) * 2)), (unsigned*)((char*)(P) + _b), 16, 0, 0); } } while (0)
; #define LDA(dst, b, h) for (int m = 0; m < 4; ++m) for (int k = 0; k < 2; ++k) \
;     dst[m][k] = *reinterpret_cast<const bf16x8*>((char*)SA(b, h) + lds_byte(wr * 64 + m * 16 + fr, k * 32 + fq * 8))
; #define LDB(dst, b, h) for (int n = 0; n < 2; ++n) for (int k = 0; k < 2; ++k) \
;     dst[n][k] = *reinterpret_cast<const bf16x8*>((char*)SB(b, h) + lds_byte(wc * 32 + n * 16 + fr, k * 32 + fq * 8))
; #define MMA(ai, bj, At_, Bt_) do { __builtin_amdgcn_s_setprio(1); \
;     for (int k = 0; k < 2; ++k) for (int m = 0; m < 4; ++m) for (int n = 0; n < 2; ++n) \
;       acc[ai][bj][m][n] = __builtin_amdgcn_mfma_f32_16x16x32_bf16(At_[m][k], Bt_[n][k], acc[ai][bj][m][n], 0, 0, 0); \
;     __builtin_amdgcn_s_setprio(0); } while (0)
; #define WAIT_L(n) asm volatile("s_waitcnt lgkmcnt(" #n ")" ::: "memory")
; #define BAR __builtin_amdgcn_s_barrier()
; #define SCHED __builtin_amdgcn_sched_barrier(0)
; template <int EPI, int lda, int ldb, int N, int K>
; __device__ __forceinline__ void gemm_phase(const u16* __restrict__ A, const u16* __restrict__ Bt, const GemmEpi ep, int wv) {
;     ...
;       LDB(B0, 0, 0); SCHED; LDA(At, 0, 0); STAGE(SA(1, 1), Ab, lda, brow + HALF, t + 1);
;       WAIT_L(8); BAR; WAIT_L(0); MMA(0, 0, At, B0); BAR; SCHED;
;       LDB(B1, 0, 1); STAGE(SB(0, 0), Bt, ldb, bcol, t + 2);
;       BAR; WAIT_L(0); MMA(0, 1, At, B1); BAR;
;       LDA(At, 0, 1); STAGE(SA(0, 0), Ab, lda, brow, t + 2);
;       BAR; WAIT_L(0); MMA(1, 0, At, B0); BAR; SCHED;
.LBB0_770:
	ds_read_b128 v[172:175], v161
	ds_read_b128 v[176:179], v161 offset:1024
	ds_read_b128 v[180:183], v161 offset:2048
	ds_read_b128 v[184:187], v161 offset:3072
	v_add_u32_e32 v169, 0xc000, v148
	v_lshl_add_u64 v[236:237], v[136:137], 0, s[50:51]
	v_readfirstlane_b32 s53, v169
	v_add_u32_e32 v170, 0xe000, v148
	v_lshl_add_u64 v[162:163], v[236:237], 0, s[18:19]
	s_mov_b32 m0, s53
	v_lshl_add_u64 v[238:239], v[134:135], 0, s[50:51]
	v_readfirstlane_b32 s53, v170
	ds_read_b128 v[164:167], v152
	ds_read_b128 v[188:191], v152 offset:1024
	ds_read_b128 v[192:195], v151
	ds_read_b128 v[196:199], v151 offset:1024
	ds_read_b128 v[200:203], v150
	ds_read_b128 v[204:207], v150 offset:1024
	ds_read_b128 v[208:211], v149
	ds_read_b128 v[212:215], v149 offset:1024
	global_load_lds_dwordx4 v[162:163], off
	s_waitcnt lgkmcnt(8)
	s_barrier
	s_waitcnt lgkmcnt(0)
	s_waitcnt lgkmcnt(0)
	v_mfma_f32_16x16x32_bf16 v[124:127], v[172:175], v[164:167], v[124:127]
	v_mfma_f32_16x16x32_bf16 v[120:123], v[180:183], v[164:167], v[120:123]
	v_mfma_f32_16x16x32_bf16 v[116:119], v[172:175], v[192:195], v[116:119]
	v_mfma_f32_16x16x32_bf16 v[112:115], v[180:183], v[192:195], v[112:115]
	v_mfma_f32_16x16x32_bf16 v[108:111], v[172:175], v[200:203], v[108:111]
	v_mfma_f32_16x16x32_bf16 v[104:107], v[180:183], v[200:203], v[104:107]
	v_mfma_f32_16x16x32_bf16 v[100:103], v[172:175], v[208:211], v[100:103]
	v_mfma_f32_16x16x32_bf16 v[96:99], v[180:183], v[208:211], v[96:99]
	v_lshl_add_u64 v[162:163], v[238:239], 0, s[18:19]
	s_mov_b32 m0, s53
	s_nop 0
	global_load_lds_dwordx4 v[162:163], off
	v_mfma_f32_16x16x32_bf16 v[124:127], v[176:179], v[188:191], v[124:127]
	v_mfma_f32_16x16x32_bf16 v[120:123], v[184:187], v[188:191], v[120:123]
	v_mfma_f32_16x16x32_bf16 v[116:119], v[176:179], v[196:199], v[116:119]
	v_mfma_f32_16x16x32_bf16 v[112:115], v[184:187], v[196:199], v[112:115]
	v_mfma_f32_16x16x32_bf16 v[108:111], v[176:179], v[204:207], v[108:111]
	v_mfma_f32_16x16x32_bf16 v[104:107], v[184:187], v[204:207], v[104:107]
	v_mfma_f32_16x16x32_bf16 v[100:103], v[176:179], v[212:215], v[100:103]
	v_mfma_f32_16x16x32_bf16 v[96:99], v[184:187], v[212:215], v[96:99]
	s_barrier
	v_add_u32_e32 v162, s64, v153
	v_lshl_add_u64 v[240:241], v[140:141], 0, s[50:51]
	v_readfirstlane_b32 s53, v162
	v_add_u32_e32 v163, 0x2000, v162
	v_lshl_add_u64 v[232:233], v[240:241], 0, s[20:21]
	s_mov_b32 m0, s53
	v_lshl_add_u64 v[242:243], v[138:139], 0, s[50:51]
	v_readfirstlane_b32 s53, v163
	ds_read_b128 v[216:219], v160
	ds_read_b128 v[220:223], v160 offset:1024
	ds_read_b128 v[224:227], v160 offset:2048
	ds_read_b128 v[228:231], v160 offset:3072
	global_load_lds_dwordx4 v[232:233], off
	v_lshl_add_u64 v[232:233], v[242:243], 0, s[20:21]
	s_mov_b32 m0, s53
	s_nop 0
	global_load_lds_dwordx4 v[232:233], off
	s_barrier
	s_waitcnt lgkmcnt(0)
	s_waitcnt lgkmcnt(0)
	v_mfma_f32_16x16x32_bf16 v[92:95], v[216:219], v[164:167], v[92:95]
	v_mfma_f32_16x16x32_bf16 v[88:91], v[224:227], v[164:167], v[88:91]
	v_mfma_f32_16x16x32_bf16 v[84:87], v[216:219], v[192:195], v[84:87]
	v_mfma_f32_16x16x32_bf16 v[80:83], v[224:227], v[192:195], v[80:83]
	v_mfma_f32_16x16x32_bf16 v[76:79], v[216:219], v[200:203], v[76:79]
	v_mfma_f32_16x16x32_bf16 v[72:75], v[224:227], v[200:203], v[72:75]
	v_mfma_f32_16x16x32_bf16 v[68:71], v[216:219], v[208:211], v[68:71]
	v_mfma_f32_16x16x32_bf16 v[64:67], v[224:227], v[208:211], v[64:67]
	v_mfma_f32_16x16x32_bf16 v[92:95], v[220:223], v[188:191], v[92:95]
	v_mfma_f32_16x16x32_bf16 v[88:91], v[228:231], v[188:191], v[88:91]
	v_mfma_f32_16x16x32_bf16 v[84:87], v[220:223], v[196:199], v[84:87]
	v_mfma_f32_16x16x32_bf16 v[80:83], v[228:231], v[196:199], v[80:83]
	v_mfma_f32_16x16x32_bf16 v[76:79], v[220:223], v[204:207], v[76:79]
	v_mfma_f32_16x16x32_bf16 v[72:75], v[228:231], v[204:207], v[72:75]
	v_mfma_f32_16x16x32_bf16 v[68:71], v[220:223], v[212:215], v[68:71]
	v_mfma_f32_16x16x32_bf16 v[64:67], v[228:231], v[212:215], v[64:67]
	s_barrier
	v_readfirstlane_b32 s53, v148
	v_lshl_add_u64 v[164:165], v[236:237], 0, s[22:23]
	s_mov_b32 m0, s53
	ds_read_b128 v[188:191], v152 offset:16384
	ds_read_b128 v[192:195], v152 offset:17408
	ds_read_b128 v[196:199], v151 offset:16384
	ds_read_b128 v[200:203], v151 offset:17408
	ds_read_b128 v[204:207], v150 offset:16384
	ds_read_b128 v[208:211], v150 offset:17408
	ds_read_b128 v[212:215], v149 offset:16384
	ds_read_b128 v[232:235], v149 offset:17408
	global_load_lds_dwordx4 v[164:165], off
	v_add_u32_e32 v164, 0x2000, v148
	v_lshl_add_u64 v[166:167], v[238:239], 0, s[22:23]
	v_readfirstlane_b32 s53, v164
	s_mov_b32 m0, s53
	s_nop 0
	global_load_lds_dwordx4 v[166:167], off
	s_barrier
	s_waitcnt lgkmcnt(0)
	s_waitcnt lgkmcnt(0)
	v_mfma_f32_16x16x32_bf16 v[60:63], v[172:175], v[188:191], v[60:63]
	v_mfma_f32_16x16x32_bf16 v[56:59], v[180:183], v[188:191], v[56:59]
	v_mfma_f32_16x16x32_bf16 v[52:55], v[172:175], v[196:199], v[52:55]
	v_mfma_f32_16x16x32_bf16 v[48:51], v[180:183], v[196:199], v[48:51]
	v_mfma_f32_16x16x32_bf16 v[44:47], v[172:175], v[204:207], v[44:47]
	v_mfma_f32_16x16x32_bf16 v[40:43], v[180:183], v[204:207], v[40:43]
	v_mfma_f32_16x16x32_bf16 v[36:39], v[172:175], v[212:215], v[36:39]
	v_mfma_f32_16x16x32_bf16 v[32:35], v[180:183], v[212:215], v[32:35]
	v_mfma_f32_16x16x32_bf16 v[60:63], v[176:179], v[192:195], v[60:63]
	v_mfma_f32_16x16x32_bf16 v[56:59], v[184:187], v[192:195], v[56:59]
	v_mfma_f32_16x16x32_bf16 v[52:55], v[176:179], v[200:203], v[52:55]
	v_mfma_f32_16x16x32_bf16 v[48:51], v[184:187], v[200:203], v[48:51]
	v_mfma_f32_16x16x32_bf16 v[44:47], v[176:179], v[208:211], v[44:47]
	v_mfma_f32_16x16x32_bf16 v[40:43], v[184:187], v[208:211], v[40:43]
	v_mfma_f32_16x16x32_bf16 v[36:39], v[176:179], v[232:235], v[36:39]
	v_mfma_f32_16x16x32_bf16 v[32:35], v[184:187], v[232:235], v[32:35]
	s_barrier
; #define STAGE(P, BASE, LD, br, kt) do { const char* _g = (const char*)((BASE) + (size_t)(br) * (LD) + (size_t)(kt) * 64); \
;     for (int _i = 0; _i < 2; ++_i) { int _b = tidx * 16 + _i * 8192; int _r, _c; stage_rc(_b, _r, _c); \
;       __builtin_amdgcn_global_load_lds((const unsigned*)(_g + (unsigned)((_r * (LD) + _c) * 2)), (unsigned*)((char*)(P) + _b), 16, 0, 0); } } while (0)
; #define LDA(dst, b, h) for (int m = 0; m < 4; ++m) for (int k = 0; k < 2; ++k) \
;     dst[m][k] = *reinterpret_cast<const bf16x8*>((char*)SA(b, h) + lds_byte(wr * 64 + m * 16 + fr, k * 32 + fq * 8))
; #define LDB(dst, b, h) for (int n = 0; n < 2; ++n) for (int k = 0; k < 2; ++k) \
;     dst[n][k] = *reinterpret_cast<const bf16x8*>((char*)SB(b, h) + lds_byte(wc * 32 + n * 16 + fr, k * 32 + fq * 8))
; #define MMA(ai, bj, At_, Bt_) do { __builtin_amdgcn_s_setprio(1); \
;     for (int k = 0; k < 2; ++k) for (int m = 0; m < 4; ++m) for (int n = 0; n < 2; ++n) \
;       acc[ai][bj][m][n] = __builtin_amdgcn_mfma_f32_16x16x32_bf16(At_[m][k], Bt_[n][k], acc[ai][bj][m][n], 0, 0, 0); \
;     __builtin_amdgcn_s_setprio(0); } while (0)
; #define WAIT_V(n) asm volatile("s_waitcnt vmcnt(" #n ")" ::: "memory")
; #define WAIT_L(n) asm volatile("s_waitcnt lgkmcnt(" #n ")" ::: "memory")
; #define BAR __builtin_amdgcn_s_barrier()
; #define SCHED __builtin_amdgcn_sched_barrier(0)
; template <int EPI, int lda, int ldb, int N, int K>
; __device__ __forceinline__ void gemm_phase(const u16* __restrict__ A, const u16* __restrict__ Bt, const GemmEpi ep, int wv) {
;     ...
;       STAGE(SB(0, 1), Bt, ldb, bcol + HALF, t + 2);
;       WAIT_V(6); BAR; MMA(1, 1, At, B1); BAR;
;       LDB(B0, 1, 0); SCHED; LDA(At, 1, 0); STAGE(SA(0, 1), Ab, lda, brow + HALF, t + 2);
;       WAIT_L(8); BAR; WAIT_L(0); MMA(0, 0, At, B0); BAR; SCHED;
;       LDB(B1, 1, 1); STAGE(SB(1, 0), Bt, ldb, bcol, t + 3);
;       BAR; WAIT_L(0); MMA(0, 1, At, B1); BAR;
;       LDA(At, 1, 1); STAGE(SA(1, 0), Ab, lda, brow, t + 3);
	v_add_u32_e32 v165, s65, v153
	v_lshl_add_u64 v[166:167], v[240:241], 0, s[24:25]
	v_readfirstlane_b32 s53, v165
	s_mov_b32 m0, s53
	v_lshl_add_u64 v[172:173], v[242:243], 0, s[24:25]
	global_load_lds_dwordx4 v[166:167], off
	v_add_u32_e32 v166, 0x2000, v165
	s_nop 0
	v_readfirstlane_b32 s53, v166
	s_mov_b32 m0, s53
	s_nop 0
	global_load_lds_dwordx4 v[172:173], off
	s_waitcnt vmcnt(6)
	s_barrier
	v_mfma_f32_16x16x32_bf16 v[28:31], v[216:219], v[188:191], v[28:31]
	v_mfma_f32_16x16x32_bf16 v[24:27], v[224:227], v[188:191], v[24:27]
	v_mfma_f32_16x16x32_bf16 v[20:23], v[216:219], v[196:199], v[20:23]
	v_mfma_f32_16x16x32_bf16 v[16:19], v[224:227], v[196:199], v[16:19]
	v_mfma_f32_16x16x32_bf16 v[12:15], v[216:219], v[204:207], v[12:15]
	v_mfma_f32_16x16x32_bf16 v[8:11], v[224:227], v[204:207], v[8:11]
	v_mfma_f32_16x16x32_bf16 v[4:7], v[216:219], v[212:215], v[4:7]
	v_mfma_f32_16x16x32_bf16 v[0:3], v[224:227], v[212:215], v[0:3]
	v_mfma_f32_16x16x32_bf16 v[28:31], v[220:223], v[192:195], v[28:31]
	v_mfma_f32_16x16x32_bf16 v[24:27], v[228:231], v[192:195], v[24:27]
	v_mfma_f32_16x16x32_bf16 v[20:23], v[220:223], v[200:203], v[20:23]
	v_mfma_f32_16x16x32_bf16 v[16:19], v[228:231], v[200:203], v[16:19]
	v_mfma_f32_16x16x32_bf16 v[12:15], v[220:223], v[208:211], v[12:15]
	v_mfma_f32_16x16x32_bf16 v[8:11], v[228:231], v[208:211], v[8:11]
	v_mfma_f32_16x16x32_bf16 v[4:7], v[220:223], v[232:235], v[4:7]
	v_mfma_f32_16x16x32_bf16 v[0:3], v[228:231], v[232:235], v[0:3]
	s_barrier
	ds_read_b128 v[172:175], v156
	ds_read_b128 v[176:179], v156 offset:1024
	ds_read_b128 v[180:183], v156 offset:2048
	ds_read_b128 v[184:187], v156 offset:3072
	v_add_u32_e32 v167, 0x4000, v148
	v_add_u32_e32 v168, 0x6000, v148
	v_readfirstlane_b32 s53, v167
	v_lshl_add_u64 v[220:221], v[236:237], 0, s[26:27]
	s_mov_b32 m0, s53
	v_readfirstlane_b32 s53, v168
	ds_read_b128 v[188:191], v152 offset:32768
	ds_read_b128 v[192:195], v152 offset:33792
	ds_read_b128 v[196:199], v151 offset:32768
	ds_read_b128 v[200:203], v151 offset:33792
	ds_read_b128 v[204:207], v150 offset:32768
	ds_read_b128 v[208:211], v150 offset:33792
	ds_read_b128 v[212:215], v149 offset:32768
	ds_read_b128 v[216:219], v149 offset:33792
	global_load_lds_dwordx4 v[220:221], off
	s_waitcnt lgkmcnt(8)
	s_barrier
	s_waitcnt lgkmcnt(0)
	s_waitcnt lgkmcnt(0)
	v_mfma_f32_16x16x32_bf16 v[124:127], v[172:175], v[188:191], v[124:127]
	v_mfma_f32_16x16x32_bf16 v[120:123], v[180:183], v[188:191], v[120:123]
	v_mfma_f32_16x16x32_bf16 v[116:119], v[172:175], v[196:199], v[116:119]
	v_mfma_f32_16x16x32_bf16 v[112:115], v[180:183], v[196:199], v[112:115]
	v_mfma_f32_16x16x32_bf16 v[108:111], v[172:175], v[204:207], v[108:111]
	v_mfma_f32_16x16x32_bf16 v[104:107], v[180:183], v[204:207], v[104:107]
	v_mfma_f32_16x16x32_bf16 v[100:103], v[172:175], v[212:215], v[100:103]
	v_mfma_f32_16x16x32_bf16 v[96:99], v[180:183], v[212:215], v[96:99]
	v_lshl_add_u64 v[220:221], v[238:239], 0, s[26:27]
	s_mov_b32 m0, s53
	s_nop 0
	global_load_lds_dwordx4 v[220:221], off
	v_mfma_f32_16x16x32_bf16 v[124:127], v[176:179], v[192:195], v[124:127]
	v_mfma_f32_16x16x32_bf16 v[120:123], v[184:187], v[192:195], v[120:123]
	v_mfma_f32_16x16x32_bf16 v[116:119], v[176:179], v[200:203], v[116:119]
	v_mfma_f32_16x16x32_bf16 v[112:115], v[184:187], v[200:203], v[112:115]
	v_mfma_f32_16x16x32_bf16 v[108:111], v[176:179], v[208:211], v[108:111]
	v_mfma_f32_16x16x32_bf16 v[104:107], v[184:187], v[208:211], v[104:107]
	v_mfma_f32_16x16x32_bf16 v[100:103], v[176:179], v[216:219], v[100:103]
	v_mfma_f32_16x16x32_bf16 v[96:99], v[184:187], v[216:219], v[96:99]
	s_barrier
	v_readfirstlane_b32 s53, v155
	v_add_u32_e32 v171, 0x2000, v155
	v_lshl_add_u64 v[244:245], v[240:241], 0, s[40:41]
	s_mov_b32 m0, s53
	v_readfirstlane_b32 s53, v171
	ds_read_b128 v[220:223], v154
	ds_read_b128 v[224:227], v154 offset:1024
	ds_read_b128 v[228:231], v154 offset:2048
	ds_read_b128 v[232:235], v154 offset:3072
	global_load_lds_dwordx4 v[244:245], off
	v_lshl_add_u64 v[244:245], v[242:243], 0, s[40:41]
	s_mov_b32 m0, s53
	s_nop 0
	global_load_lds_dwordx4 v[244:245], off
	s_barrier
	s_waitcnt lgkmcnt(0)
	s_waitcnt lgkmcnt(0)
	v_mfma_f32_16x16x32_bf16 v[92:95], v[220:223], v[188:191], v[92:95]
	v_mfma_f32_16x16x32_bf16 v[88:91], v[228:231], v[188:191], v[88:91]
	v_mfma_f32_16x16x32_bf16 v[84:87], v[220:223], v[196:199], v[84:87]
	v_mfma_f32_16x16x32_bf16 v[80:83], v[228:231], v[196:199], v[80:83]
	v_mfma_f32_16x16x32_bf16 v[76:79], v[220:223], v[204:207], v[76:79]
	v_mfma_f32_16x16x32_bf16 v[72:75], v[228:231], v[204:207], v[72:75]
	v_mfma_f32_16x16x32_bf16 v[68:71], v[220:223], v[212:215], v[68:71]
	v_mfma_f32_16x16x32_bf16 v[64:67], v[228:231], v[212:215], v[64:67]
	v_mfma_f32_16x16x32_bf16 v[92:95], v[224:227], v[192:195], v[92:95]
	v_mfma_f32_16x16x32_bf16 v[88:91], v[232:235], v[192:195], v[88:91]
	v_mfma_f32_16x16x32_bf16 v[84:87], v[224:227], v[200:203], v[84:87]
	v_mfma_f32_16x16x32_bf16 v[80:83], v[232:235], v[200:203], v[80:83]
	v_mfma_f32_16x16x32_bf16 v[76:79], v[224:227], v[208:211], v[76:79]
	v_mfma_f32_16x16x32_bf16 v[72:75], v[232:235], v[208:211], v[72:75]
	v_mfma_f32_16x16x32_bf16 v[68:71], v[224:227], v[216:219], v[68:71]
	v_mfma_f32_16x16x32_bf16 v[64:67], v[232:235], v[216:219], v[64:67]
	s_barrier
	v_readfirstlane_b32 s53, v157
	v_lshl_add_u64 v[236:237], v[236:237], 0, s[42:43]
	s_mov_b32 m0, s53
	v_readfirstlane_b32 s53, v158
	ds_read_b128 v[188:191], v152 offset:49152
	ds_read_b128 v[192:195], v152 offset:50176
	ds_read_b128 v[196:199], v151 offset:49152
	ds_read_b128 v[200:203], v151 offset:50176
	ds_read_b128 v[204:207], v150 offset:49152
	ds_read_b128 v[208:211], v150 offset:50176
	ds_read_b128 v[212:215], v149 offset:49152
	ds_read_b128 v[216:219], v149 offset:50176
	global_load_lds_dwordx4 v[236:237], off
	v_lshl_add_u64 v[236:237], v[238:239], 0, s[42:43]
	s_mov_b32 m0, s53
	s_nop 0
	global_load_lds_dwordx4 v[236:237], off
	s_barrier
; #define STAGE(P, BASE, LD, br, kt) do { const char* _g = (const char*)((BASE) + (size_t)(br) * (LD) + (size_t)(kt) * 64); \
;     for (int _i = 0; _i < 2; ++_i) { int _b = tidx * 16 + _i * 8192; int _r, _c; stage_rc(_b, _r, _c); \
;       __builtin_amdgcn_global_load_lds((const unsigned*)(_g + (unsigned)((_r * (LD) + _c) * 2)), (unsigned*)((char*)(P) + _b), 16, 0, 0); } } while (0)
; #define LDA(dst, b, h) for (int m = 0; m < 4; ++m) for (int k = 0; k < 2; ++k) \
;     dst[m][k] = *reinterpret_cast<const bf16x8*>((char*)SA(b, h) + lds_byte(wr * 64 + m * 16 + fr, k * 32 + fq * 8))
; #define LDB(dst, b, h) for (int n = 0; n < 2; ++n) for (int k = 0; k < 2; ++k) \
;     dst[n][k] = *reinterpret_cast<const bf16x8*>((char*)SB(b, h) + lds_byte(wc * 32 + n * 16 + fr, k * 32 + fq * 8))
; #define MMA(ai, bj, At_, Bt_) do { __builtin_amdgcn_s_setprio(1); \
;     for (int k = 0; k < 2; ++k) for (int m = 0; m < 4; ++m) for (int n = 0; n < 2; ++n) \
;       acc[ai][bj][m][n] = __builtin_amdgcn_mfma_f32_16x16x32_bf16(At_[m][k], Bt_[n][k], acc[ai][bj][m][n], 0, 0, 0); \
;     __builtin_amdgcn_s_setprio(0); } while (0)
; #define WAIT_V(n) asm volatile("s_waitcnt vmcnt(" #n ")" ::: "memory")
; #define WAIT_L(n) asm volatile("s_waitcnt lgkmcnt(" #n ")" ::: "memory")
; #define BAR __builtin_amdgcn_s_barrier()
; #define SCHED __builtin_amdgcn_sched_barrier(0)
; template <int EPI, int lda, int ldb, int N, int K>
; __device__ __forceinline__ void gemm_phase(const u16* __restrict__ A, const u16* __restrict__ Bt, const GemmEpi ep, int wv) {
;     ...
;       BAR; WAIT_L(0); MMA(1, 0, At, B0); BAR; SCHED;
;       STAGE(SB(1, 1), Bt, ldb, bcol + HALF, t + 3);
;       WAIT_V(6); BAR; MMA(1, 1, At, B1); BAR;
;     }
;     { LDB(B0, 0, 0); LDA(At, 0, 0); STAGE(SA(1, 1), Ab, lda, brow + HALF, nt - 1);
;       BAR; WAIT_L(0); MMA(0, 0, At, B0); BAR;
;       LDB(B1, 0, 1); BAR; WAIT_L(0); MMA(0, 1, At, B1); BAR;
	s_waitcnt lgkmcnt(0)
	s_waitcnt lgkmcnt(0)
	v_mfma_f32_16x16x32_bf16 v[60:63], v[172:175], v[188:191], v[60:63]
	v_mfma_f32_16x16x32_bf16 v[56:59], v[180:183], v[188:191], v[56:59]
	v_mfma_f32_16x16x32_bf16 v[52:55], v[172:175], v[196:199], v[52:55]
	v_mfma_f32_16x16x32_bf16 v[48:51], v[180:183], v[196:199], v[48:51]
	v_mfma_f32_16x16x32_bf16 v[44:47], v[172:175], v[204:207], v[44:47]
	v_mfma_f32_16x16x32_bf16 v[40:43], v[180:183], v[204:207], v[40:43]
	v_mfma_f32_16x16x32_bf16 v[36:39], v[172:175], v[212:215], v[36:39]
	v_mfma_f32_16x16x32_bf16 v[32:35], v[180:183], v[212:215], v[32:35]
	v_mfma_f32_16x16x32_bf16 v[60:63], v[176:179], v[192:195], v[60:63]
	v_mfma_f32_16x16x32_bf16 v[56:59], v[184:187], v[192:195], v[56:59]
	v_mfma_f32_16x16x32_bf16 v[52:55], v[176:179], v[200:203], v[52:55]
	v_mfma_f32_16x16x32_bf16 v[48:51], v[184:187], v[200:203], v[48:51]
	v_mfma_f32_16x16x32_bf16 v[44:47], v[176:179], v[208:211], v[44:47]
	v_mfma_f32_16x16x32_bf16 v[40:43], v[184:187], v[208:211], v[40:43]
	v_mfma_f32_16x16x32_bf16 v[36:39], v[176:179], v[216:219], v[36:39]
	v_mfma_f32_16x16x32_bf16 v[32:35], v[184:187], v[216:219], v[32:35]
	s_barrier
	v_readfirstlane_b32 s53, v159
	v_add_u32_e32 v171, 0x2000, v159
	v_lshl_add_u64 v[172:173], v[240:241], 0, s[44:45]
	s_mov_b32 m0, s53
	v_readfirstlane_b32 s53, v171
	global_load_lds_dwordx4 v[172:173], off
	v_lshl_add_u64 v[172:173], v[242:243], 0, s[44:45]
	s_mov_b32 m0, s53
	s_nop 0
	global_load_lds_dwordx4 v[172:173], off
	s_waitcnt vmcnt(6)
	s_barrier
	v_mfma_f32_16x16x32_bf16 v[28:31], v[220:223], v[188:191], v[28:31]
	v_mfma_f32_16x16x32_bf16 v[24:27], v[228:231], v[188:191], v[24:27]
	v_mfma_f32_16x16x32_bf16 v[20:23], v[220:223], v[196:199], v[20:23]
	v_mfma_f32_16x16x32_bf16 v[16:19], v[228:231], v[196:199], v[16:19]
	v_mfma_f32_16x16x32_bf16 v[12:15], v[220:223], v[204:207], v[12:15]
	v_mfma_f32_16x16x32_bf16 v[8:11], v[228:231], v[204:207], v[8:11]
	v_mfma_f32_16x16x32_bf16 v[4:7], v[220:223], v[212:215], v[4:7]
	v_mfma_f32_16x16x32_bf16 v[0:3], v[228:231], v[212:215], v[0:3]
	v_mfma_f32_16x16x32_bf16 v[28:31], v[224:227], v[192:195], v[28:31]
	v_mfma_f32_16x16x32_bf16 v[24:27], v[232:235], v[192:195], v[24:27]
	v_mfma_f32_16x16x32_bf16 v[20:23], v[224:227], v[200:203], v[20:23]
	v_mfma_f32_16x16x32_bf16 v[16:19], v[232:235], v[200:203], v[16:19]
	v_mfma_f32_16x16x32_bf16 v[12:15], v[224:227], v[208:211], v[12:15]
	v_mfma_f32_16x16x32_bf16 v[8:11], v[232:235], v[208:211], v[8:11]
	v_mfma_f32_16x16x32_bf16 v[4:7], v[224:227], v[216:219], v[4:7]
	v_mfma_f32_16x16x32_bf16 v[0:3], v[232:235], v[216:219], v[0:3]
	s_add_i32 s52, s52, 2
	s_add_u32 s50, s50, 0x100
	s_addc_u32 s51, s51, 0
	s_cmp_gt_u32 s52, 27
	s_barrier
	s_cbranch_scc0 .LBB0_770
	s_add_i32 s50, s48, 0x80
	s_mul_hi_i32 s51, s50, 0x1080
	s_mulk_i32 s50, 0x1080
	s_add_u32 s50, s61, s50
	s_addc_u32 s51, s62, s51
	v_lshl_add_u64 v[158:159], s[50:51], 0, v[128:129]
	v_readfirstlane_b32 s52, v169
	v_lshl_add_u64 v[158:159], v[158:159], 0, s[46:47]
	s_mov_b32 m0, s52
	ds_read_b128 v[134:137], v161
	ds_read_b128 v[138:141], v161 offset:1024
	ds_read_b128 v[172:175], v161 offset:2048
	ds_read_b128 v[176:179], v161 offset:3072
	ds_read_b128 v[180:183], v152
	ds_read_b128 v[184:187], v152 offset:1024
	ds_read_b128 v[188:191], v151
	ds_read_b128 v[192:195], v151 offset:1024
	ds_read_b128 v[196:199], v150
	ds_read_b128 v[200:203], v150 offset:1024
	ds_read_b128 v[204:207], v149
	ds_read_b128 v[208:211], v149 offset:1024
	global_load_lds_dwordx4 v[158:159], off
	v_lshl_add_u64 v[158:159], s[50:51], 0, v[132:133]
	v_readfirstlane_b32 s50, v170
	v_lshl_add_u64 v[158:159], v[158:159], 0, s[46:47]
	s_mov_b32 m0, s50
	s_nop 0
	global_load_lds_dwordx4 v[158:159], off
	s_barrier
	s_waitcnt lgkmcnt(0)
	s_waitcnt lgkmcnt(0)
	v_mfma_f32_16x16x32_bf16 v[124:127], v[134:137], v[180:183], v[124:127]
	v_mfma_f32_16x16x32_bf16 v[120:123], v[172:175], v[180:183], v[120:123]
	v_mfma_f32_16x16x32_bf16 v[116:119], v[134:137], v[188:191], v[116:119]
	v_mfma_f32_16x16x32_bf16 v[112:115], v[172:175], v[188:191], v[112:115]
	v_mfma_f32_16x16x32_bf16 v[108:111], v[134:137], v[196:199], v[108:111]
	v_mfma_f32_16x16x32_bf16 v[104:107], v[172:175], v[196:199], v[104:107]
	v_mfma_f32_16x16x32_bf16 v[100:103], v[134:137], v[204:207], v[100:103]
	v_mfma_f32_16x16x32_bf16 v[96:99], v[172:175], v[204:207], v[96:99]
	v_mfma_f32_16x16x32_bf16 v[124:127], v[138:141], v[184:187], v[124:127]
	v_mfma_f32_16x16x32_bf16 v[120:123], v[176:179], v[184:187], v[120:123]
	v_mfma_f32_16x16x32_bf16 v[116:119], v[138:141], v[192:195], v[116:119]
	v_mfma_f32_16x16x32_bf16 v[112:115], v[176:179], v[192:195], v[112:115]
	v_mfma_f32_16x16x32_bf16 v[108:111], v[138:141], v[200:203], v[108:111]
	v_mfma_f32_16x16x32_bf16 v[104:107], v[176:179], v[200:203], v[104:107]
	v_mfma_f32_16x16x32_bf16 v[100:103], v[138:141], v[208:211], v[100:103]
	v_mfma_f32_16x16x32_bf16 v[96:99], v[176:179], v[208:211], v[96:99]
	s_barrier
	ds_read_b128 v[212:215], v160
	ds_read_b128 v[216:219], v160 offset:1024
	ds_read_b128 v[220:223], v160 offset:2048
	ds_read_b128 v[158:161], v160 offset:3072
	s_barrier
; #define LDA(dst, b, h) for (int m = 0; m < 4; ++m) for (int k = 0; k < 2; ++k) \
;     dst[m][k] = *reinterpret_cast<const bf16x8*>((char*)SA(b, h) + lds_byte(wr * 64 + m * 16 + fr, k * 32 + fq * 8))
; #define LDB(dst, b, h) for (int n = 0; n < 2; ++n) for (int k = 0; k < 2; ++k) \
;     dst[n][k] = *reinterpret_cast<const bf16x8*>((char*)SB(b, h) + lds_byte(wc * 32 + n * 16 + fr, k * 32 + fq * 8))
; #define MMA(ai, bj, At_, Bt_) do { __builtin_amdgcn_s_setprio(1); \
;     for (int k = 0; k < 2; ++k) for (int m = 0; m < 4; ++m) for (int n = 0; n < 2; ++n) \
;       acc[ai][bj][m][n] = __builtin_amdgcn_mfma_f32_16x16x32_bf16(At_[m][k], Bt_[n][k], acc[ai][bj][m][n], 0, 0, 0); \
;     __builtin_amdgcn_s_setprio(0); } while (0)
; #define WAIT_V(n) asm volatile("s_waitcnt vmcnt(" #n ")" ::: "memory")
; #define WAIT_L(n) asm volatile("s_waitcnt lgkmcnt(" #n ")" ::: "memory")
; #define BAR __builtin_amdgcn_s_barrier()
; template <int EPI, int lda, int ldb, int N, int K>
; __device__ __forceinline__ void gemm_phase(const u16* __restrict__ A, const u16* __restrict__ Bt, const GemmEpi ep, int wv) {
;     ...
;       LDB(B1, 0, 1); BAR; WAIT_L(0); MMA(0, 1, At, B1); BAR;
;       LDA(At, 0, 1); WAIT_V(4); BAR; WAIT_L(0); MMA(1, 0, At, B0); MMA(1, 1, At, B1); BAR; }
;     { LDB(B0, 1, 0); LDA(At, 1, 0); WAIT_V(2); BAR; WAIT_L(0); MMA(0, 0, At, B0); BAR;
	s_waitcnt lgkmcnt(0)
	s_waitcnt lgkmcnt(0)
	v_mfma_f32_16x16x32_bf16 v[92:95], v[212:215], v[180:183], v[92:95]
	v_mfma_f32_16x16x32_bf16 v[88:91], v[220:223], v[180:183], v[88:91]
	v_mfma_f32_16x16x32_bf16 v[76:79], v[212:215], v[196:199], v[76:79]
	v_mfma_f32_16x16x32_bf16 v[72:75], v[220:223], v[196:199], v[72:75]
	v_mfma_f32_16x16x32_bf16 v[84:87], v[212:215], v[188:191], v[84:87]
	v_mfma_f32_16x16x32_bf16 v[80:83], v[220:223], v[188:191], v[80:83]
	v_mfma_f32_16x16x32_bf16 v[68:71], v[212:215], v[204:207], v[68:71]
	v_mfma_f32_16x16x32_bf16 v[64:67], v[220:223], v[204:207], v[64:67]
	v_mfma_f32_16x16x32_bf16 v[92:95], v[216:219], v[184:187], v[92:95]
	v_mfma_f32_16x16x32_bf16 v[88:91], v[158:161], v[184:187], v[88:91]
	v_mfma_f32_16x16x32_bf16 v[76:79], v[216:219], v[200:203], v[76:79]
	v_mfma_f32_16x16x32_bf16 v[72:75], v[158:161], v[200:203], v[72:75]
	v_mfma_f32_16x16x32_bf16 v[180:183], v[216:219], v[192:195], v[84:87]
	v_mfma_f32_16x16x32_bf16 v[184:187], v[158:161], v[192:195], v[80:83]
	v_mfma_f32_16x16x32_bf16 v[188:191], v[216:219], v[208:211], v[68:71]
	v_mfma_f32_16x16x32_bf16 v[192:195], v[158:161], v[208:211], v[64:67]
	s_barrier
	s_nop 0
	ds_read_b128 v[64:67], v152 offset:16384
	ds_read_b128 v[68:71], v152 offset:17408
	ds_read_b128 v[80:83], v151 offset:16384
	ds_read_b128 v[84:87], v151 offset:17408
	ds_read_b128 v[196:199], v150 offset:16384
	ds_read_b128 v[200:203], v150 offset:17408
	ds_read_b128 v[204:207], v149 offset:16384
	ds_read_b128 v[208:211], v149 offset:17408
	s_waitcnt vmcnt(4)
	s_barrier
	s_waitcnt lgkmcnt(0)
	s_waitcnt lgkmcnt(0)
	v_mfma_f32_16x16x32_bf16 v[60:63], v[134:137], v[64:67], v[60:63]
	v_mfma_f32_16x16x32_bf16 v[56:59], v[172:175], v[64:67], v[56:59]
	v_mfma_f32_16x16x32_bf16 v[52:55], v[134:137], v[80:83], v[52:55]
	v_mfma_f32_16x16x32_bf16 v[48:51], v[172:175], v[80:83], v[48:51]
	v_mfma_f32_16x16x32_bf16 v[44:47], v[134:137], v[196:199], v[44:47]
	v_mfma_f32_16x16x32_bf16 v[40:43], v[172:175], v[196:199], v[40:43]
	v_mfma_f32_16x16x32_bf16 v[36:39], v[134:137], v[204:207], v[36:39]
	v_mfma_f32_16x16x32_bf16 v[32:35], v[172:175], v[204:207], v[32:35]
	v_mfma_f32_16x16x32_bf16 v[60:63], v[138:141], v[68:71], v[60:63]
	v_mfma_f32_16x16x32_bf16 v[56:59], v[176:179], v[68:71], v[56:59]
	v_mfma_f32_16x16x32_bf16 v[52:55], v[138:141], v[84:87], v[52:55]
	v_mfma_f32_16x16x32_bf16 v[48:51], v[176:179], v[84:87], v[48:51]
	v_mfma_f32_16x16x32_bf16 v[44:47], v[138:141], v[200:203], v[44:47]
	v_mfma_f32_16x16x32_bf16 v[40:43], v[176:179], v[200:203], v[40:43]
	v_mfma_f32_16x16x32_bf16 v[36:39], v[138:141], v[208:211], v[36:39]
	v_mfma_f32_16x16x32_bf16 v[32:35], v[176:179], v[208:211], v[32:35]
	v_mfma_f32_16x16x32_bf16 v[28:31], v[212:215], v[64:67], v[28:31]
	v_mfma_f32_16x16x32_bf16 v[24:27], v[220:223], v[64:67], v[24:27]
	v_mfma_f32_16x16x32_bf16 v[12:15], v[212:215], v[196:199], v[12:15]
	v_mfma_f32_16x16x32_bf16 v[8:11], v[220:223], v[196:199], v[8:11]
	v_mfma_f32_16x16x32_bf16 v[20:23], v[212:215], v[80:83], v[20:23]
	v_mfma_f32_16x16x32_bf16 v[16:19], v[220:223], v[80:83], v[16:19]
	v_mfma_f32_16x16x32_bf16 v[4:7], v[212:215], v[204:207], v[4:7]
	v_mfma_f32_16x16x32_bf16 v[0:3], v[220:223], v[204:207], v[0:3]
	v_mfma_f32_16x16x32_bf16 v[28:31], v[216:219], v[68:71], v[28:31]
	v_mfma_f32_16x16x32_bf16 v[24:27], v[158:161], v[68:71], v[24:27]
	v_mfma_f32_16x16x32_bf16 v[12:15], v[216:219], v[200:203], v[12:15]
	v_mfma_f32_16x16x32_bf16 v[8:11], v[158:161], v[200:203], v[8:11]
	v_mfma_f32_16x16x32_bf16 v[134:137], v[216:219], v[84:87], v[20:23]
	v_mfma_f32_16x16x32_bf16 v[138:141], v[158:161], v[84:87], v[16:19]
	v_mfma_f32_16x16x32_bf16 v[170:173], v[216:219], v[208:211], v[4:7]
	v_mfma_f32_16x16x32_bf16 v[158:161], v[158:161], v[208:211], v[0:3]
	s_barrier
	s_nop 0
	ds_read_b128 v[0:3], v156
	ds_read_b128 v[4:7], v156 offset:1024
	ds_read_b128 v[16:19], v156 offset:2048
	ds_read_b128 v[174:177], v156 offset:3072
	ds_read_b128 v[20:23], v152 offset:32768
	ds_read_b128 v[196:199], v152 offset:33792
	ds_read_b128 v[200:203], v151 offset:32768
	ds_read_b128 v[204:207], v151 offset:33792
	ds_read_b128 v[208:211], v150 offset:32768
	ds_read_b128 v[212:215], v150 offset:33792
	ds_read_b128 v[216:219], v149 offset:32768
	ds_read_b128 v[220:223], v149 offset:33792
	s_waitcnt vmcnt(2)
	s_barrier
; #define LDA(dst, b, h) for (int m = 0; m < 4; ++m) for (int k = 0; k < 2; ++k) \
;     dst[m][k] = *reinterpret_cast<const bf16x8*>((char*)SA(b, h) + lds_byte(wr * 64 + m * 16 + fr, k * 32 + fq * 8))
; #define LDB(dst, b, h) for (int n = 0; n < 2; ++n) for (int k = 0; k < 2; ++k) \
;     dst[n][k] = *reinterpret_cast<const bf16x8*>((char*)SB(b, h) + lds_byte(wc * 32 + n * 16 + fr, k * 32 + fq * 8))
; #define MMA(ai, bj, At_, Bt_) do { __builtin_amdgcn_s_setprio(1); \
;     for (int k = 0; k < 2; ++k) for (int m = 0; m < 4; ++m) for (int n = 0; n < 2; ++n) \
;       acc[ai][bj][m][n] = __builtin_amdgcn_mfma_f32_16x16x32_bf16(At_[m][k], Bt_[n][k], acc[ai][bj][m][n], 0, 0, 0); \
;     __builtin_amdgcn_s_setprio(0); } while (0)
; #define WAIT_V(n) asm volatile("s_waitcnt vmcnt(" #n ")" ::: "memory")
; #define WAIT_L(n) asm volatile("s_waitcnt lgkmcnt(" #n ")" ::: "memory")
; #define BAR __builtin_amdgcn_s_barrier()
; template <int EPI, int lda, int ldb, int N, int K>
; __device__ __forceinline__ void gemm_phase(const u16* __restrict__ A, const u16* __restrict__ Bt, const GemmEpi ep, int wv) {
;     ...
;     { LDB(B0, 1, 0); LDA(At, 1, 0); WAIT_V(2); BAR; WAIT_L(0); MMA(0, 0, At, B0); BAR;
;       LDB(B1, 1, 1); WAIT_V(0); BAR; WAIT_L(0); MMA(0, 1, At, B1); BAR;
;       LDA(At, 1, 1); BAR; WAIT_L(0); MMA(1, 0, At, B0); MMA(1, 1, At, B1); BAR; }
;     if (wr == 0) BAR;
	s_waitcnt lgkmcnt(0)
	s_waitcnt lgkmcnt(0)
	v_mfma_f32_16x16x32_bf16 v[64:67], v[0:3], v[20:23], v[124:127]
	v_mfma_f32_16x16x32_bf16 v[68:71], v[16:19], v[20:23], v[120:123]
	v_mfma_f32_16x16x32_bf16 v[80:83], v[0:3], v[200:203], v[116:119]
	v_mfma_f32_16x16x32_bf16 v[84:87], v[16:19], v[200:203], v[112:115]
	v_mfma_f32_16x16x32_bf16 v[108:111], v[0:3], v[208:211], v[108:111]
	v_mfma_f32_16x16x32_bf16 v[104:107], v[16:19], v[208:211], v[104:107]
	v_mfma_f32_16x16x32_bf16 v[120:123], v[0:3], v[216:219], v[100:103]
	v_mfma_f32_16x16x32_bf16 v[124:127], v[16:19], v[216:219], v[96:99]
	v_mfma_f32_16x16x32_bf16 v[116:119], v[4:7], v[196:199], v[64:67]
	v_mfma_f32_16x16x32_bf16 v[112:115], v[174:177], v[196:199], v[68:71]
	v_mfma_f32_16x16x32_bf16 v[100:103], v[4:7], v[204:207], v[80:83]
	v_mfma_f32_16x16x32_bf16 v[96:99], v[174:177], v[204:207], v[84:87]
	v_mfma_f32_16x16x32_bf16 v[84:87], v[4:7], v[212:215], v[108:111]
	v_mfma_f32_16x16x32_bf16 v[80:83], v[174:177], v[212:215], v[104:107]
	v_mfma_f32_16x16x32_bf16 v[68:71], v[4:7], v[220:223], v[120:123]
	v_mfma_f32_16x16x32_bf16 v[64:67], v[174:177], v[220:223], v[124:127]
	s_barrier
	ds_read_b128 v[224:227], v154
	ds_read_b128 v[228:231], v154 offset:1024
	ds_read_b128 v[232:235], v154 offset:2048
	ds_read_b128 v[154:157], v154 offset:3072
	s_waitcnt vmcnt(0)
	s_barrier
	s_waitcnt lgkmcnt(0)
	s_waitcnt lgkmcnt(0)
	v_mfma_f32_16x16x32_bf16 v[92:95], v[224:227], v[20:23], v[92:95]
	v_mfma_f32_16x16x32_bf16 v[20:23], v[232:235], v[20:23], v[88:91]
	v_mfma_f32_16x16x32_bf16 v[88:91], v[224:227], v[200:203], v[180:183]
	v_mfma_f32_16x16x32_bf16 v[104:107], v[232:235], v[200:203], v[184:187]
	v_mfma_f32_16x16x32_bf16 v[76:79], v[224:227], v[208:211], v[76:79]
	v_mfma_f32_16x16x32_bf16 v[72:75], v[232:235], v[208:211], v[72:75]
	v_mfma_f32_16x16x32_bf16 v[178:181], v[224:227], v[216:219], v[188:191]
	v_mfma_f32_16x16x32_bf16 v[182:185], v[232:235], v[216:219], v[192:195]
	v_mfma_f32_16x16x32_bf16 v[124:127], v[228:231], v[196:199], v[92:95]
	v_mfma_f32_16x16x32_bf16 v[120:123], v[154:157], v[196:199], v[20:23]
	v_mfma_f32_16x16x32_bf16 v[108:111], v[228:231], v[204:207], v[88:91]
	v_mfma_f32_16x16x32_bf16 v[104:107], v[154:157], v[204:207], v[104:107]
	v_mfma_f32_16x16x32_bf16 v[92:95], v[228:231], v[212:215], v[76:79]
	v_mfma_f32_16x16x32_bf16 v[88:91], v[154:157], v[212:215], v[72:75]
	v_mfma_f32_16x16x32_bf16 v[76:79], v[228:231], v[220:223], v[178:181]
	v_mfma_f32_16x16x32_bf16 v[72:75], v[154:157], v[220:223], v[182:185]
	s_barrier
	ds_read_b128 v[178:181], v152 offset:49152
	ds_read_b128 v[182:185], v152 offset:50176
	ds_read_b128 v[186:189], v151 offset:49152
	ds_read_b128 v[190:193], v151 offset:50176
	ds_read_b128 v[194:197], v150 offset:49152
	ds_read_b128 v[150:153], v150 offset:50176
	ds_read_b128 v[198:201], v149 offset:49152
	ds_read_b128 v[202:205], v149 offset:50176
	s_barrier
	s_waitcnt lgkmcnt(0)
	s_waitcnt lgkmcnt(0)
	v_mfma_f32_16x16x32_bf16 v[20:23], v[0:3], v[178:181], v[60:63]
	v_mfma_f32_16x16x32_bf16 v[56:59], v[16:19], v[178:181], v[56:59]
	v_mfma_f32_16x16x32_bf16 v[60:63], v[0:3], v[186:189], v[52:55]
	v_mfma_f32_16x16x32_bf16 v[206:209], v[16:19], v[186:189], v[48:51]
	v_mfma_f32_16x16x32_bf16 v[44:47], v[0:3], v[194:197], v[44:47]
	v_mfma_f32_16x16x32_bf16 v[40:43], v[16:19], v[194:197], v[40:43]
	v_mfma_f32_16x16x32_bf16 v[0:3], v[0:3], v[198:201], v[36:39]
	v_mfma_f32_16x16x32_bf16 v[210:213], v[16:19], v[198:201], v[32:35]
	v_mfma_f32_16x16x32_bf16 v[52:55], v[4:7], v[182:185], v[20:23]
	v_mfma_f32_16x16x32_bf16 v[48:51], v[174:177], v[182:185], v[56:59]
	v_mfma_f32_16x16x32_bf16 v[36:39], v[4:7], v[190:193], v[60:63]
	v_mfma_f32_16x16x32_bf16 v[32:35], v[174:177], v[190:193], v[206:209]
	v_mfma_f32_16x16x32_bf16 v[20:23], v[4:7], v[150:153], v[44:47]
	v_mfma_f32_16x16x32_bf16 v[16:19], v[174:177], v[150:153], v[40:43]
	v_mfma_f32_16x16x32_bf16 v[4:7], v[4:7], v[202:205], v[0:3]
	v_mfma_f32_16x16x32_bf16 v[0:3], v[174:177], v[202:205], v[210:213]
	v_mfma_f32_16x16x32_bf16 v[28:31], v[224:227], v[178:181], v[28:31]
	v_mfma_f32_16x16x32_bf16 v[24:27], v[232:235], v[178:181], v[24:27]
	v_mfma_f32_16x16x32_bf16 v[40:43], v[224:227], v[186:189], v[134:137]
	v_mfma_f32_16x16x32_bf16 v[134:137], v[232:235], v[186:189], v[138:141]
	v_mfma_f32_16x16x32_bf16 v[12:15], v[224:227], v[194:197], v[12:15]
	v_mfma_f32_16x16x32_bf16 v[8:11], v[232:235], v[194:197], v[8:11]
	v_mfma_f32_16x16x32_bf16 v[138:141], v[224:227], v[198:201], v[170:173]
	v_mfma_f32_16x16x32_bf16 v[158:161], v[232:235], v[198:201], v[158:161]
	v_mfma_f32_16x16x32_bf16 v[60:63], v[228:231], v[182:185], v[28:31]
	v_mfma_f32_16x16x32_bf16 v[56:59], v[154:157], v[182:185], v[24:27]
	v_mfma_f32_16x16x32_bf16 v[44:47], v[228:231], v[190:193], v[40:43]
	v_mfma_f32_16x16x32_bf16 v[40:43], v[154:157], v[190:193], v[134:137]
	v_mfma_f32_16x16x32_bf16 v[28:31], v[228:231], v[150:153], v[12:15]
	v_mfma_f32_16x16x32_bf16 v[24:27], v[154:157], v[150:153], v[8:11]
	v_mfma_f32_16x16x32_bf16 v[12:15], v[228:231], v[202:205], v[138:141]
	v_mfma_f32_16x16x32_bf16 v[8:11], v[154:157], v[202:205], v[158:161]
	v_cmp_gt_u32_e32 vcc, s66, v130
	s_barrier
	s_and_saveexec_b64 s[50:51], vcc
	s_cbranch_execz .LBB0_773
	s_barrier

; #define STAGE(P, BASE, LD, br, kt) do { const char* _g = (const char*)((BASE) + (size_t)(br) * (LD) + (size_t)(kt) * 64); \
;     for (int _i = 0; _i < 2; ++_i) { int _b = tidx * 16 + _i * 8192; int _r, _c; stage_rc(_b, _r, _c); \
;       __builtin_amdgcn_global_load_lds((const unsigned*)(_g + (unsigned)((_r * (LD) + _c) * 2)), (unsigned*)((char*)(P) + _b), 16, 0, 0); } } while (0)
; #define LDA(dst, b, h) for (int m = 0; m < 4; ++m) for (int k = 0; k < 2; ++k) \
;     dst[m][k] = *reinterpret_cast<const bf16x8*>((char*)SA(b, h) + lds_byte(wr * 64 + m * 16 + fr, k * 32 + fq * 8))
; #define LDB(dst, b, h) for (int n = 0; n < 2; ++n) for (int k = 0; k < 2; ++k) \
;     dst[n][k] = *reinterpret_cast<const bf16x8*>((char*)SB(b, h) + lds_byte(wc * 32 + n * 16 + fr, k * 32 + fq * 8))
; #define MMA(ai, bj, At_, Bt_) do { __builtin_amdgcn_s_setprio(1); \
;     for (int k = 0; k < 2; ++k) for (int m = 0; m < 4; ++m) for (int n = 0; n < 2; ++n) \
;       acc[ai][bj][m][n] = __builtin_amdgcn_mfma_f32_16x16x32_bf16(At_[m][k], Bt_[n][k], acc[ai][bj][m][n], 0, 0, 0); \
;     __builtin_amdgcn_s_setprio(0); } while (0)
; #define WAIT_L(n) asm volatile("s_waitcnt lgkmcnt(" #n ")" ::: "memory")
; #define BAR __builtin_amdgcn_s_barrier()
; #define SCHED __builtin_amdgcn_sched_barrier(0)
; template <int EPI, int lda, int ldb, int N, int K>
; __device__ __forceinline__ void gemm_phase(const u16* __restrict__ A, const u16* __restrict__ Bt, const GemmEpi ep, int wv) {
;     ...
;       LDB(B0, 0, 0); SCHED; LDA(At, 0, 0); STAGE(SA(1, 1), Ab, lda, brow + HALF, t + 1);
;       WAIT_L(8); BAR; WAIT_L(0); MMA(0, 0, At, B0); BAR; SCHED;
;       LDB(B1, 0, 1); STAGE(SB(0, 0), Bt, ldb, bcol, t + 2);
;       BAR; WAIT_L(0); MMA(0, 1, At, B1); BAR;
;       LDA(At, 0, 1); STAGE(SA(0, 0), Ab, lda, brow, t + 2);
;       BAR; WAIT_L(0); MMA(1, 0, At, B0); BAR; SCHED;
.LBB0_838:
	ds_read_b128 v[168:171], v164
	ds_read_b128 v[174:177], v164 offset:1024
	ds_read_b128 v[178:181], v164 offset:2048
	ds_read_b128 v[182:185], v164 offset:3072
	v_add_u32_e32 v172, 0xc000, v147
	v_lshl_add_u64 v[238:239], v[136:137], 0, s[50:51]
	v_readfirstlane_b32 s73, v172
	v_add_u32_e32 v173, 0xe000, v147
	v_lshl_add_u64 v[166:167], v[238:239], 0, s[22:23]
	s_mov_b32 m0, s73
	v_lshl_add_u64 v[240:241], v[134:135], 0, s[50:51]
	v_readfirstlane_b32 s73, v173
	ds_read_b128 v[186:189], v155
	ds_read_b128 v[190:193], v155 offset:1024
	ds_read_b128 v[194:197], v154
	ds_read_b128 v[198:201], v154 offset:1024
	ds_read_b128 v[202:205], v153
	ds_read_b128 v[206:209], v153 offset:1024
	ds_read_b128 v[210:213], v152
	ds_read_b128 v[214:217], v152 offset:1024
	global_load_lds_dwordx4 v[166:167], off
	s_waitcnt lgkmcnt(8)
	s_barrier
	s_waitcnt lgkmcnt(0)
	s_waitcnt lgkmcnt(0)
	v_mfma_f32_16x16x32_bf16 v[124:127], v[168:171], v[186:189], v[124:127]
	v_mfma_f32_16x16x32_bf16 v[120:123], v[178:181], v[186:189], v[120:123]
	v_mfma_f32_16x16x32_bf16 v[116:119], v[168:171], v[194:197], v[116:119]
	v_mfma_f32_16x16x32_bf16 v[112:115], v[178:181], v[194:197], v[112:115]
	v_mfma_f32_16x16x32_bf16 v[108:111], v[168:171], v[202:205], v[108:111]
	v_mfma_f32_16x16x32_bf16 v[104:107], v[178:181], v[202:205], v[104:107]
	v_mfma_f32_16x16x32_bf16 v[100:103], v[168:171], v[210:213], v[100:103]
	v_mfma_f32_16x16x32_bf16 v[96:99], v[178:181], v[210:213], v[96:99]
	v_lshl_add_u64 v[166:167], v[240:241], 0, s[22:23]
	s_mov_b32 m0, s73
	s_nop 0
	global_load_lds_dwordx4 v[166:167], off
	v_mfma_f32_16x16x32_bf16 v[124:127], v[174:177], v[190:193], v[124:127]
	v_mfma_f32_16x16x32_bf16 v[120:123], v[182:185], v[190:193], v[120:123]
	v_mfma_f32_16x16x32_bf16 v[116:119], v[174:177], v[198:201], v[116:119]
	v_mfma_f32_16x16x32_bf16 v[112:115], v[182:185], v[198:201], v[112:115]
	v_mfma_f32_16x16x32_bf16 v[108:111], v[174:177], v[206:209], v[108:111]
	v_mfma_f32_16x16x32_bf16 v[104:107], v[182:185], v[206:209], v[104:107]
	v_mfma_f32_16x16x32_bf16 v[100:103], v[174:177], v[214:217], v[100:103]
	v_mfma_f32_16x16x32_bf16 v[96:99], v[182:185], v[214:217], v[96:99]
	s_barrier
	v_add_u32_e32 v165, s63, v156
	v_lshl_add_u64 v[242:243], v[144:145], 0, s[50:51]
	v_readfirstlane_b32 s73, v165
	v_lshl_add_u64 v[166:167], v[242:243], 0, s[24:25]
	s_mov_b32 m0, s73
	ds_read_b128 v[218:221], v163
	ds_read_b128 v[222:225], v163 offset:1024
	ds_read_b128 v[226:229], v163 offset:2048
	ds_read_b128 v[230:233], v163 offset:3072
	global_load_lds_dwordx4 v[166:167], off
	v_add_u32_e32 v166, 0x2000, v165
	v_lshl_add_u64 v[244:245], v[142:143], 0, s[50:51]
	v_readfirstlane_b32 s73, v166
	v_lshl_add_u64 v[234:235], v[244:245], 0, s[24:25]
	s_mov_b32 m0, s73
	s_nop 0
	global_load_lds_dwordx4 v[234:235], off
	s_barrier
	s_waitcnt lgkmcnt(0)
	s_waitcnt lgkmcnt(0)
	v_mfma_f32_16x16x32_bf16 v[92:95], v[218:221], v[186:189], v[92:95]
	v_mfma_f32_16x16x32_bf16 v[88:91], v[226:229], v[186:189], v[88:91]
	v_mfma_f32_16x16x32_bf16 v[84:87], v[218:221], v[194:197], v[84:87]
	v_mfma_f32_16x16x32_bf16 v[80:83], v[226:229], v[194:197], v[80:83]
	v_mfma_f32_16x16x32_bf16 v[76:79], v[218:221], v[202:205], v[76:79]
	v_mfma_f32_16x16x32_bf16 v[72:75], v[226:229], v[202:205], v[72:75]
	v_mfma_f32_16x16x32_bf16 v[68:71], v[218:221], v[210:213], v[68:71]
	v_mfma_f32_16x16x32_bf16 v[64:67], v[226:229], v[210:213], v[64:67]
	v_mfma_f32_16x16x32_bf16 v[92:95], v[222:225], v[190:193], v[92:95]
	v_mfma_f32_16x16x32_bf16 v[88:91], v[230:233], v[190:193], v[88:91]
	v_mfma_f32_16x16x32_bf16 v[84:87], v[222:225], v[198:201], v[84:87]
	v_mfma_f32_16x16x32_bf16 v[80:83], v[230:233], v[198:201], v[80:83]
	v_mfma_f32_16x16x32_bf16 v[76:79], v[222:225], v[206:209], v[76:79]
	v_mfma_f32_16x16x32_bf16 v[72:75], v[230:233], v[206:209], v[72:75]
	v_mfma_f32_16x16x32_bf16 v[68:71], v[222:225], v[214:217], v[68:71]
	v_mfma_f32_16x16x32_bf16 v[64:67], v[230:233], v[214:217], v[64:67]
	s_barrier
	v_readfirstlane_b32 s73, v147
	v_add_u32_e32 v167, 0x2000, v147
	v_lshl_add_u64 v[234:235], v[238:239], 0, s[26:27]
	s_mov_b32 m0, s73
	v_readfirstlane_b32 s73, v167
	ds_read_b128 v[186:189], v155 offset:16384
	ds_read_b128 v[190:193], v155 offset:17408
	ds_read_b128 v[194:197], v154 offset:16384
	ds_read_b128 v[198:201], v154 offset:17408
	ds_read_b128 v[202:205], v153 offset:16384
	ds_read_b128 v[206:209], v153 offset:17408
	ds_read_b128 v[210:213], v152 offset:16384
	ds_read_b128 v[214:217], v152 offset:17408
	global_load_lds_dwordx4 v[234:235], off
	v_lshl_add_u64 v[234:235], v[240:241], 0, s[26:27]
	s_mov_b32 m0, s73
	s_nop 0
	global_load_lds_dwordx4 v[234:235], off
	s_barrier
	s_waitcnt lgkmcnt(0)
	s_waitcnt lgkmcnt(0)
	v_mfma_f32_16x16x32_bf16 v[60:63], v[168:171], v[186:189], v[60:63]
	v_mfma_f32_16x16x32_bf16 v[56:59], v[178:181], v[186:189], v[56:59]
	v_mfma_f32_16x16x32_bf16 v[52:55], v[168:171], v[194:197], v[52:55]
	v_mfma_f32_16x16x32_bf16 v[48:51], v[178:181], v[194:197], v[48:51]
	v_mfma_f32_16x16x32_bf16 v[44:47], v[168:171], v[202:205], v[44:47]
	v_mfma_f32_16x16x32_bf16 v[40:43], v[178:181], v[202:205], v[40:43]
	v_mfma_f32_16x16x32_bf16 v[36:39], v[168:171], v[210:213], v[36:39]
	v_mfma_f32_16x16x32_bf16 v[32:35], v[178:181], v[210:213], v[32:35]
	v_mfma_f32_16x16x32_bf16 v[60:63], v[174:177], v[190:193], v[60:63]
	v_mfma_f32_16x16x32_bf16 v[56:59], v[182:185], v[190:193], v[56:59]
	v_mfma_f32_16x16x32_bf16 v[52:55], v[174:177], v[198:201], v[52:55]
	v_mfma_f32_16x16x32_bf16 v[48:51], v[182:185], v[198:201], v[48:51]
	v_mfma_f32_16x16x32_bf16 v[44:47], v[174:177], v[206:209], v[44:47]
	v_mfma_f32_16x16x32_bf16 v[40:43], v[182:185], v[206:209], v[40:43]
	v_mfma_f32_16x16x32_bf16 v[36:39], v[174:177], v[214:217], v[36:39]
	v_mfma_f32_16x16x32_bf16 v[32:35], v[182:185], v[214:217], v[32:35]
	s_barrier
; #define STAGE(P, BASE, LD, br, kt) do { const char* _g = (const char*)((BASE) + (size_t)(br) * (LD) + (size_t)(kt) * 64); \
;     for (int _i = 0; _i < 2; ++_i) { int _b = tidx * 16 + _i * 8192; int _r, _c; stage_rc(_b, _r, _c); \
;       __builtin_amdgcn_global_load_lds((const unsigned*)(_g + (unsigned)((_r * (LD) + _c) * 2)), (unsigned*)((char*)(P) + _b), 16, 0, 0); } } while (0)
; #define LDA(dst, b, h) for (int m = 0; m < 4; ++m) for (int k = 0; k < 2; ++k) \
;     dst[m][k] = *reinterpret_cast<const bf16x8*>((char*)SA(b, h) + lds_byte(wr * 64 + m * 16 + fr, k * 32 + fq * 8))
; #define LDB(dst, b, h) for (int n = 0; n < 2; ++n) for (int k = 0; k < 2; ++k) \
;     dst[n][k] = *reinterpret_cast<const bf16x8*>((char*)SB(b, h) + lds_byte(wc * 32 + n * 16 + fr, k * 32 + fq * 8))
; #define MMA(ai, bj, At_, Bt_) do { __builtin_amdgcn_s_setprio(1); \
;     for (int k = 0; k < 2; ++k) for (int m = 0; m < 4; ++m) for (int n = 0; n < 2; ++n) \
;       acc[ai][bj][m][n] = __builtin_amdgcn_mfma_f32_16x16x32_bf16(At_[m][k], Bt_[n][k], acc[ai][bj][m][n], 0, 0, 0); \
;     __builtin_amdgcn_s_setprio(0); } while (0)
; #define WAIT_V(n) asm volatile("s_waitcnt vmcnt(" #n ")" ::: "memory")
; #define WAIT_L(n) asm volatile("s_waitcnt lgkmcnt(" #n ")" ::: "memory")
; #define BAR __builtin_amdgcn_s_barrier()
; #define SCHED __builtin_amdgcn_sched_barrier(0)
; template <int EPI, int lda, int ldb, int N, int K>
; __device__ __forceinline__ void gemm_phase(const u16* __restrict__ A, const u16* __restrict__ Bt, const GemmEpi ep, int wv) {
;     ...
;       STAGE(SB(0, 1), Bt, ldb, bcol + HALF, t + 2);
;       WAIT_V(6); BAR; MMA(1, 1, At, B1); BAR;
;       LDB(B0, 1, 0); SCHED; LDA(At, 1, 0); STAGE(SA(0, 1), Ab, lda, brow + HALF, t + 2);
;       WAIT_L(8); BAR; WAIT_L(0); MMA(0, 0, At, B0); BAR; SCHED;
;       LDB(B1, 1, 1); STAGE(SB(1, 0), Bt, ldb, bcol, t + 3);
;       BAR; WAIT_L(0); MMA(0, 1, At, B1); BAR;
;       LDA(At, 1, 1); STAGE(SA(1, 0), Ab, lda, brow, t + 3);
	v_add_u32_e32 v168, s64, v156
	v_lshl_add_u64 v[246:247], v[140:141], 0, s[50:51]
	v_readfirstlane_b32 s73, v168
	v_add_u32_e32 v169, 0x2000, v168
	v_lshl_add_u64 v[170:171], v[246:247], 0, s[40:41]
	s_mov_b32 m0, s73
	v_lshl_add_u64 v[248:249], v[138:139], 0, s[50:51]
	v_readfirstlane_b32 s73, v169
	global_load_lds_dwordx4 v[170:171], off
	v_lshl_add_u64 v[170:171], v[248:249], 0, s[40:41]
	s_mov_b32 m0, s73
	s_nop 0
	global_load_lds_dwordx4 v[170:171], off
	s_waitcnt vmcnt(6)
	s_barrier
	v_mfma_f32_16x16x32_bf16 v[28:31], v[218:221], v[186:189], v[28:31]
	v_mfma_f32_16x16x32_bf16 v[24:27], v[226:229], v[186:189], v[24:27]
	v_mfma_f32_16x16x32_bf16 v[20:23], v[218:221], v[194:197], v[20:23]
	v_mfma_f32_16x16x32_bf16 v[16:19], v[226:229], v[194:197], v[16:19]
	v_mfma_f32_16x16x32_bf16 v[12:15], v[218:221], v[202:205], v[12:15]
	v_mfma_f32_16x16x32_bf16 v[8:11], v[226:229], v[202:205], v[8:11]
	v_mfma_f32_16x16x32_bf16 v[4:7], v[218:221], v[210:213], v[4:7]
	v_mfma_f32_16x16x32_bf16 v[0:3], v[226:229], v[210:213], v[0:3]
	v_mfma_f32_16x16x32_bf16 v[28:31], v[222:225], v[190:193], v[28:31]
	v_mfma_f32_16x16x32_bf16 v[24:27], v[230:233], v[190:193], v[24:27]
	v_mfma_f32_16x16x32_bf16 v[20:23], v[222:225], v[198:201], v[20:23]
	v_mfma_f32_16x16x32_bf16 v[16:19], v[230:233], v[198:201], v[16:19]
	v_mfma_f32_16x16x32_bf16 v[12:15], v[222:225], v[206:209], v[12:15]
	v_mfma_f32_16x16x32_bf16 v[8:11], v[230:233], v[206:209], v[8:11]
	v_mfma_f32_16x16x32_bf16 v[4:7], v[222:225], v[214:217], v[4:7]
	v_mfma_f32_16x16x32_bf16 v[0:3], v[230:233], v[214:217], v[0:3]
	s_barrier
	ds_read_b128 v[174:177], v159
	ds_read_b128 v[178:181], v159 offset:1024
	ds_read_b128 v[182:185], v159 offset:2048
	ds_read_b128 v[186:189], v159 offset:3072
	v_add_u32_e32 v170, 0x4000, v147
	v_add_u32_e32 v171, 0x6000, v147
	v_readfirstlane_b32 s73, v170
	v_lshl_add_u64 v[222:223], v[238:239], 0, s[42:43]
	s_mov_b32 m0, s73
	v_readfirstlane_b32 s73, v171
	ds_read_b128 v[190:193], v155 offset:32768
	ds_read_b128 v[194:197], v155 offset:33792
	ds_read_b128 v[198:201], v154 offset:32768
	ds_read_b128 v[202:205], v154 offset:33792
	ds_read_b128 v[206:209], v153 offset:32768
	ds_read_b128 v[210:213], v153 offset:33792
	ds_read_b128 v[214:217], v152 offset:32768
	ds_read_b128 v[218:221], v152 offset:33792
	global_load_lds_dwordx4 v[222:223], off
	s_waitcnt lgkmcnt(8)
	s_barrier
	s_waitcnt lgkmcnt(0)
	s_waitcnt lgkmcnt(0)
	v_mfma_f32_16x16x32_bf16 v[124:127], v[174:177], v[190:193], v[124:127]
	v_mfma_f32_16x16x32_bf16 v[120:123], v[182:185], v[190:193], v[120:123]
	v_mfma_f32_16x16x32_bf16 v[116:119], v[174:177], v[198:201], v[116:119]
	v_mfma_f32_16x16x32_bf16 v[112:115], v[182:185], v[198:201], v[112:115]
	v_mfma_f32_16x16x32_bf16 v[108:111], v[174:177], v[206:209], v[108:111]
	v_mfma_f32_16x16x32_bf16 v[104:107], v[182:185], v[206:209], v[104:107]
	v_mfma_f32_16x16x32_bf16 v[100:103], v[174:177], v[214:217], v[100:103]
	v_mfma_f32_16x16x32_bf16 v[96:99], v[182:185], v[214:217], v[96:99]
	v_lshl_add_u64 v[222:223], v[240:241], 0, s[42:43]
	s_mov_b32 m0, s73
	s_nop 0
	global_load_lds_dwordx4 v[222:223], off
	v_mfma_f32_16x16x32_bf16 v[124:127], v[178:181], v[194:197], v[124:127]
	v_mfma_f32_16x16x32_bf16 v[120:123], v[186:189], v[194:197], v[120:123]
	v_mfma_f32_16x16x32_bf16 v[116:119], v[178:181], v[202:205], v[116:119]
	v_mfma_f32_16x16x32_bf16 v[112:115], v[186:189], v[202:205], v[112:115]
	v_mfma_f32_16x16x32_bf16 v[108:111], v[178:181], v[210:213], v[108:111]
	v_mfma_f32_16x16x32_bf16 v[104:107], v[186:189], v[210:213], v[104:107]
	v_mfma_f32_16x16x32_bf16 v[100:103], v[178:181], v[218:221], v[100:103]
	v_mfma_f32_16x16x32_bf16 v[96:99], v[186:189], v[218:221], v[96:99]
	s_barrier
	v_readfirstlane_b32 s73, v158
	v_lshl_add_u64 v[242:243], v[242:243], 0, s[44:45]
	s_mov_b32 m0, s73
	ds_read_b128 v[222:225], v157
	ds_read_b128 v[226:229], v157 offset:1024
	ds_read_b128 v[230:233], v157 offset:2048
	ds_read_b128 v[234:237], v157 offset:3072
	global_load_lds_dwordx4 v[242:243], off
	v_lshl_add_u64 v[242:243], v[244:245], 0, s[44:45]
	v_add_u32_e32 v244, 0x2000, v158
	s_nop 0
	v_readfirstlane_b32 s73, v244
	s_mov_b32 m0, s73
	s_nop 0
	global_load_lds_dwordx4 v[242:243], off
	s_barrier
	s_waitcnt lgkmcnt(0)
	s_waitcnt lgkmcnt(0)
	v_mfma_f32_16x16x32_bf16 v[92:95], v[222:225], v[190:193], v[92:95]
	v_mfma_f32_16x16x32_bf16 v[88:91], v[230:233], v[190:193], v[88:91]
	v_mfma_f32_16x16x32_bf16 v[84:87], v[222:225], v[198:201], v[84:87]
	v_mfma_f32_16x16x32_bf16 v[80:83], v[230:233], v[198:201], v[80:83]
	v_mfma_f32_16x16x32_bf16 v[76:79], v[222:225], v[206:209], v[76:79]
	v_mfma_f32_16x16x32_bf16 v[72:75], v[230:233], v[206:209], v[72:75]
	v_mfma_f32_16x16x32_bf16 v[68:71], v[222:225], v[214:217], v[68:71]
	v_mfma_f32_16x16x32_bf16 v[64:67], v[230:233], v[214:217], v[64:67]
	v_mfma_f32_16x16x32_bf16 v[92:95], v[226:229], v[194:197], v[92:95]
	v_mfma_f32_16x16x32_bf16 v[88:91], v[234:237], v[194:197], v[88:91]
	v_mfma_f32_16x16x32_bf16 v[84:87], v[226:229], v[202:205], v[84:87]
	v_mfma_f32_16x16x32_bf16 v[80:83], v[234:237], v[202:205], v[80:83]
	v_mfma_f32_16x16x32_bf16 v[76:79], v[226:229], v[210:213], v[76:79]
	v_mfma_f32_16x16x32_bf16 v[72:75], v[234:237], v[210:213], v[72:75]
	v_mfma_f32_16x16x32_bf16 v[68:71], v[226:229], v[218:221], v[68:71]
	v_mfma_f32_16x16x32_bf16 v[64:67], v[234:237], v[218:221], v[64:67]
	s_barrier
; #define STAGE(P, BASE, LD, br, kt) do { const char* _g = (const char*)((BASE) + (size_t)(br) * (LD) + (size_t)(kt) * 64); \
;     for (int _i = 0; _i < 2; ++_i) { int _b = tidx * 16 + _i * 8192; int _r, _c; stage_rc(_b, _r, _c); \
;       __builtin_amdgcn_global_load_lds((const unsigned*)(_g + (unsigned)((_r * (LD) + _c) * 2)), (unsigned*)((char*)(P) + _b), 16, 0, 0); } } while (0)
; #define LDA(dst, b, h) for (int m = 0; m < 4; ++m) for (int k = 0; k < 2; ++k) \
;     dst[m][k] = *reinterpret_cast<const bf16x8*>((char*)SA(b, h) + lds_byte(wr * 64 + m * 16 + fr, k * 32 + fq * 8))
; #define LDB(dst, b, h) for (int n = 0; n < 2; ++n) for (int k = 0; k < 2; ++k) \
;     dst[n][k] = *reinterpret_cast<const bf16x8*>((char*)SB(b, h) + lds_byte(wc * 32 + n * 16 + fr, k * 32 + fq * 8))
; #define MMA(ai, bj, At_, Bt_) do { __builtin_amdgcn_s_setprio(1); \
;     for (int k = 0; k < 2; ++k) for (int m = 0; m < 4; ++m) for (int n = 0; n < 2; ++n) \
;       acc[ai][bj][m][n] = __builtin_amdgcn_mfma_f32_16x16x32_bf16(At_[m][k], Bt_[n][k], acc[ai][bj][m][n], 0, 0, 0); \
;     __builtin_amdgcn_s_setprio(0); } while (0)
; #define WAIT_V(n) asm volatile("s_waitcnt vmcnt(" #n ")" ::: "memory")
; #define WAIT_L(n) asm volatile("s_waitcnt lgkmcnt(" #n ")" ::: "memory")
; #define BAR __builtin_amdgcn_s_barrier()
; #define SCHED __builtin_amdgcn_sched_barrier(0)
; template <int EPI, int lda, int ldb, int N, int K>
; __device__ __forceinline__ void gemm_phase(const u16* __restrict__ A, const u16* __restrict__ Bt, const GemmEpi ep, int wv) {
;     ...
;       LDA(At, 1, 1); STAGE(SA(1, 0), Ab, lda, brow, t + 3);
;       BAR; WAIT_L(0); MMA(1, 0, At, B0); BAR; SCHED;
;       STAGE(SB(1, 1), Bt, ldb, bcol + HALF, t + 3);
;       WAIT_V(6); BAR; MMA(1, 1, At, B1); BAR;
;     }
;     { LDB(B0, 0, 0); LDA(At, 0, 0); STAGE(SA(1, 1), Ab, lda, brow + HALF, nt - 1);
;       BAR; WAIT_L(0); MMA(0, 0, At, B0); BAR;
;       LDB(B1, 0, 1); BAR; WAIT_L(0); MMA(0, 1, At, B1); BAR;
	v_readfirstlane_b32 s73, v160
	v_lshl_add_u64 v[238:239], v[238:239], 0, s[46:47]
	s_mov_b32 m0, s73
	v_readfirstlane_b32 s73, v161
	ds_read_b128 v[190:193], v155 offset:49152
	ds_read_b128 v[194:197], v155 offset:50176
	ds_read_b128 v[198:201], v154 offset:49152
	ds_read_b128 v[202:205], v154 offset:50176
	ds_read_b128 v[206:209], v153 offset:49152
	ds_read_b128 v[210:213], v153 offset:50176
	ds_read_b128 v[214:217], v152 offset:49152
	ds_read_b128 v[218:221], v152 offset:50176
	global_load_lds_dwordx4 v[238:239], off
	v_lshl_add_u64 v[238:239], v[240:241], 0, s[46:47]
	s_mov_b32 m0, s73
	s_nop 0
	global_load_lds_dwordx4 v[238:239], off
	s_barrier
	s_waitcnt lgkmcnt(0)
	s_waitcnt lgkmcnt(0)
	v_mfma_f32_16x16x32_bf16 v[60:63], v[174:177], v[190:193], v[60:63]
	v_mfma_f32_16x16x32_bf16 v[56:59], v[182:185], v[190:193], v[56:59]
	v_mfma_f32_16x16x32_bf16 v[52:55], v[174:177], v[198:201], v[52:55]
	v_mfma_f32_16x16x32_bf16 v[48:51], v[182:185], v[198:201], v[48:51]
	v_mfma_f32_16x16x32_bf16 v[44:47], v[174:177], v[206:209], v[44:47]
	v_mfma_f32_16x16x32_bf16 v[40:43], v[182:185], v[206:209], v[40:43]
	v_mfma_f32_16x16x32_bf16 v[36:39], v[174:177], v[214:217], v[36:39]
	v_mfma_f32_16x16x32_bf16 v[32:35], v[182:185], v[214:217], v[32:35]
	v_mfma_f32_16x16x32_bf16 v[60:63], v[178:181], v[194:197], v[60:63]
	v_mfma_f32_16x16x32_bf16 v[56:59], v[186:189], v[194:197], v[56:59]
	v_mfma_f32_16x16x32_bf16 v[52:55], v[178:181], v[202:205], v[52:55]
	v_mfma_f32_16x16x32_bf16 v[48:51], v[186:189], v[202:205], v[48:51]
	v_mfma_f32_16x16x32_bf16 v[44:47], v[178:181], v[210:213], v[44:47]
	v_mfma_f32_16x16x32_bf16 v[40:43], v[186:189], v[210:213], v[40:43]
	v_mfma_f32_16x16x32_bf16 v[36:39], v[178:181], v[218:221], v[36:39]
	v_mfma_f32_16x16x32_bf16 v[32:35], v[186:189], v[218:221], v[32:35]
	s_barrier
	v_readfirstlane_b32 s73, v162
	v_add_u32_e32 v176, 0x2000, v162
	v_lshl_add_u64 v[174:175], v[246:247], 0, s[48:49]
	s_mov_b32 m0, s73
	v_readfirstlane_b32 s73, v176
	global_load_lds_dwordx4 v[174:175], off
	v_lshl_add_u64 v[174:175], v[248:249], 0, s[48:49]
	s_mov_b32 m0, s73
	s_nop 0
	global_load_lds_dwordx4 v[174:175], off
	s_waitcnt vmcnt(6)
	s_barrier
	v_mfma_f32_16x16x32_bf16 v[28:31], v[222:225], v[190:193], v[28:31]
	v_mfma_f32_16x16x32_bf16 v[24:27], v[230:233], v[190:193], v[24:27]
	v_mfma_f32_16x16x32_bf16 v[20:23], v[222:225], v[198:201], v[20:23]
	v_mfma_f32_16x16x32_bf16 v[16:19], v[230:233], v[198:201], v[16:19]
	v_mfma_f32_16x16x32_bf16 v[12:15], v[222:225], v[206:209], v[12:15]
	v_mfma_f32_16x16x32_bf16 v[8:11], v[230:233], v[206:209], v[8:11]
	v_mfma_f32_16x16x32_bf16 v[4:7], v[222:225], v[214:217], v[4:7]
	v_mfma_f32_16x16x32_bf16 v[0:3], v[230:233], v[214:217], v[0:3]
	v_mfma_f32_16x16x32_bf16 v[28:31], v[226:229], v[194:197], v[28:31]
	v_mfma_f32_16x16x32_bf16 v[24:27], v[234:237], v[194:197], v[24:27]
	v_mfma_f32_16x16x32_bf16 v[20:23], v[226:229], v[202:205], v[20:23]
	v_mfma_f32_16x16x32_bf16 v[16:19], v[234:237], v[202:205], v[16:19]
	v_mfma_f32_16x16x32_bf16 v[12:15], v[226:229], v[210:213], v[12:15]
	v_mfma_f32_16x16x32_bf16 v[8:11], v[234:237], v[210:213], v[8:11]
	v_mfma_f32_16x16x32_bf16 v[4:7], v[226:229], v[218:221], v[4:7]
	v_mfma_f32_16x16x32_bf16 v[0:3], v[234:237], v[218:221], v[0:3]
	s_add_i32 s72, s72, 2
	s_add_u32 s50, s50, 0x100
	s_addc_u32 s51, s51, 0
	s_cmpk_gt_u32 s72, 0x51
	s_barrier
	s_cbranch_scc0 .LBB0_838
	s_add_i32 s50, s18, 0x80
	s_mul_hi_i32 s51, s50, 0x2b00
	s_mulk_i32 s50, 0x2b00
	s_add_u32 s50, s56, s50
	s_addc_u32 s51, s57, s51
	s_add_u32 s50, s50, 0x2a80
	s_addc_u32 s51, s51, 0
	v_readfirstlane_b32 s72, v172
	v_lshl_add_u64 v[160:161], s[50:51], 0, v[128:129]
	s_mov_b32 m0, s72
	ds_read_b128 v[134:137], v164
	ds_read_b128 v[138:141], v164 offset:1024
	ds_read_b128 v[142:145], v164 offset:2048
	ds_read_b128 v[174:177], v164 offset:3072
	ds_read_b128 v[178:181], v155
	ds_read_b128 v[182:185], v155 offset:1024
	ds_read_b128 v[186:189], v154
	ds_read_b128 v[190:193], v154 offset:1024
	ds_read_b128 v[194:197], v153
	ds_read_b128 v[198:201], v153 offset:1024
	ds_read_b128 v[202:205], v152
	ds_read_b128 v[206:209], v152 offset:1024
	global_load_lds_dwordx4 v[160:161], off
	v_lshl_add_u64 v[160:161], s[50:51], 0, v[132:133]
	v_readfirstlane_b32 s50, v173
	s_mov_b32 m0, s50
	s_nop 0
	global_load_lds_dwordx4 v[160:161], off
	s_barrier
	s_waitcnt lgkmcnt(0)
	s_waitcnt lgkmcnt(0)
	v_mfma_f32_16x16x32_bf16 v[124:127], v[134:137], v[178:181], v[124:127]
	v_mfma_f32_16x16x32_bf16 v[120:123], v[142:145], v[178:181], v[120:123]
	v_mfma_f32_16x16x32_bf16 v[116:119], v[134:137], v[186:189], v[116:119]
	v_mfma_f32_16x16x32_bf16 v[112:115], v[142:145], v[186:189], v[112:115]
	v_mfma_f32_16x16x32_bf16 v[108:111], v[134:137], v[194:197], v[108:111]
	v_mfma_f32_16x16x32_bf16 v[104:107], v[142:145], v[194:197], v[104:107]
	v_mfma_f32_16x16x32_bf16 v[100:103], v[134:137], v[202:205], v[100:103]
	v_mfma_f32_16x16x32_bf16 v[96:99], v[142:145], v[202:205], v[96:99]
	v_mfma_f32_16x16x32_bf16 v[124:127], v[138:141], v[182:185], v[124:127]
	v_mfma_f32_16x16x32_bf16 v[120:123], v[174:177], v[182:185], v[120:123]
	v_mfma_f32_16x16x32_bf16 v[116:119], v[138:141], v[190:193], v[116:119]
	v_mfma_f32_16x16x32_bf16 v[112:115], v[174:177], v[190:193], v[112:115]
	v_mfma_f32_16x16x32_bf16 v[108:111], v[138:141], v[198:201], v[108:111]
	v_mfma_f32_16x16x32_bf16 v[104:107], v[174:177], v[198:201], v[104:107]
	v_mfma_f32_16x16x32_bf16 v[100:103], v[138:141], v[206:209], v[100:103]
	v_mfma_f32_16x16x32_bf16 v[96:99], v[174:177], v[206:209], v[96:99]
	s_barrier
; #define LDA(dst, b, h) for (int m = 0; m < 4; ++m) for (int k = 0; k < 2; ++k) \
;     dst[m][k] = *reinterpret_cast<const bf16x8*>((char*)SA(b, h) + lds_byte(wr * 64 + m * 16 + fr, k * 32 + fq * 8))
; #define LDB(dst, b, h) for (int n = 0; n < 2; ++n) for (int k = 0; k < 2; ++k) \
;     dst[n][k] = *reinterpret_cast<const bf16x8*>((char*)SB(b, h) + lds_byte(wc * 32 + n * 16 + fr, k * 32 + fq * 8))
; #define MMA(ai, bj, At_, Bt_) do { __builtin_amdgcn_s_setprio(1); \
;     for (int k = 0; k < 2; ++k) for (int m = 0; m < 4; ++m) for (int n = 0; n < 2; ++n) \
;       acc[ai][bj][m][n] = __builtin_amdgcn_mfma_f32_16x16x32_bf16(At_[m][k], Bt_[n][k], acc[ai][bj][m][n], 0, 0, 0); \
;     __builtin_amdgcn_s_setprio(0); } while (0)
; #define WAIT_V(n) asm volatile("s_waitcnt vmcnt(" #n ")" ::: "memory")
; #define WAIT_L(n) asm volatile("s_waitcnt lgkmcnt(" #n ")" ::: "memory")
; #define BAR __builtin_amdgcn_s_barrier()
; template <int EPI, int lda, int ldb, int N, int K>
; __device__ __forceinline__ void gemm_phase(const u16* __restrict__ A, const u16* __restrict__ Bt, const GemmEpi ep, int wv) {
;     ...
;       LDB(B1, 0, 1); BAR; WAIT_L(0); MMA(0, 1, At, B1); BAR;
;       LDA(At, 0, 1); WAIT_V(4); BAR; WAIT_L(0); MMA(1, 0, At, B0); MMA(1, 1, At, B1); BAR; }
;     { LDB(B0, 1, 0); LDA(At, 1, 0); WAIT_V(2); BAR; WAIT_L(0); MMA(0, 0, At, B0); BAR;
	ds_read_b128 v[210:213], v163
	ds_read_b128 v[214:217], v163 offset:1024
	ds_read_b128 v[218:221], v163 offset:2048
	ds_read_b128 v[160:163], v163 offset:3072
	s_barrier
	s_waitcnt lgkmcnt(0)
	s_waitcnt lgkmcnt(0)
	v_mfma_f32_16x16x32_bf16 v[92:95], v[210:213], v[178:181], v[92:95]
	v_mfma_f32_16x16x32_bf16 v[88:91], v[218:221], v[178:181], v[88:91]
	v_mfma_f32_16x16x32_bf16 v[76:79], v[210:213], v[194:197], v[76:79]
	v_mfma_f32_16x16x32_bf16 v[72:75], v[218:221], v[194:197], v[72:75]
	v_mfma_f32_16x16x32_bf16 v[84:87], v[210:213], v[186:189], v[84:87]
	v_mfma_f32_16x16x32_bf16 v[80:83], v[218:221], v[186:189], v[80:83]
	v_mfma_f32_16x16x32_bf16 v[68:71], v[210:213], v[202:205], v[68:71]
	v_mfma_f32_16x16x32_bf16 v[64:67], v[218:221], v[202:205], v[64:67]
	v_mfma_f32_16x16x32_bf16 v[92:95], v[214:217], v[182:185], v[92:95]
	v_mfma_f32_16x16x32_bf16 v[88:91], v[160:163], v[182:185], v[88:91]
	v_mfma_f32_16x16x32_bf16 v[76:79], v[214:217], v[198:201], v[76:79]
	v_mfma_f32_16x16x32_bf16 v[72:75], v[160:163], v[198:201], v[72:75]
	v_mfma_f32_16x16x32_bf16 v[178:181], v[214:217], v[190:193], v[84:87]
	v_mfma_f32_16x16x32_bf16 v[182:185], v[160:163], v[190:193], v[80:83]
	v_mfma_f32_16x16x32_bf16 v[186:189], v[214:217], v[206:209], v[68:71]
	v_mfma_f32_16x16x32_bf16 v[190:193], v[160:163], v[206:209], v[64:67]
	s_barrier
	s_nop 0
	ds_read_b128 v[64:67], v155 offset:16384
	ds_read_b128 v[68:71], v155 offset:17408
	ds_read_b128 v[80:83], v154 offset:16384
	ds_read_b128 v[84:87], v154 offset:17408
	ds_read_b128 v[194:197], v153 offset:16384
	ds_read_b128 v[198:201], v153 offset:17408
	ds_read_b128 v[202:205], v152 offset:16384
	ds_read_b128 v[206:209], v152 offset:17408
	s_waitcnt vmcnt(4)
	s_barrier
	s_waitcnt lgkmcnt(0)
	s_waitcnt lgkmcnt(0)
	v_mfma_f32_16x16x32_bf16 v[60:63], v[134:137], v[64:67], v[60:63]
	v_mfma_f32_16x16x32_bf16 v[56:59], v[142:145], v[64:67], v[56:59]
	v_mfma_f32_16x16x32_bf16 v[52:55], v[134:137], v[80:83], v[52:55]
	v_mfma_f32_16x16x32_bf16 v[48:51], v[142:145], v[80:83], v[48:51]
	v_mfma_f32_16x16x32_bf16 v[44:47], v[134:137], v[194:197], v[44:47]
	v_mfma_f32_16x16x32_bf16 v[40:43], v[142:145], v[194:197], v[40:43]
	v_mfma_f32_16x16x32_bf16 v[36:39], v[134:137], v[202:205], v[36:39]
	v_mfma_f32_16x16x32_bf16 v[32:35], v[142:145], v[202:205], v[32:35]
	v_mfma_f32_16x16x32_bf16 v[60:63], v[138:141], v[68:71], v[60:63]
	v_mfma_f32_16x16x32_bf16 v[56:59], v[174:177], v[68:71], v[56:59]
	v_mfma_f32_16x16x32_bf16 v[52:55], v[138:141], v[84:87], v[52:55]
	v_mfma_f32_16x16x32_bf16 v[48:51], v[174:177], v[84:87], v[48:51]
	v_mfma_f32_16x16x32_bf16 v[44:47], v[138:141], v[198:201], v[44:47]
	v_mfma_f32_16x16x32_bf16 v[40:43], v[174:177], v[198:201], v[40:43]
	v_mfma_f32_16x16x32_bf16 v[36:39], v[138:141], v[206:209], v[36:39]
	v_mfma_f32_16x16x32_bf16 v[32:35], v[174:177], v[206:209], v[32:35]
	v_mfma_f32_16x16x32_bf16 v[28:31], v[210:213], v[64:67], v[28:31]
	v_mfma_f32_16x16x32_bf16 v[16:19], v[218:221], v[80:83], v[16:19]
	v_mfma_f32_16x16x32_bf16 v[12:15], v[210:213], v[194:197], v[12:15]
	v_mfma_f32_16x16x32_bf16 v[0:3], v[218:221], v[202:205], v[0:3]
	v_mfma_f32_16x16x32_bf16 v[24:27], v[218:221], v[64:67], v[24:27]
	v_mfma_f32_16x16x32_bf16 v[20:23], v[210:213], v[80:83], v[20:23]
	v_mfma_f32_16x16x32_bf16 v[8:11], v[218:221], v[194:197], v[8:11]
	v_mfma_f32_16x16x32_bf16 v[4:7], v[210:213], v[202:205], v[4:7]
	v_mfma_f32_16x16x32_bf16 v[28:31], v[214:217], v[68:71], v[28:31]
	v_mfma_f32_16x16x32_bf16 v[16:19], v[160:163], v[84:87], v[16:19]
	v_mfma_f32_16x16x32_bf16 v[12:15], v[214:217], v[198:201], v[12:15]
	v_mfma_f32_16x16x32_bf16 v[0:3], v[160:163], v[206:209], v[0:3]
	v_mfma_f32_16x16x32_bf16 v[134:137], v[160:163], v[68:71], v[24:27]
	v_mfma_f32_16x16x32_bf16 v[138:141], v[214:217], v[84:87], v[20:23]
	v_mfma_f32_16x16x32_bf16 v[142:145], v[160:163], v[198:201], v[8:11]
	v_mfma_f32_16x16x32_bf16 v[172:175], v[214:217], v[206:209], v[4:7]
	s_barrier
	s_nop 0
	ds_read_b128 v[4:7], v159
	ds_read_b128 v[8:11], v159 offset:1024
	ds_read_b128 v[20:23], v159 offset:2048
	ds_read_b128 v[158:161], v159 offset:3072
	ds_read_b128 v[24:27], v155 offset:32768
	ds_read_b128 v[194:197], v155 offset:33792
	ds_read_b128 v[198:201], v154 offset:32768
	ds_read_b128 v[202:205], v154 offset:33792
	ds_read_b128 v[206:209], v153 offset:32768
	ds_read_b128 v[210:213], v153 offset:33792
	ds_read_b128 v[214:217], v152 offset:32768
	ds_read_b128 v[218:221], v152 offset:33792
	s_waitcnt vmcnt(2)
	s_barrier
; #define LDA(dst, b, h) for (int m = 0; m < 4; ++m) for (int k = 0; k < 2; ++k) \
;     dst[m][k] = *reinterpret_cast<const bf16x8*>((char*)SA(b, h) + lds_byte(wr * 64 + m * 16 + fr, k * 32 + fq * 8))
; #define LDB(dst, b, h) for (int n = 0; n < 2; ++n) for (int k = 0; k < 2; ++k) \
;     dst[n][k] = *reinterpret_cast<const bf16x8*>((char*)SB(b, h) + lds_byte(wc * 32 + n * 16 + fr, k * 32 + fq * 8))
; #define MMA(ai, bj, At_, Bt_) do { __builtin_amdgcn_s_setprio(1); \
;     for (int k = 0; k < 2; ++k) for (int m = 0; m < 4; ++m) for (int n = 0; n < 2; ++n) \
;       acc[ai][bj][m][n] = __builtin_amdgcn_mfma_f32_16x16x32_bf16(At_[m][k], Bt_[n][k], acc[ai][bj][m][n], 0, 0, 0); \
;     __builtin_amdgcn_s_setprio(0); } while (0)
; #define WAIT_V(n) asm volatile("s_waitcnt vmcnt(" #n ")" ::: "memory")
; #define WAIT_L(n) asm volatile("s_waitcnt lgkmcnt(" #n ")" ::: "memory")
; #define BAR __builtin_amdgcn_s_barrier()
; template <int EPI, int lda, int ldb, int N, int K>
; __device__ __forceinline__ void gemm_phase(const u16* __restrict__ A, const u16* __restrict__ Bt, const GemmEpi ep, int wv) {
;     ...
;     { LDB(B0, 1, 0); LDA(At, 1, 0); WAIT_V(2); BAR; WAIT_L(0); MMA(0, 0, At, B0); BAR;
;       LDB(B1, 1, 1); WAIT_V(0); BAR; WAIT_L(0); MMA(0, 1, At, B1); BAR;
;       LDA(At, 1, 1); BAR; WAIT_L(0); MMA(1, 0, At, B0); MMA(1, 1, At, B1); BAR; }
;     if (wr == 0) BAR;
	s_waitcnt lgkmcnt(0)
	s_waitcnt lgkmcnt(0)
	v_mfma_f32_16x16x32_bf16 v[64:67], v[4:7], v[24:27], v[124:127]
	v_mfma_f32_16x16x32_bf16 v[68:71], v[20:23], v[24:27], v[120:123]
	v_mfma_f32_16x16x32_bf16 v[80:83], v[4:7], v[198:201], v[116:119]
	v_mfma_f32_16x16x32_bf16 v[84:87], v[20:23], v[198:201], v[112:115]
	v_mfma_f32_16x16x32_bf16 v[108:111], v[4:7], v[206:209], v[108:111]
	v_mfma_f32_16x16x32_bf16 v[104:107], v[20:23], v[206:209], v[104:107]
	v_mfma_f32_16x16x32_bf16 v[120:123], v[4:7], v[214:217], v[100:103]
	v_mfma_f32_16x16x32_bf16 v[124:127], v[20:23], v[214:217], v[96:99]
	v_mfma_f32_16x16x32_bf16 v[116:119], v[8:11], v[194:197], v[64:67]
	v_mfma_f32_16x16x32_bf16 v[112:115], v[158:161], v[194:197], v[68:71]
	v_mfma_f32_16x16x32_bf16 v[100:103], v[8:11], v[202:205], v[80:83]
	v_mfma_f32_16x16x32_bf16 v[96:99], v[158:161], v[202:205], v[84:87]
	v_mfma_f32_16x16x32_bf16 v[84:87], v[8:11], v[210:213], v[108:111]
	v_mfma_f32_16x16x32_bf16 v[80:83], v[158:161], v[210:213], v[104:107]
	v_mfma_f32_16x16x32_bf16 v[68:71], v[8:11], v[218:221], v[120:123]
	v_mfma_f32_16x16x32_bf16 v[64:67], v[158:161], v[218:221], v[124:127]
	s_barrier
	ds_read_b128 v[222:225], v157
	ds_read_b128 v[226:229], v157 offset:1024
	ds_read_b128 v[230:233], v157 offset:2048
	ds_read_b128 v[234:237], v157 offset:3072
	s_waitcnt vmcnt(0)
	s_barrier
	s_waitcnt lgkmcnt(0)
	s_waitcnt lgkmcnt(0)
	v_mfma_f32_16x16x32_bf16 v[92:95], v[222:225], v[24:27], v[92:95]
	v_mfma_f32_16x16x32_bf16 v[24:27], v[230:233], v[24:27], v[88:91]
	v_mfma_f32_16x16x32_bf16 v[88:91], v[222:225], v[198:201], v[178:181]
	v_mfma_f32_16x16x32_bf16 v[104:107], v[230:233], v[198:201], v[182:185]
	v_mfma_f32_16x16x32_bf16 v[76:79], v[222:225], v[206:209], v[76:79]
	v_mfma_f32_16x16x32_bf16 v[72:75], v[230:233], v[206:209], v[72:75]
	v_mfma_f32_16x16x32_bf16 v[176:179], v[222:225], v[214:217], v[186:189]
	v_mfma_f32_16x16x32_bf16 v[180:183], v[230:233], v[214:217], v[190:193]
	v_mfma_f32_16x16x32_bf16 v[124:127], v[226:229], v[194:197], v[92:95]
	v_mfma_f32_16x16x32_bf16 v[120:123], v[234:237], v[194:197], v[24:27]
	v_mfma_f32_16x16x32_bf16 v[108:111], v[226:229], v[202:205], v[88:91]
	v_mfma_f32_16x16x32_bf16 v[104:107], v[234:237], v[202:205], v[104:107]
	v_mfma_f32_16x16x32_bf16 v[92:95], v[226:229], v[210:213], v[76:79]
	v_mfma_f32_16x16x32_bf16 v[88:91], v[234:237], v[210:213], v[72:75]
	v_mfma_f32_16x16x32_bf16 v[76:79], v[226:229], v[218:221], v[176:179]
	v_mfma_f32_16x16x32_bf16 v[72:75], v[234:237], v[218:221], v[180:183]
	s_barrier
	ds_read_b128 v[176:179], v155 offset:49152
	ds_read_b128 v[180:183], v155 offset:50176
	ds_read_b128 v[184:187], v154 offset:49152
	ds_read_b128 v[154:157], v154 offset:50176
	ds_read_b128 v[188:191], v153 offset:49152
	ds_read_b128 v[192:195], v153 offset:50176
	ds_read_b128 v[196:199], v152 offset:49152
	ds_read_b128 v[200:203], v152 offset:50176
	s_barrier
	s_waitcnt lgkmcnt(0)
	s_waitcnt lgkmcnt(0)
	v_mfma_f32_16x16x32_bf16 v[24:27], v[4:7], v[176:179], v[60:63]
	v_mfma_f32_16x16x32_bf16 v[60:63], v[20:23], v[176:179], v[56:59]
	v_mfma_f32_16x16x32_bf16 v[204:207], v[4:7], v[184:187], v[52:55]
	v_mfma_f32_16x16x32_bf16 v[48:51], v[20:23], v[184:187], v[48:51]
	v_mfma_f32_16x16x32_bf16 v[44:47], v[4:7], v[188:191], v[44:47]
	v_mfma_f32_16x16x32_bf16 v[208:211], v[20:23], v[188:191], v[40:43]
	v_mfma_f32_16x16x32_bf16 v[4:7], v[4:7], v[196:199], v[36:39]
	v_mfma_f32_16x16x32_bf16 v[32:35], v[20:23], v[196:199], v[32:35]
	v_mfma_f32_16x16x32_bf16 v[56:59], v[8:11], v[180:183], v[24:27]
	v_mfma_f32_16x16x32_bf16 v[52:55], v[158:161], v[180:183], v[60:63]
	v_mfma_f32_16x16x32_bf16 v[40:43], v[8:11], v[154:157], v[204:207]
	v_mfma_f32_16x16x32_bf16 v[36:39], v[158:161], v[154:157], v[48:51]
	v_mfma_f32_16x16x32_bf16 v[24:27], v[8:11], v[192:195], v[44:47]
	v_mfma_f32_16x16x32_bf16 v[20:23], v[158:161], v[192:195], v[208:211]
	v_mfma_f32_16x16x32_bf16 v[8:11], v[8:11], v[200:203], v[4:7]
	v_mfma_f32_16x16x32_bf16 v[4:7], v[158:161], v[200:203], v[32:35]
	v_mfma_f32_16x16x32_bf16 v[28:31], v[222:225], v[176:179], v[28:31]
	v_mfma_f32_16x16x32_bf16 v[32:35], v[230:233], v[176:179], v[134:137]
	v_mfma_f32_16x16x32_bf16 v[44:47], v[222:225], v[184:187], v[138:141]
	v_mfma_f32_16x16x32_bf16 v[16:19], v[230:233], v[184:187], v[16:19]
	v_mfma_f32_16x16x32_bf16 v[12:15], v[222:225], v[188:191], v[12:15]
	v_mfma_f32_16x16x32_bf16 v[134:137], v[230:233], v[188:191], v[142:145]
	v_mfma_f32_16x16x32_bf16 v[138:141], v[222:225], v[196:199], v[172:175]
	v_mfma_f32_16x16x32_bf16 v[0:3], v[230:233], v[196:199], v[0:3]
	v_mfma_f32_16x16x32_bf16 v[60:63], v[226:229], v[180:183], v[28:31]
	v_mfma_f32_16x16x32_bf16 v[48:51], v[234:237], v[180:183], v[32:35]
	v_mfma_f32_16x16x32_bf16 v[44:47], v[226:229], v[154:157], v[44:47]
	v_mfma_f32_16x16x32_bf16 v[32:35], v[234:237], v[154:157], v[16:19]
	v_mfma_f32_16x16x32_bf16 v[28:31], v[226:229], v[192:195], v[12:15]
	v_mfma_f32_16x16x32_bf16 v[16:19], v[234:237], v[192:195], v[134:137]
	v_mfma_f32_16x16x32_bf16 v[12:15], v[226:229], v[200:203], v[138:141]
	v_mfma_f32_16x16x32_bf16 v[0:3], v[234:237], v[200:203], v[0:3]
	v_cmp_gt_u32_e32 vcc, s69, v130
	s_barrier
	s_and_saveexec_b64 s[50:51], vcc
	s_cbranch_execz .LBB0_841
	s_barrier

; #define STAGE(P, BASE, LD, br, kt) do { const char* _g = (const char*)((BASE) + (size_t)(br) * (LD) + (size_t)(kt) * 64); \
;     for (int _i = 0; _i < 2; ++_i) { int _b = tidx * 16 + _i * 8192; int _r, _c; stage_rc(_b, _r, _c); \
;       __builtin_amdgcn_global_load_lds((const unsigned*)(_g + (unsigned)((_r * (LD) + _c) * 2)), (unsigned*)((char*)(P) + _b), 16, 0, 0); } } while (0)
; #define LDA(dst, b, h) for (int m = 0; m < 4; ++m) for (int k = 0; k < 2; ++k) \
;     dst[m][k] = *reinterpret_cast<const bf16x8*>((char*)SA(b, h) + lds_byte(wr * 64 + m * 16 + fr, k * 32 + fq * 8))
; #define LDB(dst, b, h) for (int n = 0; n < 2; ++n) for (int k = 0; k < 2; ++k) \
;     dst[n][k] = *reinterpret_cast<const bf16x8*>((char*)SB(b, h) + lds_byte(wc * 32 + n * 16 + fr, k * 32 + fq * 8))
; #define MMA(ai, bj, At_, Bt_) do { __builtin_amdgcn_s_setprio(1); \
;     for (int k = 0; k < 2; ++k) for (int m = 0; m < 4; ++m) for (int n = 0; n < 2; ++n) \
;       acc[ai][bj][m][n] = __builtin_amdgcn_mfma_f32_16x16x32_bf16(At_[m][k], Bt_[n][k], acc[ai][bj][m][n], 0, 0, 0); \
;     __builtin_amdgcn_s_setprio(0); } while (0)
; #define WAIT_L(n) asm volatile("s_waitcnt lgkmcnt(" #n ")" ::: "memory")
; #define BAR __builtin_amdgcn_s_barrier()
; #define SCHED __builtin_amdgcn_sched_barrier(0)
; template <int EPI, int lda, int ldb, int N, int K>
; __device__ __forceinline__ void gemm_phase(const u16* __restrict__ A, const u16* __restrict__ Bt, const GemmEpi ep, int wv) {
;     ...
;       LDB(B0, 0, 0); SCHED; LDA(At, 0, 0); STAGE(SA(1, 1), Ab, lda, brow + HALF, t + 1);
;       WAIT_L(8); BAR; WAIT_L(0); MMA(0, 0, At, B0); BAR; SCHED;
;       LDB(B1, 0, 1); STAGE(SB(0, 0), Bt, ldb, bcol, t + 2);
;       BAR; WAIT_L(0); MMA(0, 1, At, B1); BAR;
;       LDA(At, 0, 1); STAGE(SA(0, 0), Ab, lda, brow, t + 2);
;       BAR; WAIT_L(0); MMA(1, 0, At, B0); BAR; SCHED;
.LBB0_1147:
	ds_read_b128 v[172:175], v161
	ds_read_b128 v[176:179], v161 offset:1024
	ds_read_b128 v[180:183], v161 offset:2048
	ds_read_b128 v[184:187], v161 offset:3072
	v_add_u32_e32 v169, 0xc000, v148
	v_lshl_add_u64 v[236:237], v[138:139], 0, s[60:61]
	v_readfirstlane_b32 s63, v169
	v_add_u32_e32 v170, 0xe000, v148
	v_lshl_add_u64 v[162:163], v[236:237], 0, s[22:23]
	s_mov_b32 m0, s63
	v_lshl_add_u64 v[238:239], v[140:141], 0, s[60:61]
	v_readfirstlane_b32 s63, v170
	ds_read_b128 v[164:167], v152
	ds_read_b128 v[188:191], v152 offset:1024
	ds_read_b128 v[192:195], v151
	ds_read_b128 v[196:199], v151 offset:1024
	ds_read_b128 v[200:203], v150
	ds_read_b128 v[204:207], v150 offset:1024
	ds_read_b128 v[208:211], v149
	ds_read_b128 v[212:215], v149 offset:1024
	global_load_lds_dwordx4 v[162:163], off
	s_waitcnt lgkmcnt(8)
	s_barrier
	s_waitcnt lgkmcnt(0)
	s_waitcnt lgkmcnt(0)
	v_mfma_f32_16x16x32_bf16 v[124:127], v[164:167], v[172:175], v[124:127]
	v_mfma_f32_16x16x32_bf16 v[120:123], v[164:167], v[180:183], v[120:123]
	v_mfma_f32_16x16x32_bf16 v[116:119], v[192:195], v[172:175], v[116:119]
	v_mfma_f32_16x16x32_bf16 v[112:115], v[192:195], v[180:183], v[112:115]
	v_mfma_f32_16x16x32_bf16 v[108:111], v[200:203], v[172:175], v[108:111]
	v_mfma_f32_16x16x32_bf16 v[104:107], v[200:203], v[180:183], v[104:107]
	v_mfma_f32_16x16x32_bf16 v[100:103], v[208:211], v[172:175], v[100:103]
	v_mfma_f32_16x16x32_bf16 v[96:99], v[208:211], v[180:183], v[96:99]
	v_lshl_add_u64 v[162:163], v[238:239], 0, s[22:23]
	s_mov_b32 m0, s63
	s_nop 0
	global_load_lds_dwordx4 v[162:163], off
	v_mfma_f32_16x16x32_bf16 v[124:127], v[188:191], v[176:179], v[124:127]
	v_mfma_f32_16x16x32_bf16 v[120:123], v[188:191], v[184:187], v[120:123]
	v_mfma_f32_16x16x32_bf16 v[116:119], v[196:199], v[176:179], v[116:119]
	v_mfma_f32_16x16x32_bf16 v[112:115], v[196:199], v[184:187], v[112:115]
	v_mfma_f32_16x16x32_bf16 v[108:111], v[204:207], v[176:179], v[108:111]
	v_mfma_f32_16x16x32_bf16 v[104:107], v[204:207], v[184:187], v[104:107]
	v_mfma_f32_16x16x32_bf16 v[100:103], v[212:215], v[176:179], v[100:103]
	v_mfma_f32_16x16x32_bf16 v[96:99], v[212:215], v[184:187], v[96:99]
	s_barrier
	v_add_u32_e32 v162, s75, v154
	v_lshl_add_u64 v[240:241], v[134:135], 0, s[60:61]
	v_readfirstlane_b32 s63, v162
	v_add_u32_e32 v163, 0x2000, v162
	v_lshl_add_u64 v[232:233], v[240:241], 0, s[24:25]
	s_mov_b32 m0, s63
	v_lshl_add_u64 v[242:243], v[136:137], 0, s[60:61]
	v_readfirstlane_b32 s63, v163
	ds_read_b128 v[216:219], v160
	ds_read_b128 v[220:223], v160 offset:1024
	ds_read_b128 v[224:227], v160 offset:2048
	ds_read_b128 v[228:231], v160 offset:3072
	global_load_lds_dwordx4 v[232:233], off
	v_lshl_add_u64 v[232:233], v[242:243], 0, s[24:25]
	s_mov_b32 m0, s63
	s_nop 0
	global_load_lds_dwordx4 v[232:233], off
	s_barrier
	s_waitcnt lgkmcnt(0)
	s_waitcnt lgkmcnt(0)
	v_mfma_f32_16x16x32_bf16 v[92:95], v[164:167], v[216:219], v[92:95]
	v_mfma_f32_16x16x32_bf16 v[88:91], v[164:167], v[224:227], v[88:91]
	v_mfma_f32_16x16x32_bf16 v[84:87], v[192:195], v[216:219], v[84:87]
	v_mfma_f32_16x16x32_bf16 v[80:83], v[192:195], v[224:227], v[80:83]
	v_mfma_f32_16x16x32_bf16 v[76:79], v[200:203], v[216:219], v[76:79]
	v_mfma_f32_16x16x32_bf16 v[72:75], v[200:203], v[224:227], v[72:75]
	v_mfma_f32_16x16x32_bf16 v[68:71], v[208:211], v[216:219], v[68:71]
	v_mfma_f32_16x16x32_bf16 v[64:67], v[208:211], v[224:227], v[64:67]
	v_mfma_f32_16x16x32_bf16 v[92:95], v[188:191], v[220:223], v[92:95]
	v_mfma_f32_16x16x32_bf16 v[88:91], v[188:191], v[228:231], v[88:91]
	v_mfma_f32_16x16x32_bf16 v[84:87], v[196:199], v[220:223], v[84:87]
	v_mfma_f32_16x16x32_bf16 v[80:83], v[196:199], v[228:231], v[80:83]
	v_mfma_f32_16x16x32_bf16 v[76:79], v[204:207], v[220:223], v[76:79]
	v_mfma_f32_16x16x32_bf16 v[72:75], v[204:207], v[228:231], v[72:75]
	v_mfma_f32_16x16x32_bf16 v[68:71], v[212:215], v[220:223], v[68:71]
	v_mfma_f32_16x16x32_bf16 v[64:67], v[212:215], v[228:231], v[64:67]
	s_barrier
	v_readfirstlane_b32 s63, v148
	v_lshl_add_u64 v[164:165], v[236:237], 0, s[26:27]
	s_mov_b32 m0, s63
	ds_read_b128 v[188:191], v152 offset:16384
	ds_read_b128 v[192:195], v152 offset:17408
	ds_read_b128 v[196:199], v151 offset:16384
	ds_read_b128 v[200:203], v151 offset:17408
	ds_read_b128 v[204:207], v150 offset:16384
	ds_read_b128 v[208:211], v150 offset:17408
	ds_read_b128 v[212:215], v149 offset:16384
	ds_read_b128 v[232:235], v149 offset:17408
	global_load_lds_dwordx4 v[164:165], off
	v_add_u32_e32 v164, 0x2000, v148
	v_lshl_add_u64 v[166:167], v[238:239], 0, s[26:27]
	v_readfirstlane_b32 s63, v164
	s_mov_b32 m0, s63
	s_nop 0
	global_load_lds_dwordx4 v[166:167], off
	s_barrier
	s_waitcnt lgkmcnt(0)
	s_waitcnt lgkmcnt(0)
	v_mfma_f32_16x16x32_bf16 v[60:63], v[188:191], v[172:175], v[60:63]
	v_mfma_f32_16x16x32_bf16 v[56:59], v[188:191], v[180:183], v[56:59]
	v_mfma_f32_16x16x32_bf16 v[52:55], v[196:199], v[172:175], v[52:55]
	v_mfma_f32_16x16x32_bf16 v[48:51], v[196:199], v[180:183], v[48:51]
	v_mfma_f32_16x16x32_bf16 v[44:47], v[204:207], v[172:175], v[44:47]
	v_mfma_f32_16x16x32_bf16 v[40:43], v[204:207], v[180:183], v[40:43]
	v_mfma_f32_16x16x32_bf16 v[36:39], v[212:215], v[172:175], v[36:39]
	v_mfma_f32_16x16x32_bf16 v[32:35], v[212:215], v[180:183], v[32:35]
	v_mfma_f32_16x16x32_bf16 v[60:63], v[192:195], v[176:179], v[60:63]
	v_mfma_f32_16x16x32_bf16 v[56:59], v[192:195], v[184:187], v[56:59]
	v_mfma_f32_16x16x32_bf16 v[52:55], v[200:203], v[176:179], v[52:55]
	v_mfma_f32_16x16x32_bf16 v[48:51], v[200:203], v[184:187], v[48:51]
	v_mfma_f32_16x16x32_bf16 v[44:47], v[208:211], v[176:179], v[44:47]
	v_mfma_f32_16x16x32_bf16 v[40:43], v[208:211], v[184:187], v[40:43]
	v_mfma_f32_16x16x32_bf16 v[36:39], v[232:235], v[176:179], v[36:39]
	v_mfma_f32_16x16x32_bf16 v[32:35], v[232:235], v[184:187], v[32:35]
	s_barrier
; #define STAGE(P, BASE, LD, br, kt) do { const char* _g = (const char*)((BASE) + (size_t)(br) * (LD) + (size_t)(kt) * 64); \
;     for (int _i = 0; _i < 2; ++_i) { int _b = tidx * 16 + _i * 8192; int _r, _c; stage_rc(_b, _r, _c); \
;       __builtin_amdgcn_global_load_lds((const unsigned*)(_g + (unsigned)((_r * (LD) + _c) * 2)), (unsigned*)((char*)(P) + _b), 16, 0, 0); } } while (0)
; #define LDA(dst, b, h) for (int m = 0; m < 4; ++m) for (int k = 0; k < 2; ++k) \
;     dst[m][k] = *reinterpret_cast<const bf16x8*>((char*)SA(b, h) + lds_byte(wr * 64 + m * 16 + fr, k * 32 + fq * 8))
; #define LDB(dst, b, h) for (int n = 0; n < 2; ++n) for (int k = 0; k < 2; ++k) \
;     dst[n][k] = *reinterpret_cast<const bf16x8*>((char*)SB(b, h) + lds_byte(wc * 32 + n * 16 + fr, k * 32 + fq * 8))
; #define MMA(ai, bj, At_, Bt_) do { __builtin_amdgcn_s_setprio(1); \
;     for (int k = 0; k < 2; ++k) for (int m = 0; m < 4; ++m) for (int n = 0; n < 2; ++n) \
;       acc[ai][bj][m][n] = __builtin_amdgcn_mfma_f32_16x16x32_bf16(At_[m][k], Bt_[n][k], acc[ai][bj][m][n], 0, 0, 0); \
;     __builtin_amdgcn_s_setprio(0); } while (0)
; #define WAIT_V(n) asm volatile("s_waitcnt vmcnt(" #n ")" ::: "memory")
; #define WAIT_L(n) asm volatile("s_waitcnt lgkmcnt(" #n ")" ::: "memory")
; #define BAR __builtin_amdgcn_s_barrier()
; #define SCHED __builtin_amdgcn_sched_barrier(0)
; template <int EPI, int lda, int ldb, int N, int K>
; __device__ __forceinline__ void gemm_phase(const u16* __restrict__ A, const u16* __restrict__ Bt, const GemmEpi ep, int wv) {
;     ...
;       STAGE(SB(0, 1), Bt, ldb, bcol + HALF, t + 2);
;       WAIT_V(6); BAR; MMA(1, 1, At, B1); BAR;
;       LDB(B0, 1, 0); SCHED; LDA(At, 1, 0); STAGE(SA(0, 1), Ab, lda, brow + HALF, t + 2);
;       WAIT_L(8); BAR; WAIT_L(0); MMA(0, 0, At, B0); BAR; SCHED;
;       LDB(B1, 1, 1); STAGE(SB(1, 0), Bt, ldb, bcol, t + 3);
;       BAR; WAIT_L(0); MMA(0, 1, At, B1); BAR;
;       LDA(At, 1, 1); STAGE(SA(1, 0), Ab, lda, brow, t + 3);
	v_add_u32_e32 v165, s76, v154
	v_lshl_add_u64 v[166:167], v[240:241], 0, s[40:41]
	v_readfirstlane_b32 s63, v165
	s_mov_b32 m0, s63
	v_lshl_add_u64 v[172:173], v[242:243], 0, s[40:41]
	global_load_lds_dwordx4 v[166:167], off
	v_add_u32_e32 v166, 0x2000, v165
	s_nop 0
	v_readfirstlane_b32 s63, v166
	s_mov_b32 m0, s63
	s_nop 0
	global_load_lds_dwordx4 v[172:173], off
	s_waitcnt vmcnt(6)
	s_barrier
	v_mfma_f32_16x16x32_bf16 v[28:31], v[188:191], v[216:219], v[28:31]
	v_mfma_f32_16x16x32_bf16 v[24:27], v[188:191], v[224:227], v[24:27]
	v_mfma_f32_16x16x32_bf16 v[20:23], v[196:199], v[216:219], v[20:23]
	v_mfma_f32_16x16x32_bf16 v[16:19], v[196:199], v[224:227], v[16:19]
	v_mfma_f32_16x16x32_bf16 v[12:15], v[204:207], v[216:219], v[12:15]
	v_mfma_f32_16x16x32_bf16 v[8:11], v[204:207], v[224:227], v[8:11]
	v_mfma_f32_16x16x32_bf16 v[4:7], v[212:215], v[216:219], v[4:7]
	v_mfma_f32_16x16x32_bf16 v[0:3], v[212:215], v[224:227], v[0:3]
	v_mfma_f32_16x16x32_bf16 v[28:31], v[192:195], v[220:223], v[28:31]
	v_mfma_f32_16x16x32_bf16 v[24:27], v[192:195], v[228:231], v[24:27]
	v_mfma_f32_16x16x32_bf16 v[20:23], v[200:203], v[220:223], v[20:23]
	v_mfma_f32_16x16x32_bf16 v[16:19], v[200:203], v[228:231], v[16:19]
	v_mfma_f32_16x16x32_bf16 v[12:15], v[208:211], v[220:223], v[12:15]
	v_mfma_f32_16x16x32_bf16 v[8:11], v[208:211], v[228:231], v[8:11]
	v_mfma_f32_16x16x32_bf16 v[4:7], v[232:235], v[220:223], v[4:7]
	v_mfma_f32_16x16x32_bf16 v[0:3], v[232:235], v[228:231], v[0:3]
	s_barrier
	ds_read_b128 v[172:175], v155
	ds_read_b128 v[176:179], v155 offset:1024
	ds_read_b128 v[180:183], v155 offset:2048
	ds_read_b128 v[184:187], v155 offset:3072
	v_add_u32_e32 v167, 0x4000, v148
	v_add_u32_e32 v168, 0x6000, v148
	v_readfirstlane_b32 s63, v167
	v_lshl_add_u64 v[220:221], v[236:237], 0, s[42:43]
	s_mov_b32 m0, s63
	v_readfirstlane_b32 s63, v168
	ds_read_b128 v[188:191], v152 offset:32768
	ds_read_b128 v[192:195], v152 offset:33792
	ds_read_b128 v[196:199], v151 offset:32768
	ds_read_b128 v[200:203], v151 offset:33792
	ds_read_b128 v[204:207], v150 offset:32768
	ds_read_b128 v[208:211], v150 offset:33792
	ds_read_b128 v[212:215], v149 offset:32768
	ds_read_b128 v[216:219], v149 offset:33792
	global_load_lds_dwordx4 v[220:221], off
	s_waitcnt lgkmcnt(8)
	s_barrier
	s_waitcnt lgkmcnt(0)
	s_waitcnt lgkmcnt(0)
	v_mfma_f32_16x16x32_bf16 v[124:127], v[188:191], v[172:175], v[124:127]
	v_mfma_f32_16x16x32_bf16 v[120:123], v[188:191], v[180:183], v[120:123]
	v_mfma_f32_16x16x32_bf16 v[116:119], v[196:199], v[172:175], v[116:119]
	v_mfma_f32_16x16x32_bf16 v[112:115], v[196:199], v[180:183], v[112:115]
	v_mfma_f32_16x16x32_bf16 v[108:111], v[204:207], v[172:175], v[108:111]
	v_mfma_f32_16x16x32_bf16 v[104:107], v[204:207], v[180:183], v[104:107]
	v_mfma_f32_16x16x32_bf16 v[100:103], v[212:215], v[172:175], v[100:103]
	v_mfma_f32_16x16x32_bf16 v[96:99], v[212:215], v[180:183], v[96:99]
	v_lshl_add_u64 v[220:221], v[238:239], 0, s[42:43]
	s_mov_b32 m0, s63
	s_nop 0
	global_load_lds_dwordx4 v[220:221], off
	v_mfma_f32_16x16x32_bf16 v[124:127], v[192:195], v[176:179], v[124:127]
	v_mfma_f32_16x16x32_bf16 v[120:123], v[192:195], v[184:187], v[120:123]
	v_mfma_f32_16x16x32_bf16 v[116:119], v[200:203], v[176:179], v[116:119]
	v_mfma_f32_16x16x32_bf16 v[112:115], v[200:203], v[184:187], v[112:115]
	v_mfma_f32_16x16x32_bf16 v[108:111], v[208:211], v[176:179], v[108:111]
	v_mfma_f32_16x16x32_bf16 v[104:107], v[208:211], v[184:187], v[104:107]
	v_mfma_f32_16x16x32_bf16 v[100:103], v[216:219], v[176:179], v[100:103]
	v_mfma_f32_16x16x32_bf16 v[96:99], v[216:219], v[184:187], v[96:99]
	s_barrier
	v_readfirstlane_b32 s63, v156
	v_add_u32_e32 v171, 0x2000, v156
	v_lshl_add_u64 v[244:245], v[240:241], 0, s[44:45]
	s_mov_b32 m0, s63
	v_readfirstlane_b32 s63, v171
	ds_read_b128 v[220:223], v153
	ds_read_b128 v[224:227], v153 offset:1024
	ds_read_b128 v[228:231], v153 offset:2048
	ds_read_b128 v[232:235], v153 offset:3072
	global_load_lds_dwordx4 v[244:245], off
	v_lshl_add_u64 v[244:245], v[242:243], 0, s[44:45]
	s_mov_b32 m0, s63
	s_nop 0
	global_load_lds_dwordx4 v[244:245], off
	s_barrier
	s_waitcnt lgkmcnt(0)
	s_waitcnt lgkmcnt(0)
	v_mfma_f32_16x16x32_bf16 v[92:95], v[188:191], v[220:223], v[92:95]
	v_mfma_f32_16x16x32_bf16 v[88:91], v[188:191], v[228:231], v[88:91]
	v_mfma_f32_16x16x32_bf16 v[84:87], v[196:199], v[220:223], v[84:87]
	v_mfma_f32_16x16x32_bf16 v[80:83], v[196:199], v[228:231], v[80:83]
	v_mfma_f32_16x16x32_bf16 v[76:79], v[204:207], v[220:223], v[76:79]
	v_mfma_f32_16x16x32_bf16 v[72:75], v[204:207], v[228:231], v[72:75]
	v_mfma_f32_16x16x32_bf16 v[68:71], v[212:215], v[220:223], v[68:71]
	v_mfma_f32_16x16x32_bf16 v[64:67], v[212:215], v[228:231], v[64:67]
	v_mfma_f32_16x16x32_bf16 v[92:95], v[192:195], v[224:227], v[92:95]
	v_mfma_f32_16x16x32_bf16 v[88:91], v[192:195], v[232:235], v[88:91]
	v_mfma_f32_16x16x32_bf16 v[84:87], v[200:203], v[224:227], v[84:87]
	v_mfma_f32_16x16x32_bf16 v[80:83], v[200:203], v[232:235], v[80:83]
	v_mfma_f32_16x16x32_bf16 v[76:79], v[208:211], v[224:227], v[76:79]
	v_mfma_f32_16x16x32_bf16 v[72:75], v[208:211], v[232:235], v[72:75]
	v_mfma_f32_16x16x32_bf16 v[68:71], v[216:219], v[224:227], v[68:71]
	v_mfma_f32_16x16x32_bf16 v[64:67], v[216:219], v[232:235], v[64:67]
	s_barrier
	v_readfirstlane_b32 s63, v157
	v_lshl_add_u64 v[236:237], v[236:237], 0, s[46:47]
	s_mov_b32 m0, s63
	v_readfirstlane_b32 s63, v158
	ds_read_b128 v[188:191], v152 offset:49152
	ds_read_b128 v[192:195], v152 offset:50176
	ds_read_b128 v[196:199], v151 offset:49152
	ds_read_b128 v[200:203], v151 offset:50176
	ds_read_b128 v[204:207], v150 offset:49152
	ds_read_b128 v[208:211], v150 offset:50176
	ds_read_b128 v[212:215], v149 offset:49152
	ds_read_b128 v[216:219], v149 offset:50176
	global_load_lds_dwordx4 v[236:237], off
	v_lshl_add_u64 v[236:237], v[238:239], 0, s[46:47]
	s_mov_b32 m0, s63
	s_nop 0
	global_load_lds_dwordx4 v[236:237], off
	s_barrier
; #define STAGE(P, BASE, LD, br, kt) do { const char* _g = (const char*)((BASE) + (size_t)(br) * (LD) + (size_t)(kt) * 64); \
;     for (int _i = 0; _i < 2; ++_i) { int _b = tidx * 16 + _i * 8192; int _r, _c; stage_rc(_b, _r, _c); \
;       __builtin_amdgcn_global_load_lds((const unsigned*)(_g + (unsigned)((_r * (LD) + _c) * 2)), (unsigned*)((char*)(P) + _b), 16, 0, 0); } } while (0)
; #define LDA(dst, b, h) for (int m = 0; m < 4; ++m) for (int k = 0; k < 2; ++k) \
;     dst[m][k] = *reinterpret_cast<const bf16x8*>((char*)SA(b, h) + lds_byte(wr * 64 + m * 16 + fr, k * 32 + fq * 8))
; #define LDB(dst, b, h) for (int n = 0; n < 2; ++n) for (int k = 0; k < 2; ++k) \
;     dst[n][k] = *reinterpret_cast<const bf16x8*>((char*)SB(b, h) + lds_byte(wc * 32 + n * 16 + fr, k * 32 + fq * 8))
; #define MMA(ai, bj, At_, Bt_) do { __builtin_amdgcn_s_setprio(1); \
;     for (int k = 0; k < 2; ++k) for (int m = 0; m < 4; ++m) for (int n = 0; n < 2; ++n) \
;       acc[ai][bj][m][n] = __builtin_amdgcn_mfma_f32_16x16x32_bf16(At_[m][k], Bt_[n][k], acc[ai][bj][m][n], 0, 0, 0); \
;     __builtin_amdgcn_s_setprio(0); } while (0)
; #define WAIT_V(n) asm volatile("s_waitcnt vmcnt(" #n ")" ::: "memory")
; #define WAIT_L(n) asm volatile("s_waitcnt lgkmcnt(" #n ")" ::: "memory")
; #define BAR __builtin_amdgcn_s_barrier()
; #define SCHED __builtin_amdgcn_sched_barrier(0)
; template <int EPI, int lda, int ldb, int N, int K>
; __device__ __forceinline__ void gemm_phase(const u16* __restrict__ A, const u16* __restrict__ Bt, const GemmEpi ep, int wv) {
;     ...
;       BAR; WAIT_L(0); MMA(1, 0, At, B0); BAR; SCHED;
;       STAGE(SB(1, 1), Bt, ldb, bcol + HALF, t + 3);
;       WAIT_V(6); BAR; MMA(1, 1, At, B1); BAR;
;     }
;     { LDB(B0, 0, 0); LDA(At, 0, 0); STAGE(SA(1, 1), Ab, lda, brow + HALF, nt - 1);
;       BAR; WAIT_L(0); MMA(0, 0, At, B0); BAR;
;       LDB(B1, 0, 1); BAR; WAIT_L(0); MMA(0, 1, At, B1); BAR;
	s_waitcnt lgkmcnt(0)
	s_waitcnt lgkmcnt(0)
	v_mfma_f32_16x16x32_bf16 v[60:63], v[188:191], v[172:175], v[60:63]
	v_mfma_f32_16x16x32_bf16 v[56:59], v[188:191], v[180:183], v[56:59]
	v_mfma_f32_16x16x32_bf16 v[52:55], v[196:199], v[172:175], v[52:55]
	v_mfma_f32_16x16x32_bf16 v[48:51], v[196:199], v[180:183], v[48:51]
	v_mfma_f32_16x16x32_bf16 v[44:47], v[204:207], v[172:175], v[44:47]
	v_mfma_f32_16x16x32_bf16 v[40:43], v[204:207], v[180:183], v[40:43]
	v_mfma_f32_16x16x32_bf16 v[36:39], v[212:215], v[172:175], v[36:39]
	v_mfma_f32_16x16x32_bf16 v[32:35], v[212:215], v[180:183], v[32:35]
	v_mfma_f32_16x16x32_bf16 v[60:63], v[192:195], v[176:179], v[60:63]
	v_mfma_f32_16x16x32_bf16 v[56:59], v[192:195], v[184:187], v[56:59]
	v_mfma_f32_16x16x32_bf16 v[52:55], v[200:203], v[176:179], v[52:55]
	v_mfma_f32_16x16x32_bf16 v[48:51], v[200:203], v[184:187], v[48:51]
	v_mfma_f32_16x16x32_bf16 v[44:47], v[208:211], v[176:179], v[44:47]
	v_mfma_f32_16x16x32_bf16 v[40:43], v[208:211], v[184:187], v[40:43]
	v_mfma_f32_16x16x32_bf16 v[36:39], v[216:219], v[176:179], v[36:39]
	v_mfma_f32_16x16x32_bf16 v[32:35], v[216:219], v[184:187], v[32:35]
	s_barrier
	v_readfirstlane_b32 s63, v159
	v_add_u32_e32 v171, 0x2000, v159
	v_lshl_add_u64 v[172:173], v[240:241], 0, s[48:49]
	s_mov_b32 m0, s63
	v_readfirstlane_b32 s63, v171
	global_load_lds_dwordx4 v[172:173], off
	v_lshl_add_u64 v[172:173], v[242:243], 0, s[48:49]
	s_mov_b32 m0, s63
	s_nop 0
	global_load_lds_dwordx4 v[172:173], off
	s_waitcnt vmcnt(6)
	s_barrier
	v_mfma_f32_16x16x32_bf16 v[28:31], v[188:191], v[220:223], v[28:31]
	v_mfma_f32_16x16x32_bf16 v[24:27], v[188:191], v[228:231], v[24:27]
	v_mfma_f32_16x16x32_bf16 v[20:23], v[196:199], v[220:223], v[20:23]
	v_mfma_f32_16x16x32_bf16 v[16:19], v[196:199], v[228:231], v[16:19]
	v_mfma_f32_16x16x32_bf16 v[12:15], v[204:207], v[220:223], v[12:15]
	v_mfma_f32_16x16x32_bf16 v[8:11], v[204:207], v[228:231], v[8:11]
	v_mfma_f32_16x16x32_bf16 v[4:7], v[212:215], v[220:223], v[4:7]
	v_mfma_f32_16x16x32_bf16 v[0:3], v[212:215], v[228:231], v[0:3]
	v_mfma_f32_16x16x32_bf16 v[28:31], v[192:195], v[224:227], v[28:31]
	v_mfma_f32_16x16x32_bf16 v[24:27], v[192:195], v[232:235], v[24:27]
	v_mfma_f32_16x16x32_bf16 v[20:23], v[200:203], v[224:227], v[20:23]
	v_mfma_f32_16x16x32_bf16 v[16:19], v[200:203], v[232:235], v[16:19]
	v_mfma_f32_16x16x32_bf16 v[12:15], v[208:211], v[224:227], v[12:15]
	v_mfma_f32_16x16x32_bf16 v[8:11], v[208:211], v[232:235], v[8:11]
	v_mfma_f32_16x16x32_bf16 v[4:7], v[216:219], v[224:227], v[4:7]
	v_mfma_f32_16x16x32_bf16 v[0:3], v[216:219], v[232:235], v[0:3]
	s_add_i32 s62, s62, 2
	s_add_u32 s60, s60, 0x100
	s_addc_u32 s61, s61, 0
	s_cmp_gt_u32 s62, 27
	s_barrier
	s_cbranch_scc0 .LBB0_1147
	s_add_i32 s60, s58, 0x80
	s_mul_hi_i32 s61, s60, 0x1080
	s_mulk_i32 s60, 0x1080
	s_add_u32 s60, s69, s60
	s_addc_u32 s61, s70, s61
	v_lshl_add_u64 v[208:209], s[60:61], 0, v[128:129]
	v_readfirstlane_b32 s62, v169
	v_lshl_add_u64 v[208:209], v[208:209], 0, s[50:51]
	s_mov_b32 m0, s62
	ds_read_b128 v[134:137], v161
	ds_read_b128 v[138:141], v161 offset:1024
	ds_read_b128 v[156:159], v161 offset:2048
	ds_read_b128 v[172:175], v161 offset:3072
	ds_read_b128 v[176:179], v152
	ds_read_b128 v[180:183], v152 offset:1024
	ds_read_b128 v[184:187], v151
	ds_read_b128 v[188:191], v151 offset:1024
	ds_read_b128 v[192:195], v150
	ds_read_b128 v[196:199], v150 offset:1024
	ds_read_b128 v[200:203], v149
	ds_read_b128 v[204:207], v149 offset:1024
	global_load_lds_dwordx4 v[208:209], off
	v_lshl_add_u64 v[208:209], s[60:61], 0, v[132:133]
	v_readfirstlane_b32 s60, v170
	v_lshl_add_u64 v[208:209], v[208:209], 0, s[50:51]
	s_mov_b32 m0, s60
	s_nop 0
	global_load_lds_dwordx4 v[208:209], off
	s_barrier
	s_waitcnt lgkmcnt(0)
	s_waitcnt lgkmcnt(0)
	v_mfma_f32_16x16x32_bf16 v[124:127], v[176:179], v[134:137], v[124:127]
	v_mfma_f32_16x16x32_bf16 v[120:123], v[176:179], v[156:159], v[120:123]
	v_mfma_f32_16x16x32_bf16 v[116:119], v[184:187], v[134:137], v[116:119]
	v_mfma_f32_16x16x32_bf16 v[112:115], v[184:187], v[156:159], v[112:115]
	v_mfma_f32_16x16x32_bf16 v[108:111], v[192:195], v[134:137], v[108:111]
	v_mfma_f32_16x16x32_bf16 v[104:107], v[192:195], v[156:159], v[104:107]
	v_mfma_f32_16x16x32_bf16 v[100:103], v[200:203], v[134:137], v[100:103]
	v_mfma_f32_16x16x32_bf16 v[96:99], v[200:203], v[156:159], v[96:99]
	v_mfma_f32_16x16x32_bf16 v[124:127], v[180:183], v[138:141], v[124:127]
	v_mfma_f32_16x16x32_bf16 v[120:123], v[180:183], v[172:175], v[120:123]
	v_mfma_f32_16x16x32_bf16 v[116:119], v[188:191], v[138:141], v[116:119]
	v_mfma_f32_16x16x32_bf16 v[112:115], v[188:191], v[172:175], v[112:115]
	v_mfma_f32_16x16x32_bf16 v[108:111], v[196:199], v[138:141], v[108:111]
	v_mfma_f32_16x16x32_bf16 v[104:107], v[196:199], v[172:175], v[104:107]
	v_mfma_f32_16x16x32_bf16 v[100:103], v[204:207], v[138:141], v[100:103]
	v_mfma_f32_16x16x32_bf16 v[96:99], v[204:207], v[172:175], v[96:99]
	s_barrier
	ds_read_b128 v[208:211], v160
	ds_read_b128 v[212:215], v160 offset:1024
	ds_read_b128 v[216:219], v160 offset:2048
	ds_read_b128 v[220:223], v160 offset:3072
	s_barrier
; #define LDA(dst, b, h) for (int m = 0; m < 4; ++m) for (int k = 0; k < 2; ++k) \
;     dst[m][k] = *reinterpret_cast<const bf16x8*>((char*)SA(b, h) + lds_byte(wr * 64 + m * 16 + fr, k * 32 + fq * 8))
; #define LDB(dst, b, h) for (int n = 0; n < 2; ++n) for (int k = 0; k < 2; ++k) \
;     dst[n][k] = *reinterpret_cast<const bf16x8*>((char*)SB(b, h) + lds_byte(wc * 32 + n * 16 + fr, k * 32 + fq * 8))
; #define MMA(ai, bj, At_, Bt_) do { __builtin_amdgcn_s_setprio(1); \
;     for (int k = 0; k < 2; ++k) for (int m = 0; m < 4; ++m) for (int n = 0; n < 2; ++n) \
;       acc[ai][bj][m][n] = __builtin_amdgcn_mfma_f32_16x16x32_bf16(At_[m][k], Bt_[n][k], acc[ai][bj][m][n], 0, 0, 0); \
;     __builtin_amdgcn_s_setprio(0); } while (0)
; #define WAIT_V(n) asm volatile("s_waitcnt vmcnt(" #n ")" ::: "memory")
; #define WAIT_L(n) asm volatile("s_waitcnt lgkmcnt(" #n ")" ::: "memory")
; #define BAR __builtin_amdgcn_s_barrier()
; template <int EPI, int lda, int ldb, int N, int K>
; __device__ __forceinline__ void gemm_phase(const u16* __restrict__ A, const u16* __restrict__ Bt, const GemmEpi ep, int wv) {
;     ...
;       LDB(B1, 0, 1); BAR; WAIT_L(0); MMA(0, 1, At, B1); BAR;
;       LDA(At, 0, 1); WAIT_V(4); BAR; WAIT_L(0); MMA(1, 0, At, B0); MMA(1, 1, At, B1); BAR; }
;     { LDB(B0, 1, 0); LDA(At, 1, 0); WAIT_V(2); BAR; WAIT_L(0); MMA(0, 0, At, B0); BAR;
	s_waitcnt lgkmcnt(0)
	s_waitcnt lgkmcnt(0)
	v_mfma_f32_16x16x32_bf16 v[92:95], v[176:179], v[208:211], v[92:95]
	v_mfma_f32_16x16x32_bf16 v[88:91], v[176:179], v[216:219], v[88:91]
	v_mfma_f32_16x16x32_bf16 v[76:79], v[192:195], v[208:211], v[76:79]
	v_mfma_f32_16x16x32_bf16 v[72:75], v[192:195], v[216:219], v[72:75]
	v_mfma_f32_16x16x32_bf16 v[84:87], v[184:187], v[208:211], v[84:87]
	v_mfma_f32_16x16x32_bf16 v[80:83], v[184:187], v[216:219], v[80:83]
	v_mfma_f32_16x16x32_bf16 v[68:71], v[200:203], v[208:211], v[68:71]
	v_mfma_f32_16x16x32_bf16 v[64:67], v[200:203], v[216:219], v[64:67]
	v_mfma_f32_16x16x32_bf16 v[92:95], v[180:183], v[212:215], v[92:95]
	v_mfma_f32_16x16x32_bf16 v[88:91], v[180:183], v[220:223], v[88:91]
	v_mfma_f32_16x16x32_bf16 v[76:79], v[196:199], v[212:215], v[76:79]
	v_mfma_f32_16x16x32_bf16 v[72:75], v[196:199], v[220:223], v[72:75]
	v_mfma_f32_16x16x32_bf16 v[176:179], v[188:191], v[212:215], v[84:87]
	v_mfma_f32_16x16x32_bf16 v[180:183], v[188:191], v[220:223], v[80:83]
	v_mfma_f32_16x16x32_bf16 v[184:187], v[204:207], v[212:215], v[68:71]
	v_mfma_f32_16x16x32_bf16 v[188:191], v[204:207], v[220:223], v[64:67]
	s_barrier
	s_nop 0
	ds_read_b128 v[64:67], v152 offset:16384
	ds_read_b128 v[68:71], v152 offset:17408
	ds_read_b128 v[80:83], v151 offset:16384
	ds_read_b128 v[84:87], v151 offset:17408
	ds_read_b128 v[192:195], v150 offset:16384
	ds_read_b128 v[196:199], v150 offset:17408
	ds_read_b128 v[200:203], v149 offset:16384
	ds_read_b128 v[204:207], v149 offset:17408
	s_waitcnt vmcnt(4)
	s_barrier
	s_waitcnt lgkmcnt(0)
	s_waitcnt lgkmcnt(0)
	v_mfma_f32_16x16x32_bf16 v[60:63], v[64:67], v[134:137], v[60:63]
	v_mfma_f32_16x16x32_bf16 v[56:59], v[64:67], v[156:159], v[56:59]
	v_mfma_f32_16x16x32_bf16 v[52:55], v[80:83], v[134:137], v[52:55]
	v_mfma_f32_16x16x32_bf16 v[48:51], v[80:83], v[156:159], v[48:51]
	v_mfma_f32_16x16x32_bf16 v[44:47], v[192:195], v[134:137], v[44:47]
	v_mfma_f32_16x16x32_bf16 v[40:43], v[192:195], v[156:159], v[40:43]
	v_mfma_f32_16x16x32_bf16 v[36:39], v[200:203], v[134:137], v[36:39]
	v_mfma_f32_16x16x32_bf16 v[32:35], v[200:203], v[156:159], v[32:35]
	v_mfma_f32_16x16x32_bf16 v[60:63], v[68:71], v[138:141], v[60:63]
	v_mfma_f32_16x16x32_bf16 v[56:59], v[68:71], v[172:175], v[56:59]
	v_mfma_f32_16x16x32_bf16 v[52:55], v[84:87], v[138:141], v[52:55]
	v_mfma_f32_16x16x32_bf16 v[48:51], v[84:87], v[172:175], v[48:51]
	v_mfma_f32_16x16x32_bf16 v[44:47], v[196:199], v[138:141], v[44:47]
	v_mfma_f32_16x16x32_bf16 v[40:43], v[196:199], v[172:175], v[40:43]
	v_mfma_f32_16x16x32_bf16 v[36:39], v[204:207], v[138:141], v[36:39]
	v_mfma_f32_16x16x32_bf16 v[32:35], v[204:207], v[172:175], v[32:35]
	v_mfma_f32_16x16x32_bf16 v[28:31], v[64:67], v[208:211], v[28:31]
	v_mfma_f32_16x16x32_bf16 v[24:27], v[64:67], v[216:219], v[24:27]
	v_mfma_f32_16x16x32_bf16 v[12:15], v[192:195], v[208:211], v[12:15]
	v_mfma_f32_16x16x32_bf16 v[8:11], v[192:195], v[216:219], v[8:11]
	v_mfma_f32_16x16x32_bf16 v[20:23], v[80:83], v[208:211], v[20:23]
	v_mfma_f32_16x16x32_bf16 v[16:19], v[80:83], v[216:219], v[16:19]
	v_mfma_f32_16x16x32_bf16 v[4:7], v[200:203], v[208:211], v[4:7]
	v_mfma_f32_16x16x32_bf16 v[0:3], v[200:203], v[216:219], v[0:3]
	v_mfma_f32_16x16x32_bf16 v[28:31], v[68:71], v[212:215], v[28:31]
	v_mfma_f32_16x16x32_bf16 v[24:27], v[68:71], v[220:223], v[24:27]
	v_mfma_f32_16x16x32_bf16 v[12:15], v[196:199], v[212:215], v[12:15]
	v_mfma_f32_16x16x32_bf16 v[8:11], v[196:199], v[220:223], v[8:11]
	v_mfma_f32_16x16x32_bf16 v[134:137], v[84:87], v[212:215], v[20:23]
	v_mfma_f32_16x16x32_bf16 v[138:141], v[84:87], v[220:223], v[16:19]
	v_mfma_f32_16x16x32_bf16 v[156:159], v[204:207], v[212:215], v[4:7]
	v_mfma_f32_16x16x32_bf16 v[170:173], v[204:207], v[220:223], v[0:3]
	s_barrier
	s_nop 0
	ds_read_b128 v[0:3], v155
	ds_read_b128 v[4:7], v155 offset:1024
	ds_read_b128 v[16:19], v155 offset:2048
	ds_read_b128 v[192:195], v155 offset:3072
	ds_read_b128 v[20:23], v152 offset:32768
	ds_read_b128 v[196:199], v152 offset:33792
	ds_read_b128 v[200:203], v151 offset:32768
	ds_read_b128 v[204:207], v151 offset:33792
	ds_read_b128 v[208:211], v150 offset:32768
	ds_read_b128 v[212:215], v150 offset:33792
	ds_read_b128 v[216:219], v149 offset:32768
	ds_read_b128 v[220:223], v149 offset:33792
	s_waitcnt vmcnt(2)
	s_barrier
; #define LDA(dst, b, h) for (int m = 0; m < 4; ++m) for (int k = 0; k < 2; ++k) \
;     dst[m][k] = *reinterpret_cast<const bf16x8*>((char*)SA(b, h) + lds_byte(wr * 64 + m * 16 + fr, k * 32 + fq * 8))
; #define LDB(dst, b, h) for (int n = 0; n < 2; ++n) for (int k = 0; k < 2; ++k) \
;     dst[n][k] = *reinterpret_cast<const bf16x8*>((char*)SB(b, h) + lds_byte(wc * 32 + n * 16 + fr, k * 32 + fq * 8))
; #define MMA(ai, bj, At_, Bt_) do { __builtin_amdgcn_s_setprio(1); \
;     for (int k = 0; k < 2; ++k) for (int m = 0; m < 4; ++m) for (int n = 0; n < 2; ++n) \
;       acc[ai][bj][m][n] = __builtin_amdgcn_mfma_f32_16x16x32_bf16(At_[m][k], Bt_[n][k], acc[ai][bj][m][n], 0, 0, 0); \
;     __builtin_amdgcn_s_setprio(0); } while (0)
; #define WAIT_V(n) asm volatile("s_waitcnt vmcnt(" #n ")" ::: "memory")
; #define WAIT_L(n) asm volatile("s_waitcnt lgkmcnt(" #n ")" ::: "memory")
; #define BAR __builtin_amdgcn_s_barrier()
; template <int EPI, int lda, int ldb, int N, int K>
; __device__ __forceinline__ void gemm_phase(const u16* __restrict__ A, const u16* __restrict__ Bt, const GemmEpi ep, int wv) {
;     ...
;     { LDB(B0, 1, 0); LDA(At, 1, 0); WAIT_V(2); BAR; WAIT_L(0); MMA(0, 0, At, B0); BAR;
;       LDB(B1, 1, 1); WAIT_V(0); BAR; WAIT_L(0); MMA(0, 1, At, B1); BAR;
;       LDA(At, 1, 1); BAR; WAIT_L(0); MMA(1, 0, At, B0); MMA(1, 1, At, B1); BAR; }
;     if (wr == 0) BAR;
	s_waitcnt lgkmcnt(0)
	s_waitcnt lgkmcnt(0)
	v_mfma_f32_16x16x32_bf16 v[64:67], v[20:23], v[0:3], v[124:127]
	v_mfma_f32_16x16x32_bf16 v[68:71], v[20:23], v[16:19], v[120:123]
	v_mfma_f32_16x16x32_bf16 v[80:83], v[200:203], v[0:3], v[116:119]
	v_mfma_f32_16x16x32_bf16 v[84:87], v[200:203], v[16:19], v[112:115]
	v_mfma_f32_16x16x32_bf16 v[108:111], v[208:211], v[0:3], v[108:111]
	v_mfma_f32_16x16x32_bf16 v[104:107], v[208:211], v[16:19], v[104:107]
	v_mfma_f32_16x16x32_bf16 v[120:123], v[216:219], v[0:3], v[100:103]
	v_mfma_f32_16x16x32_bf16 v[124:127], v[216:219], v[16:19], v[96:99]
	v_mfma_f32_16x16x32_bf16 v[116:119], v[196:199], v[4:7], v[64:67]
	v_mfma_f32_16x16x32_bf16 v[112:115], v[196:199], v[192:195], v[68:71]
	v_mfma_f32_16x16x32_bf16 v[100:103], v[204:207], v[4:7], v[80:83]
	v_mfma_f32_16x16x32_bf16 v[96:99], v[204:207], v[192:195], v[84:87]
	v_mfma_f32_16x16x32_bf16 v[84:87], v[212:215], v[4:7], v[108:111]
	v_mfma_f32_16x16x32_bf16 v[80:83], v[212:215], v[192:195], v[104:107]
	v_mfma_f32_16x16x32_bf16 v[68:71], v[220:223], v[4:7], v[120:123]
	v_mfma_f32_16x16x32_bf16 v[64:67], v[220:223], v[192:195], v[124:127]
	s_barrier
	ds_read_b128 v[224:227], v153
	ds_read_b128 v[228:231], v153 offset:1024
	ds_read_b128 v[232:235], v153 offset:2048
	ds_read_b128 v[236:239], v153 offset:3072
	s_waitcnt vmcnt(0)
	s_barrier
	s_waitcnt lgkmcnt(0)
	s_waitcnt lgkmcnt(0)
	v_mfma_f32_16x16x32_bf16 v[92:95], v[20:23], v[224:227], v[92:95]
	v_mfma_f32_16x16x32_bf16 v[20:23], v[20:23], v[232:235], v[88:91]
	v_mfma_f32_16x16x32_bf16 v[88:91], v[200:203], v[224:227], v[176:179]
	v_mfma_f32_16x16x32_bf16 v[104:107], v[200:203], v[232:235], v[180:183]
	v_mfma_f32_16x16x32_bf16 v[76:79], v[208:211], v[224:227], v[76:79]
	v_mfma_f32_16x16x32_bf16 v[72:75], v[208:211], v[232:235], v[72:75]
	v_mfma_f32_16x16x32_bf16 v[174:177], v[216:219], v[224:227], v[184:187]
	v_mfma_f32_16x16x32_bf16 v[178:181], v[216:219], v[232:235], v[188:191]
	v_mfma_f32_16x16x32_bf16 v[124:127], v[196:199], v[228:231], v[92:95]
	v_mfma_f32_16x16x32_bf16 v[120:123], v[196:199], v[236:239], v[20:23]
	v_mfma_f32_16x16x32_bf16 v[108:111], v[204:207], v[228:231], v[88:91]
	v_mfma_f32_16x16x32_bf16 v[104:107], v[204:207], v[236:239], v[104:107]
	v_mfma_f32_16x16x32_bf16 v[92:95], v[212:215], v[228:231], v[76:79]
	v_mfma_f32_16x16x32_bf16 v[88:91], v[212:215], v[236:239], v[72:75]
	v_mfma_f32_16x16x32_bf16 v[76:79], v[220:223], v[228:231], v[174:177]
	v_mfma_f32_16x16x32_bf16 v[72:75], v[220:223], v[236:239], v[178:181]
	s_barrier
	ds_read_b128 v[174:177], v152 offset:49152
	ds_read_b128 v[152:155], v152 offset:50176
	ds_read_b128 v[178:181], v151 offset:49152
	ds_read_b128 v[182:185], v151 offset:50176
	ds_read_b128 v[186:189], v150 offset:49152
	ds_read_b128 v[196:199], v150 offset:50176
	ds_read_b128 v[200:203], v149 offset:49152
	ds_read_b128 v[204:207], v149 offset:50176
	s_barrier
	s_waitcnt lgkmcnt(0)
	s_waitcnt lgkmcnt(0)
	v_mfma_f32_16x16x32_bf16 v[20:23], v[174:177], v[0:3], v[60:63]
	v_mfma_f32_16x16x32_bf16 v[56:59], v[174:177], v[16:19], v[56:59]
	v_mfma_f32_16x16x32_bf16 v[60:63], v[178:181], v[0:3], v[52:55]
	v_mfma_f32_16x16x32_bf16 v[208:211], v[178:181], v[16:19], v[48:51]
	v_mfma_f32_16x16x32_bf16 v[44:47], v[186:189], v[0:3], v[44:47]
	v_mfma_f32_16x16x32_bf16 v[40:43], v[186:189], v[16:19], v[40:43]
	v_mfma_f32_16x16x32_bf16 v[0:3], v[200:203], v[0:3], v[36:39]
	v_mfma_f32_16x16x32_bf16 v[212:215], v[200:203], v[16:19], v[32:35]
	v_mfma_f32_16x16x32_bf16 v[52:55], v[152:155], v[4:7], v[20:23]
	v_mfma_f32_16x16x32_bf16 v[48:51], v[152:155], v[192:195], v[56:59]
	v_mfma_f32_16x16x32_bf16 v[36:39], v[182:185], v[4:7], v[60:63]
	v_mfma_f32_16x16x32_bf16 v[32:35], v[182:185], v[192:195], v[208:211]
	v_mfma_f32_16x16x32_bf16 v[20:23], v[196:199], v[4:7], v[44:47]
	v_mfma_f32_16x16x32_bf16 v[16:19], v[196:199], v[192:195], v[40:43]
	v_mfma_f32_16x16x32_bf16 v[4:7], v[204:207], v[4:7], v[0:3]
	v_mfma_f32_16x16x32_bf16 v[0:3], v[204:207], v[192:195], v[212:215]
	v_mfma_f32_16x16x32_bf16 v[28:31], v[174:177], v[224:227], v[28:31]
	v_mfma_f32_16x16x32_bf16 v[24:27], v[174:177], v[232:235], v[24:27]
	v_mfma_f32_16x16x32_bf16 v[40:43], v[178:181], v[224:227], v[134:137]
	v_mfma_f32_16x16x32_bf16 v[134:137], v[178:181], v[232:235], v[138:141]
	v_mfma_f32_16x16x32_bf16 v[12:15], v[186:189], v[224:227], v[12:15]
	v_mfma_f32_16x16x32_bf16 v[8:11], v[186:189], v[232:235], v[8:11]
	v_mfma_f32_16x16x32_bf16 v[138:141], v[200:203], v[224:227], v[156:159]
	v_mfma_f32_16x16x32_bf16 v[156:159], v[200:203], v[232:235], v[170:173]
	v_mfma_f32_16x16x32_bf16 v[60:63], v[152:155], v[228:231], v[28:31]
	v_mfma_f32_16x16x32_bf16 v[56:59], v[152:155], v[236:239], v[24:27]
	v_mfma_f32_16x16x32_bf16 v[44:47], v[182:185], v[228:231], v[40:43]
	v_mfma_f32_16x16x32_bf16 v[40:43], v[182:185], v[236:239], v[134:137]
	v_mfma_f32_16x16x32_bf16 v[28:31], v[196:199], v[228:231], v[12:15]
	v_mfma_f32_16x16x32_bf16 v[24:27], v[196:199], v[236:239], v[8:11]
	v_mfma_f32_16x16x32_bf16 v[12:15], v[204:207], v[228:231], v[138:141]
	v_mfma_f32_16x16x32_bf16 v[8:11], v[204:207], v[236:239], v[156:159]
	v_cmp_gt_u32_e32 vcc, s80, v130
	s_barrier
	s_and_saveexec_b64 s[60:61], vcc
	s_cbranch_execz .LBB0_1150
	s_barrier

; #define STAGE(P, BASE, LD, br, kt) do { const char* _g = (const char*)((BASE) + (size_t)(br) * (LD) + (size_t)(kt) * 64); \
;     for (int _i = 0; _i < 2; ++_i) { int _b = tidx * 16 + _i * 8192; int _r, _c; stage_rc(_b, _r, _c); \
;       __builtin_amdgcn_global_load_lds((const unsigned*)(_g + (unsigned)((_r * (LD) + _c) * 2)), (unsigned*)((char*)(P) + _b), 16, 0, 0); } } while (0)
; #define LDA(dst, b, h) for (int m = 0; m < 4; ++m) for (int k = 0; k < 2; ++k) \
;     dst[m][k] = *reinterpret_cast<const bf16x8*>((char*)SA(b, h) + lds_byte(wr * 64 + m * 16 + fr, k * 32 + fq * 8))
; #define LDB(dst, b, h) for (int n = 0; n < 2; ++n) for (int k = 0; k < 2; ++k) \
;     dst[n][k] = *reinterpret_cast<const bf16x8*>((char*)SB(b, h) + lds_byte(wc * 32 + n * 16 + fr, k * 32 + fq * 8))
; #define MMA(ai, bj, At_, Bt_) do { __builtin_amdgcn_s_setprio(1); \
;     for (int k = 0; k < 2; ++k) for (int m = 0; m < 4; ++m) for (int n = 0; n < 2; ++n) \
;       acc[ai][bj][m][n] = __builtin_amdgcn_mfma_f32_16x16x32_bf16(At_[m][k], Bt_[n][k], acc[ai][bj][m][n], 0, 0, 0); \
;     __builtin_amdgcn_s_setprio(0); } while (0)
; #define WAIT_L(n) asm volatile("s_waitcnt lgkmcnt(" #n ")" ::: "memory")
; #define BAR __builtin_amdgcn_s_barrier()
; #define SCHED __builtin_amdgcn_sched_barrier(0)
; template <int EPI, int lda, int ldb, int N, int K>
; __device__ __forceinline__ void gemm_phase(const u16* __restrict__ A, const u16* __restrict__ Bt, const GemmEpi ep, int wv) {
;     ...
;       LDB(B0, 0, 0); SCHED; LDA(At, 0, 0); STAGE(SA(1, 1), Ab, lda, brow + HALF, t + 1);
;       WAIT_L(8); BAR; WAIT_L(0); MMA(0, 0, At, B0); BAR; SCHED;
;       LDB(B1, 0, 1); STAGE(SB(0, 0), Bt, ldb, bcol, t + 2);
;       BAR; WAIT_L(0); MMA(0, 1, At, B1); BAR;
;       LDA(At, 0, 1); STAGE(SA(0, 0), Ab, lda, brow, t + 2);
;       BAR; WAIT_L(0); MMA(1, 0, At, B0); BAR; SCHED;
.LBB0_1448:
	ds_read_b128 v[164:167], v160
	ds_read_b128 v[170:173], v160 offset:1024
	ds_read_b128 v[174:177], v160 offset:2048
	ds_read_b128 v[178:181], v160 offset:3072
	v_add_u32_e32 v168, 0xc000, v143
	v_lshl_add_u64 v[234:235], v[138:139], 0, s[44:45]
	v_readfirstlane_b32 s47, v168
	v_add_u32_e32 v169, 0xe000, v143
	v_lshl_add_u64 v[162:163], v[234:235], 0, s[20:21]
	s_mov_b32 m0, s47
	v_lshl_add_u64 v[236:237], v[140:141], 0, s[44:45]
	v_readfirstlane_b32 s47, v169
	ds_read_b128 v[182:185], v151
	ds_read_b128 v[186:189], v151 offset:1024
	ds_read_b128 v[190:193], v150
	ds_read_b128 v[194:197], v150 offset:1024
	ds_read_b128 v[198:201], v149
	ds_read_b128 v[202:205], v149 offset:1024
	ds_read_b128 v[206:209], v148
	ds_read_b128 v[210:213], v148 offset:1024
	global_load_lds_dwordx4 v[162:163], off
	s_waitcnt lgkmcnt(8)
	s_barrier
	s_waitcnt lgkmcnt(0)
	s_waitcnt lgkmcnt(0)
	v_mfma_f32_16x16x32_bf16 v[124:127], v[164:167], v[182:185], v[124:127]
	v_mfma_f32_16x16x32_bf16 v[120:123], v[174:177], v[182:185], v[120:123]
	v_mfma_f32_16x16x32_bf16 v[116:119], v[164:167], v[190:193], v[116:119]
	v_mfma_f32_16x16x32_bf16 v[112:115], v[174:177], v[190:193], v[112:115]
	v_mfma_f32_16x16x32_bf16 v[108:111], v[164:167], v[198:201], v[108:111]
	v_mfma_f32_16x16x32_bf16 v[104:107], v[174:177], v[198:201], v[104:107]
	v_mfma_f32_16x16x32_bf16 v[100:103], v[164:167], v[206:209], v[100:103]
	v_mfma_f32_16x16x32_bf16 v[96:99], v[174:177], v[206:209], v[96:99]
	v_lshl_add_u64 v[162:163], v[236:237], 0, s[20:21]
	s_mov_b32 m0, s47
	s_nop 0
	global_load_lds_dwordx4 v[162:163], off
	v_mfma_f32_16x16x32_bf16 v[124:127], v[170:173], v[186:189], v[124:127]
	v_mfma_f32_16x16x32_bf16 v[120:123], v[178:181], v[186:189], v[120:123]
	v_mfma_f32_16x16x32_bf16 v[116:119], v[170:173], v[194:197], v[116:119]
	v_mfma_f32_16x16x32_bf16 v[112:115], v[178:181], v[194:197], v[112:115]
	v_mfma_f32_16x16x32_bf16 v[108:111], v[170:173], v[202:205], v[108:111]
	v_mfma_f32_16x16x32_bf16 v[104:107], v[178:181], v[202:205], v[104:107]
	v_mfma_f32_16x16x32_bf16 v[100:103], v[170:173], v[210:213], v[100:103]
	v_mfma_f32_16x16x32_bf16 v[96:99], v[178:181], v[210:213], v[96:99]
	s_barrier
	v_add_u32_e32 v161, s55, v153
	v_lshl_add_u64 v[238:239], v[134:135], 0, s[44:45]
	v_readfirstlane_b32 s47, v161
	v_lshl_add_u64 v[162:163], v[238:239], 0, s[22:23]
	s_mov_b32 m0, s47
	ds_read_b128 v[214:217], v159
	ds_read_b128 v[218:221], v159 offset:1024
	ds_read_b128 v[222:225], v159 offset:2048
	ds_read_b128 v[226:229], v159 offset:3072
	global_load_lds_dwordx4 v[162:163], off
	v_add_u32_e32 v162, 0x2000, v161
	v_lshl_add_u64 v[240:241], v[136:137], 0, s[44:45]
	v_readfirstlane_b32 s47, v162
	v_lshl_add_u64 v[230:231], v[240:241], 0, s[22:23]
	s_mov_b32 m0, s47
	s_nop 0
	global_load_lds_dwordx4 v[230:231], off
	s_barrier
	s_waitcnt lgkmcnt(0)
	s_waitcnt lgkmcnt(0)
	v_mfma_f32_16x16x32_bf16 v[92:95], v[214:217], v[182:185], v[92:95]
	v_mfma_f32_16x16x32_bf16 v[88:91], v[222:225], v[182:185], v[88:91]
	v_mfma_f32_16x16x32_bf16 v[84:87], v[214:217], v[190:193], v[84:87]
	v_mfma_f32_16x16x32_bf16 v[80:83], v[222:225], v[190:193], v[80:83]
	v_mfma_f32_16x16x32_bf16 v[76:79], v[214:217], v[198:201], v[76:79]
	v_mfma_f32_16x16x32_bf16 v[72:75], v[222:225], v[198:201], v[72:75]
	v_mfma_f32_16x16x32_bf16 v[68:71], v[214:217], v[206:209], v[68:71]
	v_mfma_f32_16x16x32_bf16 v[64:67], v[222:225], v[206:209], v[64:67]
	v_mfma_f32_16x16x32_bf16 v[92:95], v[218:221], v[186:189], v[92:95]
	v_mfma_f32_16x16x32_bf16 v[88:91], v[226:229], v[186:189], v[88:91]
	v_mfma_f32_16x16x32_bf16 v[84:87], v[218:221], v[194:197], v[84:87]
	v_mfma_f32_16x16x32_bf16 v[80:83], v[226:229], v[194:197], v[80:83]
	v_mfma_f32_16x16x32_bf16 v[76:79], v[218:221], v[202:205], v[76:79]
	v_mfma_f32_16x16x32_bf16 v[72:75], v[226:229], v[202:205], v[72:75]
	v_mfma_f32_16x16x32_bf16 v[68:71], v[218:221], v[210:213], v[68:71]
	v_mfma_f32_16x16x32_bf16 v[64:67], v[226:229], v[210:213], v[64:67]
	s_barrier
	v_readfirstlane_b32 s47, v143
	v_add_u32_e32 v163, 0x2000, v143
	v_lshl_add_u64 v[230:231], v[234:235], 0, s[24:25]
	s_mov_b32 m0, s47
	v_readfirstlane_b32 s47, v163
	ds_read_b128 v[182:185], v151 offset:16384
	ds_read_b128 v[186:189], v151 offset:17408
	ds_read_b128 v[190:193], v150 offset:16384
	ds_read_b128 v[194:197], v150 offset:17408
	ds_read_b128 v[198:201], v149 offset:16384
	ds_read_b128 v[202:205], v149 offset:17408
	ds_read_b128 v[206:209], v148 offset:16384
	ds_read_b128 v[210:213], v148 offset:17408
	global_load_lds_dwordx4 v[230:231], off
	v_lshl_add_u64 v[230:231], v[236:237], 0, s[24:25]
	s_mov_b32 m0, s47
	s_nop 0
	global_load_lds_dwordx4 v[230:231], off
	s_barrier
	s_waitcnt lgkmcnt(0)
	s_waitcnt lgkmcnt(0)
	v_mfma_f32_16x16x32_bf16 v[60:63], v[164:167], v[182:185], v[60:63]
	v_mfma_f32_16x16x32_bf16 v[56:59], v[174:177], v[182:185], v[56:59]
	v_mfma_f32_16x16x32_bf16 v[52:55], v[164:167], v[190:193], v[52:55]
	v_mfma_f32_16x16x32_bf16 v[48:51], v[174:177], v[190:193], v[48:51]
	v_mfma_f32_16x16x32_bf16 v[44:47], v[164:167], v[198:201], v[44:47]
	v_mfma_f32_16x16x32_bf16 v[40:43], v[174:177], v[198:201], v[40:43]
	v_mfma_f32_16x16x32_bf16 v[36:39], v[164:167], v[206:209], v[36:39]
	v_mfma_f32_16x16x32_bf16 v[32:35], v[174:177], v[206:209], v[32:35]
	v_mfma_f32_16x16x32_bf16 v[60:63], v[170:173], v[186:189], v[60:63]
	v_mfma_f32_16x16x32_bf16 v[56:59], v[178:181], v[186:189], v[56:59]
	v_mfma_f32_16x16x32_bf16 v[52:55], v[170:173], v[194:197], v[52:55]
	v_mfma_f32_16x16x32_bf16 v[48:51], v[178:181], v[194:197], v[48:51]
	v_mfma_f32_16x16x32_bf16 v[44:47], v[170:173], v[202:205], v[44:47]
	v_mfma_f32_16x16x32_bf16 v[40:43], v[178:181], v[202:205], v[40:43]
	v_mfma_f32_16x16x32_bf16 v[36:39], v[170:173], v[210:213], v[36:39]
	v_mfma_f32_16x16x32_bf16 v[32:35], v[178:181], v[210:213], v[32:35]
	s_barrier
; #define STAGE(P, BASE, LD, br, kt) do { const char* _g = (const char*)((BASE) + (size_t)(br) * (LD) + (size_t)(kt) * 64); \
;     for (int _i = 0; _i < 2; ++_i) { int _b = tidx * 16 + _i * 8192; int _r, _c; stage_rc(_b, _r, _c); \
;       __builtin_amdgcn_global_load_lds((const unsigned*)(_g + (unsigned)((_r * (LD) + _c) * 2)), (unsigned*)((char*)(P) + _b), 16, 0, 0); } } while (0)
; #define LDA(dst, b, h) for (int m = 0; m < 4; ++m) for (int k = 0; k < 2; ++k) \
;     dst[m][k] = *reinterpret_cast<const bf16x8*>((char*)SA(b, h) + lds_byte(wr * 64 + m * 16 + fr, k * 32 + fq * 8))
; #define LDB(dst, b, h) for (int n = 0; n < 2; ++n) for (int k = 0; k < 2; ++k) \
;     dst[n][k] = *reinterpret_cast<const bf16x8*>((char*)SB(b, h) + lds_byte(wc * 32 + n * 16 + fr, k * 32 + fq * 8))
; #define MMA(ai, bj, At_, Bt_) do { __builtin_amdgcn_s_setprio(1); \
;     for (int k = 0; k < 2; ++k) for (int m = 0; m < 4; ++m) for (int n = 0; n < 2; ++n) \
;       acc[ai][bj][m][n] = __builtin_amdgcn_mfma_f32_16x16x32_bf16(At_[m][k], Bt_[n][k], acc[ai][bj][m][n], 0, 0, 0); \
;     __builtin_amdgcn_s_setprio(0); } while (0)
; #define WAIT_V(n) asm volatile("s_waitcnt vmcnt(" #n ")" ::: "memory")
; #define WAIT_L(n) asm volatile("s_waitcnt lgkmcnt(" #n ")" ::: "memory")
; #define BAR __builtin_amdgcn_s_barrier()
; #define SCHED __builtin_amdgcn_sched_barrier(0)
; template <int EPI, int lda, int ldb, int N, int K>
; __device__ __forceinline__ void gemm_phase(const u16* __restrict__ A, const u16* __restrict__ Bt, const GemmEpi ep, int wv) {
;     ...
;       STAGE(SB(0, 1), Bt, ldb, bcol + HALF, t + 2);
;       WAIT_V(6); BAR; MMA(1, 1, At, B1); BAR;
;       LDB(B0, 1, 0); SCHED; LDA(At, 1, 0); STAGE(SA(0, 1), Ab, lda, brow + HALF, t + 2);
;       WAIT_L(8); BAR; WAIT_L(0); MMA(0, 0, At, B0); BAR; SCHED;
;       LDB(B1, 1, 1); STAGE(SB(1, 0), Bt, ldb, bcol, t + 3);
;       BAR; WAIT_L(0); MMA(0, 1, At, B1); BAR;
;       LDA(At, 1, 1); STAGE(SA(1, 0), Ab, lda, brow, t + 3);
	v_add_u32_e32 v164, s56, v153
	v_add_u32_e32 v165, 0x2000, v164
	v_readfirstlane_b32 s47, v164
	v_lshl_add_u64 v[166:167], v[238:239], 0, s[26:27]
	s_mov_b32 m0, s47
	v_readfirstlane_b32 s47, v165
	global_load_lds_dwordx4 v[166:167], off
	v_lshl_add_u64 v[166:167], v[240:241], 0, s[26:27]
	s_mov_b32 m0, s47
	s_nop 0
	global_load_lds_dwordx4 v[166:167], off
	s_waitcnt vmcnt(6)
	s_barrier
	v_mfma_f32_16x16x32_bf16 v[28:31], v[214:217], v[182:185], v[28:31]
	v_mfma_f32_16x16x32_bf16 v[24:27], v[222:225], v[182:185], v[24:27]
	v_mfma_f32_16x16x32_bf16 v[20:23], v[214:217], v[190:193], v[20:23]
	v_mfma_f32_16x16x32_bf16 v[16:19], v[222:225], v[190:193], v[16:19]
	v_mfma_f32_16x16x32_bf16 v[12:15], v[214:217], v[198:201], v[12:15]
	v_mfma_f32_16x16x32_bf16 v[8:11], v[222:225], v[198:201], v[8:11]
	v_mfma_f32_16x16x32_bf16 v[4:7], v[214:217], v[206:209], v[4:7]
	v_mfma_f32_16x16x32_bf16 v[0:3], v[222:225], v[206:209], v[0:3]
	v_mfma_f32_16x16x32_bf16 v[28:31], v[218:221], v[186:189], v[28:31]
	v_mfma_f32_16x16x32_bf16 v[24:27], v[226:229], v[186:189], v[24:27]
	v_mfma_f32_16x16x32_bf16 v[20:23], v[218:221], v[194:197], v[20:23]
	v_mfma_f32_16x16x32_bf16 v[16:19], v[226:229], v[194:197], v[16:19]
	v_mfma_f32_16x16x32_bf16 v[12:15], v[218:221], v[202:205], v[12:15]
	v_mfma_f32_16x16x32_bf16 v[8:11], v[226:229], v[202:205], v[8:11]
	v_mfma_f32_16x16x32_bf16 v[4:7], v[218:221], v[210:213], v[4:7]
	v_mfma_f32_16x16x32_bf16 v[0:3], v[226:229], v[210:213], v[0:3]
	s_barrier
	ds_read_b128 v[170:173], v154
	ds_read_b128 v[174:177], v154 offset:1024
	ds_read_b128 v[178:181], v154 offset:2048
	ds_read_b128 v[182:185], v154 offset:3072
	v_add_u32_e32 v166, 0x4000, v143
	v_add_u32_e32 v167, 0x6000, v143
	v_readfirstlane_b32 s47, v166
	v_lshl_add_u64 v[218:219], v[234:235], 0, s[34:35]
	s_mov_b32 m0, s47
	v_readfirstlane_b32 s47, v167
	ds_read_b128 v[186:189], v151 offset:32768
	ds_read_b128 v[190:193], v151 offset:33792
	ds_read_b128 v[194:197], v150 offset:32768
	ds_read_b128 v[198:201], v150 offset:33792
	ds_read_b128 v[202:205], v149 offset:32768
	ds_read_b128 v[206:209], v149 offset:33792
	ds_read_b128 v[210:213], v148 offset:32768
	ds_read_b128 v[214:217], v148 offset:33792
	global_load_lds_dwordx4 v[218:219], off
	s_waitcnt lgkmcnt(8)
	s_barrier
	s_waitcnt lgkmcnt(0)
	s_waitcnt lgkmcnt(0)
	v_mfma_f32_16x16x32_bf16 v[124:127], v[170:173], v[186:189], v[124:127]
	v_mfma_f32_16x16x32_bf16 v[120:123], v[178:181], v[186:189], v[120:123]
	v_mfma_f32_16x16x32_bf16 v[116:119], v[170:173], v[194:197], v[116:119]
	v_mfma_f32_16x16x32_bf16 v[112:115], v[178:181], v[194:197], v[112:115]
	v_mfma_f32_16x16x32_bf16 v[108:111], v[170:173], v[202:205], v[108:111]
	v_mfma_f32_16x16x32_bf16 v[104:107], v[178:181], v[202:205], v[104:107]
	v_mfma_f32_16x16x32_bf16 v[100:103], v[170:173], v[210:213], v[100:103]
	v_mfma_f32_16x16x32_bf16 v[96:99], v[178:181], v[210:213], v[96:99]
	v_lshl_add_u64 v[218:219], v[236:237], 0, s[34:35]
	s_mov_b32 m0, s47
	s_nop 0
	global_load_lds_dwordx4 v[218:219], off
	v_mfma_f32_16x16x32_bf16 v[124:127], v[174:177], v[190:193], v[124:127]
	v_mfma_f32_16x16x32_bf16 v[120:123], v[182:185], v[190:193], v[120:123]
	v_mfma_f32_16x16x32_bf16 v[116:119], v[174:177], v[198:201], v[116:119]
	v_mfma_f32_16x16x32_bf16 v[112:115], v[182:185], v[198:201], v[112:115]
	v_mfma_f32_16x16x32_bf16 v[108:111], v[174:177], v[206:209], v[108:111]
	v_mfma_f32_16x16x32_bf16 v[104:107], v[182:185], v[206:209], v[104:107]
	v_mfma_f32_16x16x32_bf16 v[100:103], v[174:177], v[214:217], v[100:103]
	v_mfma_f32_16x16x32_bf16 v[96:99], v[182:185], v[214:217], v[96:99]
	s_barrier
	v_readfirstlane_b32 s47, v155
	v_add_u32_e32 v244, 0x2000, v155
	v_lshl_add_u64 v[242:243], v[238:239], 0, s[36:37]
	s_mov_b32 m0, s47
	v_readfirstlane_b32 s47, v244
	ds_read_b128 v[218:221], v152
	ds_read_b128 v[222:225], v152 offset:1024
	ds_read_b128 v[226:229], v152 offset:2048
	ds_read_b128 v[230:233], v152 offset:3072
	global_load_lds_dwordx4 v[242:243], off
	v_lshl_add_u64 v[242:243], v[240:241], 0, s[36:37]
	s_mov_b32 m0, s47
	s_nop 0
	global_load_lds_dwordx4 v[242:243], off
	s_barrier
	s_waitcnt lgkmcnt(0)
	s_waitcnt lgkmcnt(0)
	v_mfma_f32_16x16x32_bf16 v[92:95], v[218:221], v[186:189], v[92:95]
	v_mfma_f32_16x16x32_bf16 v[88:91], v[226:229], v[186:189], v[88:91]
	v_mfma_f32_16x16x32_bf16 v[84:87], v[218:221], v[194:197], v[84:87]
	v_mfma_f32_16x16x32_bf16 v[80:83], v[226:229], v[194:197], v[80:83]
	v_mfma_f32_16x16x32_bf16 v[76:79], v[218:221], v[202:205], v[76:79]
	v_mfma_f32_16x16x32_bf16 v[72:75], v[226:229], v[202:205], v[72:75]
	v_mfma_f32_16x16x32_bf16 v[68:71], v[218:221], v[210:213], v[68:71]
	v_mfma_f32_16x16x32_bf16 v[64:67], v[226:229], v[210:213], v[64:67]
	v_mfma_f32_16x16x32_bf16 v[92:95], v[222:225], v[190:193], v[92:95]
	v_mfma_f32_16x16x32_bf16 v[88:91], v[230:233], v[190:193], v[88:91]
	v_mfma_f32_16x16x32_bf16 v[84:87], v[222:225], v[198:201], v[84:87]
	v_mfma_f32_16x16x32_bf16 v[80:83], v[230:233], v[198:201], v[80:83]
	v_mfma_f32_16x16x32_bf16 v[76:79], v[222:225], v[206:209], v[76:79]
	v_mfma_f32_16x16x32_bf16 v[72:75], v[230:233], v[206:209], v[72:75]
	v_mfma_f32_16x16x32_bf16 v[68:71], v[222:225], v[214:217], v[68:71]
	v_mfma_f32_16x16x32_bf16 v[64:67], v[230:233], v[214:217], v[64:67]
	s_barrier
	v_readfirstlane_b32 s47, v156
	v_lshl_add_u64 v[234:235], v[234:235], 0, s[38:39]
	s_mov_b32 m0, s47
	v_readfirstlane_b32 s47, v157
	ds_read_b128 v[186:189], v151 offset:49152
	ds_read_b128 v[190:193], v151 offset:50176
	ds_read_b128 v[194:197], v150 offset:49152
	ds_read_b128 v[198:201], v150 offset:50176
	ds_read_b128 v[202:205], v149 offset:49152
	ds_read_b128 v[206:209], v149 offset:50176
	ds_read_b128 v[210:213], v148 offset:49152
	ds_read_b128 v[214:217], v148 offset:50176
	global_load_lds_dwordx4 v[234:235], off
	v_lshl_add_u64 v[234:235], v[236:237], 0, s[38:39]
	s_mov_b32 m0, s47
	s_nop 0
	global_load_lds_dwordx4 v[234:235], off
	s_barrier
; #define STAGE(P, BASE, LD, br, kt) do { const char* _g = (const char*)((BASE) + (size_t)(br) * (LD) + (size_t)(kt) * 64); \
;     for (int _i = 0; _i < 2; ++_i) { int _b = tidx * 16 + _i * 8192; int _r, _c; stage_rc(_b, _r, _c); \
;       __builtin_amdgcn_global_load_lds((const unsigned*)(_g + (unsigned)((_r * (LD) + _c) * 2)), (unsigned*)((char*)(P) + _b), 16, 0, 0); } } while (0)
; #define LDA(dst, b, h) for (int m = 0; m < 4; ++m) for (int k = 0; k < 2; ++k) \
;     dst[m][k] = *reinterpret_cast<const bf16x8*>((char*)SA(b, h) + lds_byte(wr * 64 + m * 16 + fr, k * 32 + fq * 8))
; #define LDB(dst, b, h) for (int n = 0; n < 2; ++n) for (int k = 0; k < 2; ++k) \
;     dst[n][k] = *reinterpret_cast<const bf16x8*>((char*)SB(b, h) + lds_byte(wc * 32 + n * 16 + fr, k * 32 + fq * 8))
; #define MMA(ai, bj, At_, Bt_) do { __builtin_amdgcn_s_setprio(1); \
;     for (int k = 0; k < 2; ++k) for (int m = 0; m < 4; ++m) for (int n = 0; n < 2; ++n) \
;       acc[ai][bj][m][n] = __builtin_amdgcn_mfma_f32_16x16x32_bf16(At_[m][k], Bt_[n][k], acc[ai][bj][m][n], 0, 0, 0); \
;     __builtin_amdgcn_s_setprio(0); } while (0)
; #define WAIT_V(n) asm volatile("s_waitcnt vmcnt(" #n ")" ::: "memory")
; #define WAIT_L(n) asm volatile("s_waitcnt lgkmcnt(" #n ")" ::: "memory")
; #define BAR __builtin_amdgcn_s_barrier()
; #define SCHED __builtin_amdgcn_sched_barrier(0)
; template <int EPI, int lda, int ldb, int N, int K>
; __device__ __forceinline__ void gemm_phase(const u16* __restrict__ A, const u16* __restrict__ Bt, const GemmEpi ep, int wv) {
;     ...
;       BAR; WAIT_L(0); MMA(1, 0, At, B0); BAR; SCHED;
;       STAGE(SB(1, 1), Bt, ldb, bcol + HALF, t + 3);
;       WAIT_V(6); BAR; MMA(1, 1, At, B1); BAR;
;     }
;     { LDB(B0, 0, 0); LDA(At, 0, 0); STAGE(SA(1, 1), Ab, lda, brow + HALF, nt - 1);
;       BAR; WAIT_L(0); MMA(0, 0, At, B0); BAR;
;       LDB(B1, 0, 1); BAR; WAIT_L(0); MMA(0, 1, At, B1); BAR;
	s_waitcnt lgkmcnt(0)
	s_waitcnt lgkmcnt(0)
	v_mfma_f32_16x16x32_bf16 v[60:63], v[170:173], v[186:189], v[60:63]
	v_mfma_f32_16x16x32_bf16 v[56:59], v[178:181], v[186:189], v[56:59]
	v_mfma_f32_16x16x32_bf16 v[52:55], v[170:173], v[194:197], v[52:55]
	v_mfma_f32_16x16x32_bf16 v[48:51], v[178:181], v[194:197], v[48:51]
	v_mfma_f32_16x16x32_bf16 v[44:47], v[170:173], v[202:205], v[44:47]
	v_mfma_f32_16x16x32_bf16 v[40:43], v[178:181], v[202:205], v[40:43]
	v_mfma_f32_16x16x32_bf16 v[36:39], v[170:173], v[210:213], v[36:39]
	v_mfma_f32_16x16x32_bf16 v[32:35], v[178:181], v[210:213], v[32:35]
	v_mfma_f32_16x16x32_bf16 v[60:63], v[174:177], v[190:193], v[60:63]
	v_mfma_f32_16x16x32_bf16 v[56:59], v[182:185], v[190:193], v[56:59]
	v_mfma_f32_16x16x32_bf16 v[52:55], v[174:177], v[198:201], v[52:55]
	v_mfma_f32_16x16x32_bf16 v[48:51], v[182:185], v[198:201], v[48:51]
	v_mfma_f32_16x16x32_bf16 v[44:47], v[174:177], v[206:209], v[44:47]
	v_mfma_f32_16x16x32_bf16 v[40:43], v[182:185], v[206:209], v[40:43]
	v_mfma_f32_16x16x32_bf16 v[36:39], v[174:177], v[214:217], v[36:39]
	v_mfma_f32_16x16x32_bf16 v[32:35], v[182:185], v[214:217], v[32:35]
	s_barrier
	v_readfirstlane_b32 s47, v158
	v_add_u32_e32 v172, 0x2000, v158
	v_lshl_add_u64 v[170:171], v[238:239], 0, s[40:41]
	s_mov_b32 m0, s47
	v_readfirstlane_b32 s47, v172
	global_load_lds_dwordx4 v[170:171], off
	v_lshl_add_u64 v[170:171], v[240:241], 0, s[40:41]
	s_mov_b32 m0, s47
	s_nop 0
	global_load_lds_dwordx4 v[170:171], off
	s_waitcnt vmcnt(6)
	s_barrier
	v_mfma_f32_16x16x32_bf16 v[28:31], v[218:221], v[186:189], v[28:31]
	v_mfma_f32_16x16x32_bf16 v[24:27], v[226:229], v[186:189], v[24:27]
	v_mfma_f32_16x16x32_bf16 v[20:23], v[218:221], v[194:197], v[20:23]
	v_mfma_f32_16x16x32_bf16 v[16:19], v[226:229], v[194:197], v[16:19]
	v_mfma_f32_16x16x32_bf16 v[12:15], v[218:221], v[202:205], v[12:15]
	v_mfma_f32_16x16x32_bf16 v[8:11], v[226:229], v[202:205], v[8:11]
	v_mfma_f32_16x16x32_bf16 v[4:7], v[218:221], v[210:213], v[4:7]
	v_mfma_f32_16x16x32_bf16 v[0:3], v[226:229], v[210:213], v[0:3]
	v_mfma_f32_16x16x32_bf16 v[28:31], v[222:225], v[190:193], v[28:31]
	v_mfma_f32_16x16x32_bf16 v[24:27], v[230:233], v[190:193], v[24:27]
	v_mfma_f32_16x16x32_bf16 v[20:23], v[222:225], v[198:201], v[20:23]
	v_mfma_f32_16x16x32_bf16 v[16:19], v[230:233], v[198:201], v[16:19]
	v_mfma_f32_16x16x32_bf16 v[12:15], v[222:225], v[206:209], v[12:15]
	v_mfma_f32_16x16x32_bf16 v[8:11], v[230:233], v[206:209], v[8:11]
	v_mfma_f32_16x16x32_bf16 v[4:7], v[222:225], v[214:217], v[4:7]
	v_mfma_f32_16x16x32_bf16 v[0:3], v[230:233], v[214:217], v[0:3]
	s_add_i32 s46, s46, 2
	s_add_u32 s44, s44, 0x100
	s_addc_u32 s45, s45, 0
	s_cmp_gt_u32 s46, 27
	s_barrier
	s_cbranch_scc0 .LBB0_1448
	s_lshl_b64 s[44:45], s[16:17], 12
	s_add_u32 s44, s14, s44
	s_addc_u32 s45, s15, s45
	s_add_u32 s44, s44, 0x80000
	s_addc_u32 s45, s45, 0
	v_lshl_add_u64 v[156:157], s[44:45], 0, v[128:129]
	v_readfirstlane_b32 s46, v168
	v_lshl_add_u64 v[156:157], v[156:157], 0, s[42:43]
	s_mov_b32 m0, s46
	ds_read_b128 v[134:137], v160
	ds_read_b128 v[138:141], v160 offset:1024
	ds_read_b128 v[170:173], v160 offset:2048
	ds_read_b128 v[174:177], v160 offset:3072
	ds_read_b128 v[178:181], v151
	ds_read_b128 v[182:185], v151 offset:1024
	ds_read_b128 v[186:189], v150
	ds_read_b128 v[190:193], v150 offset:1024
	ds_read_b128 v[194:197], v149
	ds_read_b128 v[198:201], v149 offset:1024
	ds_read_b128 v[202:205], v148
	ds_read_b128 v[206:209], v148 offset:1024
	global_load_lds_dwordx4 v[156:157], off
	v_lshl_add_u64 v[156:157], s[44:45], 0, v[132:133]
	v_readfirstlane_b32 s44, v169
	v_lshl_add_u64 v[156:157], v[156:157], 0, s[42:43]
	s_mov_b32 m0, s44
	s_nop 0
	global_load_lds_dwordx4 v[156:157], off
	s_barrier
	s_waitcnt lgkmcnt(0)
	s_waitcnt lgkmcnt(0)
	v_mfma_f32_16x16x32_bf16 v[124:127], v[134:137], v[178:181], v[124:127]
	v_mfma_f32_16x16x32_bf16 v[120:123], v[170:173], v[178:181], v[120:123]
	v_mfma_f32_16x16x32_bf16 v[116:119], v[134:137], v[186:189], v[116:119]
	v_mfma_f32_16x16x32_bf16 v[112:115], v[170:173], v[186:189], v[112:115]
	v_mfma_f32_16x16x32_bf16 v[108:111], v[134:137], v[194:197], v[108:111]
	v_mfma_f32_16x16x32_bf16 v[104:107], v[170:173], v[194:197], v[104:107]
	v_mfma_f32_16x16x32_bf16 v[100:103], v[134:137], v[202:205], v[100:103]
	v_mfma_f32_16x16x32_bf16 v[96:99], v[170:173], v[202:205], v[96:99]
	v_mfma_f32_16x16x32_bf16 v[124:127], v[138:141], v[182:185], v[124:127]
	v_mfma_f32_16x16x32_bf16 v[120:123], v[174:177], v[182:185], v[120:123]
	v_mfma_f32_16x16x32_bf16 v[116:119], v[138:141], v[190:193], v[116:119]
	v_mfma_f32_16x16x32_bf16 v[112:115], v[174:177], v[190:193], v[112:115]
	v_mfma_f32_16x16x32_bf16 v[108:111], v[138:141], v[198:201], v[108:111]
	v_mfma_f32_16x16x32_bf16 v[104:107], v[174:177], v[198:201], v[104:107]
	v_mfma_f32_16x16x32_bf16 v[100:103], v[138:141], v[206:209], v[100:103]
	v_mfma_f32_16x16x32_bf16 v[96:99], v[174:177], v[206:209], v[96:99]
	s_barrier
	ds_read_b128 v[210:213], v159
	ds_read_b128 v[214:217], v159 offset:1024
	ds_read_b128 v[218:221], v159 offset:2048
	ds_read_b128 v[156:159], v159 offset:3072
	s_barrier
; #define LDA(dst, b, h) for (int m = 0; m < 4; ++m) for (int k = 0; k < 2; ++k) \
;     dst[m][k] = *reinterpret_cast<const bf16x8*>((char*)SA(b, h) + lds_byte(wr * 64 + m * 16 + fr, k * 32 + fq * 8))
; #define LDB(dst, b, h) for (int n = 0; n < 2; ++n) for (int k = 0; k < 2; ++k) \
;     dst[n][k] = *reinterpret_cast<const bf16x8*>((char*)SB(b, h) + lds_byte(wc * 32 + n * 16 + fr, k * 32 + fq * 8))
; #define MMA(ai, bj, At_, Bt_) do { __builtin_amdgcn_s_setprio(1); \
;     for (int k = 0; k < 2; ++k) for (int m = 0; m < 4; ++m) for (int n = 0; n < 2; ++n) \
;       acc[ai][bj][m][n] = __builtin_amdgcn_mfma_f32_16x16x32_bf16(At_[m][k], Bt_[n][k], acc[ai][bj][m][n], 0, 0, 0); \
;     __builtin_amdgcn_s_setprio(0); } while (0)
; #define WAIT_V(n) asm volatile("s_waitcnt vmcnt(" #n ")" ::: "memory")
; #define WAIT_L(n) asm volatile("s_waitcnt lgkmcnt(" #n ")" ::: "memory")
; #define BAR __builtin_amdgcn_s_barrier()
; template <int EPI, int lda, int ldb, int N, int K>
; __device__ __forceinline__ void gemm_phase(const u16* __restrict__ A, const u16* __restrict__ Bt, const GemmEpi ep, int wv) {
;     ...
;       LDB(B1, 0, 1); BAR; WAIT_L(0); MMA(0, 1, At, B1); BAR;
;       LDA(At, 0, 1); WAIT_V(4); BAR; WAIT_L(0); MMA(1, 0, At, B0); MMA(1, 1, At, B1); BAR; }
;     { LDB(B0, 1, 0); LDA(At, 1, 0); WAIT_V(2); BAR; WAIT_L(0); MMA(0, 0, At, B0); BAR;
	s_waitcnt lgkmcnt(0)
	s_waitcnt lgkmcnt(0)
	v_mfma_f32_16x16x32_bf16 v[92:95], v[210:213], v[178:181], v[92:95]
	v_mfma_f32_16x16x32_bf16 v[88:91], v[218:221], v[178:181], v[88:91]
	v_mfma_f32_16x16x32_bf16 v[76:79], v[210:213], v[194:197], v[76:79]
	v_mfma_f32_16x16x32_bf16 v[72:75], v[218:221], v[194:197], v[72:75]
	v_mfma_f32_16x16x32_bf16 v[84:87], v[210:213], v[186:189], v[84:87]
	v_mfma_f32_16x16x32_bf16 v[80:83], v[218:221], v[186:189], v[80:83]
	v_mfma_f32_16x16x32_bf16 v[68:71], v[210:213], v[202:205], v[68:71]
	v_mfma_f32_16x16x32_bf16 v[64:67], v[218:221], v[202:205], v[64:67]
	v_mfma_f32_16x16x32_bf16 v[92:95], v[214:217], v[182:185], v[92:95]
	v_mfma_f32_16x16x32_bf16 v[88:91], v[156:159], v[182:185], v[88:91]
	v_mfma_f32_16x16x32_bf16 v[76:79], v[214:217], v[198:201], v[76:79]
	v_mfma_f32_16x16x32_bf16 v[72:75], v[156:159], v[198:201], v[72:75]
	v_mfma_f32_16x16x32_bf16 v[178:181], v[214:217], v[190:193], v[84:87]
	v_mfma_f32_16x16x32_bf16 v[182:185], v[156:159], v[190:193], v[80:83]
	v_mfma_f32_16x16x32_bf16 v[186:189], v[214:217], v[206:209], v[68:71]
	v_mfma_f32_16x16x32_bf16 v[190:193], v[156:159], v[206:209], v[64:67]
	s_barrier
	s_nop 0
	ds_read_b128 v[64:67], v151 offset:16384
	ds_read_b128 v[68:71], v151 offset:17408
	ds_read_b128 v[80:83], v150 offset:16384
	ds_read_b128 v[84:87], v150 offset:17408
	ds_read_b128 v[194:197], v149 offset:16384
	ds_read_b128 v[198:201], v149 offset:17408
	ds_read_b128 v[202:205], v148 offset:16384
	ds_read_b128 v[206:209], v148 offset:17408
	s_waitcnt vmcnt(4)
	s_barrier
	s_waitcnt lgkmcnt(0)
	s_waitcnt lgkmcnt(0)
	v_mfma_f32_16x16x32_bf16 v[60:63], v[134:137], v[64:67], v[60:63]
	v_mfma_f32_16x16x32_bf16 v[56:59], v[170:173], v[64:67], v[56:59]
	v_mfma_f32_16x16x32_bf16 v[52:55], v[134:137], v[80:83], v[52:55]
	v_mfma_f32_16x16x32_bf16 v[48:51], v[170:173], v[80:83], v[48:51]
	v_mfma_f32_16x16x32_bf16 v[44:47], v[134:137], v[194:197], v[44:47]
	v_mfma_f32_16x16x32_bf16 v[40:43], v[170:173], v[194:197], v[40:43]
	v_mfma_f32_16x16x32_bf16 v[36:39], v[134:137], v[202:205], v[36:39]
	v_mfma_f32_16x16x32_bf16 v[32:35], v[170:173], v[202:205], v[32:35]
	v_mfma_f32_16x16x32_bf16 v[60:63], v[138:141], v[68:71], v[60:63]
	v_mfma_f32_16x16x32_bf16 v[56:59], v[174:177], v[68:71], v[56:59]
	v_mfma_f32_16x16x32_bf16 v[52:55], v[138:141], v[84:87], v[52:55]
	v_mfma_f32_16x16x32_bf16 v[48:51], v[174:177], v[84:87], v[48:51]
	v_mfma_f32_16x16x32_bf16 v[44:47], v[138:141], v[198:201], v[44:47]
	v_mfma_f32_16x16x32_bf16 v[40:43], v[174:177], v[198:201], v[40:43]
	v_mfma_f32_16x16x32_bf16 v[36:39], v[138:141], v[206:209], v[36:39]
	v_mfma_f32_16x16x32_bf16 v[32:35], v[174:177], v[206:209], v[32:35]
	v_mfma_f32_16x16x32_bf16 v[28:31], v[210:213], v[64:67], v[28:31]
	v_mfma_f32_16x16x32_bf16 v[20:23], v[210:213], v[80:83], v[20:23]
	v_mfma_f32_16x16x32_bf16 v[12:15], v[210:213], v[194:197], v[12:15]
	v_mfma_f32_16x16x32_bf16 v[4:7], v[210:213], v[202:205], v[4:7]
	v_mfma_f32_16x16x32_bf16 v[24:27], v[218:221], v[64:67], v[24:27]
	v_mfma_f32_16x16x32_bf16 v[16:19], v[218:221], v[80:83], v[16:19]
	v_mfma_f32_16x16x32_bf16 v[8:11], v[218:221], v[194:197], v[8:11]
	v_mfma_f32_16x16x32_bf16 v[0:3], v[218:221], v[202:205], v[0:3]
	v_mfma_f32_16x16x32_bf16 v[28:31], v[214:217], v[68:71], v[28:31]
	v_mfma_f32_16x16x32_bf16 v[20:23], v[214:217], v[84:87], v[20:23]
	v_mfma_f32_16x16x32_bf16 v[12:15], v[214:217], v[198:201], v[12:15]
	v_mfma_f32_16x16x32_bf16 v[4:7], v[214:217], v[206:209], v[4:7]
	v_mfma_f32_16x16x32_bf16 v[134:137], v[156:159], v[68:71], v[24:27]
	v_mfma_f32_16x16x32_bf16 v[138:141], v[156:159], v[84:87], v[16:19]
	v_mfma_f32_16x16x32_bf16 v[168:171], v[156:159], v[198:201], v[8:11]
	v_mfma_f32_16x16x32_bf16 v[156:159], v[156:159], v[206:209], v[0:3]
	s_barrier
	s_nop 0
	ds_read_b128 v[0:3], v154
	ds_read_b128 v[8:11], v154 offset:1024
	ds_read_b128 v[16:19], v154 offset:2048
	ds_read_b128 v[172:175], v154 offset:3072
	ds_read_b128 v[24:27], v151 offset:32768
	ds_read_b128 v[194:197], v151 offset:33792
	ds_read_b128 v[198:201], v150 offset:32768
	ds_read_b128 v[202:205], v150 offset:33792
	ds_read_b128 v[206:209], v149 offset:32768
	ds_read_b128 v[210:213], v149 offset:33792
	ds_read_b128 v[214:217], v148 offset:32768
	ds_read_b128 v[218:221], v148 offset:33792
	s_waitcnt vmcnt(2)
	s_barrier
; #define LDA(dst, b, h) for (int m = 0; m < 4; ++m) for (int k = 0; k < 2; ++k) \
;     dst[m][k] = *reinterpret_cast<const bf16x8*>((char*)SA(b, h) + lds_byte(wr * 64 + m * 16 + fr, k * 32 + fq * 8))
; #define LDB(dst, b, h) for (int n = 0; n < 2; ++n) for (int k = 0; k < 2; ++k) \
;     dst[n][k] = *reinterpret_cast<const bf16x8*>((char*)SB(b, h) + lds_byte(wc * 32 + n * 16 + fr, k * 32 + fq * 8))
; #define MMA(ai, bj, At_, Bt_) do { __builtin_amdgcn_s_setprio(1); \
;     for (int k = 0; k < 2; ++k) for (int m = 0; m < 4; ++m) for (int n = 0; n < 2; ++n) \
;       acc[ai][bj][m][n] = __builtin_amdgcn_mfma_f32_16x16x32_bf16(At_[m][k], Bt_[n][k], acc[ai][bj][m][n], 0, 0, 0); \
;     __builtin_amdgcn_s_setprio(0); } while (0)
; #define WAIT_V(n) asm volatile("s_waitcnt vmcnt(" #n ")" ::: "memory")
; #define WAIT_L(n) asm volatile("s_waitcnt lgkmcnt(" #n ")" ::: "memory")
; #define BAR __builtin_amdgcn_s_barrier()
; template <int EPI, int lda, int ldb, int N, int K>
; __device__ __forceinline__ void gemm_phase(const u16* __restrict__ A, const u16* __restrict__ Bt, const GemmEpi ep, int wv) {
;     ...
;     { LDB(B0, 1, 0); LDA(At, 1, 0); WAIT_V(2); BAR; WAIT_L(0); MMA(0, 0, At, B0); BAR;
;       LDB(B1, 1, 1); WAIT_V(0); BAR; WAIT_L(0); MMA(0, 1, At, B1); BAR;
;       LDA(At, 1, 1); BAR; WAIT_L(0); MMA(1, 0, At, B0); MMA(1, 1, At, B1); BAR; }
;     if (wr == 0) BAR;
	s_waitcnt lgkmcnt(0)
	s_waitcnt lgkmcnt(0)
	v_mfma_f32_16x16x32_bf16 v[64:67], v[0:3], v[24:27], v[124:127]
	v_mfma_f32_16x16x32_bf16 v[68:71], v[16:19], v[24:27], v[120:123]
	v_mfma_f32_16x16x32_bf16 v[80:83], v[0:3], v[198:201], v[116:119]
	v_mfma_f32_16x16x32_bf16 v[84:87], v[16:19], v[198:201], v[112:115]
	v_mfma_f32_16x16x32_bf16 v[108:111], v[0:3], v[206:209], v[108:111]
	v_mfma_f32_16x16x32_bf16 v[104:107], v[16:19], v[206:209], v[104:107]
	v_mfma_f32_16x16x32_bf16 v[120:123], v[0:3], v[214:217], v[100:103]
	v_mfma_f32_16x16x32_bf16 v[124:127], v[16:19], v[214:217], v[96:99]
	v_mfma_f32_16x16x32_bf16 v[116:119], v[8:11], v[194:197], v[64:67]
	v_mfma_f32_16x16x32_bf16 v[112:115], v[172:175], v[194:197], v[68:71]
	v_mfma_f32_16x16x32_bf16 v[100:103], v[8:11], v[202:205], v[80:83]
	v_mfma_f32_16x16x32_bf16 v[96:99], v[172:175], v[202:205], v[84:87]
	v_mfma_f32_16x16x32_bf16 v[84:87], v[8:11], v[210:213], v[108:111]
	v_mfma_f32_16x16x32_bf16 v[80:83], v[172:175], v[210:213], v[104:107]
	v_mfma_f32_16x16x32_bf16 v[68:71], v[8:11], v[218:221], v[120:123]
	v_mfma_f32_16x16x32_bf16 v[64:67], v[172:175], v[218:221], v[124:127]
	s_barrier
	ds_read_b128 v[222:225], v152
	ds_read_b128 v[226:229], v152 offset:1024
	ds_read_b128 v[230:233], v152 offset:2048
	ds_read_b128 v[152:155], v152 offset:3072
	s_waitcnt vmcnt(0)
	s_barrier
	s_waitcnt lgkmcnt(0)
	s_waitcnt lgkmcnt(0)
	v_mfma_f32_16x16x32_bf16 v[92:95], v[222:225], v[24:27], v[92:95]
	v_mfma_f32_16x16x32_bf16 v[24:27], v[230:233], v[24:27], v[88:91]
	v_mfma_f32_16x16x32_bf16 v[88:91], v[222:225], v[198:201], v[178:181]
	v_mfma_f32_16x16x32_bf16 v[104:107], v[230:233], v[198:201], v[182:185]
	v_mfma_f32_16x16x32_bf16 v[76:79], v[222:225], v[206:209], v[76:79]
	v_mfma_f32_16x16x32_bf16 v[72:75], v[230:233], v[206:209], v[72:75]
	v_mfma_f32_16x16x32_bf16 v[176:179], v[222:225], v[214:217], v[186:189]
	v_mfma_f32_16x16x32_bf16 v[180:183], v[230:233], v[214:217], v[190:193]
	v_mfma_f32_16x16x32_bf16 v[124:127], v[226:229], v[194:197], v[92:95]
	v_mfma_f32_16x16x32_bf16 v[120:123], v[152:155], v[194:197], v[24:27]
	v_mfma_f32_16x16x32_bf16 v[108:111], v[226:229], v[202:205], v[88:91]
	v_mfma_f32_16x16x32_bf16 v[104:107], v[152:155], v[202:205], v[104:107]
	v_mfma_f32_16x16x32_bf16 v[92:95], v[226:229], v[210:213], v[76:79]
	v_mfma_f32_16x16x32_bf16 v[88:91], v[152:155], v[210:213], v[72:75]
	v_mfma_f32_16x16x32_bf16 v[76:79], v[226:229], v[218:221], v[176:179]
	v_mfma_f32_16x16x32_bf16 v[72:75], v[152:155], v[218:221], v[180:183]
	s_barrier
	ds_read_b128 v[176:179], v151 offset:49152
	ds_read_b128 v[180:183], v151 offset:50176
	ds_read_b128 v[184:187], v150 offset:49152
	ds_read_b128 v[188:191], v150 offset:50176
	ds_read_b128 v[192:195], v149 offset:49152
	ds_read_b128 v[196:199], v149 offset:50176
	ds_read_b128 v[200:203], v148 offset:49152
	ds_read_b128 v[148:151], v148 offset:50176
	s_barrier
	s_waitcnt lgkmcnt(0)
	s_waitcnt lgkmcnt(0)
	v_mfma_f32_16x16x32_bf16 v[24:27], v[0:3], v[176:179], v[60:63]
	v_mfma_f32_16x16x32_bf16 v[60:63], v[16:19], v[176:179], v[56:59]
	v_mfma_f32_16x16x32_bf16 v[52:55], v[0:3], v[184:187], v[52:55]
	v_mfma_f32_16x16x32_bf16 v[204:207], v[16:19], v[184:187], v[48:51]
	v_mfma_f32_16x16x32_bf16 v[44:47], v[0:3], v[192:195], v[44:47]
	v_mfma_f32_16x16x32_bf16 v[208:211], v[16:19], v[192:195], v[40:43]
	v_mfma_f32_16x16x32_bf16 v[0:3], v[0:3], v[200:203], v[36:39]
	v_mfma_f32_16x16x32_bf16 v[36:39], v[16:19], v[200:203], v[32:35]
	v_mfma_f32_16x16x32_bf16 v[56:59], v[8:11], v[180:183], v[24:27]
	v_mfma_f32_16x16x32_bf16 v[48:51], v[172:175], v[180:183], v[60:63]
	v_mfma_f32_16x16x32_bf16 v[40:43], v[8:11], v[188:191], v[52:55]
	v_mfma_f32_16x16x32_bf16 v[32:35], v[172:175], v[188:191], v[204:207]
	v_mfma_f32_16x16x32_bf16 v[24:27], v[8:11], v[196:199], v[44:47]
	v_mfma_f32_16x16x32_bf16 v[16:19], v[172:175], v[196:199], v[208:211]
	v_mfma_f32_16x16x32_bf16 v[8:11], v[8:11], v[148:151], v[0:3]
	v_mfma_f32_16x16x32_bf16 v[0:3], v[172:175], v[148:151], v[36:39]
	v_mfma_f32_16x16x32_bf16 v[28:31], v[222:225], v[176:179], v[28:31]
	v_mfma_f32_16x16x32_bf16 v[36:39], v[230:233], v[176:179], v[134:137]
	v_mfma_f32_16x16x32_bf16 v[20:23], v[222:225], v[184:187], v[20:23]
	v_mfma_f32_16x16x32_bf16 v[134:137], v[230:233], v[184:187], v[138:141]
	v_mfma_f32_16x16x32_bf16 v[12:15], v[222:225], v[192:195], v[12:15]
	v_mfma_f32_16x16x32_bf16 v[138:141], v[230:233], v[192:195], v[168:171]
	v_mfma_f32_16x16x32_bf16 v[4:7], v[222:225], v[200:203], v[4:7]
	v_mfma_f32_16x16x32_bf16 v[156:159], v[230:233], v[200:203], v[156:159]
	v_mfma_f32_16x16x32_bf16 v[60:63], v[226:229], v[180:183], v[28:31]
	v_mfma_f32_16x16x32_bf16 v[52:55], v[152:155], v[180:183], v[36:39]
	v_mfma_f32_16x16x32_bf16 v[44:47], v[226:229], v[188:191], v[20:23]
	v_mfma_f32_16x16x32_bf16 v[36:39], v[152:155], v[188:191], v[134:137]
	v_mfma_f32_16x16x32_bf16 v[28:31], v[226:229], v[196:199], v[12:15]
	v_mfma_f32_16x16x32_bf16 v[20:23], v[152:155], v[196:199], v[138:141]
	v_mfma_f32_16x16x32_bf16 v[12:15], v[226:229], v[148:151], v[4:7]
	v_mfma_f32_16x16x32_bf16 v[4:7], v[152:155], v[148:151], v[156:159]
	v_cmp_gt_u32_e32 vcc, s60, v130
	s_barrier
	s_and_saveexec_b64 s[44:45], vcc
	s_cbranch_execz .LBB0_1451
	s_barrier

; #define STAGE(P, BASE, LD, br, kt) do { const char* _g = (const char*)((BASE) + (size_t)(br) * (LD) + (size_t)(kt) * 64); \
;     for (int _i = 0; _i < 2; ++_i) { int _b = tidx * 16 + _i * 8192; int _r, _c; stage_rc(_b, _r, _c); \
;       __builtin_amdgcn_global_load_lds((const unsigned*)(_g + (unsigned)((_r * (LD) + _c) * 2)), (unsigned*)((char*)(P) + _b), 16, 0, 0); } } while (0)
; #define LDA(dst, b, h) for (int m = 0; m < 4; ++m) for (int k = 0; k < 2; ++k) \
;     dst[m][k] = *reinterpret_cast<const bf16x8*>((char*)SA(b, h) + lds_byte(wr * 64 + m * 16 + fr, k * 32 + fq * 8))
; #define LDB(dst, b, h) for (int n = 0; n < 2; ++n) for (int k = 0; k < 2; ++k) \
;     dst[n][k] = *reinterpret_cast<const bf16x8*>((char*)SB(b, h) + lds_byte(wc * 32 + n * 16 + fr, k * 32 + fq * 8))
; #define MMA(ai, bj, At_, Bt_) do { __builtin_amdgcn_s_setprio(1); \
;     for (int k = 0; k < 2; ++k) for (int m = 0; m < 4; ++m) for (int n = 0; n < 2; ++n) \
;       acc[ai][bj][m][n] = __builtin_amdgcn_mfma_f32_16x16x32_bf16(At_[m][k], Bt_[n][k], acc[ai][bj][m][n], 0, 0, 0); \
;     __builtin_amdgcn_s_setprio(0); } while (0)
; #define WAIT_L(n) asm volatile("s_waitcnt lgkmcnt(" #n ")" ::: "memory")
; #define BAR __builtin_amdgcn_s_barrier()
; #define SCHED __builtin_amdgcn_sched_barrier(0)
; template <int EPI, int lda, int ldb, int N, int K>
; __device__ __forceinline__ void gemm_phase(const u16* __restrict__ A, const u16* __restrict__ Bt, const GemmEpi ep, int wv) {
;     ...
;     for (int t = 0; t < nt - 2; t += 2) {
;       LDB(B0, 0, 0); SCHED; LDA(At, 0, 0); STAGE(SA(1, 1), Ab, lda, brow + HALF, t + 1);
;       WAIT_L(8); BAR; WAIT_L(0); MMA(0, 0, At, B0); BAR; SCHED;
;       LDB(B1, 0, 1); STAGE(SB(0, 0), Bt, ldb, bcol, t + 2);
;       BAR; WAIT_L(0); MMA(0, 1, At, B1); BAR;
;       LDA(At, 0, 1); STAGE(SA(0, 0), Ab, lda, brow, t + 2);
;       BAR; WAIT_L(0); MMA(1, 0, At, B0); BAR; SCHED;
.LBB0_1564:
	ds_read_b128 v[172:175], v161
	ds_read_b128 v[176:179], v161 offset:1024
	ds_read_b128 v[180:183], v161 offset:2048
	ds_read_b128 v[184:187], v161 offset:3072
	v_add_u32_e32 v169, 0xc000, v148
	v_lshl_add_u64 v[236:237], v[136:137], 0, s[40:41]
	v_readfirstlane_b32 s43, v169
	v_add_u32_e32 v170, 0xe000, v148
	v_lshl_add_u64 v[162:163], v[236:237], 0, s[14:15]
	s_mov_b32 m0, s43
	v_lshl_add_u64 v[238:239], v[134:135], 0, s[40:41]
	v_readfirstlane_b32 s43, v170
	ds_read_b128 v[164:167], v152
	ds_read_b128 v[188:191], v152 offset:1024
	ds_read_b128 v[192:195], v151
	ds_read_b128 v[196:199], v151 offset:1024
	ds_read_b128 v[200:203], v150
	ds_read_b128 v[204:207], v150 offset:1024
	ds_read_b128 v[208:211], v149
	ds_read_b128 v[212:215], v149 offset:1024
	global_load_lds_dwordx4 v[162:163], off
	s_waitcnt lgkmcnt(8)
	s_barrier
	s_waitcnt lgkmcnt(0)
	s_waitcnt lgkmcnt(0)
	v_mfma_f32_16x16x32_bf16 v[124:127], v[172:175], v[164:167], v[124:127]
	v_mfma_f32_16x16x32_bf16 v[120:123], v[180:183], v[164:167], v[120:123]
	v_mfma_f32_16x16x32_bf16 v[116:119], v[172:175], v[192:195], v[116:119]
	v_mfma_f32_16x16x32_bf16 v[112:115], v[180:183], v[192:195], v[112:115]
	v_mfma_f32_16x16x32_bf16 v[108:111], v[172:175], v[200:203], v[108:111]
	v_mfma_f32_16x16x32_bf16 v[104:107], v[180:183], v[200:203], v[104:107]
	v_mfma_f32_16x16x32_bf16 v[100:103], v[172:175], v[208:211], v[100:103]
	v_mfma_f32_16x16x32_bf16 v[96:99], v[180:183], v[208:211], v[96:99]
	v_lshl_add_u64 v[162:163], v[238:239], 0, s[14:15]
	s_mov_b32 m0, s43
	s_nop 0
	global_load_lds_dwordx4 v[162:163], off
	v_mfma_f32_16x16x32_bf16 v[124:127], v[176:179], v[188:191], v[124:127]
	v_mfma_f32_16x16x32_bf16 v[120:123], v[184:187], v[188:191], v[120:123]
	v_mfma_f32_16x16x32_bf16 v[116:119], v[176:179], v[196:199], v[116:119]
	v_mfma_f32_16x16x32_bf16 v[112:115], v[184:187], v[196:199], v[112:115]
	v_mfma_f32_16x16x32_bf16 v[108:111], v[176:179], v[204:207], v[108:111]
	v_mfma_f32_16x16x32_bf16 v[104:107], v[184:187], v[204:207], v[104:107]
	v_mfma_f32_16x16x32_bf16 v[100:103], v[176:179], v[212:215], v[100:103]
	v_mfma_f32_16x16x32_bf16 v[96:99], v[184:187], v[212:215], v[96:99]
	s_barrier
	v_add_u32_e32 v162, s52, v153
	v_lshl_add_u64 v[240:241], v[140:141], 0, s[40:41]
	v_readfirstlane_b32 s43, v162
	v_add_u32_e32 v163, 0x2000, v162
	v_lshl_add_u64 v[232:233], v[240:241], 0, s[16:17]
	s_mov_b32 m0, s43
	v_lshl_add_u64 v[242:243], v[138:139], 0, s[40:41]
	v_readfirstlane_b32 s43, v163
	ds_read_b128 v[216:219], v160
	ds_read_b128 v[220:223], v160 offset:1024
	ds_read_b128 v[224:227], v160 offset:2048
	ds_read_b128 v[228:231], v160 offset:3072
	global_load_lds_dwordx4 v[232:233], off
	v_lshl_add_u64 v[232:233], v[242:243], 0, s[16:17]
	s_mov_b32 m0, s43
	s_nop 0
	global_load_lds_dwordx4 v[232:233], off
	s_barrier
	s_waitcnt lgkmcnt(0)
	s_waitcnt lgkmcnt(0)
	v_mfma_f32_16x16x32_bf16 v[92:95], v[216:219], v[164:167], v[92:95]
	v_mfma_f32_16x16x32_bf16 v[88:91], v[224:227], v[164:167], v[88:91]
	v_mfma_f32_16x16x32_bf16 v[84:87], v[216:219], v[192:195], v[84:87]
	v_mfma_f32_16x16x32_bf16 v[80:83], v[224:227], v[192:195], v[80:83]
	v_mfma_f32_16x16x32_bf16 v[76:79], v[216:219], v[200:203], v[76:79]
	v_mfma_f32_16x16x32_bf16 v[72:75], v[224:227], v[200:203], v[72:75]
	v_mfma_f32_16x16x32_bf16 v[68:71], v[216:219], v[208:211], v[68:71]
	v_mfma_f32_16x16x32_bf16 v[64:67], v[224:227], v[208:211], v[64:67]
	v_mfma_f32_16x16x32_bf16 v[92:95], v[220:223], v[188:191], v[92:95]
	v_mfma_f32_16x16x32_bf16 v[88:91], v[228:231], v[188:191], v[88:91]
	v_mfma_f32_16x16x32_bf16 v[84:87], v[220:223], v[196:199], v[84:87]
	v_mfma_f32_16x16x32_bf16 v[80:83], v[228:231], v[196:199], v[80:83]
	v_mfma_f32_16x16x32_bf16 v[76:79], v[220:223], v[204:207], v[76:79]
	v_mfma_f32_16x16x32_bf16 v[72:75], v[228:231], v[204:207], v[72:75]
	v_mfma_f32_16x16x32_bf16 v[68:71], v[220:223], v[212:215], v[68:71]
	v_mfma_f32_16x16x32_bf16 v[64:67], v[228:231], v[212:215], v[64:67]
	s_barrier
	v_readfirstlane_b32 s43, v148
	v_lshl_add_u64 v[164:165], v[236:237], 0, s[18:19]
	s_mov_b32 m0, s43
	ds_read_b128 v[188:191], v152 offset:16384
	ds_read_b128 v[192:195], v152 offset:17408
	ds_read_b128 v[196:199], v151 offset:16384
	ds_read_b128 v[200:203], v151 offset:17408
	ds_read_b128 v[204:207], v150 offset:16384
	ds_read_b128 v[208:211], v150 offset:17408
	ds_read_b128 v[212:215], v149 offset:16384
	ds_read_b128 v[232:235], v149 offset:17408
	global_load_lds_dwordx4 v[164:165], off
	v_add_u32_e32 v164, 0x2000, v148
	v_lshl_add_u64 v[166:167], v[238:239], 0, s[18:19]
	v_readfirstlane_b32 s43, v164
	s_mov_b32 m0, s43
	s_nop 0
	global_load_lds_dwordx4 v[166:167], off
	s_barrier
	s_waitcnt lgkmcnt(0)
	s_waitcnt lgkmcnt(0)
	v_mfma_f32_16x16x32_bf16 v[60:63], v[172:175], v[188:191], v[60:63]
	v_mfma_f32_16x16x32_bf16 v[56:59], v[180:183], v[188:191], v[56:59]
	v_mfma_f32_16x16x32_bf16 v[52:55], v[172:175], v[196:199], v[52:55]
	v_mfma_f32_16x16x32_bf16 v[48:51], v[180:183], v[196:199], v[48:51]
	v_mfma_f32_16x16x32_bf16 v[44:47], v[172:175], v[204:207], v[44:47]
	v_mfma_f32_16x16x32_bf16 v[40:43], v[180:183], v[204:207], v[40:43]
	v_mfma_f32_16x16x32_bf16 v[36:39], v[172:175], v[212:215], v[36:39]
	v_mfma_f32_16x16x32_bf16 v[32:35], v[180:183], v[212:215], v[32:35]
	v_mfma_f32_16x16x32_bf16 v[60:63], v[176:179], v[192:195], v[60:63]
	v_mfma_f32_16x16x32_bf16 v[56:59], v[184:187], v[192:195], v[56:59]
	v_mfma_f32_16x16x32_bf16 v[52:55], v[176:179], v[200:203], v[52:55]
	v_mfma_f32_16x16x32_bf16 v[48:51], v[184:187], v[200:203], v[48:51]
	v_mfma_f32_16x16x32_bf16 v[44:47], v[176:179], v[208:211], v[44:47]
	v_mfma_f32_16x16x32_bf16 v[40:43], v[184:187], v[208:211], v[40:43]
	v_mfma_f32_16x16x32_bf16 v[36:39], v[176:179], v[232:235], v[36:39]
	v_mfma_f32_16x16x32_bf16 v[32:35], v[184:187], v[232:235], v[32:35]
	s_barrier
; #define STAGE(P, BASE, LD, br, kt) do { const char* _g = (const char*)((BASE) + (size_t)(br) * (LD) + (size_t)(kt) * 64); \
;     for (int _i = 0; _i < 2; ++_i) { int _b = tidx * 16 + _i * 8192; int _r, _c; stage_rc(_b, _r, _c); \
;       __builtin_amdgcn_global_load_lds((const unsigned*)(_g + (unsigned)((_r * (LD) + _c) * 2)), (unsigned*)((char*)(P) + _b), 16, 0, 0); } } while (0)
; #define LDA(dst, b, h) for (int m = 0; m < 4; ++m) for (int k = 0; k < 2; ++k) \
;     dst[m][k] = *reinterpret_cast<const bf16x8*>((char*)SA(b, h) + lds_byte(wr * 64 + m * 16 + fr, k * 32 + fq * 8))
; #define LDB(dst, b, h) for (int n = 0; n < 2; ++n) for (int k = 0; k < 2; ++k) \
;     dst[n][k] = *reinterpret_cast<const bf16x8*>((char*)SB(b, h) + lds_byte(wc * 32 + n * 16 + fr, k * 32 + fq * 8))
; #define MMA(ai, bj, At_, Bt_) do { __builtin_amdgcn_s_setprio(1); \
;     for (int k = 0; k < 2; ++k) for (int m = 0; m < 4; ++m) for (int n = 0; n < 2; ++n) \
;       acc[ai][bj][m][n] = __builtin_amdgcn_mfma_f32_16x16x32_bf16(At_[m][k], Bt_[n][k], acc[ai][bj][m][n], 0, 0, 0); \
;     __builtin_amdgcn_s_setprio(0); } while (0)
; #define WAIT_V(n) asm volatile("s_waitcnt vmcnt(" #n ")" ::: "memory")
; #define WAIT_L(n) asm volatile("s_waitcnt lgkmcnt(" #n ")" ::: "memory")
; #define BAR __builtin_amdgcn_s_barrier()
; #define SCHED __builtin_amdgcn_sched_barrier(0)
; template <int EPI, int lda, int ldb, int N, int K>
; __device__ __forceinline__ void gemm_phase(const u16* __restrict__ A, const u16* __restrict__ Bt, const GemmEpi ep, int wv) {
;     ...
;       STAGE(SB(0, 1), Bt, ldb, bcol + HALF, t + 2);
;       WAIT_V(6); BAR; MMA(1, 1, At, B1); BAR;
;       LDB(B0, 1, 0); SCHED; LDA(At, 1, 0); STAGE(SA(0, 1), Ab, lda, brow + HALF, t + 2);
;       WAIT_L(8); BAR; WAIT_L(0); MMA(0, 0, At, B0); BAR; SCHED;
;       LDB(B1, 1, 1); STAGE(SB(1, 0), Bt, ldb, bcol, t + 3);
;       BAR; WAIT_L(0); MMA(0, 1, At, B1); BAR;
;       LDA(At, 1, 1); STAGE(SA(1, 0), Ab, lda, brow, t + 3);
	v_add_u32_e32 v165, s53, v153
	v_lshl_add_u64 v[166:167], v[240:241], 0, s[20:21]
	v_readfirstlane_b32 s43, v165
	s_mov_b32 m0, s43
	v_lshl_add_u64 v[172:173], v[242:243], 0, s[20:21]
	global_load_lds_dwordx4 v[166:167], off
	v_add_u32_e32 v166, 0x2000, v165
	s_nop 0
	v_readfirstlane_b32 s43, v166
	s_mov_b32 m0, s43
	s_nop 0
	global_load_lds_dwordx4 v[172:173], off
	s_waitcnt vmcnt(6)
	s_barrier
	v_mfma_f32_16x16x32_bf16 v[28:31], v[216:219], v[188:191], v[28:31]
	v_mfma_f32_16x16x32_bf16 v[24:27], v[224:227], v[188:191], v[24:27]
	v_mfma_f32_16x16x32_bf16 v[20:23], v[216:219], v[196:199], v[20:23]
	v_mfma_f32_16x16x32_bf16 v[16:19], v[224:227], v[196:199], v[16:19]
	v_mfma_f32_16x16x32_bf16 v[12:15], v[216:219], v[204:207], v[12:15]
	v_mfma_f32_16x16x32_bf16 v[8:11], v[224:227], v[204:207], v[8:11]
	v_mfma_f32_16x16x32_bf16 v[4:7], v[216:219], v[212:215], v[4:7]
	v_mfma_f32_16x16x32_bf16 v[0:3], v[224:227], v[212:215], v[0:3]
	v_mfma_f32_16x16x32_bf16 v[28:31], v[220:223], v[192:195], v[28:31]
	v_mfma_f32_16x16x32_bf16 v[24:27], v[228:231], v[192:195], v[24:27]
	v_mfma_f32_16x16x32_bf16 v[20:23], v[220:223], v[200:203], v[20:23]
	v_mfma_f32_16x16x32_bf16 v[16:19], v[228:231], v[200:203], v[16:19]
	v_mfma_f32_16x16x32_bf16 v[12:15], v[220:223], v[208:211], v[12:15]
	v_mfma_f32_16x16x32_bf16 v[8:11], v[228:231], v[208:211], v[8:11]
	v_mfma_f32_16x16x32_bf16 v[4:7], v[220:223], v[232:235], v[4:7]
	v_mfma_f32_16x16x32_bf16 v[0:3], v[228:231], v[232:235], v[0:3]
	s_barrier
	ds_read_b128 v[172:175], v156
	ds_read_b128 v[176:179], v156 offset:1024
	ds_read_b128 v[180:183], v156 offset:2048
	ds_read_b128 v[184:187], v156 offset:3072
	v_add_u32_e32 v167, 0x4000, v148
	v_add_u32_e32 v168, 0x6000, v148
	v_readfirstlane_b32 s43, v167
	v_lshl_add_u64 v[220:221], v[236:237], 0, s[22:23]
	s_mov_b32 m0, s43
	v_readfirstlane_b32 s43, v168
	ds_read_b128 v[188:191], v152 offset:32768
	ds_read_b128 v[192:195], v152 offset:33792
	ds_read_b128 v[196:199], v151 offset:32768
	ds_read_b128 v[200:203], v151 offset:33792
	ds_read_b128 v[204:207], v150 offset:32768
	ds_read_b128 v[208:211], v150 offset:33792
	ds_read_b128 v[212:215], v149 offset:32768
	ds_read_b128 v[216:219], v149 offset:33792
	global_load_lds_dwordx4 v[220:221], off
	s_waitcnt lgkmcnt(8)
	s_barrier
	s_waitcnt lgkmcnt(0)
	s_waitcnt lgkmcnt(0)
	v_mfma_f32_16x16x32_bf16 v[124:127], v[172:175], v[188:191], v[124:127]
	v_mfma_f32_16x16x32_bf16 v[120:123], v[180:183], v[188:191], v[120:123]
	v_mfma_f32_16x16x32_bf16 v[116:119], v[172:175], v[196:199], v[116:119]
	v_mfma_f32_16x16x32_bf16 v[112:115], v[180:183], v[196:199], v[112:115]
	v_mfma_f32_16x16x32_bf16 v[108:111], v[172:175], v[204:207], v[108:111]
	v_mfma_f32_16x16x32_bf16 v[104:107], v[180:183], v[204:207], v[104:107]
	v_mfma_f32_16x16x32_bf16 v[100:103], v[172:175], v[212:215], v[100:103]
	v_mfma_f32_16x16x32_bf16 v[96:99], v[180:183], v[212:215], v[96:99]
	v_lshl_add_u64 v[220:221], v[238:239], 0, s[22:23]
	s_mov_b32 m0, s43
	s_nop 0
	global_load_lds_dwordx4 v[220:221], off
	v_mfma_f32_16x16x32_bf16 v[124:127], v[176:179], v[192:195], v[124:127]
	v_mfma_f32_16x16x32_bf16 v[120:123], v[184:187], v[192:195], v[120:123]
	v_mfma_f32_16x16x32_bf16 v[116:119], v[176:179], v[200:203], v[116:119]
	v_mfma_f32_16x16x32_bf16 v[112:115], v[184:187], v[200:203], v[112:115]
	v_mfma_f32_16x16x32_bf16 v[108:111], v[176:179], v[208:211], v[108:111]
	v_mfma_f32_16x16x32_bf16 v[104:107], v[184:187], v[208:211], v[104:107]
	v_mfma_f32_16x16x32_bf16 v[100:103], v[176:179], v[216:219], v[100:103]
	v_mfma_f32_16x16x32_bf16 v[96:99], v[184:187], v[216:219], v[96:99]
	s_barrier
	v_readfirstlane_b32 s43, v155
	v_add_u32_e32 v171, 0x2000, v155
	v_lshl_add_u64 v[244:245], v[240:241], 0, s[24:25]
	s_mov_b32 m0, s43
	v_readfirstlane_b32 s43, v171
	ds_read_b128 v[220:223], v154
	ds_read_b128 v[224:227], v154 offset:1024
	ds_read_b128 v[228:231], v154 offset:2048
	ds_read_b128 v[232:235], v154 offset:3072
	global_load_lds_dwordx4 v[244:245], off
	v_lshl_add_u64 v[244:245], v[242:243], 0, s[24:25]
	s_mov_b32 m0, s43
	s_nop 0
	global_load_lds_dwordx4 v[244:245], off
	s_barrier
	s_waitcnt lgkmcnt(0)
	s_waitcnt lgkmcnt(0)
	v_mfma_f32_16x16x32_bf16 v[92:95], v[220:223], v[188:191], v[92:95]
	v_mfma_f32_16x16x32_bf16 v[88:91], v[228:231], v[188:191], v[88:91]
	v_mfma_f32_16x16x32_bf16 v[84:87], v[220:223], v[196:199], v[84:87]
	v_mfma_f32_16x16x32_bf16 v[80:83], v[228:231], v[196:199], v[80:83]
	v_mfma_f32_16x16x32_bf16 v[76:79], v[220:223], v[204:207], v[76:79]
	v_mfma_f32_16x16x32_bf16 v[72:75], v[228:231], v[204:207], v[72:75]
	v_mfma_f32_16x16x32_bf16 v[68:71], v[220:223], v[212:215], v[68:71]
	v_mfma_f32_16x16x32_bf16 v[64:67], v[228:231], v[212:215], v[64:67]
	v_mfma_f32_16x16x32_bf16 v[92:95], v[224:227], v[192:195], v[92:95]
	v_mfma_f32_16x16x32_bf16 v[88:91], v[232:235], v[192:195], v[88:91]
	v_mfma_f32_16x16x32_bf16 v[84:87], v[224:227], v[200:203], v[84:87]
	v_mfma_f32_16x16x32_bf16 v[80:83], v[232:235], v[200:203], v[80:83]
	v_mfma_f32_16x16x32_bf16 v[76:79], v[224:227], v[208:211], v[76:79]
	v_mfma_f32_16x16x32_bf16 v[72:75], v[232:235], v[208:211], v[72:75]
	v_mfma_f32_16x16x32_bf16 v[68:71], v[224:227], v[216:219], v[68:71]
	v_mfma_f32_16x16x32_bf16 v[64:67], v[232:235], v[216:219], v[64:67]
	s_barrier
	v_readfirstlane_b32 s43, v157
	v_lshl_add_u64 v[236:237], v[236:237], 0, s[26:27]
	s_mov_b32 m0, s43
	v_readfirstlane_b32 s43, v158
	ds_read_b128 v[188:191], v152 offset:49152
	ds_read_b128 v[192:195], v152 offset:50176
	ds_read_b128 v[196:199], v151 offset:49152
	ds_read_b128 v[200:203], v151 offset:50176
	ds_read_b128 v[204:207], v150 offset:49152
	ds_read_b128 v[208:211], v150 offset:50176
	ds_read_b128 v[212:215], v149 offset:49152
	ds_read_b128 v[216:219], v149 offset:50176
	global_load_lds_dwordx4 v[236:237], off
	v_lshl_add_u64 v[236:237], v[238:239], 0, s[26:27]
	s_mov_b32 m0, s43
	s_nop 0
	global_load_lds_dwordx4 v[236:237], off
	s_barrier
; #define STAGE(P, BASE, LD, br, kt) do { const char* _g = (const char*)((BASE) + (size_t)(br) * (LD) + (size_t)(kt) * 64); \
;     for (int _i = 0; _i < 2; ++_i) { int _b = tidx * 16 + _i * 8192; int _r, _c; stage_rc(_b, _r, _c); \
;       __builtin_amdgcn_global_load_lds((const unsigned*)(_g + (unsigned)((_r * (LD) + _c) * 2)), (unsigned*)((char*)(P) + _b), 16, 0, 0); } } while (0)
; #define LDA(dst, b, h) for (int m = 0; m < 4; ++m) for (int k = 0; k < 2; ++k) \
;     dst[m][k] = *reinterpret_cast<const bf16x8*>((char*)SA(b, h) + lds_byte(wr * 64 + m * 16 + fr, k * 32 + fq * 8))
; #define LDB(dst, b, h) for (int n = 0; n < 2; ++n) for (int k = 0; k < 2; ++k) \
;     dst[n][k] = *reinterpret_cast<const bf16x8*>((char*)SB(b, h) + lds_byte(wc * 32 + n * 16 + fr, k * 32 + fq * 8))
; #define MMA(ai, bj, At_, Bt_) do { __builtin_amdgcn_s_setprio(1); \
;     for (int k = 0; k < 2; ++k) for (int m = 0; m < 4; ++m) for (int n = 0; n < 2; ++n) \
;       acc[ai][bj][m][n] = __builtin_amdgcn_mfma_f32_16x16x32_bf16(At_[m][k], Bt_[n][k], acc[ai][bj][m][n], 0, 0, 0); \
;     __builtin_amdgcn_s_setprio(0); } while (0)
; #define WAIT_V(n) asm volatile("s_waitcnt vmcnt(" #n ")" ::: "memory")
; #define WAIT_L(n) asm volatile("s_waitcnt lgkmcnt(" #n ")" ::: "memory")
; #define BAR __builtin_amdgcn_s_barrier()
; #define SCHED __builtin_amdgcn_sched_barrier(0)
; template <int EPI, int lda, int ldb, int N, int K>
; __device__ __forceinline__ void gemm_phase(const u16* __restrict__ A, const u16* __restrict__ Bt, const GemmEpi ep, int wv) {
;     ...
;       BAR; WAIT_L(0); MMA(1, 0, At, B0); BAR; SCHED;
;       STAGE(SB(1, 1), Bt, ldb, bcol + HALF, t + 3);
;       WAIT_V(6); BAR; MMA(1, 1, At, B1); BAR;
;     }
;     { LDB(B0, 0, 0); LDA(At, 0, 0); STAGE(SA(1, 1), Ab, lda, brow + HALF, nt - 1);
;       BAR; WAIT_L(0); MMA(0, 0, At, B0); BAR;
;       LDB(B1, 0, 1); BAR; WAIT_L(0); MMA(0, 1, At, B1); BAR;
	s_waitcnt lgkmcnt(0)
	s_waitcnt lgkmcnt(0)
	v_mfma_f32_16x16x32_bf16 v[60:63], v[172:175], v[188:191], v[60:63]
	v_mfma_f32_16x16x32_bf16 v[56:59], v[180:183], v[188:191], v[56:59]
	v_mfma_f32_16x16x32_bf16 v[52:55], v[172:175], v[196:199], v[52:55]
	v_mfma_f32_16x16x32_bf16 v[48:51], v[180:183], v[196:199], v[48:51]
	v_mfma_f32_16x16x32_bf16 v[44:47], v[172:175], v[204:207], v[44:47]
	v_mfma_f32_16x16x32_bf16 v[40:43], v[180:183], v[204:207], v[40:43]
	v_mfma_f32_16x16x32_bf16 v[36:39], v[172:175], v[212:215], v[36:39]
	v_mfma_f32_16x16x32_bf16 v[32:35], v[180:183], v[212:215], v[32:35]
	v_mfma_f32_16x16x32_bf16 v[60:63], v[176:179], v[192:195], v[60:63]
	v_mfma_f32_16x16x32_bf16 v[56:59], v[184:187], v[192:195], v[56:59]
	v_mfma_f32_16x16x32_bf16 v[52:55], v[176:179], v[200:203], v[52:55]
	v_mfma_f32_16x16x32_bf16 v[48:51], v[184:187], v[200:203], v[48:51]
	v_mfma_f32_16x16x32_bf16 v[44:47], v[176:179], v[208:211], v[44:47]
	v_mfma_f32_16x16x32_bf16 v[40:43], v[184:187], v[208:211], v[40:43]
	v_mfma_f32_16x16x32_bf16 v[36:39], v[176:179], v[216:219], v[36:39]
	v_mfma_f32_16x16x32_bf16 v[32:35], v[184:187], v[216:219], v[32:35]
	s_barrier
	v_readfirstlane_b32 s43, v159
	v_add_u32_e32 v171, 0x2000, v159
	v_lshl_add_u64 v[172:173], v[240:241], 0, s[34:35]
	s_mov_b32 m0, s43
	v_readfirstlane_b32 s43, v171
	global_load_lds_dwordx4 v[172:173], off
	v_lshl_add_u64 v[172:173], v[242:243], 0, s[34:35]
	s_mov_b32 m0, s43
	s_nop 0
	global_load_lds_dwordx4 v[172:173], off
	s_waitcnt vmcnt(6)
	s_barrier
	v_mfma_f32_16x16x32_bf16 v[28:31], v[220:223], v[188:191], v[28:31]
	v_mfma_f32_16x16x32_bf16 v[24:27], v[228:231], v[188:191], v[24:27]
	v_mfma_f32_16x16x32_bf16 v[20:23], v[220:223], v[196:199], v[20:23]
	v_mfma_f32_16x16x32_bf16 v[16:19], v[228:231], v[196:199], v[16:19]
	v_mfma_f32_16x16x32_bf16 v[12:15], v[220:223], v[204:207], v[12:15]
	v_mfma_f32_16x16x32_bf16 v[8:11], v[228:231], v[204:207], v[8:11]
	v_mfma_f32_16x16x32_bf16 v[4:7], v[220:223], v[212:215], v[4:7]
	v_mfma_f32_16x16x32_bf16 v[0:3], v[228:231], v[212:215], v[0:3]
	v_mfma_f32_16x16x32_bf16 v[28:31], v[224:227], v[192:195], v[28:31]
	v_mfma_f32_16x16x32_bf16 v[24:27], v[232:235], v[192:195], v[24:27]
	v_mfma_f32_16x16x32_bf16 v[20:23], v[224:227], v[200:203], v[20:23]
	v_mfma_f32_16x16x32_bf16 v[16:19], v[232:235], v[200:203], v[16:19]
	v_mfma_f32_16x16x32_bf16 v[12:15], v[224:227], v[208:211], v[12:15]
	v_mfma_f32_16x16x32_bf16 v[8:11], v[232:235], v[208:211], v[8:11]
	v_mfma_f32_16x16x32_bf16 v[4:7], v[224:227], v[216:219], v[4:7]
	v_mfma_f32_16x16x32_bf16 v[0:3], v[232:235], v[216:219], v[0:3]
	s_add_i32 s42, s42, 2
	s_add_u32 s40, s40, 0x100
	s_addc_u32 s41, s41, 0
	s_cmp_gt_u32 s42, 27
	s_barrier
	s_cbranch_scc0 .LBB0_1564
	s_add_i32 s40, s38, 0x80
	s_mul_hi_i32 s41, s40, 0x1080
	s_mulk_i32 s40, 0x1080
	s_add_u32 s40, s49, s40
	s_addc_u32 s41, s50, s41
	v_lshl_add_u64 v[158:159], s[40:41], 0, v[128:129]
	v_readfirstlane_b32 s42, v169
	v_lshl_add_u64 v[158:159], v[158:159], 0, s[36:37]
	s_mov_b32 m0, s42
	ds_read_b128 v[134:137], v161
	ds_read_b128 v[138:141], v161 offset:1024
	ds_read_b128 v[172:175], v161 offset:2048
	ds_read_b128 v[176:179], v161 offset:3072
	ds_read_b128 v[180:183], v152
	ds_read_b128 v[184:187], v152 offset:1024
	ds_read_b128 v[188:191], v151
	ds_read_b128 v[192:195], v151 offset:1024
	ds_read_b128 v[196:199], v150
	ds_read_b128 v[200:203], v150 offset:1024
	ds_read_b128 v[204:207], v149
	ds_read_b128 v[208:211], v149 offset:1024
	global_load_lds_dwordx4 v[158:159], off
	v_lshl_add_u64 v[158:159], s[40:41], 0, v[132:133]
	v_readfirstlane_b32 s40, v170
	v_lshl_add_u64 v[158:159], v[158:159], 0, s[36:37]
	s_mov_b32 m0, s40
	s_nop 0
	global_load_lds_dwordx4 v[158:159], off
	s_barrier
	s_waitcnt lgkmcnt(0)
	s_waitcnt lgkmcnt(0)
	v_mfma_f32_16x16x32_bf16 v[124:127], v[134:137], v[180:183], v[124:127]
	v_mfma_f32_16x16x32_bf16 v[120:123], v[172:175], v[180:183], v[120:123]
	v_mfma_f32_16x16x32_bf16 v[116:119], v[134:137], v[188:191], v[116:119]
	v_mfma_f32_16x16x32_bf16 v[112:115], v[172:175], v[188:191], v[112:115]
	v_mfma_f32_16x16x32_bf16 v[108:111], v[134:137], v[196:199], v[108:111]
	v_mfma_f32_16x16x32_bf16 v[104:107], v[172:175], v[196:199], v[104:107]
	v_mfma_f32_16x16x32_bf16 v[100:103], v[134:137], v[204:207], v[100:103]
	v_mfma_f32_16x16x32_bf16 v[96:99], v[172:175], v[204:207], v[96:99]
	v_mfma_f32_16x16x32_bf16 v[124:127], v[138:141], v[184:187], v[124:127]
	v_mfma_f32_16x16x32_bf16 v[120:123], v[176:179], v[184:187], v[120:123]
	v_mfma_f32_16x16x32_bf16 v[116:119], v[138:141], v[192:195], v[116:119]
	v_mfma_f32_16x16x32_bf16 v[112:115], v[176:179], v[192:195], v[112:115]
	v_mfma_f32_16x16x32_bf16 v[108:111], v[138:141], v[200:203], v[108:111]
	v_mfma_f32_16x16x32_bf16 v[104:107], v[176:179], v[200:203], v[104:107]
	v_mfma_f32_16x16x32_bf16 v[100:103], v[138:141], v[208:211], v[100:103]
	v_mfma_f32_16x16x32_bf16 v[96:99], v[176:179], v[208:211], v[96:99]
	s_barrier
	ds_read_b128 v[212:215], v160
	ds_read_b128 v[216:219], v160 offset:1024
	ds_read_b128 v[220:223], v160 offset:2048
	ds_read_b128 v[158:161], v160 offset:3072
	s_barrier
; #define LDA(dst, b, h) for (int m = 0; m < 4; ++m) for (int k = 0; k < 2; ++k) \
;     dst[m][k] = *reinterpret_cast<const bf16x8*>((char*)SA(b, h) + lds_byte(wr * 64 + m * 16 + fr, k * 32 + fq * 8))
; #define LDB(dst, b, h) for (int n = 0; n < 2; ++n) for (int k = 0; k < 2; ++k) \
;     dst[n][k] = *reinterpret_cast<const bf16x8*>((char*)SB(b, h) + lds_byte(wc * 32 + n * 16 + fr, k * 32 + fq * 8))
; #define MMA(ai, bj, At_, Bt_) do { __builtin_amdgcn_s_setprio(1); \
;     for (int k = 0; k < 2; ++k) for (int m = 0; m < 4; ++m) for (int n = 0; n < 2; ++n) \
;       acc[ai][bj][m][n] = __builtin_amdgcn_mfma_f32_16x16x32_bf16(At_[m][k], Bt_[n][k], acc[ai][bj][m][n], 0, 0, 0); \
;     __builtin_amdgcn_s_setprio(0); } while (0)
; #define WAIT_V(n) asm volatile("s_waitcnt vmcnt(" #n ")" ::: "memory")
; #define WAIT_L(n) asm volatile("s_waitcnt lgkmcnt(" #n ")" ::: "memory")
; #define BAR __builtin_amdgcn_s_barrier()
; template <int EPI, int lda, int ldb, int N, int K>
; __device__ __forceinline__ void gemm_phase(const u16* __restrict__ A, const u16* __restrict__ Bt, const GemmEpi ep, int wv) {
;     ...
;       LDB(B1, 0, 1); BAR; WAIT_L(0); MMA(0, 1, At, B1); BAR;
;       LDA(At, 0, 1); WAIT_V(4); BAR; WAIT_L(0); MMA(1, 0, At, B0); MMA(1, 1, At, B1); BAR; }
;     { LDB(B0, 1, 0); LDA(At, 1, 0); WAIT_V(2); BAR; WAIT_L(0); MMA(0, 0, At, B0); BAR;
	s_waitcnt lgkmcnt(0)
	s_waitcnt lgkmcnt(0)
	v_mfma_f32_16x16x32_bf16 v[92:95], v[212:215], v[180:183], v[92:95]
	v_mfma_f32_16x16x32_bf16 v[88:91], v[220:223], v[180:183], v[88:91]
	v_mfma_f32_16x16x32_bf16 v[76:79], v[212:215], v[196:199], v[76:79]
	v_mfma_f32_16x16x32_bf16 v[72:75], v[220:223], v[196:199], v[72:75]
	v_mfma_f32_16x16x32_bf16 v[84:87], v[212:215], v[188:191], v[84:87]
	v_mfma_f32_16x16x32_bf16 v[80:83], v[220:223], v[188:191], v[80:83]
	v_mfma_f32_16x16x32_bf16 v[68:71], v[212:215], v[204:207], v[68:71]
	v_mfma_f32_16x16x32_bf16 v[64:67], v[220:223], v[204:207], v[64:67]
	v_mfma_f32_16x16x32_bf16 v[92:95], v[216:219], v[184:187], v[92:95]
	v_mfma_f32_16x16x32_bf16 v[88:91], v[158:161], v[184:187], v[88:91]
	v_mfma_f32_16x16x32_bf16 v[76:79], v[216:219], v[200:203], v[76:79]
	v_mfma_f32_16x16x32_bf16 v[72:75], v[158:161], v[200:203], v[72:75]
	v_mfma_f32_16x16x32_bf16 v[180:183], v[216:219], v[192:195], v[84:87]
	v_mfma_f32_16x16x32_bf16 v[184:187], v[158:161], v[192:195], v[80:83]
	v_mfma_f32_16x16x32_bf16 v[188:191], v[216:219], v[208:211], v[68:71]
	v_mfma_f32_16x16x32_bf16 v[192:195], v[158:161], v[208:211], v[64:67]
	s_barrier
	s_nop 0
	ds_read_b128 v[64:67], v152 offset:16384
	ds_read_b128 v[68:71], v152 offset:17408
	ds_read_b128 v[80:83], v151 offset:16384
	ds_read_b128 v[84:87], v151 offset:17408
	ds_read_b128 v[196:199], v150 offset:16384
	ds_read_b128 v[200:203], v150 offset:17408
	ds_read_b128 v[204:207], v149 offset:16384
	ds_read_b128 v[208:211], v149 offset:17408
	s_waitcnt vmcnt(4)
	s_barrier
	s_waitcnt lgkmcnt(0)
	s_waitcnt lgkmcnt(0)
	v_mfma_f32_16x16x32_bf16 v[60:63], v[134:137], v[64:67], v[60:63]
	v_mfma_f32_16x16x32_bf16 v[56:59], v[172:175], v[64:67], v[56:59]
	v_mfma_f32_16x16x32_bf16 v[52:55], v[134:137], v[80:83], v[52:55]
	v_mfma_f32_16x16x32_bf16 v[48:51], v[172:175], v[80:83], v[48:51]
	v_mfma_f32_16x16x32_bf16 v[44:47], v[134:137], v[196:199], v[44:47]
	v_mfma_f32_16x16x32_bf16 v[40:43], v[172:175], v[196:199], v[40:43]
	v_mfma_f32_16x16x32_bf16 v[36:39], v[134:137], v[204:207], v[36:39]
	v_mfma_f32_16x16x32_bf16 v[32:35], v[172:175], v[204:207], v[32:35]
	v_mfma_f32_16x16x32_bf16 v[60:63], v[138:141], v[68:71], v[60:63]
	v_mfma_f32_16x16x32_bf16 v[56:59], v[176:179], v[68:71], v[56:59]
	v_mfma_f32_16x16x32_bf16 v[52:55], v[138:141], v[84:87], v[52:55]
	v_mfma_f32_16x16x32_bf16 v[48:51], v[176:179], v[84:87], v[48:51]
	v_mfma_f32_16x16x32_bf16 v[44:47], v[138:141], v[200:203], v[44:47]
	v_mfma_f32_16x16x32_bf16 v[40:43], v[176:179], v[200:203], v[40:43]
	v_mfma_f32_16x16x32_bf16 v[36:39], v[138:141], v[208:211], v[36:39]
	v_mfma_f32_16x16x32_bf16 v[32:35], v[176:179], v[208:211], v[32:35]
	v_mfma_f32_16x16x32_bf16 v[28:31], v[212:215], v[64:67], v[28:31]
	v_mfma_f32_16x16x32_bf16 v[24:27], v[220:223], v[64:67], v[24:27]
	v_mfma_f32_16x16x32_bf16 v[12:15], v[212:215], v[196:199], v[12:15]
	v_mfma_f32_16x16x32_bf16 v[8:11], v[220:223], v[196:199], v[8:11]
	v_mfma_f32_16x16x32_bf16 v[20:23], v[212:215], v[80:83], v[20:23]
	v_mfma_f32_16x16x32_bf16 v[16:19], v[220:223], v[80:83], v[16:19]
	v_mfma_f32_16x16x32_bf16 v[4:7], v[212:215], v[204:207], v[4:7]
	v_mfma_f32_16x16x32_bf16 v[0:3], v[220:223], v[204:207], v[0:3]
	v_mfma_f32_16x16x32_bf16 v[28:31], v[216:219], v[68:71], v[28:31]
	v_mfma_f32_16x16x32_bf16 v[24:27], v[158:161], v[68:71], v[24:27]
	v_mfma_f32_16x16x32_bf16 v[12:15], v[216:219], v[200:203], v[12:15]
	v_mfma_f32_16x16x32_bf16 v[8:11], v[158:161], v[200:203], v[8:11]
	v_mfma_f32_16x16x32_bf16 v[134:137], v[216:219], v[84:87], v[20:23]
	v_mfma_f32_16x16x32_bf16 v[138:141], v[158:161], v[84:87], v[16:19]
	v_mfma_f32_16x16x32_bf16 v[170:173], v[216:219], v[208:211], v[4:7]
	v_mfma_f32_16x16x32_bf16 v[158:161], v[158:161], v[208:211], v[0:3]
	s_barrier
	s_nop 0
	ds_read_b128 v[0:3], v156
	ds_read_b128 v[4:7], v156 offset:1024
	ds_read_b128 v[16:19], v156 offset:2048
	ds_read_b128 v[174:177], v156 offset:3072
	ds_read_b128 v[20:23], v152 offset:32768
	ds_read_b128 v[196:199], v152 offset:33792
	ds_read_b128 v[200:203], v151 offset:32768
	ds_read_b128 v[204:207], v151 offset:33792
	ds_read_b128 v[208:211], v150 offset:32768
	ds_read_b128 v[212:215], v150 offset:33792
	ds_read_b128 v[216:219], v149 offset:32768
	ds_read_b128 v[220:223], v149 offset:33792
	s_waitcnt vmcnt(2)
	s_barrier
; #define LDA(dst, b, h) for (int m = 0; m < 4; ++m) for (int k = 0; k < 2; ++k) \
;     dst[m][k] = *reinterpret_cast<const bf16x8*>((char*)SA(b, h) + lds_byte(wr * 64 + m * 16 + fr, k * 32 + fq * 8))
; #define LDB(dst, b, h) for (int n = 0; n < 2; ++n) for (int k = 0; k < 2; ++k) \
;     dst[n][k] = *reinterpret_cast<const bf16x8*>((char*)SB(b, h) + lds_byte(wc * 32 + n * 16 + fr, k * 32 + fq * 8))
; #define MMA(ai, bj, At_, Bt_) do { __builtin_amdgcn_s_setprio(1); \
;     for (int k = 0; k < 2; ++k) for (int m = 0; m < 4; ++m) for (int n = 0; n < 2; ++n) \
;       acc[ai][bj][m][n] = __builtin_amdgcn_mfma_f32_16x16x32_bf16(At_[m][k], Bt_[n][k], acc[ai][bj][m][n], 0, 0, 0); \
;     __builtin_amdgcn_s_setprio(0); } while (0)
; #define WAIT_V(n) asm volatile("s_waitcnt vmcnt(" #n ")" ::: "memory")
; #define WAIT_L(n) asm volatile("s_waitcnt lgkmcnt(" #n ")" ::: "memory")
; #define BAR __builtin_amdgcn_s_barrier()
; template <int EPI, int lda, int ldb, int N, int K>
; __device__ __forceinline__ void gemm_phase(const u16* __restrict__ A, const u16* __restrict__ Bt, const GemmEpi ep, int wv) {
;     ...
;     { LDB(B0, 1, 0); LDA(At, 1, 0); WAIT_V(2); BAR; WAIT_L(0); MMA(0, 0, At, B0); BAR;
;       LDB(B1, 1, 1); WAIT_V(0); BAR; WAIT_L(0); MMA(0, 1, At, B1); BAR;
;       LDA(At, 1, 1); BAR; WAIT_L(0); MMA(1, 0, At, B0); MMA(1, 1, At, B1); BAR; }
;     if (wr == 0) BAR;
	s_waitcnt lgkmcnt(0)
	s_waitcnt lgkmcnt(0)
	v_mfma_f32_16x16x32_bf16 v[64:67], v[0:3], v[20:23], v[124:127]
	v_mfma_f32_16x16x32_bf16 v[68:71], v[16:19], v[20:23], v[120:123]
	v_mfma_f32_16x16x32_bf16 v[80:83], v[0:3], v[200:203], v[116:119]
	v_mfma_f32_16x16x32_bf16 v[84:87], v[16:19], v[200:203], v[112:115]
	v_mfma_f32_16x16x32_bf16 v[108:111], v[0:3], v[208:211], v[108:111]
	v_mfma_f32_16x16x32_bf16 v[104:107], v[16:19], v[208:211], v[104:107]
	v_mfma_f32_16x16x32_bf16 v[120:123], v[0:3], v[216:219], v[100:103]
	v_mfma_f32_16x16x32_bf16 v[124:127], v[16:19], v[216:219], v[96:99]
	v_mfma_f32_16x16x32_bf16 v[116:119], v[4:7], v[196:199], v[64:67]
	v_mfma_f32_16x16x32_bf16 v[112:115], v[174:177], v[196:199], v[68:71]
	v_mfma_f32_16x16x32_bf16 v[100:103], v[4:7], v[204:207], v[80:83]
	v_mfma_f32_16x16x32_bf16 v[96:99], v[174:177], v[204:207], v[84:87]
	v_mfma_f32_16x16x32_bf16 v[84:87], v[4:7], v[212:215], v[108:111]
	v_mfma_f32_16x16x32_bf16 v[80:83], v[174:177], v[212:215], v[104:107]
	v_mfma_f32_16x16x32_bf16 v[68:71], v[4:7], v[220:223], v[120:123]
	v_mfma_f32_16x16x32_bf16 v[64:67], v[174:177], v[220:223], v[124:127]
	s_barrier
	ds_read_b128 v[224:227], v154
	ds_read_b128 v[228:231], v154 offset:1024
	ds_read_b128 v[232:235], v154 offset:2048
	ds_read_b128 v[154:157], v154 offset:3072
	s_waitcnt vmcnt(0)
	s_barrier
	s_waitcnt lgkmcnt(0)
	s_waitcnt lgkmcnt(0)
	v_mfma_f32_16x16x32_bf16 v[92:95], v[224:227], v[20:23], v[92:95]
	v_mfma_f32_16x16x32_bf16 v[20:23], v[232:235], v[20:23], v[88:91]
	v_mfma_f32_16x16x32_bf16 v[88:91], v[224:227], v[200:203], v[180:183]
	v_mfma_f32_16x16x32_bf16 v[104:107], v[232:235], v[200:203], v[184:187]
	v_mfma_f32_16x16x32_bf16 v[76:79], v[224:227], v[208:211], v[76:79]
	v_mfma_f32_16x16x32_bf16 v[72:75], v[232:235], v[208:211], v[72:75]
	v_mfma_f32_16x16x32_bf16 v[178:181], v[224:227], v[216:219], v[188:191]
	v_mfma_f32_16x16x32_bf16 v[182:185], v[232:235], v[216:219], v[192:195]
	v_mfma_f32_16x16x32_bf16 v[124:127], v[228:231], v[196:199], v[92:95]
	v_mfma_f32_16x16x32_bf16 v[120:123], v[154:157], v[196:199], v[20:23]
	v_mfma_f32_16x16x32_bf16 v[108:111], v[228:231], v[204:207], v[88:91]
	v_mfma_f32_16x16x32_bf16 v[104:107], v[154:157], v[204:207], v[104:107]
	v_mfma_f32_16x16x32_bf16 v[92:95], v[228:231], v[212:215], v[76:79]
	v_mfma_f32_16x16x32_bf16 v[88:91], v[154:157], v[212:215], v[72:75]
	v_mfma_f32_16x16x32_bf16 v[76:79], v[228:231], v[220:223], v[178:181]
	v_mfma_f32_16x16x32_bf16 v[72:75], v[154:157], v[220:223], v[182:185]
	s_barrier
	ds_read_b128 v[178:181], v152 offset:49152
	ds_read_b128 v[182:185], v152 offset:50176
	ds_read_b128 v[186:189], v151 offset:49152
	ds_read_b128 v[190:193], v151 offset:50176
	ds_read_b128 v[194:197], v150 offset:49152
	ds_read_b128 v[150:153], v150 offset:50176
	ds_read_b128 v[198:201], v149 offset:49152
	ds_read_b128 v[202:205], v149 offset:50176
	s_barrier
	s_waitcnt lgkmcnt(0)
	s_waitcnt lgkmcnt(0)
	v_mfma_f32_16x16x32_bf16 v[20:23], v[0:3], v[178:181], v[60:63]
	v_mfma_f32_16x16x32_bf16 v[56:59], v[16:19], v[178:181], v[56:59]
	v_mfma_f32_16x16x32_bf16 v[60:63], v[0:3], v[186:189], v[52:55]
	v_mfma_f32_16x16x32_bf16 v[206:209], v[16:19], v[186:189], v[48:51]
	v_mfma_f32_16x16x32_bf16 v[44:47], v[0:3], v[194:197], v[44:47]
	v_mfma_f32_16x16x32_bf16 v[40:43], v[16:19], v[194:197], v[40:43]
	v_mfma_f32_16x16x32_bf16 v[0:3], v[0:3], v[198:201], v[36:39]
	v_mfma_f32_16x16x32_bf16 v[210:213], v[16:19], v[198:201], v[32:35]
	v_mfma_f32_16x16x32_bf16 v[52:55], v[4:7], v[182:185], v[20:23]
	v_mfma_f32_16x16x32_bf16 v[48:51], v[174:177], v[182:185], v[56:59]
	v_mfma_f32_16x16x32_bf16 v[36:39], v[4:7], v[190:193], v[60:63]
	v_mfma_f32_16x16x32_bf16 v[32:35], v[174:177], v[190:193], v[206:209]
	v_mfma_f32_16x16x32_bf16 v[20:23], v[4:7], v[150:153], v[44:47]
	v_mfma_f32_16x16x32_bf16 v[16:19], v[174:177], v[150:153], v[40:43]
	v_mfma_f32_16x16x32_bf16 v[4:7], v[4:7], v[202:205], v[0:3]
	v_mfma_f32_16x16x32_bf16 v[0:3], v[174:177], v[202:205], v[210:213]
	v_mfma_f32_16x16x32_bf16 v[28:31], v[224:227], v[178:181], v[28:31]
	v_mfma_f32_16x16x32_bf16 v[24:27], v[232:235], v[178:181], v[24:27]
	v_mfma_f32_16x16x32_bf16 v[40:43], v[224:227], v[186:189], v[134:137]
	v_mfma_f32_16x16x32_bf16 v[134:137], v[232:235], v[186:189], v[138:141]
	v_mfma_f32_16x16x32_bf16 v[12:15], v[224:227], v[194:197], v[12:15]
	v_mfma_f32_16x16x32_bf16 v[8:11], v[232:235], v[194:197], v[8:11]
	v_mfma_f32_16x16x32_bf16 v[138:141], v[224:227], v[198:201], v[170:173]
	v_mfma_f32_16x16x32_bf16 v[158:161], v[232:235], v[198:201], v[158:161]
	v_mfma_f32_16x16x32_bf16 v[60:63], v[228:231], v[182:185], v[28:31]
	v_mfma_f32_16x16x32_bf16 v[56:59], v[154:157], v[182:185], v[24:27]
	v_mfma_f32_16x16x32_bf16 v[44:47], v[228:231], v[190:193], v[40:43]
	v_mfma_f32_16x16x32_bf16 v[40:43], v[154:157], v[190:193], v[134:137]
	v_mfma_f32_16x16x32_bf16 v[28:31], v[228:231], v[150:153], v[12:15]
	v_mfma_f32_16x16x32_bf16 v[24:27], v[154:157], v[150:153], v[8:11]
	v_mfma_f32_16x16x32_bf16 v[12:15], v[228:231], v[202:205], v[138:141]
	v_mfma_f32_16x16x32_bf16 v[8:11], v[154:157], v[202:205], v[158:161]
	v_cmp_gt_u32_e32 vcc, s54, v130
	s_barrier
	s_and_saveexec_b64 s[40:41], vcc
	s_cbranch_execz .LBB0_1567
	s_barrier

; #define STAGE(P, BASE, LD, br, kt) do { const char* _g = (const char*)((BASE) + (size_t)(br) * (LD) + (size_t)(kt) * 64); \
;     for (int _i = 0; _i < 2; ++_i) { int _b = tidx * 16 + _i * 8192; int _r, _c; stage_rc(_b, _r, _c); \
;       __builtin_amdgcn_global_load_lds((const unsigned*)(_g + (unsigned)((_r * (LD) + _c) * 2)), (unsigned*)((char*)(P) + _b), 16, 0, 0); } } while (0)
; #define LDA(dst, b, h) for (int m = 0; m < 4; ++m) for (int k = 0; k < 2; ++k) \
;     dst[m][k] = *reinterpret_cast<const bf16x8*>((char*)SA(b, h) + lds_byte(wr * 64 + m * 16 + fr, k * 32 + fq * 8))
; #define LDB(dst, b, h) for (int n = 0; n < 2; ++n) for (int k = 0; k < 2; ++k) \
;     dst[n][k] = *reinterpret_cast<const bf16x8*>((char*)SB(b, h) + lds_byte(wc * 32 + n * 16 + fr, k * 32 + fq * 8))
; #define MMA(ai, bj, At_, Bt_) do { __builtin_amdgcn_s_setprio(1); \
;     for (int k = 0; k < 2; ++k) for (int m = 0; m < 4; ++m) for (int n = 0; n < 2; ++n) \
;       acc[ai][bj][m][n] = __builtin_amdgcn_mfma_f32_16x16x32_bf16(At_[m][k], Bt_[n][k], acc[ai][bj][m][n], 0, 0, 0); \
;     __builtin_amdgcn_s_setprio(0); } while (0)
; #define WAIT_L(n) asm volatile("s_waitcnt lgkmcnt(" #n ")" ::: "memory")
; #define BAR __builtin_amdgcn_s_barrier()
; #define SCHED __builtin_amdgcn_sched_barrier(0)
; template <int EPI, int lda, int ldb, int N, int K>
; __device__ __forceinline__ void gemm_phase(const u16* __restrict__ A, const u16* __restrict__ Bt, const GemmEpi ep, int wv) {
;     ...
;     for (int t = 0; t < nt - 2; t += 2) {
;       LDB(B0, 0, 0); SCHED; LDA(At, 0, 0); STAGE(SA(1, 1), Ab, lda, brow + HALF, t + 1);
;       WAIT_L(8); BAR; WAIT_L(0); MMA(0, 0, At, B0); BAR; SCHED;
;       LDB(B1, 0, 1); STAGE(SB(0, 0), Bt, ldb, bcol, t + 2);
;       BAR; WAIT_L(0); MMA(0, 1, At, B1); BAR;
;       LDA(At, 0, 1); STAGE(SA(0, 0), Ab, lda, brow, t + 2);
;       BAR; WAIT_L(0); MMA(1, 0, At, B0); BAR; SCHED;
.LBB0_1624:
	ds_read_b128 v[174:177], v163
	ds_read_b128 v[178:181], v163 offset:1024
	ds_read_b128 v[182:185], v163 offset:2048
	ds_read_b128 v[186:189], v163 offset:3072
	v_add_u32_e32 v171, 0xc000, v149
	v_lshl_add_u64 v[238:239], v[134:135], 0, s[28:29]
	v_readfirstlane_b32 s50, v171
	v_add_u32_e32 v172, 0xe000, v149
	v_lshl_add_u64 v[164:165], v[238:239], 0, s[10:11]
	s_mov_b32 m0, s50
	v_lshl_add_u64 v[240:241], v[132:133], 0, s[28:29]
	v_readfirstlane_b32 s50, v172
	ds_read_b128 v[166:169], v154
	ds_read_b128 v[190:193], v154 offset:1024
	ds_read_b128 v[194:197], v153
	ds_read_b128 v[198:201], v153 offset:1024
	ds_read_b128 v[202:205], v151
	ds_read_b128 v[206:209], v151 offset:1024
	ds_read_b128 v[210:213], v150
	ds_read_b128 v[214:217], v150 offset:1024
	global_load_lds_dwordx4 v[164:165], off
	s_waitcnt lgkmcnt(8)
	s_barrier
	s_waitcnt lgkmcnt(0)
	s_waitcnt lgkmcnt(0)
	v_mfma_f32_16x16x32_bf16 v[124:127], v[166:169], v[174:177], v[124:127]
	v_mfma_f32_16x16x32_bf16 v[120:123], v[166:169], v[182:185], v[120:123]
	v_mfma_f32_16x16x32_bf16 v[116:119], v[194:197], v[174:177], v[116:119]
	v_mfma_f32_16x16x32_bf16 v[112:115], v[194:197], v[182:185], v[112:115]
	v_mfma_f32_16x16x32_bf16 v[108:111], v[202:205], v[174:177], v[108:111]
	v_mfma_f32_16x16x32_bf16 v[104:107], v[202:205], v[182:185], v[104:107]
	v_mfma_f32_16x16x32_bf16 v[100:103], v[210:213], v[174:177], v[100:103]
	v_mfma_f32_16x16x32_bf16 v[96:99], v[210:213], v[182:185], v[96:99]
	v_lshl_add_u64 v[164:165], v[240:241], 0, s[10:11]
	s_mov_b32 m0, s50
	s_nop 0
	global_load_lds_dwordx4 v[164:165], off
	v_mfma_f32_16x16x32_bf16 v[124:127], v[190:193], v[178:181], v[124:127]
	v_mfma_f32_16x16x32_bf16 v[120:123], v[190:193], v[186:189], v[120:123]
	v_mfma_f32_16x16x32_bf16 v[116:119], v[198:201], v[178:181], v[116:119]
	v_mfma_f32_16x16x32_bf16 v[112:115], v[198:201], v[186:189], v[112:115]
	v_mfma_f32_16x16x32_bf16 v[108:111], v[206:209], v[178:181], v[108:111]
	v_mfma_f32_16x16x32_bf16 v[104:107], v[206:209], v[186:189], v[104:107]
	v_mfma_f32_16x16x32_bf16 v[100:103], v[214:217], v[178:181], v[100:103]
	v_mfma_f32_16x16x32_bf16 v[96:99], v[214:217], v[186:189], v[96:99]
	s_barrier
	v_add_u32_e32 v164, s40, v155
	v_lshl_add_u64 v[242:243], v[142:143], 0, s[28:29]
	v_readfirstlane_b32 s50, v164
	v_add_u32_e32 v165, 0x2000, v164
	v_lshl_add_u64 v[234:235], v[242:243], 0, s[12:13]
	s_mov_b32 m0, s50
	v_lshl_add_u64 v[244:245], v[140:141], 0, s[28:29]
	v_readfirstlane_b32 s50, v165
	ds_read_b128 v[218:221], v162
	ds_read_b128 v[222:225], v162 offset:1024
	ds_read_b128 v[226:229], v162 offset:2048
	ds_read_b128 v[230:233], v162 offset:3072
	global_load_lds_dwordx4 v[234:235], off
	v_lshl_add_u64 v[234:235], v[244:245], 0, s[12:13]
	s_mov_b32 m0, s50
	s_nop 0
	global_load_lds_dwordx4 v[234:235], off
	s_barrier
	s_waitcnt lgkmcnt(0)
	s_waitcnt lgkmcnt(0)
	v_mfma_f32_16x16x32_bf16 v[92:95], v[166:169], v[218:221], v[92:95]
	v_mfma_f32_16x16x32_bf16 v[88:91], v[166:169], v[226:229], v[88:91]
	v_mfma_f32_16x16x32_bf16 v[84:87], v[194:197], v[218:221], v[84:87]
	v_mfma_f32_16x16x32_bf16 v[80:83], v[194:197], v[226:229], v[80:83]
	v_mfma_f32_16x16x32_bf16 v[76:79], v[202:205], v[218:221], v[76:79]
	v_mfma_f32_16x16x32_bf16 v[72:75], v[202:205], v[226:229], v[72:75]
	v_mfma_f32_16x16x32_bf16 v[68:71], v[210:213], v[218:221], v[68:71]
	v_mfma_f32_16x16x32_bf16 v[64:67], v[210:213], v[226:229], v[64:67]
	v_mfma_f32_16x16x32_bf16 v[92:95], v[190:193], v[222:225], v[92:95]
	v_mfma_f32_16x16x32_bf16 v[88:91], v[190:193], v[230:233], v[88:91]
	v_mfma_f32_16x16x32_bf16 v[84:87], v[198:201], v[222:225], v[84:87]
	v_mfma_f32_16x16x32_bf16 v[80:83], v[198:201], v[230:233], v[80:83]
	v_mfma_f32_16x16x32_bf16 v[76:79], v[206:209], v[222:225], v[76:79]
	v_mfma_f32_16x16x32_bf16 v[72:75], v[206:209], v[230:233], v[72:75]
	v_mfma_f32_16x16x32_bf16 v[68:71], v[214:217], v[222:225], v[68:71]
	v_mfma_f32_16x16x32_bf16 v[64:67], v[214:217], v[230:233], v[64:67]
	s_barrier
	v_readfirstlane_b32 s50, v149
	v_lshl_add_u64 v[166:167], v[238:239], 0, s[14:15]
	s_mov_b32 m0, s50
	ds_read_b128 v[190:193], v154 offset:16384
	ds_read_b128 v[194:197], v154 offset:17408
	ds_read_b128 v[198:201], v153 offset:16384
	ds_read_b128 v[202:205], v153 offset:17408
	ds_read_b128 v[206:209], v151 offset:16384
	ds_read_b128 v[210:213], v151 offset:17408
	ds_read_b128 v[214:217], v150 offset:16384
	ds_read_b128 v[234:237], v150 offset:17408
	global_load_lds_dwordx4 v[166:167], off
	v_add_u32_e32 v166, 0x2000, v149
	v_lshl_add_u64 v[168:169], v[240:241], 0, s[14:15]
	v_readfirstlane_b32 s50, v166
	s_mov_b32 m0, s50
	s_nop 0
	global_load_lds_dwordx4 v[168:169], off
	s_barrier
	s_waitcnt lgkmcnt(0)
	s_waitcnt lgkmcnt(0)
	v_mfma_f32_16x16x32_bf16 v[60:63], v[190:193], v[174:177], v[60:63]
	v_mfma_f32_16x16x32_bf16 v[56:59], v[190:193], v[182:185], v[56:59]
	v_mfma_f32_16x16x32_bf16 v[52:55], v[198:201], v[174:177], v[52:55]
	v_mfma_f32_16x16x32_bf16 v[48:51], v[198:201], v[182:185], v[48:51]
	v_mfma_f32_16x16x32_bf16 v[44:47], v[206:209], v[174:177], v[44:47]
	v_mfma_f32_16x16x32_bf16 v[40:43], v[206:209], v[182:185], v[40:43]
	v_mfma_f32_16x16x32_bf16 v[36:39], v[214:217], v[174:177], v[36:39]
	v_mfma_f32_16x16x32_bf16 v[32:35], v[214:217], v[182:185], v[32:35]
	v_mfma_f32_16x16x32_bf16 v[60:63], v[194:197], v[178:181], v[60:63]
	v_mfma_f32_16x16x32_bf16 v[56:59], v[194:197], v[186:189], v[56:59]
	v_mfma_f32_16x16x32_bf16 v[52:55], v[202:205], v[178:181], v[52:55]
	v_mfma_f32_16x16x32_bf16 v[48:51], v[202:205], v[186:189], v[48:51]
	v_mfma_f32_16x16x32_bf16 v[44:47], v[210:213], v[178:181], v[44:47]
	v_mfma_f32_16x16x32_bf16 v[40:43], v[210:213], v[186:189], v[40:43]
	v_mfma_f32_16x16x32_bf16 v[36:39], v[234:237], v[178:181], v[36:39]
	v_mfma_f32_16x16x32_bf16 v[32:35], v[234:237], v[186:189], v[32:35]
	s_barrier
; #define STAGE(P, BASE, LD, br, kt) do { const char* _g = (const char*)((BASE) + (size_t)(br) * (LD) + (size_t)(kt) * 64); \
;     for (int _i = 0; _i < 2; ++_i) { int _b = tidx * 16 + _i * 8192; int _r, _c; stage_rc(_b, _r, _c); \
;       __builtin_amdgcn_global_load_lds((const unsigned*)(_g + (unsigned)((_r * (LD) + _c) * 2)), (unsigned*)((char*)(P) + _b), 16, 0, 0); } } while (0)
; #define LDA(dst, b, h) for (int m = 0; m < 4; ++m) for (int k = 0; k < 2; ++k) \
;     dst[m][k] = *reinterpret_cast<const bf16x8*>((char*)SA(b, h) + lds_byte(wr * 64 + m * 16 + fr, k * 32 + fq * 8))
; #define LDB(dst, b, h) for (int n = 0; n < 2; ++n) for (int k = 0; k < 2; ++k) \
;     dst[n][k] = *reinterpret_cast<const bf16x8*>((char*)SB(b, h) + lds_byte(wc * 32 + n * 16 + fr, k * 32 + fq * 8))
; #define MMA(ai, bj, At_, Bt_) do { __builtin_amdgcn_s_setprio(1); \
;     for (int k = 0; k < 2; ++k) for (int m = 0; m < 4; ++m) for (int n = 0; n < 2; ++n) \
;       acc[ai][bj][m][n] = __builtin_amdgcn_mfma_f32_16x16x32_bf16(At_[m][k], Bt_[n][k], acc[ai][bj][m][n], 0, 0, 0); \
;     __builtin_amdgcn_s_setprio(0); } while (0)
; #define WAIT_V(n) asm volatile("s_waitcnt vmcnt(" #n ")" ::: "memory")
; #define WAIT_L(n) asm volatile("s_waitcnt lgkmcnt(" #n ")" ::: "memory")
; #define BAR __builtin_amdgcn_s_barrier()
; #define SCHED __builtin_amdgcn_sched_barrier(0)
; template <int EPI, int lda, int ldb, int N, int K>
; __device__ __forceinline__ void gemm_phase(const u16* __restrict__ A, const u16* __restrict__ Bt, const GemmEpi ep, int wv) {
;     ...
;       STAGE(SB(0, 1), Bt, ldb, bcol + HALF, t + 2);
;       WAIT_V(6); BAR; MMA(1, 1, At, B1); BAR;
;       LDB(B0, 1, 0); SCHED; LDA(At, 1, 0); STAGE(SA(0, 1), Ab, lda, brow + HALF, t + 2);
;       WAIT_L(8); BAR; WAIT_L(0); MMA(0, 0, At, B0); BAR; SCHED;
;       LDB(B1, 1, 1); STAGE(SB(1, 0), Bt, ldb, bcol, t + 3);
;       BAR; WAIT_L(0); MMA(0, 1, At, B1); BAR;
;       LDA(At, 1, 1); STAGE(SA(1, 0), Ab, lda, brow, t + 3);
	v_add_u32_e32 v167, s41, v155
	v_lshl_add_u64 v[246:247], v[138:139], 0, s[28:29]
	v_readfirstlane_b32 s50, v167
	v_lshl_add_u64 v[168:169], v[246:247], 0, s[16:17]
	s_mov_b32 m0, s50
	v_lshl_add_u64 v[248:249], v[136:137], 0, s[28:29]
	global_load_lds_dwordx4 v[168:169], off
	v_add_u32_e32 v168, 0x2000, v167
	v_lshl_add_u64 v[174:175], v[248:249], 0, s[16:17]
	v_readfirstlane_b32 s50, v168
	s_mov_b32 m0, s50
	s_nop 0
	global_load_lds_dwordx4 v[174:175], off
	s_waitcnt vmcnt(6)
	s_barrier
	v_mfma_f32_16x16x32_bf16 v[28:31], v[190:193], v[218:221], v[28:31]
	v_mfma_f32_16x16x32_bf16 v[24:27], v[190:193], v[226:229], v[24:27]
	v_mfma_f32_16x16x32_bf16 v[20:23], v[198:201], v[218:221], v[20:23]
	v_mfma_f32_16x16x32_bf16 v[16:19], v[198:201], v[226:229], v[16:19]
	v_mfma_f32_16x16x32_bf16 v[12:15], v[206:209], v[218:221], v[12:15]
	v_mfma_f32_16x16x32_bf16 v[8:11], v[206:209], v[226:229], v[8:11]
	v_mfma_f32_16x16x32_bf16 v[4:7], v[214:217], v[218:221], v[4:7]
	v_mfma_f32_16x16x32_bf16 v[0:3], v[214:217], v[226:229], v[0:3]
	v_mfma_f32_16x16x32_bf16 v[28:31], v[194:197], v[222:225], v[28:31]
	v_mfma_f32_16x16x32_bf16 v[24:27], v[194:197], v[230:233], v[24:27]
	v_mfma_f32_16x16x32_bf16 v[20:23], v[202:205], v[222:225], v[20:23]
	v_mfma_f32_16x16x32_bf16 v[16:19], v[202:205], v[230:233], v[16:19]
	v_mfma_f32_16x16x32_bf16 v[12:15], v[210:213], v[222:225], v[12:15]
	v_mfma_f32_16x16x32_bf16 v[8:11], v[210:213], v[230:233], v[8:11]
	v_mfma_f32_16x16x32_bf16 v[4:7], v[234:237], v[222:225], v[4:7]
	v_mfma_f32_16x16x32_bf16 v[0:3], v[234:237], v[230:233], v[0:3]
	s_barrier
	ds_read_b128 v[174:177], v158
	ds_read_b128 v[178:181], v158 offset:1024
	ds_read_b128 v[182:185], v158 offset:2048
	ds_read_b128 v[186:189], v158 offset:3072
	v_add_u32_e32 v169, 0x4000, v149
	v_add_u32_e32 v170, 0x6000, v149
	v_readfirstlane_b32 s50, v169
	v_lshl_add_u64 v[222:223], v[238:239], 0, s[18:19]
	s_mov_b32 m0, s50
	v_readfirstlane_b32 s50, v170
	ds_read_b128 v[190:193], v154 offset:32768
	ds_read_b128 v[194:197], v154 offset:33792
	ds_read_b128 v[198:201], v153 offset:32768
	ds_read_b128 v[202:205], v153 offset:33792
	ds_read_b128 v[206:209], v151 offset:32768
	ds_read_b128 v[210:213], v151 offset:33792
	ds_read_b128 v[214:217], v150 offset:32768
	ds_read_b128 v[218:221], v150 offset:33792
	global_load_lds_dwordx4 v[222:223], off
	s_waitcnt lgkmcnt(8)
	s_barrier
	s_waitcnt lgkmcnt(0)
	s_waitcnt lgkmcnt(0)
	v_mfma_f32_16x16x32_bf16 v[124:127], v[190:193], v[174:177], v[124:127]
	v_mfma_f32_16x16x32_bf16 v[120:123], v[190:193], v[182:185], v[120:123]
	v_mfma_f32_16x16x32_bf16 v[116:119], v[198:201], v[174:177], v[116:119]
	v_mfma_f32_16x16x32_bf16 v[112:115], v[198:201], v[182:185], v[112:115]
	v_mfma_f32_16x16x32_bf16 v[108:111], v[206:209], v[174:177], v[108:111]
	v_mfma_f32_16x16x32_bf16 v[104:107], v[206:209], v[182:185], v[104:107]
	v_mfma_f32_16x16x32_bf16 v[100:103], v[214:217], v[174:177], v[100:103]
	v_mfma_f32_16x16x32_bf16 v[96:99], v[214:217], v[182:185], v[96:99]
	v_lshl_add_u64 v[222:223], v[240:241], 0, s[18:19]
	s_mov_b32 m0, s50
	s_nop 0
	global_load_lds_dwordx4 v[222:223], off
	v_mfma_f32_16x16x32_bf16 v[124:127], v[194:197], v[178:181], v[124:127]
	v_mfma_f32_16x16x32_bf16 v[120:123], v[194:197], v[186:189], v[120:123]
	v_mfma_f32_16x16x32_bf16 v[116:119], v[202:205], v[178:181], v[116:119]
	v_mfma_f32_16x16x32_bf16 v[112:115], v[202:205], v[186:189], v[112:115]
	v_mfma_f32_16x16x32_bf16 v[108:111], v[210:213], v[178:181], v[108:111]
	v_mfma_f32_16x16x32_bf16 v[104:107], v[210:213], v[186:189], v[104:107]
	v_mfma_f32_16x16x32_bf16 v[100:103], v[218:221], v[178:181], v[100:103]
	v_mfma_f32_16x16x32_bf16 v[96:99], v[218:221], v[186:189], v[96:99]
	s_barrier
	v_readfirstlane_b32 s50, v157
	v_add_u32_e32 v173, 0x2000, v157
	v_lshl_add_u64 v[242:243], v[242:243], 0, s[20:21]
	s_mov_b32 m0, s50
	v_readfirstlane_b32 s50, v173
	ds_read_b128 v[222:225], v156
	ds_read_b128 v[226:229], v156 offset:1024
	ds_read_b128 v[230:233], v156 offset:2048
	ds_read_b128 v[234:237], v156 offset:3072
	global_load_lds_dwordx4 v[242:243], off
	v_lshl_add_u64 v[242:243], v[244:245], 0, s[20:21]
	s_mov_b32 m0, s50
	s_nop 0
	global_load_lds_dwordx4 v[242:243], off
	s_barrier
	s_waitcnt lgkmcnt(0)
	s_waitcnt lgkmcnt(0)
	v_mfma_f32_16x16x32_bf16 v[92:95], v[190:193], v[222:225], v[92:95]
	v_mfma_f32_16x16x32_bf16 v[88:91], v[190:193], v[230:233], v[88:91]
	v_mfma_f32_16x16x32_bf16 v[84:87], v[198:201], v[222:225], v[84:87]
	v_mfma_f32_16x16x32_bf16 v[80:83], v[198:201], v[230:233], v[80:83]
	v_mfma_f32_16x16x32_bf16 v[76:79], v[206:209], v[222:225], v[76:79]
	v_mfma_f32_16x16x32_bf16 v[72:75], v[206:209], v[230:233], v[72:75]
	v_mfma_f32_16x16x32_bf16 v[68:71], v[214:217], v[222:225], v[68:71]
	v_mfma_f32_16x16x32_bf16 v[64:67], v[214:217], v[230:233], v[64:67]
	v_mfma_f32_16x16x32_bf16 v[92:95], v[194:197], v[226:229], v[92:95]
	v_mfma_f32_16x16x32_bf16 v[88:91], v[194:197], v[234:237], v[88:91]
	v_mfma_f32_16x16x32_bf16 v[84:87], v[202:205], v[226:229], v[84:87]
	v_mfma_f32_16x16x32_bf16 v[80:83], v[202:205], v[234:237], v[80:83]
	v_mfma_f32_16x16x32_bf16 v[76:79], v[210:213], v[226:229], v[76:79]
	v_mfma_f32_16x16x32_bf16 v[72:75], v[210:213], v[234:237], v[72:75]
	v_mfma_f32_16x16x32_bf16 v[68:71], v[218:221], v[226:229], v[68:71]
	v_mfma_f32_16x16x32_bf16 v[64:67], v[218:221], v[234:237], v[64:67]
	s_barrier
; #define STAGE(P, BASE, LD, br, kt) do { const char* _g = (const char*)((BASE) + (size_t)(br) * (LD) + (size_t)(kt) * 64); \
;     for (int _i = 0; _i < 2; ++_i) { int _b = tidx * 16 + _i * 8192; int _r, _c; stage_rc(_b, _r, _c); \
;       __builtin_amdgcn_global_load_lds((const unsigned*)(_g + (unsigned)((_r * (LD) + _c) * 2)), (unsigned*)((char*)(P) + _b), 16, 0, 0); } } while (0)
; #define LDA(dst, b, h) for (int m = 0; m < 4; ++m) for (int k = 0; k < 2; ++k) \
;     dst[m][k] = *reinterpret_cast<const bf16x8*>((char*)SA(b, h) + lds_byte(wr * 64 + m * 16 + fr, k * 32 + fq * 8))
; #define LDB(dst, b, h) for (int n = 0; n < 2; ++n) for (int k = 0; k < 2; ++k) \
;     dst[n][k] = *reinterpret_cast<const bf16x8*>((char*)SB(b, h) + lds_byte(wc * 32 + n * 16 + fr, k * 32 + fq * 8))
; #define MMA(ai, bj, At_, Bt_) do { __builtin_amdgcn_s_setprio(1); \
;     for (int k = 0; k < 2; ++k) for (int m = 0; m < 4; ++m) for (int n = 0; n < 2; ++n) \
;       acc[ai][bj][m][n] = __builtin_amdgcn_mfma_f32_16x16x32_bf16(At_[m][k], Bt_[n][k], acc[ai][bj][m][n], 0, 0, 0); \
;     __builtin_amdgcn_s_setprio(0); } while (0)
; #define WAIT_V(n) asm volatile("s_waitcnt vmcnt(" #n ")" ::: "memory")
; #define WAIT_L(n) asm volatile("s_waitcnt lgkmcnt(" #n ")" ::: "memory")
; #define BAR __builtin_amdgcn_s_barrier()
; #define SCHED __builtin_amdgcn_sched_barrier(0)
; template <int EPI, int lda, int ldb, int N, int K>
; __device__ __forceinline__ void gemm_phase(const u16* __restrict__ A, const u16* __restrict__ Bt, const GemmEpi ep, int wv) {
;     ...
;       BAR; WAIT_L(0); MMA(1, 0, At, B0); BAR; SCHED;
;       STAGE(SB(1, 1), Bt, ldb, bcol + HALF, t + 3);
;       WAIT_V(6); BAR; MMA(1, 1, At, B1); BAR;
;     }
;     { LDB(B0, 0, 0); LDA(At, 0, 0); STAGE(SA(1, 1), Ab, lda, brow + HALF, nt - 1);
;       BAR; WAIT_L(0); MMA(0, 0, At, B0); BAR;
;       LDB(B1, 0, 1); BAR; WAIT_L(0); MMA(0, 1, At, B1); BAR;
	v_readfirstlane_b32 s50, v159
	v_lshl_add_u64 v[238:239], v[238:239], 0, s[22:23]
	s_mov_b32 m0, s50
	v_readfirstlane_b32 s50, v160
	ds_read_b128 v[190:193], v154 offset:49152
	ds_read_b128 v[194:197], v154 offset:50176
	ds_read_b128 v[198:201], v153 offset:49152
	ds_read_b128 v[202:205], v153 offset:50176
	ds_read_b128 v[206:209], v151 offset:49152
	ds_read_b128 v[210:213], v151 offset:50176
	ds_read_b128 v[214:217], v150 offset:49152
	ds_read_b128 v[218:221], v150 offset:50176
	global_load_lds_dwordx4 v[238:239], off
	v_lshl_add_u64 v[238:239], v[240:241], 0, s[22:23]
	s_mov_b32 m0, s50
	s_nop 0
	global_load_lds_dwordx4 v[238:239], off
	s_barrier
	s_waitcnt lgkmcnt(0)
	s_waitcnt lgkmcnt(0)
	v_mfma_f32_16x16x32_bf16 v[60:63], v[190:193], v[174:177], v[60:63]
	v_mfma_f32_16x16x32_bf16 v[56:59], v[190:193], v[182:185], v[56:59]
	v_mfma_f32_16x16x32_bf16 v[52:55], v[198:201], v[174:177], v[52:55]
	v_mfma_f32_16x16x32_bf16 v[48:51], v[198:201], v[182:185], v[48:51]
	v_mfma_f32_16x16x32_bf16 v[44:47], v[206:209], v[174:177], v[44:47]
	v_mfma_f32_16x16x32_bf16 v[40:43], v[206:209], v[182:185], v[40:43]
	v_mfma_f32_16x16x32_bf16 v[36:39], v[214:217], v[174:177], v[36:39]
	v_mfma_f32_16x16x32_bf16 v[32:35], v[214:217], v[182:185], v[32:35]
	v_mfma_f32_16x16x32_bf16 v[60:63], v[194:197], v[178:181], v[60:63]
	v_mfma_f32_16x16x32_bf16 v[56:59], v[194:197], v[186:189], v[56:59]
	v_mfma_f32_16x16x32_bf16 v[52:55], v[202:205], v[178:181], v[52:55]
	v_mfma_f32_16x16x32_bf16 v[48:51], v[202:205], v[186:189], v[48:51]
	v_mfma_f32_16x16x32_bf16 v[44:47], v[210:213], v[178:181], v[44:47]
	v_mfma_f32_16x16x32_bf16 v[40:43], v[210:213], v[186:189], v[40:43]
	v_mfma_f32_16x16x32_bf16 v[36:39], v[218:221], v[178:181], v[36:39]
	v_mfma_f32_16x16x32_bf16 v[32:35], v[218:221], v[186:189], v[32:35]
	s_barrier
	v_readfirstlane_b32 s50, v161
	v_add_u32_e32 v173, 0x2000, v161
	v_lshl_add_u64 v[174:175], v[246:247], 0, s[24:25]
	s_mov_b32 m0, s50
	v_readfirstlane_b32 s50, v173
	global_load_lds_dwordx4 v[174:175], off
	v_lshl_add_u64 v[174:175], v[248:249], 0, s[24:25]
	s_mov_b32 m0, s50
	s_nop 0
	global_load_lds_dwordx4 v[174:175], off
	s_waitcnt vmcnt(6)
	s_barrier
	v_mfma_f32_16x16x32_bf16 v[28:31], v[190:193], v[222:225], v[28:31]
	v_mfma_f32_16x16x32_bf16 v[24:27], v[190:193], v[230:233], v[24:27]
	v_mfma_f32_16x16x32_bf16 v[20:23], v[198:201], v[222:225], v[20:23]
	v_mfma_f32_16x16x32_bf16 v[16:19], v[198:201], v[230:233], v[16:19]
	v_mfma_f32_16x16x32_bf16 v[12:15], v[206:209], v[222:225], v[12:15]
	v_mfma_f32_16x16x32_bf16 v[8:11], v[206:209], v[230:233], v[8:11]
	v_mfma_f32_16x16x32_bf16 v[4:7], v[214:217], v[222:225], v[4:7]
	v_mfma_f32_16x16x32_bf16 v[0:3], v[214:217], v[230:233], v[0:3]
	v_mfma_f32_16x16x32_bf16 v[28:31], v[194:197], v[226:229], v[28:31]
	v_mfma_f32_16x16x32_bf16 v[24:27], v[194:197], v[234:237], v[24:27]
	v_mfma_f32_16x16x32_bf16 v[20:23], v[202:205], v[226:229], v[20:23]
	v_mfma_f32_16x16x32_bf16 v[16:19], v[202:205], v[234:237], v[16:19]
	v_mfma_f32_16x16x32_bf16 v[12:15], v[210:213], v[226:229], v[12:15]
	v_mfma_f32_16x16x32_bf16 v[8:11], v[210:213], v[234:237], v[8:11]
	v_mfma_f32_16x16x32_bf16 v[4:7], v[218:221], v[226:229], v[4:7]
	v_mfma_f32_16x16x32_bf16 v[0:3], v[218:221], v[234:237], v[0:3]
	s_add_i32 s49, s49, 2
	s_add_u32 s28, s28, 0x100
	s_addc_u32 s29, s29, 0
	s_cmpk_gt_u32 s49, 0x51
	s_barrier
	s_cbranch_scc0 .LBB0_1624
	s_add_i32 s28, s48, 0x80
	s_mul_hi_i32 s29, s28, 0x2b00
	s_mulk_i32 s28, 0x2b00
	s_add_u32 s28, s34, s28
	s_addc_u32 s29, s35, s29
	s_add_u32 s28, s28, 0x2a80
	s_addc_u32 s29, s29, 0
	v_readfirstlane_b32 s49, v171
	v_lshl_add_u64 v[160:161], s[28:29], 0, v[128:129]
	s_mov_b32 m0, s49
	ds_read_b128 v[132:135], v163
	ds_read_b128 v[136:139], v163 offset:1024
	ds_read_b128 v[140:143], v163 offset:2048
	ds_read_b128 v[174:177], v163 offset:3072
	ds_read_b128 v[178:181], v154
	ds_read_b128 v[182:185], v154 offset:1024
	ds_read_b128 v[186:189], v153
	ds_read_b128 v[190:193], v153 offset:1024
	ds_read_b128 v[194:197], v151
	ds_read_b128 v[198:201], v151 offset:1024
	ds_read_b128 v[202:205], v150
	ds_read_b128 v[206:209], v150 offset:1024
	global_load_lds_dwordx4 v[160:161], off
	v_lshl_add_u64 v[160:161], s[28:29], 0, v[130:131]
	v_readfirstlane_b32 s28, v172
	s_mov_b32 m0, s28
	s_nop 0
	global_load_lds_dwordx4 v[160:161], off
	s_barrier
	s_waitcnt lgkmcnt(0)
	s_waitcnt lgkmcnt(0)
	v_mfma_f32_16x16x32_bf16 v[124:127], v[178:181], v[132:135], v[124:127]
	v_mfma_f32_16x16x32_bf16 v[120:123], v[178:181], v[140:143], v[120:123]
	v_mfma_f32_16x16x32_bf16 v[116:119], v[186:189], v[132:135], v[116:119]
	v_mfma_f32_16x16x32_bf16 v[112:115], v[186:189], v[140:143], v[112:115]
	v_mfma_f32_16x16x32_bf16 v[108:111], v[194:197], v[132:135], v[108:111]
	v_mfma_f32_16x16x32_bf16 v[104:107], v[194:197], v[140:143], v[104:107]
	v_mfma_f32_16x16x32_bf16 v[100:103], v[202:205], v[132:135], v[100:103]
	v_mfma_f32_16x16x32_bf16 v[96:99], v[202:205], v[140:143], v[96:99]
	v_mfma_f32_16x16x32_bf16 v[124:127], v[182:185], v[136:139], v[124:127]
	v_mfma_f32_16x16x32_bf16 v[120:123], v[182:185], v[174:177], v[120:123]
	v_mfma_f32_16x16x32_bf16 v[116:119], v[190:193], v[136:139], v[116:119]
	v_mfma_f32_16x16x32_bf16 v[112:115], v[190:193], v[174:177], v[112:115]
	v_mfma_f32_16x16x32_bf16 v[108:111], v[198:201], v[136:139], v[108:111]
	v_mfma_f32_16x16x32_bf16 v[104:107], v[198:201], v[174:177], v[104:107]
	v_mfma_f32_16x16x32_bf16 v[100:103], v[206:209], v[136:139], v[100:103]
	v_mfma_f32_16x16x32_bf16 v[96:99], v[206:209], v[174:177], v[96:99]
	s_barrier
; #define LDA(dst, b, h) for (int m = 0; m < 4; ++m) for (int k = 0; k < 2; ++k) \
;     dst[m][k] = *reinterpret_cast<const bf16x8*>((char*)SA(b, h) + lds_byte(wr * 64 + m * 16 + fr, k * 32 + fq * 8))
; #define LDB(dst, b, h) for (int n = 0; n < 2; ++n) for (int k = 0; k < 2; ++k) \
;     dst[n][k] = *reinterpret_cast<const bf16x8*>((char*)SB(b, h) + lds_byte(wc * 32 + n * 16 + fr, k * 32 + fq * 8))
; #define MMA(ai, bj, At_, Bt_) do { __builtin_amdgcn_s_setprio(1); \
;     for (int k = 0; k < 2; ++k) for (int m = 0; m < 4; ++m) for (int n = 0; n < 2; ++n) \
;       acc[ai][bj][m][n] = __builtin_amdgcn_mfma_f32_16x16x32_bf16(At_[m][k], Bt_[n][k], acc[ai][bj][m][n], 0, 0, 0); \
;     __builtin_amdgcn_s_setprio(0); } while (0)
; #define WAIT_V(n) asm volatile("s_waitcnt vmcnt(" #n ")" ::: "memory")
; #define WAIT_L(n) asm volatile("s_waitcnt lgkmcnt(" #n ")" ::: "memory")
; #define BAR __builtin_amdgcn_s_barrier()
; template <int EPI, int lda, int ldb, int N, int K>
; __device__ __forceinline__ void gemm_phase(const u16* __restrict__ A, const u16* __restrict__ Bt, const GemmEpi ep, int wv) {
;     ...
;       LDB(B1, 0, 1); BAR; WAIT_L(0); MMA(0, 1, At, B1); BAR;
;       LDA(At, 0, 1); WAIT_V(4); BAR; WAIT_L(0); MMA(1, 0, At, B0); MMA(1, 1, At, B1); BAR; }
;     { LDB(B0, 1, 0); LDA(At, 1, 0); WAIT_V(2); BAR; WAIT_L(0); MMA(0, 0, At, B0); BAR;
	ds_read_b128 v[210:213], v162
	ds_read_b128 v[214:217], v162 offset:1024
	ds_read_b128 v[218:221], v162 offset:2048
	ds_read_b128 v[160:163], v162 offset:3072
	s_barrier
	s_waitcnt lgkmcnt(0)
	s_waitcnt lgkmcnt(0)
	v_mfma_f32_16x16x32_bf16 v[92:95], v[178:181], v[210:213], v[92:95]
	v_mfma_f32_16x16x32_bf16 v[88:91], v[178:181], v[218:221], v[88:91]
	v_mfma_f32_16x16x32_bf16 v[72:75], v[194:197], v[218:221], v[72:75]
	v_mfma_f32_16x16x32_bf16 v[68:71], v[202:205], v[210:213], v[68:71]
	v_mfma_f32_16x16x32_bf16 v[84:87], v[186:189], v[210:213], v[84:87]
	v_mfma_f32_16x16x32_bf16 v[80:83], v[186:189], v[218:221], v[80:83]
	v_mfma_f32_16x16x32_bf16 v[76:79], v[194:197], v[210:213], v[76:79]
	v_mfma_f32_16x16x32_bf16 v[64:67], v[202:205], v[218:221], v[64:67]
	v_mfma_f32_16x16x32_bf16 v[92:95], v[182:185], v[214:217], v[92:95]
	v_mfma_f32_16x16x32_bf16 v[88:91], v[182:185], v[160:163], v[88:91]
	v_mfma_f32_16x16x32_bf16 v[72:75], v[198:201], v[160:163], v[72:75]
	v_mfma_f32_16x16x32_bf16 v[68:71], v[206:209], v[214:217], v[68:71]
	v_mfma_f32_16x16x32_bf16 v[178:181], v[190:193], v[214:217], v[84:87]
	v_mfma_f32_16x16x32_bf16 v[182:185], v[190:193], v[160:163], v[80:83]
	v_mfma_f32_16x16x32_bf16 v[186:189], v[198:201], v[214:217], v[76:79]
	v_mfma_f32_16x16x32_bf16 v[190:193], v[206:209], v[160:163], v[64:67]
	s_barrier
	s_nop 0
	ds_read_b128 v[64:67], v154 offset:16384
	ds_read_b128 v[76:79], v154 offset:17408
	ds_read_b128 v[80:83], v153 offset:16384
	ds_read_b128 v[84:87], v153 offset:17408
	ds_read_b128 v[194:197], v151 offset:16384
	ds_read_b128 v[198:201], v151 offset:17408
	ds_read_b128 v[202:205], v150 offset:16384
	ds_read_b128 v[206:209], v150 offset:17408
	s_waitcnt vmcnt(4)
	s_barrier
	s_waitcnt lgkmcnt(0)
	s_waitcnt lgkmcnt(0)
	v_mfma_f32_16x16x32_bf16 v[60:63], v[64:67], v[132:135], v[60:63]
	v_mfma_f32_16x16x32_bf16 v[56:59], v[64:67], v[140:143], v[56:59]
	v_mfma_f32_16x16x32_bf16 v[52:55], v[80:83], v[132:135], v[52:55]
	v_mfma_f32_16x16x32_bf16 v[48:51], v[80:83], v[140:143], v[48:51]
	v_mfma_f32_16x16x32_bf16 v[44:47], v[194:197], v[132:135], v[44:47]
	v_mfma_f32_16x16x32_bf16 v[40:43], v[194:197], v[140:143], v[40:43]
	v_mfma_f32_16x16x32_bf16 v[36:39], v[202:205], v[132:135], v[36:39]
	v_mfma_f32_16x16x32_bf16 v[32:35], v[202:205], v[140:143], v[32:35]
	v_mfma_f32_16x16x32_bf16 v[60:63], v[76:79], v[136:139], v[60:63]
	v_mfma_f32_16x16x32_bf16 v[56:59], v[76:79], v[174:177], v[56:59]
	v_mfma_f32_16x16x32_bf16 v[52:55], v[84:87], v[136:139], v[52:55]
	v_mfma_f32_16x16x32_bf16 v[48:51], v[84:87], v[174:177], v[48:51]
	v_mfma_f32_16x16x32_bf16 v[44:47], v[198:201], v[136:139], v[44:47]
	v_mfma_f32_16x16x32_bf16 v[40:43], v[198:201], v[174:177], v[40:43]
	v_mfma_f32_16x16x32_bf16 v[36:39], v[206:209], v[136:139], v[36:39]
	v_mfma_f32_16x16x32_bf16 v[32:35], v[206:209], v[174:177], v[32:35]
	v_mfma_f32_16x16x32_bf16 v[28:31], v[64:67], v[210:213], v[28:31]
	v_mfma_f32_16x16x32_bf16 v[24:27], v[64:67], v[218:221], v[24:27]
	v_mfma_f32_16x16x32_bf16 v[12:15], v[194:197], v[210:213], v[12:15]
	v_mfma_f32_16x16x32_bf16 v[8:11], v[194:197], v[218:221], v[8:11]
	v_mfma_f32_16x16x32_bf16 v[20:23], v[80:83], v[210:213], v[20:23]
	v_mfma_f32_16x16x32_bf16 v[16:19], v[80:83], v[218:221], v[16:19]
	v_mfma_f32_16x16x32_bf16 v[4:7], v[202:205], v[210:213], v[4:7]
	v_mfma_f32_16x16x32_bf16 v[0:3], v[202:205], v[218:221], v[0:3]
	v_mfma_f32_16x16x32_bf16 v[28:31], v[76:79], v[214:217], v[28:31]
	v_mfma_f32_16x16x32_bf16 v[24:27], v[76:79], v[160:163], v[24:27]
	v_mfma_f32_16x16x32_bf16 v[12:15], v[198:201], v[214:217], v[12:15]
	v_mfma_f32_16x16x32_bf16 v[8:11], v[198:201], v[160:163], v[8:11]
	v_mfma_f32_16x16x32_bf16 v[132:135], v[84:87], v[214:217], v[20:23]
	v_mfma_f32_16x16x32_bf16 v[136:139], v[84:87], v[160:163], v[16:19]
	v_mfma_f32_16x16x32_bf16 v[140:143], v[206:209], v[214:217], v[4:7]
	v_mfma_f32_16x16x32_bf16 v[160:163], v[206:209], v[160:163], v[0:3]
	s_barrier
	s_nop 0
	ds_read_b128 v[0:3], v158
	ds_read_b128 v[4:7], v158 offset:1024
	ds_read_b128 v[16:19], v158 offset:2048
	ds_read_b128 v[172:175], v158 offset:3072
	ds_read_b128 v[20:23], v154 offset:32768
	ds_read_b128 v[194:197], v154 offset:33792
	ds_read_b128 v[198:201], v153 offset:32768
	ds_read_b128 v[202:205], v153 offset:33792
	ds_read_b128 v[206:209], v151 offset:32768
	ds_read_b128 v[210:213], v151 offset:33792
	ds_read_b128 v[214:217], v150 offset:32768
	ds_read_b128 v[218:221], v150 offset:33792
	s_waitcnt vmcnt(2)
	s_barrier
; #define LDA(dst, b, h) for (int m = 0; m < 4; ++m) for (int k = 0; k < 2; ++k) \
;     dst[m][k] = *reinterpret_cast<const bf16x8*>((char*)SA(b, h) + lds_byte(wr * 64 + m * 16 + fr, k * 32 + fq * 8))
; #define LDB(dst, b, h) for (int n = 0; n < 2; ++n) for (int k = 0; k < 2; ++k) \
;     dst[n][k] = *reinterpret_cast<const bf16x8*>((char*)SB(b, h) + lds_byte(wc * 32 + n * 16 + fr, k * 32 + fq * 8))
; #define MMA(ai, bj, At_, Bt_) do { __builtin_amdgcn_s_setprio(1); \
;     for (int k = 0; k < 2; ++k) for (int m = 0; m < 4; ++m) for (int n = 0; n < 2; ++n) \
;       acc[ai][bj][m][n] = __builtin_amdgcn_mfma_f32_16x16x32_bf16(At_[m][k], Bt_[n][k], acc[ai][bj][m][n], 0, 0, 0); \
;     __builtin_amdgcn_s_setprio(0); } while (0)
; #define WAIT_V(n) asm volatile("s_waitcnt vmcnt(" #n ")" ::: "memory")
; #define WAIT_L(n) asm volatile("s_waitcnt lgkmcnt(" #n ")" ::: "memory")
; #define BAR __builtin_amdgcn_s_barrier()
; template <int EPI, int lda, int ldb, int N, int K>
; __device__ __forceinline__ void gemm_phase(const u16* __restrict__ A, const u16* __restrict__ Bt, const GemmEpi ep, int wv) {
;     ...
;     { LDB(B0, 1, 0); LDA(At, 1, 0); WAIT_V(2); BAR; WAIT_L(0); MMA(0, 0, At, B0); BAR;
;       LDB(B1, 1, 1); WAIT_V(0); BAR; WAIT_L(0); MMA(0, 1, At, B1); BAR;
;       LDA(At, 1, 1); BAR; WAIT_L(0); MMA(1, 0, At, B0); MMA(1, 1, At, B1); BAR; }
;     if (wr == 0) BAR;
	s_waitcnt lgkmcnt(0)
	s_waitcnt lgkmcnt(0)
	v_mfma_f32_16x16x32_bf16 v[64:67], v[20:23], v[0:3], v[124:127]
	v_mfma_f32_16x16x32_bf16 v[76:79], v[20:23], v[16:19], v[120:123]
	v_mfma_f32_16x16x32_bf16 v[80:83], v[198:201], v[0:3], v[116:119]
	v_mfma_f32_16x16x32_bf16 v[84:87], v[198:201], v[16:19], v[112:115]
	v_mfma_f32_16x16x32_bf16 v[108:111], v[206:209], v[0:3], v[108:111]
	v_mfma_f32_16x16x32_bf16 v[104:107], v[206:209], v[16:19], v[104:107]
	v_mfma_f32_16x16x32_bf16 v[120:123], v[214:217], v[0:3], v[100:103]
	v_mfma_f32_16x16x32_bf16 v[124:127], v[214:217], v[16:19], v[96:99]
	v_mfma_f32_16x16x32_bf16 v[116:119], v[194:197], v[4:7], v[64:67]
	v_mfma_f32_16x16x32_bf16 v[112:115], v[194:197], v[172:175], v[76:79]
	v_mfma_f32_16x16x32_bf16 v[100:103], v[202:205], v[4:7], v[80:83]
	v_mfma_f32_16x16x32_bf16 v[96:99], v[202:205], v[172:175], v[84:87]
	v_mfma_f32_16x16x32_bf16 v[84:87], v[210:213], v[4:7], v[108:111]
	v_mfma_f32_16x16x32_bf16 v[80:83], v[210:213], v[172:175], v[104:107]
	v_mfma_f32_16x16x32_bf16 v[76:79], v[218:221], v[4:7], v[120:123]
	v_mfma_f32_16x16x32_bf16 v[64:67], v[218:221], v[172:175], v[124:127]
	s_barrier
	ds_read_b128 v[222:225], v156
	ds_read_b128 v[226:229], v156 offset:1024
	ds_read_b128 v[230:233], v156 offset:2048
	ds_read_b128 v[156:159], v156 offset:3072
	s_waitcnt vmcnt(0)
	s_barrier
	s_waitcnt lgkmcnt(0)
	s_waitcnt lgkmcnt(0)
	v_mfma_f32_16x16x32_bf16 v[92:95], v[20:23], v[222:225], v[92:95]
	v_mfma_f32_16x16x32_bf16 v[20:23], v[20:23], v[230:233], v[88:91]
	v_mfma_f32_16x16x32_bf16 v[88:91], v[198:201], v[222:225], v[178:181]
	v_mfma_f32_16x16x32_bf16 v[104:107], v[198:201], v[230:233], v[182:185]
	v_mfma_f32_16x16x32_bf16 v[176:179], v[206:209], v[222:225], v[186:189]
	v_mfma_f32_16x16x32_bf16 v[72:75], v[206:209], v[230:233], v[72:75]
	v_mfma_f32_16x16x32_bf16 v[68:71], v[214:217], v[222:225], v[68:71]
	v_mfma_f32_16x16x32_bf16 v[180:183], v[214:217], v[230:233], v[190:193]
	v_mfma_f32_16x16x32_bf16 v[124:127], v[194:197], v[226:229], v[92:95]
	v_mfma_f32_16x16x32_bf16 v[120:123], v[194:197], v[156:159], v[20:23]
	v_mfma_f32_16x16x32_bf16 v[108:111], v[202:205], v[226:229], v[88:91]
	v_mfma_f32_16x16x32_bf16 v[104:107], v[202:205], v[156:159], v[104:107]
	v_mfma_f32_16x16x32_bf16 v[92:95], v[210:213], v[226:229], v[176:179]
	v_mfma_f32_16x16x32_bf16 v[88:91], v[210:213], v[156:159], v[72:75]
	v_mfma_f32_16x16x32_bf16 v[72:75], v[218:221], v[226:229], v[68:71]
	v_mfma_f32_16x16x32_bf16 v[68:71], v[218:221], v[156:159], v[180:183]
	s_barrier
	ds_read_b128 v[176:179], v154 offset:49152
	ds_read_b128 v[180:183], v154 offset:50176
	ds_read_b128 v[184:187], v153 offset:49152
	ds_read_b128 v[188:191], v153 offset:50176
	ds_read_b128 v[192:195], v151 offset:49152
	ds_read_b128 v[196:199], v151 offset:50176
	ds_read_b128 v[200:203], v150 offset:49152
	ds_read_b128 v[204:207], v150 offset:50176
	s_barrier
	s_waitcnt lgkmcnt(0)
	s_waitcnt lgkmcnt(0)
	v_mfma_f32_16x16x32_bf16 v[20:23], v[176:179], v[0:3], v[60:63]
	v_mfma_f32_16x16x32_bf16 v[56:59], v[176:179], v[16:19], v[56:59]
	v_mfma_f32_16x16x32_bf16 v[60:63], v[184:187], v[0:3], v[52:55]
	v_mfma_f32_16x16x32_bf16 v[208:211], v[184:187], v[16:19], v[48:51]
	v_mfma_f32_16x16x32_bf16 v[44:47], v[192:195], v[0:3], v[44:47]
	v_mfma_f32_16x16x32_bf16 v[40:43], v[192:195], v[16:19], v[40:43]
	v_mfma_f32_16x16x32_bf16 v[0:3], v[200:203], v[0:3], v[36:39]
	v_mfma_f32_16x16x32_bf16 v[212:215], v[200:203], v[16:19], v[32:35]
	v_mfma_f32_16x16x32_bf16 v[52:55], v[180:183], v[4:7], v[20:23]
	v_mfma_f32_16x16x32_bf16 v[48:51], v[180:183], v[172:175], v[56:59]
	v_mfma_f32_16x16x32_bf16 v[36:39], v[188:191], v[4:7], v[60:63]
	v_mfma_f32_16x16x32_bf16 v[32:35], v[188:191], v[172:175], v[208:211]
	v_mfma_f32_16x16x32_bf16 v[20:23], v[196:199], v[4:7], v[44:47]
	v_mfma_f32_16x16x32_bf16 v[16:19], v[196:199], v[172:175], v[40:43]
	v_mfma_f32_16x16x32_bf16 v[4:7], v[204:207], v[4:7], v[0:3]
	v_mfma_f32_16x16x32_bf16 v[0:3], v[204:207], v[172:175], v[212:215]
	v_mfma_f32_16x16x32_bf16 v[28:31], v[176:179], v[222:225], v[28:31]
	v_mfma_f32_16x16x32_bf16 v[24:27], v[176:179], v[230:233], v[24:27]
	v_mfma_f32_16x16x32_bf16 v[40:43], v[184:187], v[222:225], v[132:135]
	v_mfma_f32_16x16x32_bf16 v[132:135], v[184:187], v[230:233], v[136:139]
	v_mfma_f32_16x16x32_bf16 v[12:15], v[192:195], v[222:225], v[12:15]
	v_mfma_f32_16x16x32_bf16 v[8:11], v[192:195], v[230:233], v[8:11]
	v_mfma_f32_16x16x32_bf16 v[136:139], v[200:203], v[222:225], v[140:143]
	v_mfma_f32_16x16x32_bf16 v[140:143], v[200:203], v[230:233], v[160:163]
	v_mfma_f32_16x16x32_bf16 v[60:63], v[180:183], v[226:229], v[28:31]
	v_mfma_f32_16x16x32_bf16 v[56:59], v[180:183], v[156:159], v[24:27]
	v_mfma_f32_16x16x32_bf16 v[44:47], v[188:191], v[226:229], v[40:43]
	v_mfma_f32_16x16x32_bf16 v[40:43], v[188:191], v[156:159], v[132:135]
	v_mfma_f32_16x16x32_bf16 v[28:31], v[196:199], v[226:229], v[12:15]
	v_mfma_f32_16x16x32_bf16 v[24:27], v[196:199], v[156:159], v[8:11]
	v_mfma_f32_16x16x32_bf16 v[12:15], v[204:207], v[226:229], v[136:139]
	v_mfma_f32_16x16x32_bf16 v[8:11], v[204:207], v[156:159], v[140:143]
	v_cmp_gt_u32_e32 vcc, s46, v147
	s_barrier
	s_and_saveexec_b64 s[28:29], vcc
	s_cbranch_execz .LBB0_1627
	s_barrier
